# 219 sdwa-style f32->bf16 bit-trick packs (6 VALU each) replaced by v_cvt_pk_bf16_f32 (same RNE rounding), removed slots filled with s_nop to keep hazard distances; mostly FFN-up epilogues
# speedup vs baseline: 1.0052x; 1.0052x over previous
; __device__ __forceinline__ unsigned pk2(float lo, float hi) { return f2bf(lo) | (f2bf(hi) << 16); }
; __device__ __forceinline__ void rms_row_bf16(const Ctx& c, const float* xrow, const float* gain, bf16* orow, float* copy) {
;     const f32x4* xr = (const f32x4*)xrow + c.lane; f32x4 v[8]; float s = 0.f;
; #pragma unroll
;     for (int j = 0; j < 8; ++j) { v[j] = xr[64 * j]; s += (v[j].x * v[j].x + v[j].y * v[j].y) + (v[j].z * v[j].z + v[j].w * v[j].w); }
;     const float rs = rsqrtf(wave_sum(s) * (1.f / DM) + EPS);
;     if (copy) {
; #pragma unroll
;         for (int j = 0; j < 8; ++j) ((f32x4*)copy + c.lane)[64 * j] = v[j]; }
;     const f32x4* gr = (const f32x4*)gain + c.lane; v2u* o8 = (v2u*)orow + c.lane;
; #pragma unroll
;     for (int j = 0; j < 8; ++j) { const f32x4 g = gr[64 * j]; v2u o; o.x = pk2(v[j].x * rs * g.x, v[j].y * rs * g.y); o.y = pk2(v[j].z * rs * g.z, v[j].w * rs * g.w); o8[64 * j] = o; }
.LBB0_187:
	global_load_dwordx4 v[30:33], v[44:45], off offset:-4096
	global_load_dwordx4 v[26:29], v[44:45], off offset:-3072
	global_load_dwordx4 v[22:25], v[44:45], off offset:-2048
	global_load_dwordx4 v[14:17], v[44:45], off
	global_load_dwordx4 v[18:21], v[44:45], off offset:-1024
	global_load_dwordx4 v[10:13], v[44:45], off offset:1024
	global_load_dwordx4 v[2:5], v[44:45], off offset:3072
	global_load_dwordx4 v[6:9], v[44:45], off offset:2048
	global_load_dwordx4 v[56:59], v[34:35], off
	s_add_i32 s2, s2, s86
	v_lshl_add_u64 v[44:45], v[44:45], 0, s[6:7]
	s_cmpk_gt_i32 s2, 0x3ff
	s_waitcnt vmcnt(8)
	v_mov_b32_e32 v62, v31
	s_waitcnt vmcnt(7)
	v_mov_b32_e32 v63, v27
	v_mov_b32_e32 v66, v33
	v_mov_b32_e32 v67, v29
	v_mov_b32_e32 v60, v30
	v_mov_b32_e32 v61, v26
	v_mov_b32_e32 v64, v32
	v_mov_b32_e32 v65, v28
	s_waitcnt vmcnt(6)
	v_pk_mul_f32 v[68:69], v[24:25], v[24:25]
	v_pk_mul_f32 v[70:71], v[22:23], v[22:23]
	v_pk_mul_f32 v[62:63], v[62:63], v[62:63]
	v_pk_mul_f32 v[66:67], v[66:67], v[66:67]
	v_mov_b32_e32 v84, v30
	v_mov_b32_e32 v85, v32
	v_mov_b32_e32 v32, v31
	v_mov_b32_e32 v30, v26
	v_mov_b32_e32 v31, v28
	v_mov_b32_e32 v28, v27
	v_pk_mov_b32 v[26:27], v[70:71], v[68:69] op_sel:[1,0]
	v_mov_b32_e32 v71, v69
	v_pk_fma_f32 v[60:61], v[60:61], v[60:61], v[62:63]
	v_pk_fma_f32 v[62:63], v[64:65], v[64:65], v[66:67]
	s_waitcnt vmcnt(4)
	v_mul_f32_e32 v72, v19, v19
	v_mul_f32_e32 v74, v21, v21
	v_pk_add_f32 v[26:27], v[26:27], v[70:71]
	v_pk_add_f32 v[60:61], v[60:61], v[62:63]
	v_mul_f32_e32 v55, v14, v14
	v_mul_f32_e32 v81, v15, v15
	v_mul_f32_e32 v83, v16, v16
	v_mul_f32_e32 v88, v17, v17
	v_pk_fma_f32 v[68:69], v[18:19], v[18:19], v[72:73] op_sel_hi:[1,1,0]
	v_pk_fma_f32 v[72:73], v[20:21], v[20:21], v[74:75] op_sel_hi:[1,1,0]
	v_pk_add_f32 v[26:27], v[26:27], v[26:27] op_sel:[0,1] op_sel_hi:[1,0]
	v_pk_add_f32 v[60:61], v[60:61], v[60:61] op_sel:[0,1] op_sel_hi:[1,0]
	s_waitcnt vmcnt(3)
	v_pk_mul_f32 v[76:77], v[12:13], v[12:13]
	v_pk_mul_f32 v[78:79], v[10:11], v[10:11]
	v_mov_b32_e32 v69, v83
	v_mov_b32_e32 v73, v88
	v_mov_b32_e32 v27, v81
	v_mov_b32_e32 v61, v55
	s_waitcnt vmcnt(0)
	v_mov_b32_e32 v86, v56
	v_mov_b32_e32 v87, v58
	v_mov_b32_e32 v58, v57
	v_pk_mov_b32 v[56:57], v[78:79], v[76:77] op_sel:[1,0]
	v_mov_b32_e32 v79, v77
	v_pk_add_f32 v[62:63], v[68:69], v[72:73]
	v_pk_add_f32 v[26:27], v[60:61], v[26:27]
	v_mul_f32_e32 v80, v7, v7
	v_mul_f32_e32 v82, v9, v9
	v_pk_add_f32 v[56:57], v[56:57], v[78:79]
	v_pk_add_f32 v[26:27], v[26:27], v[62:63]
	v_mul_f32_e32 v89, v2, v2
	v_mul_f32_e32 v90, v3, v3
	v_mul_f32_e32 v91, v4, v4
	v_mul_f32_e32 v92, v5, v5
	v_pk_fma_f32 v[74:75], v[6:7], v[6:7], v[80:81] op_sel_hi:[1,1,0]
	v_pk_fma_f32 v[76:77], v[8:9], v[8:9], v[82:83] op_sel_hi:[1,1,0]
	v_pk_add_f32 v[56:57], v[56:57], v[56:57] op_sel:[0,1] op_sel_hi:[1,0]
	v_pk_add_f32 v[26:27], v[26:27], v[26:27] op_sel:[0,1] op_sel_hi:[1,0]
	v_mov_b32_e32 v75, v91
	v_mov_b32_e32 v77, v92
	v_mov_b32_e32 v57, v90
	v_mov_b32_e32 v27, v89
	v_pk_add_f32 v[64:65], v[74:75], v[76:77]
	v_pk_add_f32 v[26:27], v[26:27], v[56:57]
	s_nop 0
	v_pk_add_f32 v[26:27], v[26:27], v[64:65]
	s_nop 0
	v_add_f32_e32 v26, v26, v27
	ds_bpermute_b32 v27, v1, v26
	s_waitcnt lgkmcnt(0)
	v_add_f32_e32 v26, v26, v27
	ds_bpermute_b32 v27, v48, v26
	s_waitcnt lgkmcnt(0)
	v_add_f32_e32 v26, v26, v27
	ds_bpermute_b32 v27, v49, v26
	s_waitcnt lgkmcnt(0)
	v_add_f32_e32 v26, v26, v27
	ds_bpermute_b32 v27, v50, v26
	s_waitcnt lgkmcnt(0)
	v_add_f32_e32 v26, v26, v27
	ds_bpermute_b32 v27, v51, v26
	s_waitcnt lgkmcnt(0)
	v_add_f32_e32 v26, v26, v27
	ds_bpermute_b32 v27, v52, v26
	s_waitcnt lgkmcnt(0)
	v_add_f32_e32 v26, v26, v27
	v_fmamk_f32 v26, v26, 0x3a000000, v53
	v_mul_f32_e32 v27, 0x4b800000, v26
	v_cmp_gt_f32_e32 vcc, s0, v26
	s_nop 1
	v_cndmask_b32_e32 v26, v26, v27, vcc
	v_rsq_f32_e32 v26, v26
	s_nop 0
	v_mul_f32_e32 v27, 0x45800000, v26
	v_cndmask_b32_e32 v26, v26, v27, vcc
	v_pk_mul_f32 v[56:57], v[84:85], v[26:27] op_sel_hi:[1,0]
	v_pk_mul_f32 v[32:33], v[32:33], v[26:27] op_sel_hi:[1,0]
	v_pk_mul_f32 v[60:61], v[30:31], v[26:27] op_sel_hi:[1,0]
	v_pk_mul_f32 v[30:31], v[86:87], v[56:57]
	v_pk_mul_f32 v[32:33], v[58:59], v[32:33]
	v_and_b32_sdwa v27, v31, v54 dst_sel:DWORD dst_unused:UNUSED_PAD src0_sel:WORD_1 src1_sel:DWORD
	v_and_b32_sdwa v56, v33, v54 dst_sel:DWORD dst_unused:UNUSED_PAD src0_sel:WORD_1 src1_sel:DWORD
	s_nop 1
	v_add3_u32 v27, v31, v27, s1
	v_add3_u32 v31, v33, v56, s1
	s_nop 1
	v_and_b32_e32 v31, 0xffff0000, v31
	s_nop 0
	v_or_b32_sdwa v31, v31, v27 dst_sel:DWORD dst_unused:UNUSED_PAD src0_sel:DWORD src1_sel:WORD_1
	v_cvt_pk_bf16_f32 v30, v30, v32
	global_store_dwordx2 v[46:47], v[30:31], off
	global_load_dwordx4 v[30:33], v[34:35], off offset:1024
	v_pk_mul_f32 v[28:29], v[28:29], v[26:27] op_sel_hi:[1,0]
	s_waitcnt vmcnt(0)
; __device__ __forceinline__ unsigned pk2(float lo, float hi) { return f2bf(lo) | (f2bf(hi) << 16); }
; __device__ __forceinline__ void rms_row_bf16(const Ctx& c, const float* xrow, const float* gain, bf16* orow, float* copy) {
;     ...
;     const f32x4* gr = (const f32x4*)gain + c.lane; v2u* o8 = (v2u*)orow + c.lane;
; #pragma unroll
;     for (int j = 0; j < 8; ++j) { const f32x4 g = gr[64 * j]; v2u o; o.x = pk2(v[j].x * rs * g.x, v[j].y * rs * g.y); o.y = pk2(v[j].z * rs * g.z, v[j].w * rs * g.w); o8[64 * j] = o; }
	v_mov_b32_e32 v57, v32
	v_mov_b32_e32 v32, v31
	v_mov_b32_e32 v56, v30
	v_pk_mul_f32 v[28:29], v[32:33], v[28:29]
	v_pk_mul_f32 v[30:31], v[56:57], v[60:61]
	v_and_b32_sdwa v33, v29, v54 dst_sel:DWORD dst_unused:UNUSED_PAD src0_sel:WORD_1 src1_sel:DWORD
	s_nop 0
	v_and_b32_sdwa v27, v31, v54 dst_sel:DWORD dst_unused:UNUSED_PAD src0_sel:WORD_1 src1_sel:DWORD
	s_nop 0
	v_add3_u32 v29, v29, v33, s1
	s_nop 1
	v_add3_u32 v27, v31, v27, s1
	v_and_b32_e32 v29, 0xffff0000, v29
	s_nop 0
	v_or_b32_sdwa v29, v29, v27 dst_sel:DWORD dst_unused:UNUSED_PAD src0_sel:DWORD src1_sel:WORD_1
	v_cvt_pk_bf16_f32 v28, v30, v28
	global_store_dwordx2 v[46:47], v[28:29], off offset:512
	global_load_dwordx4 v[28:31], v[34:35], off offset:2048
	v_mov_b32_e32 v32, v22
	v_mov_b32_e32 v33, v24
	v_mov_b32_e32 v24, v23
	v_pk_mul_f32 v[22:23], v[32:33], v[26:27] op_sel_hi:[1,0]
	v_pk_mul_f32 v[24:25], v[24:25], v[26:27] op_sel_hi:[1,0]
	s_waitcnt vmcnt(0)
	v_mov_b32_e32 v33, v30
	v_mov_b32_e32 v30, v29
	v_mov_b32_e32 v32, v28
	v_pk_mul_f32 v[24:25], v[30:31], v[24:25]
	v_pk_mul_f32 v[22:23], v[32:33], v[22:23]
	v_and_b32_sdwa v29, v25, v54 dst_sel:DWORD dst_unused:UNUSED_PAD src0_sel:WORD_1 src1_sel:DWORD
	s_nop 0
	v_and_b32_sdwa v27, v23, v54 dst_sel:DWORD dst_unused:UNUSED_PAD src0_sel:WORD_1 src1_sel:DWORD
	s_nop 0
	v_add3_u32 v25, v25, v29, s1
	s_nop 1
	v_add3_u32 v23, v23, v27, s1
	v_and_b32_e32 v25, 0xffff0000, v25
	s_nop 0
	v_or_b32_sdwa v23, v25, v23 dst_sel:DWORD dst_unused:UNUSED_PAD src0_sel:DWORD src1_sel:WORD_1
	v_cvt_pk_bf16_f32 v22, v22, v24
	global_store_dwordx2 v[46:47], v[22:23], off offset:1024
	global_load_dwordx4 v[22:25], v[34:35], off offset:3072
	v_mov_b32_e32 v28, v18
	v_mov_b32_e32 v29, v20
	v_mov_b32_e32 v20, v19
	v_pk_mul_f32 v[18:19], v[28:29], v[26:27] op_sel_hi:[1,0]
	v_pk_mul_f32 v[20:21], v[20:21], v[26:27] op_sel_hi:[1,0]
	s_waitcnt vmcnt(0)
	v_mov_b32_e32 v29, v24
	v_mov_b32_e32 v24, v23
	v_mov_b32_e32 v28, v22
	v_pk_mul_f32 v[20:21], v[24:25], v[20:21]
	v_pk_mul_f32 v[18:19], v[28:29], v[18:19]
	s_nop 7
	s_nop 1
	v_cvt_pk_bf16_f32 v19, v19, v21
	v_cvt_pk_bf16_f32 v18, v18, v20
	global_store_dwordx2 v[46:47], v[18:19], off offset:1536
	global_load_dwordx4 v[18:21], v[36:37], off
	v_mov_b32_e32 v22, v14
	v_mov_b32_e32 v23, v16
	v_mov_b32_e32 v16, v15
	v_pk_mul_f32 v[14:15], v[22:23], v[26:27] op_sel_hi:[1,0]
	v_pk_mul_f32 v[16:17], v[16:17], v[26:27] op_sel_hi:[1,0]
	s_waitcnt vmcnt(0)
	v_mov_b32_e32 v23, v20
	v_mov_b32_e32 v20, v19
	v_mov_b32_e32 v22, v18
	v_pk_mul_f32 v[16:17], v[20:21], v[16:17]
	v_pk_mul_f32 v[14:15], v[22:23], v[14:15]
	s_nop 7
	s_nop 1
	v_cvt_pk_bf16_f32 v15, v15, v17
	v_cvt_pk_bf16_f32 v14, v14, v16
	global_store_dwordx2 v[46:47], v[14:15], off offset:2048
	global_load_dwordx4 v[14:17], v[38:39], off
	v_mov_b32_e32 v18, v10
	v_mov_b32_e32 v19, v12
	v_mov_b32_e32 v12, v11
	v_pk_mul_f32 v[10:11], v[18:19], v[26:27] op_sel_hi:[1,0]
	v_pk_mul_f32 v[12:13], v[12:13], v[26:27] op_sel_hi:[1,0]
	s_waitcnt vmcnt(0)
	v_mov_b32_e32 v19, v16
	v_mov_b32_e32 v16, v15
	v_mov_b32_e32 v18, v14
	v_pk_mul_f32 v[12:13], v[16:17], v[12:13]
	v_pk_mul_f32 v[10:11], v[18:19], v[10:11]
	s_nop 7
	s_nop 1
	v_cvt_pk_bf16_f32 v11, v11, v13
	v_cvt_pk_bf16_f32 v10, v10, v12
	global_store_dwordx2 v[46:47], v[10:11], off offset:2560
	global_load_dwordx4 v[10:13], v[40:41], off
	v_mov_b32_e32 v14, v6
	v_mov_b32_e32 v15, v8
	v_mov_b32_e32 v8, v7
	v_pk_mul_f32 v[6:7], v[14:15], v[26:27] op_sel_hi:[1,0]
	v_pk_mul_f32 v[8:9], v[8:9], v[26:27] op_sel_hi:[1,0]
	s_waitcnt vmcnt(0)
	v_mov_b32_e32 v15, v12
	v_mov_b32_e32 v12, v11
	v_mov_b32_e32 v14, v10
	v_pk_mul_f32 v[8:9], v[8:9], v[12:13]
	v_pk_mul_f32 v[6:7], v[6:7], v[14:15]
	s_nop 7
	s_nop 1
	v_cvt_pk_bf16_f32 v7, v7, v9
	v_cvt_pk_bf16_f32 v6, v6, v8
	global_store_dwordx2 v[46:47], v[6:7], off offset:3072
	global_load_dwordx4 v[6:9], v[42:43], off
	v_mov_b32_e32 v10, v2
	v_mov_b32_e32 v11, v4
	v_mov_b32_e32 v4, v3
	v_pk_mul_f32 v[2:3], v[10:11], v[26:27] op_sel_hi:[1,0]
	v_pk_mul_f32 v[4:5], v[4:5], v[26:27] op_sel_hi:[1,0]
	s_waitcnt vmcnt(0)
	v_mov_b32_e32 v11, v8
	v_mov_b32_e32 v8, v7
	v_mov_b32_e32 v10, v6
	v_pk_mul_f32 v[4:5], v[4:5], v[8:9]
	v_pk_mul_f32 v[2:3], v[2:3], v[10:11]
	v_and_b32_sdwa v8, v5, v54 dst_sel:DWORD dst_unused:UNUSED_PAD src0_sel:WORD_1 src1_sel:DWORD
	v_and_b32_sdwa v9, v4, v54 dst_sel:DWORD dst_unused:UNUSED_PAD src0_sel:WORD_1 src1_sel:DWORD
	v_and_b32_sdwa v6, v3, v54 dst_sel:DWORD dst_unused:UNUSED_PAD src0_sel:WORD_1 src1_sel:DWORD
	v_and_b32_sdwa v7, v2, v54 dst_sel:DWORD dst_unused:UNUSED_PAD src0_sel:WORD_1 src1_sel:DWORD
	v_add3_u32 v5, v5, v8, s1
	v_add3_u32 v4, v4, v9, s1
	v_add3_u32 v2, v2, v7, s1
	v_add3_u32 v3, v3, v6, s1
	v_and_b32_e32 v5, 0xffff0000, v5
	v_and_b32_e32 v4, 0xffff0000, v4
	v_or_b32_sdwa v3, v5, v3 dst_sel:DWORD dst_unused:UNUSED_PAD src0_sel:DWORD src1_sel:WORD_1
	v_or_b32_sdwa v2, v4, v2 dst_sel:DWORD dst_unused:UNUSED_PAD src0_sel:DWORD src1_sel:WORD_1
	global_store_dwordx2 v[46:47], v[2:3], off offset:3584
	v_lshl_add_u64 v[46:47], v[46:47], 0, s[8:9]
	s_cbranch_scc0 .LBB0_187

; #define LAS __attribute__((address_space(3)))
; __device__ __forceinline__ unsigned pk2(float lo, float hi) { return f2bf(lo) | (f2bf(hi) << 16); }
; __device__ __forceinline__ s16x4 tr16(const LAS unsigned char* p) { return __builtin_amdgcn_ds_read_tr16_b64_v4i16((LAS s16x4*)p); }
; __device__ __forceinline__ void ssd_scan_mfma(const Ctx& c, bf16* X2, const float* DT, const float* a_log, const float* dskip, bool do_store) {
;     ...
;                     for (int ks = 0; ks < 4; ++ks) { const bf16x8 sb = *(const LAS bf16x8*)(SBr + (16 * pt + l15) * 272 + (32 * ks + 8 * lg) * 2); Yo = __builtin_amdgcn_mfma_f32_16x16x32_bf16(sb, Cf[ks], Yo, 0, 0, 0); }
;                     const v2u xr = *(const LAS v2u*)(L + SS_XR + (16 * lt + l15) * 144 + (16 * pt + 4 * lg) * 2);
;                     const float y0 = Y[0] + el * Yo[0] + Dh * bflo(xr.x), y1 = Y[1] + el * Yo[1] + Dh * bfhi(xr.x), y2 = Y[2] + el * Yo[2] + Dh * bflo(xr.y), y3 = Y[3] + el * Yo[3] + Dh * bfhi(xr.y);
;                     v2u o; o.x = pk2(y0, y1); o.y = pk2(y2, y3);
;                     if (do_store) *(v2u*)(X2 + ((size_t)b * SEQ + t0 + 16 * lt + l15) * 6144 + h * 64 + 16 * pt + 4 * lg) = o; }
;                 const float e63 = __expf(CS[63]); const int pts = w >> 1;
;                 const LAS unsigned char* bb = L + SS_B + (8 * lg + tq) * 272 + tp * 8; const LAS unsigned char* xwb = L + SS_XW + (8 * lg + tq) * 144 + tp * 8 + pts * 32;
;                 bf16x8 Xf[2];
; #pragma unroll
;                 for (int ks = 0; ks < 2; ++ks) Xf[ks] = cat8(tr16(xwb + ks * 32 * 144), tr16(xwb + ks * 32 * 144 + 4 * 144));
; #pragma unroll
;                 for (int i = 0; i < 4; ++i) { const int nt = 4 * (w & 1) + i; ST[i] *= e63;
; #pragma unroll
;                     for (int ks = 0; ks < 2; ++ks) { const LAS unsigned char* bp = bb + ks * 32 * 272 + nt * 32;
;                         ST[i] = __builtin_amdgcn_mfma_f32_16x16x32_bf16(cat8(tr16(bp), tr16(bp + 4 * 272)), Xf[ks], ST[i], 0, 0, 0); }
;                     v2u q; q.x = pk2(ST[i][0], ST[i][1]); q.y = pk2(ST[i][2], ST[i][3]);
;                     *(LAS v2u*)(SBw + (16 * pts + l15) * 272 + (16 * nt + 4 * lg) * 2) = q; }
.LBB0_460:
	v_add_u32_e32 v46, v118, v121
	ds_read_b128 v[38:41], v46 offset:17408
	v_mov_b32_e32 v53, v52
	s_mov_b32 s63, s77
	s_add_i32 s64, s64, s33
	s_add_i32 s85, s85, s33
	s_cmpk_gt_i32 s64, 0xff
	s_waitcnt lgkmcnt(0)
	v_mfma_f32_16x16x32_bf16 v[34:37], v[38:41], v[34:37], 0
	ds_read_b128 v[38:41], v46 offset:17472
	s_waitcnt lgkmcnt(0)
	v_mfma_f32_16x16x32_bf16 v[30:33], v[38:41], v[30:33], v[34:37]
	s_nop 4
	ds_read_b128 v[34:37], v46 offset:17536
	s_waitcnt lgkmcnt(0)
	v_mfma_f32_16x16x32_bf16 v[26:29], v[34:37], v[26:29], v[30:33]
	s_nop 2
	ds_read_b128 v[30:33], v46 offset:17600
	s_waitcnt lgkmcnt(0)
	v_mfma_f32_16x16x32_bf16 v[22:25], v[30:33], v[22:25], v[26:29]
	s_nop 2
	ds_read_b64 v[26:27], v136 offset:34816
	v_mov_b32_e32 v31, v44
	v_mov_b32_e32 v44, v43
	s_nop 1
	v_mov_b32_e32 v29, v24
	v_mov_b32_e32 v24, v23
	v_mov_b32_e32 v28, v22
	v_mov_b32_e32 v30, v42
	v_pk_fma_f32 v[22:23], v[52:53], v[24:25], v[44:45]
	s_waitcnt lgkmcnt(0)
	v_and_b32_e32 v25, 0xffff0000, v27
	v_and_b32_e32 v24, 0xffff0000, v26
	v_pk_fma_f32 v[28:29], v[52:53], v[28:29], v[30:31]
	v_lshlrev_b32_e32 v31, 16, v27
	v_lshlrev_b32_e32 v30, 16, v26
	v_pk_fma_f32 v[22:23], v[94:95], v[24:25], v[22:23]
	v_pk_fma_f32 v[28:29], v[94:95], v[30:31], v[28:29]
	s_nop 7
	s_nop 1
	v_cvt_pk_bf16_f32 v23, v29, v23
	v_cvt_pk_bf16_f32 v22, v28, v22
	v_lshl_add_u64 v[24:25], v[50:51], 0, s[62:63]
	global_store_dwordx2 v[24:25], v[22:23], off
	v_mov_b32_e32 v22, s89
	ds_read_b32 v22, v22
	s_waitcnt lgkmcnt(0)
	v_mul_f32_e32 v30, 0x3fb8aa3b, v22
	ds_read_b64_tr_b16 v[26:27], v137 offset:53248
	ds_read_b64_tr_b16 v[28:29], v137 offset:53824
	ds_read_b64_tr_b16 v[22:23], v137 offset:57856
	ds_read_b64_tr_b16 v[24:25], v137 offset:58432
	v_exp_f32_e32 v30, v30
	ds_read_b64_tr_b16 v[32:33], v54
	ds_read_b64_tr_b16 v[34:35], v54 offset:1088
	v_pk_mul_f32 v[20:21], v[20:21], v[30:31] op_sel_hi:[1,0]
	v_pk_mul_f32 v[18:19], v[18:19], v[30:31] op_sel_hi:[1,0]
	s_waitcnt lgkmcnt(0)
	s_nop 0
	v_mfma_f32_16x16x32_bf16 v[18:21], v[32:35], v[26:29], v[18:21]
	ds_read_b64_tr_b16 v[32:33], v54 offset:8704
	ds_read_b64_tr_b16 v[34:35], v54 offset:9792
	s_waitcnt lgkmcnt(0)
	v_mfma_f32_16x16x32_bf16 v[18:21], v[32:35], v[22:25], v[18:21]
	s_nop 7
	v_bfe_u32 v31, v18, 16, 1
	v_add3_u32 v18, v18, v31, s88
	v_bfe_u32 v31, v19, 16, 1
	v_lshrrev_b32_e32 v18, 16, v18
	v_add3_u32 v19, v19, v31, s88
	v_and_or_b32 v18, v19, s87, v18
	v_bfe_u32 v19, v20, 16, 1
	v_add3_u32 v19, v20, v19, s88
	v_bfe_u32 v20, v21, 16, 1
	v_lshrrev_b32_e32 v19, 16, v19
	v_add3_u32 v20, v21, v20, s88
	v_and_or_b32 v19, v20, s87, v19
	ds_write_b64 v125, v[18:19] offset:62464
	ds_read_b64_tr_b16 v[18:19], v54 offset:32
	ds_read_b64_tr_b16 v[20:21], v54 offset:1120
	v_pk_mul_f32 v[16:17], v[16:17], v[30:31] op_sel_hi:[1,0]
	v_pk_mul_f32 v[14:15], v[14:15], v[30:31] op_sel_hi:[1,0]
	v_pk_mul_f32 v[12:13], v[12:13], v[30:31] op_sel_hi:[1,0]
	v_pk_mul_f32 v[10:11], v[10:11], v[30:31] op_sel_hi:[1,0]
	s_waitcnt lgkmcnt(0)
	v_mfma_f32_16x16x32_bf16 v[14:17], v[18:21], v[26:29], v[14:17]
	ds_read_b64_tr_b16 v[18:19], v54 offset:8736
	ds_read_b64_tr_b16 v[20:21], v54 offset:9824
	v_pk_mul_f32 v[8:9], v[8:9], v[30:31] op_sel_hi:[1,0]
	v_pk_mul_f32 v[6:7], v[6:7], v[30:31] op_sel_hi:[1,0]
	s_waitcnt lgkmcnt(0)
	v_mfma_f32_16x16x32_bf16 v[14:17], v[18:21], v[22:25], v[14:17]
	s_nop 7
	v_bfe_u32 v18, v14, 16, 1
	v_add3_u32 v14, v14, v18, s88
	v_bfe_u32 v18, v15, 16, 1
	v_lshrrev_b32_e32 v14, 16, v14
	v_add3_u32 v15, v15, v18, s88
	v_and_or_b32 v14, v15, s87, v14
	v_bfe_u32 v15, v16, 16, 1
	v_add3_u32 v15, v16, v15, s88
	v_bfe_u32 v16, v17, 16, 1
	v_lshrrev_b32_e32 v15, 16, v15
	v_add3_u32 v16, v17, v16, s88
	v_and_or_b32 v15, v16, s87, v15
	ds_write_b64 v125, v[14:15] offset:62496
	ds_read_b64_tr_b16 v[14:15], v54 offset:64
	ds_read_b64_tr_b16 v[16:17], v54 offset:1152
	s_waitcnt lgkmcnt(0)
	v_mfma_f32_16x16x32_bf16 v[10:13], v[14:17], v[26:29], v[10:13]
	ds_read_b64_tr_b16 v[14:15], v54 offset:8768
	ds_read_b64_tr_b16 v[16:17], v54 offset:9856
	s_waitcnt lgkmcnt(0)
	v_mfma_f32_16x16x32_bf16 v[10:13], v[14:17], v[22:25], v[10:13]
	s_nop 7
	v_bfe_u32 v14, v10, 16, 1
	v_add3_u32 v10, v10, v14, s88
	v_bfe_u32 v14, v11, 16, 1
	v_lshrrev_b32_e32 v10, 16, v10
	v_add3_u32 v11, v11, v14, s88
	v_and_or_b32 v10, v11, s87, v10
	v_bfe_u32 v11, v12, 16, 1
	v_add3_u32 v11, v12, v11, s88
	v_bfe_u32 v12, v13, 16, 1
	v_lshrrev_b32_e32 v11, 16, v11
	v_add3_u32 v12, v13, v12, s88
	v_and_or_b32 v11, v12, s87, v11
	ds_write_b64 v125, v[10:11] offset:62528
	ds_read_b64_tr_b16 v[10:11], v54 offset:96
	ds_read_b64_tr_b16 v[12:13], v54 offset:1184
	s_waitcnt lgkmcnt(0)
	v_mfma_f32_16x16x32_bf16 v[6:9], v[10:13], v[26:29], v[6:9]
	ds_read_b64_tr_b16 v[10:11], v54 offset:8800
	ds_read_b64_tr_b16 v[12:13], v54 offset:9888
	s_waitcnt lgkmcnt(0)
	v_mfma_f32_16x16x32_bf16 v[6:9], v[10:13], v[22:25], v[6:9]
	s_nop 7
	v_bfe_u32 v10, v6, 16, 1
	v_add3_u32 v6, v6, v10, s88
	v_bfe_u32 v10, v7, 16, 1
	v_lshrrev_b32_e32 v6, 16, v6
	v_add3_u32 v7, v7, v10, s88
	v_and_or_b32 v6, v7, s87, v6
	v_bfe_u32 v7, v8, 16, 1
	v_add3_u32 v7, v8, v7, s88
	v_bfe_u32 v8, v9, 16, 1
	v_lshrrev_b32_e32 v7, 16, v7
	v_add3_u32 v8, v9, v8, s88
	v_and_or_b32 v7, v8, s87, v7
	ds_write_b64 v125, v[6:7] offset:62560
	s_cbranch_scc1 .LBB0_493

; #define LAS __attribute__((address_space(3)))
; __device__ __forceinline__ unsigned pk2(float lo, float hi) { return f2bf(lo) | (f2bf(hi) << 16); }
; __device__ __forceinline__ s16x4 tr16(const LAS unsigned char* p) { return __builtin_amdgcn_ds_read_tr16_b64_v4i16((LAS s16x4*)p); }
; __device__ __forceinline__ void ssd_scan_mfma(const Ctx& c, bf16* X2, const float* DT, const float* a_log, const float* dskip, bool do_store) {
;     ...
;                 const float el = __expf(csl);
;                 const LAS unsigned char* xdb = L + SS_XD + (4 * lg + tq) * 144 + tp * 8;
; #pragma unroll
;                 for (int pp = 0; pp < 2; ++pp) { const int pt = 2 * ph + pp; f32x4 Y = (f32x4){0.f, 0.f, 0.f, 0.f}, Yo = (f32x4){0.f, 0.f, 0.f, 0.f};
; #pragma unroll
;                     for (int k2 = 0; k2 < 2; ++k2) if (2 * k2 <= lt) { const LAS unsigned char* xp = xdb + k2 * 32 * 144 + pt * 32;
;                         Y = __builtin_amdgcn_mfma_f32_16x16x32_bf16(cat8(tr16(xp), tr16(xp + 16 * 144)), Lf[k2], Y, 0, 0, 0); }
; #pragma unroll
;                     for (int ks = 0; ks < 4; ++ks) { const bf16x8 sb = *(const LAS bf16x8*)(SBr + (16 * pt + l15) * 272 + (32 * ks + 8 * lg) * 2); Yo = __builtin_amdgcn_mfma_f32_16x16x32_bf16(sb, Cf[ks], Yo, 0, 0, 0); }
;                     const v2u xr = *(const LAS v2u*)(L + SS_XR + (16 * lt + l15) * 144 + (16 * pt + 4 * lg) * 2);
;                     const float y0 = Y[0] + el * Yo[0] + Dh * bflo(xr.x), y1 = Y[1] + el * Yo[1] + Dh * bfhi(xr.x), y2 = Y[2] + el * Yo[2] + Dh * bflo(xr.y), y3 = Y[3] + el * Yo[3] + Dh * bfhi(xr.y);
;                     v2u o; o.x = pk2(y0, y1); o.y = pk2(y2, y3);
;                     if (do_store) *(v2u*)(X2 + ((size_t)b * SEQ + t0 + 16 * lt + l15) * 6144 + h * 64 + 16 * pt + 4 * lg) = o; }
.LBB0_491:
	s_lshl_b32 s76, s2, 1
	v_lshl_add_u64 v[56:57], s[0:1], 0, v[74:75]
	v_lshl_add_u64 v[58:59], v[76:77], 0, s[76:77]
	v_mul_f32_e32 v50, 0x3fb8aa3b, v50
	s_movk_i32 s0, 0x3000
	v_exp_f32_e32 v52, v50
	v_mad_u64_u32 v[50:51], s[50:51], v56, s0, v[58:59]
	v_add_u32_e32 v53, v118, v120
	v_mad_i32_i24 v51, v57, s0, v51
	ds_read_b128 v[56:59], v53 offset:17408
	ds_read_b128 v[60:63], v53 offset:17472
	s_waitcnt lgkmcnt(1)
	v_mfma_f32_16x16x32_bf16 v[56:59], v[56:59], v[34:37], 0
	v_mov_b32_e32 v65, v48
	v_mov_b32_e32 v48, v47
	v_mov_b32_e32 v64, v46
	s_waitcnt lgkmcnt(0)
	v_mfma_f32_16x16x32_bf16 v[56:59], v[60:63], v[30:33], v[56:59]
	ds_read_b128 v[60:63], v53 offset:17536
	v_readlane_b32 s0, v254, 50
	s_mov_b64 s[50:51], 0x2f40000
	s_waitcnt lgkmcnt(0)
	v_mfma_f32_16x16x32_bf16 v[56:59], v[60:63], v[26:29], v[56:59]
	ds_read_b128 v[60:63], v53 offset:17600
	v_readlane_b32 s1, v254, 51
	v_lshl_add_u64 v[50:51], v[50:51], 0, s[50:51]
	s_waitcnt lgkmcnt(0)
	v_mfma_f32_16x16x32_bf16 v[56:59], v[60:63], v[22:25], v[56:59]
	ds_read_b64 v[60:61], v134 offset:34816
	s_mov_b32 s1, s77
	s_and_b64 vcc, exec, s[52:53]
	s_nop 4
	v_mov_b32_e32 v63, v58
	v_mov_b32_e32 v58, v57
	v_mov_b32_e32 v62, v56
	v_pk_fma_f32 v[46:47], v[52:53], v[58:59], v[48:49] op_sel_hi:[0,1,1]
	s_waitcnt lgkmcnt(0)
	v_and_b32_e32 v49, 0xffff0000, v61
	v_and_b32_e32 v48, 0xffff0000, v60
	v_pk_fma_f32 v[62:63], v[52:53], v[62:63], v[64:65] op_sel_hi:[0,1,1]
	v_lshlrev_b32_e32 v65, 16, v61
	v_lshlrev_b32_e32 v64, 16, v60
	v_pk_fma_f32 v[46:47], v[94:95], v[48:49], v[46:47]
	v_pk_fma_f32 v[62:63], v[94:95], v[64:65], v[62:63]
	s_nop 7
	s_nop 1
	v_cvt_pk_bf16_f32 v47, v63, v47
	v_cvt_pk_bf16_f32 v46, v62, v46
	v_lshl_add_u64 v[48:49], v[50:51], 0, s[0:1]
	global_store_dwordx2 v[48:49], v[46:47], off
	ds_read_b64_tr_b16 v[46:47], v68 offset:44032
	ds_read_b64_tr_b16 v[48:49], v68 offset:46336
	s_waitcnt lgkmcnt(0)
	v_mfma_f32_16x16x32_bf16 v[42:45], v[46:49], v[42:45], 0
	s_cbranch_vccnz .LBB0_460
	ds_read_b64_tr_b16 v[46:47], v68 offset:48640
	ds_read_b64_tr_b16 v[48:49], v68 offset:50944
	s_waitcnt lgkmcnt(0)
	v_mfma_f32_16x16x32_bf16 v[42:45], v[46:49], v[38:41], v[42:45]
	s_branch .LBB0_460

; __device__ __forceinline__ unsigned pk2(float lo, float hi) { return f2bf(lo) | (f2bf(hi) << 16); }
; __device__ __forceinline__ float silu_fast(float x) { return x * __builtin_amdgcn_rcpf(1.f + __builtin_amdgcn_exp2f(-1.4426950408889634f * x)); }
; __device__ __forceinline__ float dpp_shr1(float x) { return __builtin_bit_cast(float, __builtin_amdgcn_update_dpp(0, __builtin_bit_cast(int, x), 0x111, 0xf, 0xf, true)); }
;     __device__ __forceinline__ void operator()(const f32x4 (&acc)[2][2][4][2], const pg8::Unit& u, int wr, int wc, int fr, int fq) const {
;     ...
;             const int cc = ch0 + 4 * n;
;             const f32x4 wg0 = *(CF4)(cw + cc), wg1 = *(CF4)(cw + FF2 + cc), wg2 = *(CF4)(cw + 2 * FF2 + cc), wv0 = *(CF4)(cw + FFH + cc), wv1 = *(CF4)(cw + FF2 + FFH + cc), wv2 = *(CF4)(cw + 2 * FF2 + FFH + cc);
;             const f32x4 bg = *(CF4)(cb + cc), bv = *(CF4)(cb + FFH + cc);
; #pragma unroll
;             for (int jj = 0; jj < 4; ++jj) {
;                 float g2 = dpp_shr1(g[6][jj]), g1 = dpp_shr1(g[7][jj]), v2 = dpp_shr1(v[6][jj]), v1 = dpp_shr1(v[7][jj]);
; #pragma unroll
;                 for (int e = 0; e < 8; ++e) { const float g0 = g[e][jj], v0 = v[e][jj];
;                     const float cg = bg[jj] + wg0[jj] * g2 + wg1[jj] * g1 + wg2[jj] * g0, cv = bv[jj] + wv0[jj] * v2 + wv1[jj] * v1 + wv2[jj] * v0;
;                     g[e][jj] = silu_fast(cg) * cv; g2 = g1; g1 = g0; v2 = v1; v1 = v0; } }
; #pragma unroll
;             for (int e = 0; e < 8; ++e) { v2u w; w.x = pk2(g[e][0], g[e][1]); w.y = pk2(g[e][2], g[e][3]); *(v2u*)(ACT + (size_t)(tok0 + e) * FFH + cc) = w; }
.LBB0_1249:
	s_or_b64 exec, exec, s[28:29]
	v_or_b32_e32 v38, 4, v132
	v_ashrrev_i32_e32 v39, 31, v38
	v_lshlrev_b64 v[64:65], 2, v[38:39]
	v_lshl_add_u64 v[38:39], s[8:9], 0, v[64:65]
	v_lshl_add_u64 v[44:45], s[14:15], 0, v[64:65]
	global_load_dwordx4 v[56:59], v[38:39], off
	global_load_dwordx4 v[52:55], v[138:139], off offset:16
	v_lshl_add_u64 v[48:49], s[16:17], 0, v[64:65]
	global_load_dwordx4 v[44:47], v[44:45], off
	v_lshl_add_u64 v[38:39], s[10:11], 0, v[64:65]
	global_load_dwordx4 v[60:63], v[38:39], off
	v_lshl_add_u64 v[38:39], s[12:13], 0, v[64:65]
	global_load_dwordx4 v[38:41], v[38:39], off
	s_nop 0
	global_load_dwordx4 v[48:51], v[48:49], off
	s_nop 0
	global_load_dwordx4 v[68:71], v[134:135], off offset:16
	v_lshl_add_u64 v[64:65], s[18:19], 0, v[64:65]
	global_load_dwordx4 v[64:67], v[64:65], off
	v_mov_b32_dpp v106, v88 row_shr:1 row_mask:0xf bank_mask:0xf bound_ctrl:1
	v_mov_b32_dpp v107, v89 row_shr:1 row_mask:0xf bank_mask:0xf bound_ctrl:1
	v_mov_b32_dpp v136, v94 row_shr:1 row_mask:0xf bank_mask:0xf bound_ctrl:1
	v_mov_b32_dpp v137, v95 row_shr:1 row_mask:0xf bank_mask:0xf bound_ctrl:1
	v_mov_b32_dpp v158, v86 row_shr:1 row_mask:0xf bank_mask:0xf bound_ctrl:1
	v_mov_b32_dpp v159, v87 row_shr:1 row_mask:0xf bank_mask:0xf bound_ctrl:1
	v_mov_b32_dpp v134, v90 row_shr:1 row_mask:0xf bank_mask:0xf bound_ctrl:1
	v_mov_b32_dpp v135, v91 row_shr:1 row_mask:0xf bank_mask:0xf bound_ctrl:1
	v_mov_b32_dpp v138, v82 row_shr:1 row_mask:0xf bank_mask:0xf bound_ctrl:1
	v_mov_b32_dpp v160, v72 row_shr:1 row_mask:0xf bank_mask:0xf bound_ctrl:1
	v_mov_b32_dpp v139, v83 row_shr:1 row_mask:0xf bank_mask:0xf bound_ctrl:1
	v_mov_b32_dpp v161, v73 row_shr:1 row_mask:0xf bank_mask:0xf bound_ctrl:1
	v_mov_b32_dpp v132, v84 row_shr:1 row_mask:0xf bank_mask:0xf bound_ctrl:1
	v_mov_b32_dpp v130, v74 row_shr:1 row_mask:0xf bank_mask:0xf bound_ctrl:1
	v_mov_b32_dpp v133, v85 row_shr:1 row_mask:0xf bank_mask:0xf bound_ctrl:1
	v_mov_b32_dpp v131, v75 row_shr:1 row_mask:0xf bank_mask:0xf bound_ctrl:1
	s_andn2_b64 vcc, exec, s[0:1]
	s_mov_b32 s57, s20
	s_mov_b32 s28, s22
	s_mov_b64 s[34:35], s[26:27]
	s_mov_b64 s[30:31], s[24:25]
	s_waitcnt vmcnt(0)
	v_mov_b32_e32 v98, v52
	v_mov_b32_e32 v99, v54
	v_mov_b32_e32 v54, v53
	v_mov_b32_e32 v102, v68
	v_mov_b32_e32 v103, v70
	v_pk_fma_f32 v[110:111], v[98:99], v[106:107], v[102:103]
	v_mov_b32_e32 v106, v56
	v_mov_b32_e32 v107, v58
	v_pk_fma_f32 v[162:163], v[106:107], v[136:137], v[110:111]
	v_mov_b32_e32 v110, v60
	v_mov_b32_e32 v111, v62
	v_pk_fma_f32 v[162:163], v[126:127], v[110:111], v[162:163]
	v_mov_b32_e32 v70, v69
	v_mul_f32_e32 v52, 0xbfb8aa3b, v162
	v_exp_f32_e32 v52, v52
	v_mov_b32_e32 v58, v57
	v_mov_b32_e32 v62, v61
	v_mov_b32_e32 v60, v44
	v_add_f32_e32 v52, 1.0, v52
	v_rcp_f32_e32 v168, v52
	v_pk_fma_f32 v[52:53], v[54:55], v[158:159], v[70:71]
	v_mov_b32_e32 v56, v64
	v_pk_fma_f32 v[52:53], v[58:59], v[134:135], v[52:53]
	v_mov_b32_e32 v57, v66
	v_pk_fma_f32 v[158:159], v[124:125], v[62:63], v[52:53]
	v_mov_b32_e32 v53, v40
	v_mul_f32_e32 v52, 0xbfb8aa3b, v158
	v_exp_f32_e32 v52, v52
	v_mul_f32_e32 v44, 0xbfb8aa3b, v159
	v_exp_f32_e32 v44, v44
	v_mov_b32_e32 v40, v39
	v_add_f32_e32 v52, 1.0, v52
	v_rcp_f32_e32 v172, v52
	v_mov_b32_e32 v52, v38
	v_mul_f32_e32 v38, 0xbfb8aa3b, v163
	v_exp_f32_e32 v38, v38
	v_add_f32_e32 v44, 1.0, v44
	v_rcp_f32_e32 v173, v44
	v_mov_b32_e32 v66, v65
	v_add_f32_e32 v38, 1.0, v38
	v_pk_fma_f32 v[68:69], v[52:53], v[138:139], v[56:57]
	v_mov_b32_e32 v61, v46
	v_rcp_f32_e32 v169, v38
	v_pk_fma_f32 v[38:39], v[40:41], v[160:161], v[66:67]
	v_mov_b32_e32 v46, v45
	v_pk_fma_f32 v[138:139], v[60:61], v[132:133], v[68:69]
	v_mov_b32_e32 v69, v50
	v_pk_fma_f32 v[38:39], v[46:47], v[130:131], v[38:39]
	v_mov_b32_e32 v50, v49
	v_pk_fma_f32 v[38:39], v[120:121], v[50:51], v[38:39]
	v_pk_mul_f32 v[44:45], v[158:159], v[172:173]
	v_mov_b32_e32 v68, v48
	v_pk_mul_f32 v[38:39], v[38:39], v[44:45]
	v_pk_fma_f32 v[138:139], v[122:123], v[68:69], v[138:139]
	v_pk_mul_f32 v[162:163], v[162:163], v[168:169]
	v_and_b32_sdwa v48, v39, v238 dst_sel:DWORD dst_unused:UNUSED_PAD src0_sel:WORD_1 src1_sel:DWORD
	v_and_b32_sdwa v49, v38, v238 dst_sel:DWORD dst_unused:UNUSED_PAD src0_sel:WORD_1 src1_sel:DWORD
	v_pk_mul_f32 v[138:139], v[138:139], v[162:163]
	v_add3_u32 v39, v39, v48, s55
	v_add3_u32 v38, v38, v49, s55
	v_pk_fma_f32 v[48:49], v[54:55], v[134:135], v[70:71]
	v_and_b32_sdwa v45, v138, v238 dst_sel:DWORD dst_unused:UNUSED_PAD src0_sel:WORD_1 src1_sel:DWORD
	v_pk_fma_f32 v[48:49], v[124:125], v[58:59], v[48:49]
	v_add3_u32 v45, v138, v45, s55
	v_and_b32_e32 v38, 0xffff0000, v38
	v_pk_fma_f32 v[48:49], v[116:117], v[62:63], v[48:49]
	v_and_b32_sdwa v44, v139, v238 dst_sel:DWORD dst_unused:UNUSED_PAD src0_sel:WORD_1 src1_sel:DWORD
	v_or_b32_sdwa v38, v38, v45 dst_sel:DWORD dst_unused:UNUSED_PAD src0_sel:DWORD src1_sel:WORD_1
	v_mul_f32_e32 v45, 0xbfb8aa3b, v48
	v_add3_u32 v44, v139, v44, s55
	v_and_b32_e32 v39, 0xffff0000, v39
	v_exp_f32_e32 v45, v45
	v_or_b32_sdwa v39, v39, v44 dst_sel:DWORD dst_unused:UNUSED_PAD src0_sel:DWORD src1_sel:WORD_1
	global_store_dwordx2 v[170:171], v[38:39], off offset:8
	v_pk_fma_f32 v[38:39], v[98:99], v[136:137], v[102:103]
	v_add_f32_e32 v45, 1.0, v45
	v_pk_fma_f32 v[38:39], v[126:127], v[106:107], v[38:39]
	v_rcp_f32_e32 v64, v45
	v_pk_fma_f32 v[38:39], v[112:113], v[110:111], v[38:39]
	v_mul_f32_e32 v65, 0xbfb8aa3b, v49
	v_mul_f32_e32 v44, 0xbfb8aa3b, v38
	v_mul_f32_e32 v45, 0xbfb8aa3b, v39
	v_exp_f32_e32 v44, v44
	v_exp_f32_e32 v45, v45
	v_exp_f32_e32 v65, v65
	v_pk_fma_f32 v[132:133], v[52:53], v[132:133], v[56:57]
	v_add_f32_e32 v44, 1.0, v44
; __device__ __forceinline__ unsigned pk2(float lo, float hi) { return f2bf(lo) | (f2bf(hi) << 16); }
; __device__ __forceinline__ float silu_fast(float x) { return x * __builtin_amdgcn_rcpf(1.f + __builtin_amdgcn_exp2f(-1.4426950408889634f * x)); }
; __device__ __forceinline__ float dpp_shr1(float x) { return __builtin_bit_cast(float, __builtin_amdgcn_update_dpp(0, __builtin_bit_cast(int, x), 0x111, 0xf, 0xf, true)); }
;     __device__ __forceinline__ void operator()(const f32x4 (&acc)[2][2][4][2], const pg8::Unit& u, int wr, int wc, int fr, int fq) const {
;     ...
;             const int cc = ch0 + 4 * n;
;             const f32x4 wg0 = *(CF4)(cw + cc), wg1 = *(CF4)(cw + FF2 + cc), wg2 = *(CF4)(cw + 2 * FF2 + cc), wv0 = *(CF4)(cw + FFH + cc), wv1 = *(CF4)(cw + FF2 + FFH + cc), wv2 = *(CF4)(cw + 2 * FF2 + FFH + cc);
;             const f32x4 bg = *(CF4)(cb + cc), bv = *(CF4)(cb + FFH + cc);
; #pragma unroll
;             for (int jj = 0; jj < 4; ++jj) {
;                 float g2 = dpp_shr1(g[6][jj]), g1 = dpp_shr1(g[7][jj]), v2 = dpp_shr1(v[6][jj]), v1 = dpp_shr1(v[7][jj]);
; #pragma unroll
;                 for (int e = 0; e < 8; ++e) { const float g0 = g[e][jj], v0 = v[e][jj];
;                     const float cg = bg[jj] + wg0[jj] * g2 + wg1[jj] * g1 + wg2[jj] * g0, cv = bv[jj] + wv0[jj] * v2 + wv1[jj] * v1 + wv2[jj] * v0;
;                     g[e][jj] = silu_fast(cg) * cv; g2 = g1; g1 = g0; v2 = v1; v1 = v0; } }
; #pragma unroll
;             for (int e = 0; e < 8; ++e) { v2u w; w.x = pk2(g[e][0], g[e][1]); w.y = pk2(g[e][2], g[e][3]); *(v2u*)(ACT + (size_t)(tok0 + e) * FFH + cc) = w; }
	v_add_f32_e32 v45, 1.0, v45
	v_rcp_f32_e32 v44, v44
	v_rcp_f32_e32 v45, v45
	v_add_f32_e32 v65, 1.0, v65
	v_rcp_f32_e32 v65, v65
	v_pk_fma_f32 v[132:133], v[122:123], v[60:61], v[132:133]
	v_pk_mul_f32 v[38:39], v[38:39], v[44:45]
	v_pk_fma_f32 v[44:45], v[40:41], v[130:131], v[66:67]
	v_pk_fma_f32 v[132:133], v[114:115], v[68:69], v[132:133]
	v_pk_fma_f32 v[44:45], v[120:121], v[46:47], v[44:45]
	v_pk_mul_f32 v[38:39], v[132:133], v[38:39]
	v_pk_fma_f32 v[44:45], v[118:119], v[50:51], v[44:45]
	v_pk_mul_f32 v[48:49], v[48:49], v[64:65]
	s_nop 0
	v_pk_mul_f32 v[44:45], v[44:45], v[48:49]
	s_nop 7
	s_nop 1
	v_cvt_pk_bf16_f32 v39, v39, v45
	v_cvt_pk_bf16_f32 v38, v38, v44
	v_mov_b32_e32 v44, v33
	v_mov_b32_e32 v45, v35
	v_mov_b32_e32 v33, v34
	v_pk_fma_f32 v[34:35], v[124:125], v[54:55], v[70:71]
	v_pk_mul_f32 v[44:45], v[44:45], v[128:129]
	v_pk_fma_f32 v[34:35], v[116:117], v[58:59], v[34:35]
	global_store_dwordx2 v[108:109], v[38:39], off offset:8
	v_pk_fma_f32 v[34:35], v[44:45], v[62:63], v[34:35]
	v_mov_b32_e32 v39, v31
	v_mul_f32_e32 v31, 0xbfb8aa3b, v34
	v_exp_f32_e32 v31, v31
	v_mov_b32_e32 v38, v29
	v_mov_b32_e32 v29, v30
	v_pk_mul_f32 v[48:49], v[28:29], v[128:129]
	v_pk_fma_f32 v[28:29], v[126:127], v[98:99], v[102:103]
	v_pk_mul_f32 v[32:33], v[32:33], v[128:129]
	v_pk_fma_f32 v[28:29], v[112:113], v[106:107], v[28:29]
	v_add_f32_e32 v31, 1.0, v31
	v_pk_fma_f32 v[28:29], v[32:33], v[110:111], v[28:29]
	v_rcp_f32_e32 v64, v31
	v_mul_f32_e32 v30, 0xbfb8aa3b, v28
	v_mul_f32_e32 v31, 0xbfb8aa3b, v29
	v_exp_f32_e32 v30, v30
	v_exp_f32_e32 v31, v31
	v_mul_f32_e32 v65, 0xbfb8aa3b, v35
	v_exp_f32_e32 v65, v65
	v_add_f32_e32 v30, 1.0, v30
	v_add_f32_e32 v31, 1.0, v31
	v_rcp_f32_e32 v30, v30
	v_rcp_f32_e32 v31, v31
	v_add_f32_e32 v65, 1.0, v65
	v_rcp_f32_e32 v65, v65
	v_pk_fma_f32 v[108:109], v[122:123], v[52:53], v[56:57]
	v_pk_mul_f32 v[28:29], v[28:29], v[30:31]
	v_pk_fma_f32 v[108:109], v[114:115], v[60:61], v[108:109]
	v_pk_fma_f32 v[30:31], v[120:121], v[40:41], v[66:67]
	v_pk_mul_f32 v[38:39], v[38:39], v[128:129]
	v_pk_fma_f32 v[108:109], v[48:49], v[68:69], v[108:109]
	v_pk_fma_f32 v[30:31], v[118:119], v[46:47], v[30:31]
	v_pk_mul_f32 v[28:29], v[108:109], v[28:29]
	v_pk_fma_f32 v[30:31], v[38:39], v[50:51], v[30:31]
	v_pk_mul_f32 v[34:35], v[34:35], v[64:65]
	s_nop 0
	v_pk_mul_f32 v[30:31], v[30:31], v[34:35]
	s_nop 7
	s_nop 1
	v_cvt_pk_bf16_f32 v29, v29, v31
	v_cvt_pk_bf16_f32 v28, v28, v30
	v_mov_b32_e32 v30, v25
	v_mov_b32_e32 v31, v27
	v_pk_fma_f32 v[34:35], v[116:117], v[54:55], v[70:71]
	v_pk_mul_f32 v[30:31], v[30:31], v[42:43]
	v_pk_fma_f32 v[34:35], v[44:45], v[58:59], v[34:35]
	v_mov_b32_e32 v25, v26
	v_pk_fma_f32 v[34:35], v[30:31], v[62:63], v[34:35]
	global_store_dwordx2 v[104:105], v[28:29], off offset:8
	v_mul_f32_e32 v65, 0xbfb8aa3b, v34
	v_exp_f32_e32 v65, v65
	v_mov_b32_e32 v28, v21
	v_mov_b32_e32 v29, v23
	v_mov_b32_e32 v21, v22
	v_pk_mul_f32 v[22:23], v[24:25], v[42:43]
	v_pk_fma_f32 v[24:25], v[112:113], v[98:99], v[102:103]
	v_add_f32_e32 v65, 1.0, v65
	v_pk_fma_f32 v[24:25], v[32:33], v[106:107], v[24:25]
	v_rcp_f32_e32 v104, v65
	v_pk_fma_f32 v[24:25], v[22:23], v[110:111], v[24:25]
	v_pk_fma_f32 v[26:27], v[114:115], v[52:53], v[56:57]
	v_mul_f32_e32 v64, 0xbfb8aa3b, v24
	v_mul_f32_e32 v65, 0xbfb8aa3b, v25
	v_exp_f32_e32 v64, v64
	v_exp_f32_e32 v65, v65
	v_pk_mul_f32 v[20:21], v[20:21], v[42:43]
	v_pk_fma_f32 v[26:27], v[48:49], v[60:61], v[26:27]
	v_add_f32_e32 v64, 1.0, v64
	v_add_f32_e32 v65, 1.0, v65
	v_rcp_f32_e32 v64, v64
	v_rcp_f32_e32 v65, v65
	v_pk_mul_f32 v[28:29], v[28:29], v[42:43]
	v_pk_fma_f32 v[42:43], v[118:119], v[40:41], v[66:67]
	v_pk_fma_f32 v[26:27], v[20:21], v[68:69], v[26:27]
	v_pk_mul_f32 v[24:25], v[24:25], v[64:65]
	s_nop 0
	v_pk_mul_f32 v[24:25], v[26:27], v[24:25]
	v_pk_fma_f32 v[26:27], v[38:39], v[46:47], v[42:43]
	v_mul_f32_e32 v42, 0xbfb8aa3b, v35
	v_exp_f32_e32 v42, v42
	v_pk_fma_f32 v[26:27], v[28:29], v[50:51], v[26:27]
	v_add_f32_e32 v42, 1.0, v42
	v_rcp_f32_e32 v105, v42
	s_nop 0
	v_pk_mul_f32 v[34:35], v[34:35], v[104:105]
	s_nop 0
	v_pk_mul_f32 v[26:27], v[26:27], v[34:35]
	s_nop 7
	s_nop 1
	v_cvt_pk_bf16_f32 v25, v25, v27
	v_cvt_pk_bf16_f32 v24, v24, v26
	v_mov_b32_e32 v26, v17
	v_mov_b32_e32 v27, v19
	v_mov_b32_e32 v17, v18
	v_pk_fma_f32 v[18:19], v[44:45], v[54:55], v[70:71]
	v_pk_mul_f32 v[26:27], v[26:27], v[92:93]
	v_pk_fma_f32 v[18:19], v[30:31], v[58:59], v[18:19]
	global_store_dwordx2 v[100:101], v[24:25], off offset:8
	v_mov_b32_e32 v24, v13
	v_mov_b32_e32 v13, v14
	v_pk_fma_f32 v[18:19], v[26:27], v[62:63], v[18:19]
	v_pk_mul_f32 v[34:35], v[12:13], v[92:93]
	v_pk_fma_f32 v[12:13], v[32:33], v[98:99], v[102:103]
	v_pk_fma_f32 v[32:33], v[38:39], v[40:41], v[66:67]
	v_mul_f32_e32 v39, 0xbfb8aa3b, v18
	v_exp_f32_e32 v39, v39
	v_pk_mul_f32 v[16:17], v[16:17], v[92:93]
	v_pk_fma_f32 v[12:13], v[22:23], v[106:107], v[12:13]
	v_mov_b32_e32 v25, v15
	v_pk_fma_f32 v[12:13], v[16:17], v[110:111], v[12:13]
	v_add_f32_e32 v39, 1.0, v39
	v_mul_f32_e32 v38, 0xbfb8aa3b, v12
	v_rcp_f32_e32 v42, v39
	v_mul_f32_e32 v39, 0xbfb8aa3b, v13
	v_exp_f32_e32 v38, v38
	v_exp_f32_e32 v39, v39
	v_pk_fma_f32 v[14:15], v[48:49], v[52:53], v[56:57]
	v_pk_mul_f32 v[24:25], v[24:25], v[92:93]
	v_add_f32_e32 v38, 1.0, v38
	v_add_f32_e32 v39, 1.0, v39
	v_rcp_f32_e32 v38, v38
	v_rcp_f32_e32 v39, v39
	v_pk_fma_f32 v[14:15], v[20:21], v[60:61], v[14:15]
	v_pk_mul_f32 v[12:13], v[12:13], v[38:39]
	v_pk_fma_f32 v[14:15], v[34:35], v[68:69], v[14:15]
	s_nop 0
	v_pk_mul_f32 v[12:13], v[14:15], v[12:13]
; __device__ __forceinline__ unsigned pk2(float lo, float hi) { return f2bf(lo) | (f2bf(hi) << 16); }
; __device__ __forceinline__ float silu_fast(float x) { return x * __builtin_amdgcn_rcpf(1.f + __builtin_amdgcn_exp2f(-1.4426950408889634f * x)); }
; __device__ __forceinline__ float dpp_shr1(float x) { return __builtin_bit_cast(float, __builtin_amdgcn_update_dpp(0, __builtin_bit_cast(int, x), 0x111, 0xf, 0xf, true)); }
;     __device__ __forceinline__ void operator()(const f32x4 (&acc)[2][2][4][2], const pg8::Unit& u, int wr, int wc, int fr, int fq) const {
;     ...
;             const int cc = ch0 + 4 * n;
;             const f32x4 wg0 = *(CF4)(cw + cc), wg1 = *(CF4)(cw + FF2 + cc), wg2 = *(CF4)(cw + 2 * FF2 + cc), wv0 = *(CF4)(cw + FFH + cc), wv1 = *(CF4)(cw + FF2 + FFH + cc), wv2 = *(CF4)(cw + 2 * FF2 + FFH + cc);
;             const f32x4 bg = *(CF4)(cb + cc), bv = *(CF4)(cb + FFH + cc);
; #pragma unroll
;             for (int jj = 0; jj < 4; ++jj) {
;                 float g2 = dpp_shr1(g[6][jj]), g1 = dpp_shr1(g[7][jj]), v2 = dpp_shr1(v[6][jj]), v1 = dpp_shr1(v[7][jj]);
; #pragma unroll
;                 for (int e = 0; e < 8; ++e) { const float g0 = g[e][jj], v0 = v[e][jj];
;                     const float cg = bg[jj] + wg0[jj] * g2 + wg1[jj] * g1 + wg2[jj] * g0, cv = bv[jj] + wv0[jj] * v2 + wv1[jj] * v1 + wv2[jj] * v0;
;                     g[e][jj] = silu_fast(cg) * cv; g2 = g1; g1 = g0; v2 = v1; v1 = v0; } }
; #pragma unroll
;             for (int e = 0; e < 8; ++e) { v2u w; w.x = pk2(g[e][0], g[e][1]); w.y = pk2(g[e][2], g[e][3]); *(v2u*)(ACT + (size_t)(tok0 + e) * FFH + cc) = w; }
	v_pk_fma_f32 v[14:15], v[28:29], v[46:47], v[32:33]
	v_mul_f32_e32 v32, 0xbfb8aa3b, v19
	v_exp_f32_e32 v32, v32
	v_pk_fma_f32 v[14:15], v[24:25], v[50:51], v[14:15]
	v_add_f32_e32 v32, 1.0, v32
	v_rcp_f32_e32 v43, v32
	s_nop 0
	v_pk_mul_f32 v[18:19], v[18:19], v[42:43]
	s_nop 0
	v_pk_mul_f32 v[14:15], v[14:15], v[18:19]
	s_nop 7
	s_nop 1
	v_cvt_pk_bf16_f32 v13, v13, v15
	v_cvt_pk_bf16_f32 v12, v12, v14
	v_mov_b32_e32 v14, v9
	v_mov_b32_e32 v15, v11
	v_pk_fma_f32 v[18:19], v[30:31], v[54:55], v[70:71]
	v_pk_mul_f32 v[14:15], v[14:15], v[36:37]
	v_pk_fma_f32 v[18:19], v[26:27], v[58:59], v[18:19]
	v_mov_b32_e32 v9, v10
	v_pk_fma_f32 v[18:19], v[14:15], v[62:63], v[18:19]
	global_store_dwordx2 v[96:97], v[12:13], off offset:8
	v_mov_b32_e32 v12, v5
	v_mov_b32_e32 v13, v7
	v_mov_b32_e32 v5, v6
	v_pk_mul_f32 v[6:7], v[8:9], v[36:37]
	v_pk_fma_f32 v[8:9], v[22:23], v[98:99], v[102:103]
	v_mul_f32_e32 v23, 0xbfb8aa3b, v18
	v_exp_f32_e32 v23, v23
	v_pk_fma_f32 v[8:9], v[16:17], v[106:107], v[8:9]
	v_pk_fma_f32 v[10:11], v[20:21], v[52:53], v[56:57]
	v_pk_fma_f32 v[8:9], v[6:7], v[110:111], v[8:9]
	v_add_f32_e32 v23, 1.0, v23
	v_pk_fma_f32 v[20:21], v[28:29], v[40:41], v[66:67]
	v_mul_f32_e32 v22, 0xbfb8aa3b, v8
	v_rcp_f32_e32 v28, v23
	v_mul_f32_e32 v23, 0xbfb8aa3b, v9
	v_exp_f32_e32 v22, v22
	v_exp_f32_e32 v23, v23
	v_pk_mul_f32 v[4:5], v[4:5], v[36:37]
	v_pk_fma_f32 v[10:11], v[34:35], v[60:61], v[10:11]
	v_add_f32_e32 v22, 1.0, v22
	v_add_f32_e32 v23, 1.0, v23
	v_rcp_f32_e32 v22, v22
	v_rcp_f32_e32 v23, v23
	v_pk_fma_f32 v[10:11], v[4:5], v[68:69], v[10:11]
	v_pk_mul_f32 v[12:13], v[12:13], v[36:37]
	v_pk_mul_f32 v[8:9], v[8:9], v[22:23]
	s_nop 0
	v_pk_mul_f32 v[8:9], v[10:11], v[8:9]
	v_pk_fma_f32 v[10:11], v[24:25], v[46:47], v[20:21]
	v_mul_f32_e32 v20, 0xbfb8aa3b, v19
	v_exp_f32_e32 v20, v20
	v_pk_fma_f32 v[10:11], v[12:13], v[50:51], v[10:11]
	v_add_f32_e32 v20, 1.0, v20
	v_rcp_f32_e32 v29, v20
	s_nop 0
	v_pk_mul_f32 v[18:19], v[18:19], v[28:29]
	s_nop 0
	v_pk_mul_f32 v[10:11], v[10:11], v[18:19]
	s_nop 7
	s_nop 1
	v_cvt_pk_bf16_f32 v9, v9, v11
	v_cvt_pk_bf16_f32 v8, v8, v10
	global_store_dwordx2 v[80:81], v[8:9], off offset:8
	v_pk_fma_f32 v[8:9], v[16:17], v[98:99], v[102:103]
	v_pk_fma_f32 v[16:17], v[26:27], v[54:55], v[70:71]
	v_pk_fma_f32 v[8:9], v[6:7], v[106:107], v[8:9]
	v_pk_fma_f32 v[16:17], v[14:15], v[58:59], v[16:17]
	v_pk_fma_f32 v[8:9], v[88:89], v[110:111], v[8:9]
	v_pk_fma_f32 v[16:17], v[86:87], v[62:63], v[16:17]
	v_mul_f32_e32 v20, 0xbfb8aa3b, v8
	v_mul_f32_e32 v21, 0xbfb8aa3b, v16
	v_exp_f32_e32 v21, v21
	v_exp_f32_e32 v20, v20
	v_pk_fma_f32 v[10:11], v[34:35], v[52:53], v[56:57]
	v_pk_fma_f32 v[18:19], v[24:25], v[40:41], v[66:67]
	v_add_f32_e32 v21, 1.0, v21
	v_rcp_f32_e32 v22, v21
	v_mul_f32_e32 v21, 0xbfb8aa3b, v9
	v_exp_f32_e32 v21, v21
	v_add_f32_e32 v20, 1.0, v20
	v_rcp_f32_e32 v20, v20
	v_pk_fma_f32 v[10:11], v[4:5], v[60:61], v[10:11]
	v_add_f32_e32 v21, 1.0, v21
	v_rcp_f32_e32 v21, v21
	v_pk_fma_f32 v[10:11], v[82:83], v[68:69], v[10:11]
	v_pk_fma_f32 v[6:7], v[6:7], v[98:99], v[102:103]
	v_pk_fma_f32 v[4:5], v[4:5], v[52:53], v[56:57]
	v_pk_mul_f32 v[8:9], v[8:9], v[20:21]
	v_pk_fma_f32 v[6:7], v[88:89], v[106:107], v[6:7]
	v_pk_mul_f32 v[8:9], v[10:11], v[8:9]
	v_pk_fma_f32 v[10:11], v[12:13], v[46:47], v[18:19]
	v_mul_f32_e32 v18, 0xbfb8aa3b, v17
	v_exp_f32_e32 v18, v18
	v_pk_fma_f32 v[10:11], v[72:73], v[50:51], v[10:11]
	v_pk_fma_f32 v[6:7], v[94:95], v[110:111], v[6:7]
	v_pk_fma_f32 v[4:5], v[82:83], v[60:61], v[4:5]
	v_add_f32_e32 v18, 1.0, v18
	v_rcp_f32_e32 v23, v18
	v_pk_fma_f32 v[4:5], v[84:85], v[68:69], v[4:5]
	v_pk_mul_f32 v[16:17], v[16:17], v[22:23]
	s_nop 0
	v_pk_mul_f32 v[10:11], v[10:11], v[16:17]
	s_nop 7
	s_nop 1
	v_cvt_pk_bf16_f32 v9, v9, v11
	v_cvt_pk_bf16_f32 v8, v8, v10
	v_pk_fma_f32 v[10:11], v[14:15], v[54:55], v[70:71]
	global_store_dwordx2 v[78:79], v[8:9], off offset:8
	v_pk_fma_f32 v[10:11], v[86:87], v[58:59], v[10:11]
	v_mul_f32_e32 v8, 0xbfb8aa3b, v6
	v_pk_fma_f32 v[10:11], v[90:91], v[62:63], v[10:11]
	v_exp_f32_e32 v8, v8
	v_mul_f32_e32 v9, 0xbfb8aa3b, v10
	v_exp_f32_e32 v9, v9
	v_add_f32_e32 v8, 1.0, v8
	v_rcp_f32_e32 v8, v8
	v_add_f32_e32 v9, 1.0, v9
	v_rcp_f32_e32 v14, v9
	v_mul_f32_e32 v9, 0xbfb8aa3b, v7
	v_exp_f32_e32 v9, v9
	s_nop 0
	v_add_f32_e32 v9, 1.0, v9
	v_rcp_f32_e32 v9, v9
	s_nop 0
	v_pk_mul_f32 v[6:7], v[6:7], v[8:9]
	v_mul_f32_e32 v8, 0xbfb8aa3b, v11
	v_exp_f32_e32 v8, v8
	v_pk_mul_f32 v[4:5], v[4:5], v[6:7]
	v_pk_fma_f32 v[6:7], v[12:13], v[40:41], v[66:67]
	v_add_f32_e32 v8, 1.0, v8
	v_rcp_f32_e32 v15, v8
	v_pk_fma_f32 v[6:7], v[72:73], v[46:47], v[6:7]
	v_pk_mul_f32 v[8:9], v[10:11], v[14:15]
	v_pk_fma_f32 v[6:7], v[74:75], v[50:51], v[6:7]
	s_nop 0
	v_pk_mul_f32 v[6:7], v[6:7], v[8:9]
	v_and_b32_sdwa v8, v5, v238 dst_sel:DWORD dst_unused:UNUSED_PAD src0_sel:WORD_1 src1_sel:DWORD
	v_and_b32_sdwa v9, v4, v238 dst_sel:DWORD dst_unused:UNUSED_PAD src0_sel:WORD_1 src1_sel:DWORD
	v_add3_u32 v4, v4, v9, s55
	v_add3_u32 v5, v5, v8, s55
	v_and_b32_sdwa v8, v7, v238 dst_sel:DWORD dst_unused:UNUSED_PAD src0_sel:WORD_1 src1_sel:DWORD
	v_and_b32_sdwa v9, v6, v238 dst_sel:DWORD dst_unused:UNUSED_PAD src0_sel:WORD_1 src1_sel:DWORD
	v_add3_u32 v7, v7, v8, s55
	v_add3_u32 v6, v6, v9, s55
	v_and_b32_e32 v7, 0xffff0000, v7
	v_and_b32_e32 v6, 0xffff0000, v6
	v_or_b32_sdwa v5, v7, v5 dst_sel:DWORD dst_unused:UNUSED_PAD src0_sel:DWORD src1_sel:WORD_1
	v_or_b32_sdwa v4, v6, v4 dst_sel:DWORD dst_unused:UNUSED_PAD src0_sel:DWORD src1_sel:WORD_1
	global_store_dwordx2 v[76:77], v[4:5], off offset:8
	s_cbranch_vccz .LBB0_1268

; #define PG8_STAGE(bufoff, gbase, voff) do { _Pragma("unroll") for (int _i = 0; _i < 2; ++_i) \
;         __builtin_amdgcn_global_load_lds((const unsigned*)((const char*)(gbase) + (voff)[_i]), (LAS unsigned*)(lds + (bufoff) + ldsw + _i * 8192), 16, 0, 0); } while (0)
; #define PG8_LDA(dst, b, h) do { _Pragma("unroll") for (int m = 0; m < 4; ++m) _Pragma("unroll") for (int k = 0; k < 2; ++k) dst[m][k] = *(const LAS bf16x8*)(lds + PG8_SA(b, h) + aoff + m * 2048 + k * 1024); } while (0)
; #define PG8_LDB(dst, b, h) do { _Pragma("unroll") for (int n = 0; n < 2; ++n) _Pragma("unroll") for (int k = 0; k < 2; ++k) dst[n][k] = *(const LAS bf16x8*)(lds + PG8_SB(b, h) + boff + n * 2048 + k * 1024); } while (0)
; #define PG8_WAIT_V(n) asm volatile("s_waitcnt vmcnt(" #n ")" ::: "memory")
; #define PG8_WAIT_L(n) asm volatile("s_waitcnt lgkmcnt(" #n ")" ::: "memory")
; #define PG8_BAR __builtin_amdgcn_s_barrier()
; #define PG8_SCHED __builtin_amdgcn_sched_barrier(0)
; template <class PT, class Epi>
; __device__ __forceinline__ void gemm_phase_once(LAS unsigned char* lds, const PT& S, const Epi& E, bool epi_on) {
;     ...
;             PG8_LDB(B0, 0, 0); PG8_SCHED; PG8_LDA(At, 0, 0); PG8_STAGE(PG8_SA(1, 1), a1 + hstepA, voffA);
;             PG8_WAIT_L(8); PG8_BAR; PG8_WAIT_L(0); PG8_MMA(0, 0, At, B0); PG8_BAR; PG8_SCHED;
;             PG8_LDB(B1, 0, 1); PG8_STAGE(PG8_SB(0, 0), b2, voffB);
;             PG8_BAR; PG8_WAIT_L(0); PG8_MMA(0, 1, At, B1); PG8_BAR;
;             PG8_LDA(At, 0, 1); PG8_STAGE(PG8_SA(0, 0), a2, voffA);
;             PG8_BAR; PG8_WAIT_L(0); PG8_MMA(1, 0, At, B0); PG8_BAR; PG8_SCHED;
;             PG8_STAGE(PG8_SB(0, 1), b2 + hstepB, voffB);
;             PG8_WAIT_V(6); PG8_BAR; PG8_MMA(1, 1, At, B1); PG8_BAR;
;             PG8_LDB(B0, 1, 0); PG8_SCHED; PG8_LDA(At, 1, 0); PG8_STAGE(PG8_SA(0, 1), a2 + hstepA, voffA);
;             PG8_WAIT_L(8); PG8_BAR; PG8_WAIT_L(0); PG8_MMA(0, 0, At, B0); PG8_BAR; PG8_SCHED;
;             PG8_LDB(B1, 1, 1); PG8_STAGE(PG8_SB(1, 0), b3, voffB);
;             PG8_BAR; PG8_WAIT_L(0); PG8_MMA(0, 1, At, B1); PG8_BAR;
;             PG8_LDA(At, 1, 1); PG8_STAGE(PG8_SA(1, 0), a3, voffA);
;             PG8_BAR; PG8_WAIT_L(0); PG8_MMA(1, 0, At, B0); PG8_BAR; PG8_SCHED;
;             PG8_STAGE(PG8_SB(1, 1), b3 + hstepB, voffB);
;             PG8_WAIT_V(6); PG8_BAR; PG8_MMA(1, 1, At, B1); PG8_BAR;
.LBB0_1253:
	ds_read_b128 v[36:39], v235
	ds_read_b128 v[40:43], v235 offset:1024
	ds_read_b128 v[158:161], v235 offset:2048
	ds_read_b128 v[168:171], v235 offset:3072
	s_add_u32 s34, s30, 0x100
	s_addc_u32 s35, s31, 0
	s_cmp_eq_u32 s61, 28
	s_cselect_b32 s39, s23, s35
	s_cselect_b32 s38, s29, s34
	s_cselect_b32 s37, s21, s60
	s_cselect_b32 s36, s58, s59
	v_lshl_add_u64 v[162:163], s[30:31], 0, v[150:151]
	s_add_i32 m0, s45, 0xc000
	ds_read_b128 v[172:175], v236
	ds_read_b128 v[176:179], v236 offset:1024
	ds_read_b128 v[180:183], v236 offset:2048
	ds_read_b128 v[184:187], v236 offset:3072
	ds_read_b128 v[188:191], v236 offset:4096
	ds_read_b128 v[192:195], v236 offset:5120
	ds_read_b128 v[196:199], v236 offset:6144
	ds_read_b128 v[200:203], v236 offset:7168
	global_load_lds_dwordx4 v[162:163], off
	v_lshl_add_u64 v[162:163], s[30:31], 0, v[152:153]
	s_add_i32 m0, s45, 0xe000
	s_nop 0
	global_load_lds_dwordx4 v[162:163], off
	s_waitcnt lgkmcnt(8)
	s_barrier
	s_waitcnt lgkmcnt(0)
	s_setprio 1
	s_waitcnt lgkmcnt(0)
	v_mfma_f32_16x16x32_bf16 v[132:135], v[36:39], v[172:175], v[132:135]
	v_mfma_f32_16x16x32_bf16 v[72:75], v[158:161], v[172:175], v[72:75]
	v_mfma_f32_16x16x32_bf16 v[124:127], v[36:39], v[180:183], v[124:127]
	v_mfma_f32_16x16x32_bf16 v[68:71], v[158:161], v[180:183], v[68:71]
	v_mfma_f32_16x16x32_bf16 v[104:107], v[36:39], v[188:191], v[104:107]
	v_mfma_f32_16x16x32_bf16 v[32:35], v[158:161], v[188:191], v[32:35]
	v_mfma_f32_16x16x32_bf16 v[100:103], v[36:39], v[196:199], v[100:103]
	v_mfma_f32_16x16x32_bf16 v[24:27], v[158:161], v[196:199], v[24:27]
	v_mfma_f32_16x16x32_bf16 v[132:135], v[40:43], v[176:179], v[132:135]
	v_mfma_f32_16x16x32_bf16 v[72:75], v[168:171], v[176:179], v[72:75]
	v_mfma_f32_16x16x32_bf16 v[124:127], v[40:43], v[184:187], v[124:127]
	v_mfma_f32_16x16x32_bf16 v[68:71], v[168:171], v[184:187], v[68:71]
	v_mfma_f32_16x16x32_bf16 v[104:107], v[40:43], v[192:195], v[104:107]
	v_mfma_f32_16x16x32_bf16 v[32:35], v[168:171], v[192:195], v[32:35]
	v_mfma_f32_16x16x32_bf16 v[100:103], v[40:43], v[200:203], v[100:103]
	v_mfma_f32_16x16x32_bf16 v[24:27], v[168:171], v[200:203], v[24:27]
	s_setprio 0
	s_barrier
	s_add_i32 s30, s53, s42
	v_lshl_add_u64 v[162:163], s[36:37], 0, v[146:147]
	s_mov_b32 m0, s30
	ds_read_b128 v[204:207], v237
	ds_read_b128 v[208:211], v237 offset:1024
	ds_read_b128 v[212:215], v237 offset:2048
	ds_read_b128 v[216:219], v237 offset:3072
	global_load_lds_dwordx4 v[162:163], off
	v_lshl_add_u64 v[220:221], s[36:37], 0, v[140:141]
	s_add_i32 m0, s30, 0x2000
	s_nop 0
	global_load_lds_dwordx4 v[220:221], off
	s_barrier
	s_waitcnt lgkmcnt(0)
	s_setprio 1
	s_waitcnt lgkmcnt(0)
	v_mfma_f32_16x16x32_bf16 v[120:123], v[204:207], v[172:175], v[120:123]
	v_mfma_f32_16x16x32_bf16 v[64:67], v[212:215], v[172:175], v[64:67]
	v_mfma_f32_16x16x32_bf16 v[116:119], v[204:207], v[180:183], v[116:119]
	v_mfma_f32_16x16x32_bf16 v[60:63], v[212:215], v[180:183], v[60:63]
	v_mfma_f32_16x16x32_bf16 v[96:99], v[204:207], v[188:191], v[96:99]
	v_mfma_f32_16x16x32_bf16 v[28:31], v[212:215], v[188:191], v[28:31]
	v_mfma_f32_16x16x32_bf16 v[92:95], v[204:207], v[196:199], v[92:95]
	v_mfma_f32_16x16x32_bf16 v[20:23], v[212:215], v[196:199], v[20:23]
	v_mfma_f32_16x16x32_bf16 v[120:123], v[208:211], v[176:179], v[120:123]
	v_mfma_f32_16x16x32_bf16 v[64:67], v[216:219], v[176:179], v[64:67]
	v_mfma_f32_16x16x32_bf16 v[116:119], v[208:211], v[184:187], v[116:119]
	v_mfma_f32_16x16x32_bf16 v[60:63], v[216:219], v[184:187], v[60:63]
	v_mfma_f32_16x16x32_bf16 v[96:99], v[208:211], v[192:195], v[96:99]
	v_mfma_f32_16x16x32_bf16 v[28:31], v[216:219], v[192:195], v[28:31]
	v_mfma_f32_16x16x32_bf16 v[92:95], v[208:211], v[200:203], v[92:95]
	v_mfma_f32_16x16x32_bf16 v[20:23], v[216:219], v[200:203], v[20:23]
	s_setprio 0
	s_mov_b32 m0, s45
	v_lshl_add_u64 v[222:223], s[38:39], 0, v[142:143]
	s_barrier
	ds_read_b128 v[172:175], v236 offset:16384
	ds_read_b128 v[176:179], v236 offset:17408
	ds_read_b128 v[180:183], v236 offset:18432
	ds_read_b128 v[184:187], v236 offset:19456
	ds_read_b128 v[188:191], v236 offset:20480
	ds_read_b128 v[192:195], v236 offset:21504
	ds_read_b128 v[196:199], v236 offset:22528
	ds_read_b128 v[200:203], v236 offset:23552
	global_load_lds_dwordx4 v[222:223], off
	v_lshl_add_u64 v[224:225], s[38:39], 0, v[144:145]
	s_mov_b32 m0, s46
	s_nop 0
	global_load_lds_dwordx4 v[224:225], off
	s_barrier
	s_waitcnt lgkmcnt(0)
	s_setprio 1
	s_waitcnt lgkmcnt(0)
	v_mfma_f32_16x16x32_bf16 v[88:91], v[36:39], v[172:175], v[88:91]
	v_mfma_f32_16x16x32_bf16 v[16:19], v[158:161], v[172:175], v[16:19]
	v_mfma_f32_16x16x32_bf16 v[84:87], v[36:39], v[180:183], v[84:87]
	v_mfma_f32_16x16x32_bf16 v[8:11], v[158:161], v[180:183], v[8:11]
	v_mfma_f32_16x16x32_bf16 v[136:139], v[36:39], v[188:191], v[136:139]
	v_mfma_f32_16x16x32_bf16 v[56:59], v[158:161], v[188:191], v[56:59]
	v_mfma_f32_16x16x32_bf16 v[36:39], v[36:39], v[196:199], v[112:115]
	v_mfma_f32_16x16x32_bf16 v[88:91], v[40:43], v[176:179], v[88:91]
	v_mfma_f32_16x16x32_bf16 v[16:19], v[168:171], v[176:179], v[16:19]
	v_mfma_f32_16x16x32_bf16 v[84:87], v[40:43], v[184:187], v[84:87]
	v_mfma_f32_16x16x32_bf16 v[8:11], v[168:171], v[184:187], v[8:11]
	v_mfma_f32_16x16x32_bf16 v[136:139], v[40:43], v[192:195], v[136:139]
	v_mfma_f32_16x16x32_bf16 v[56:59], v[168:171], v[192:195], v[56:59]
	v_mfma_f32_16x16x32_bf16 v[36:39], v[40:43], v[200:203], v[36:39]
	v_mfma_f32_16x16x32_bf16 v[40:43], v[158:161], v[196:199], v[52:55]
	v_mfma_f32_16x16x32_bf16 v[40:43], v[168:171], v[200:203], v[40:43]
	s_setprio 0
	s_barrier
; #define PG8_STAGE(bufoff, gbase, voff) do { _Pragma("unroll") for (int _i = 0; _i < 2; ++_i) \
;         __builtin_amdgcn_global_load_lds((const unsigned*)((const char*)(gbase) + (voff)[_i]), (LAS unsigned*)(lds + (bufoff) + ldsw + _i * 8192), 16, 0, 0); } while (0)
; #define PG8_LDA(dst, b, h) do { _Pragma("unroll") for (int m = 0; m < 4; ++m) _Pragma("unroll") for (int k = 0; k < 2; ++k) dst[m][k] = *(const LAS bf16x8*)(lds + PG8_SA(b, h) + aoff + m * 2048 + k * 1024); } while (0)
; #define PG8_LDB(dst, b, h) do { _Pragma("unroll") for (int n = 0; n < 2; ++n) _Pragma("unroll") for (int k = 0; k < 2; ++k) dst[n][k] = *(const LAS bf16x8*)(lds + PG8_SB(b, h) + boff + n * 2048 + k * 1024); } while (0)
; #define PG8_WAIT_V(n) asm volatile("s_waitcnt vmcnt(" #n ")" ::: "memory")
; #define PG8_WAIT_L(n) asm volatile("s_waitcnt lgkmcnt(" #n ")" ::: "memory")
; #define PG8_BAR __builtin_amdgcn_s_barrier()
; #define PG8_SCHED __builtin_amdgcn_sched_barrier(0)
; template <class PT, class Epi>
; __device__ __forceinline__ void gemm_phase_once(LAS unsigned char* lds, const PT& S, const Epi& E, bool epi_on) {
;     ...
;             PG8_LDB(B0, 0, 0); PG8_SCHED; PG8_LDA(At, 0, 0); PG8_STAGE(PG8_SA(1, 1), a1 + hstepA, voffA);
;             PG8_WAIT_L(8); PG8_BAR; PG8_WAIT_L(0); PG8_MMA(0, 0, At, B0); PG8_BAR; PG8_SCHED;
;             PG8_LDB(B1, 0, 1); PG8_STAGE(PG8_SB(0, 0), b2, voffB);
;             PG8_BAR; PG8_WAIT_L(0); PG8_MMA(0, 1, At, B1); PG8_BAR;
;             PG8_LDA(At, 0, 1); PG8_STAGE(PG8_SA(0, 0), a2, voffA);
;             PG8_BAR; PG8_WAIT_L(0); PG8_MMA(1, 0, At, B0); PG8_BAR; PG8_SCHED;
;             PG8_STAGE(PG8_SB(0, 1), b2 + hstepB, voffB);
;             PG8_WAIT_V(6); PG8_BAR; PG8_MMA(1, 1, At, B1); PG8_BAR;
;             PG8_LDB(B0, 1, 0); PG8_SCHED; PG8_LDA(At, 1, 0); PG8_STAGE(PG8_SA(0, 1), a2 + hstepA, voffA);
;             PG8_WAIT_L(8); PG8_BAR; PG8_WAIT_L(0); PG8_MMA(0, 0, At, B0); PG8_BAR; PG8_SCHED;
;             PG8_LDB(B1, 1, 1); PG8_STAGE(PG8_SB(1, 0), b3, voffB);
;             PG8_BAR; PG8_WAIT_L(0); PG8_MMA(0, 1, At, B1); PG8_BAR;
;             PG8_LDA(At, 1, 1); PG8_STAGE(PG8_SA(1, 0), a3, voffA);
;             PG8_BAR; PG8_WAIT_L(0); PG8_MMA(1, 0, At, B0); PG8_BAR; PG8_SCHED;
;             PG8_STAGE(PG8_SB(1, 1), b3 + hstepB, voffB);
;             PG8_WAIT_V(6); PG8_BAR; PG8_MMA(1, 1, At, B1); PG8_BAR;
	s_add_u32 s30, s36, 0x80000
	s_addc_u32 s31, s37, 0
	s_add_i32 s62, s54, s42
	v_lshl_add_u64 v[52:53], s[30:31], 0, v[146:147]
	s_mov_b32 m0, s62
	s_nop 0
	global_load_lds_dwordx4 v[52:53], off
	v_lshl_add_u64 v[52:53], s[30:31], 0, v[140:141]
	s_add_i32 m0, s62, 0x2000
	s_nop 0
	global_load_lds_dwordx4 v[52:53], off
	s_waitcnt vmcnt(6)
	s_barrier
	s_setprio 1
	v_mfma_f32_16x16x32_bf16 v[52:55], v[204:207], v[172:175], v[80:83]
	v_mfma_f32_16x16x32_bf16 v[80:83], v[208:211], v[176:179], v[52:55]
	v_mfma_f32_16x16x32_bf16 v[52:55], v[204:207], v[180:183], v[76:79]
	v_mfma_f32_16x16x32_bf16 v[76:79], v[208:211], v[184:187], v[52:55]
	v_mfma_f32_16x16x32_bf16 v[52:55], v[204:207], v[188:191], v[128:131]
	v_mfma_f32_16x16x32_bf16 v[12:15], v[212:215], v[172:175], v[12:15]
	v_mfma_f32_16x16x32_bf16 v[4:7], v[212:215], v[180:183], v[4:7]
	v_mfma_f32_16x16x32_bf16 v[128:131], v[208:211], v[192:195], v[52:55]
	v_mfma_f32_16x16x32_bf16 v[48:51], v[212:215], v[188:191], v[48:51]
	v_mfma_f32_16x16x32_bf16 v[52:55], v[204:207], v[196:199], v[108:111]
	v_mfma_f32_16x16x32_bf16 v[44:47], v[212:215], v[196:199], v[44:47]
	v_mfma_f32_16x16x32_bf16 v[12:15], v[216:219], v[176:179], v[12:15]
	v_mfma_f32_16x16x32_bf16 v[4:7], v[216:219], v[184:187], v[4:7]
	v_mfma_f32_16x16x32_bf16 v[48:51], v[216:219], v[192:195], v[48:51]
	v_mfma_f32_16x16x32_bf16 v[108:111], v[208:211], v[200:203], v[52:55]
	v_mfma_f32_16x16x32_bf16 v[44:47], v[216:219], v[200:203], v[44:47]
	s_setprio 0
	s_add_i32 s62, 0, 0x18000
	v_add_u32_e32 v165, s62, v167
	s_barrier
	ds_read_b128 v[52:55], v165
	ds_read_b128 v[112:115], v165 offset:1024
	ds_read_b128 v[158:161], v165 offset:2048
	ds_read_b128 v[168:171], v165 offset:3072
	s_add_u32 s30, s38, 0x4000
	s_addc_u32 s31, s39, 0
	s_mov_b32 m0, s47
	v_lshl_add_u64 v[204:205], s[30:31], 0, v[142:143]
	ds_read_b128 v[172:175], v236 offset:32768
	ds_read_b128 v[176:179], v236 offset:33792
	ds_read_b128 v[180:183], v236 offset:34816
	ds_read_b128 v[184:187], v236 offset:35840
	ds_read_b128 v[188:191], v236 offset:36864
	ds_read_b128 v[192:195], v236 offset:37888
	ds_read_b128 v[196:199], v236 offset:38912
	ds_read_b128 v[200:203], v236 offset:39936
	global_load_lds_dwordx4 v[204:205], off
	v_lshl_add_u64 v[204:205], s[30:31], 0, v[144:145]
	s_mov_b32 m0, s48
	s_nop 0
	global_load_lds_dwordx4 v[204:205], off
	s_waitcnt lgkmcnt(8)
	s_barrier
	s_waitcnt lgkmcnt(0)
	s_setprio 1
	s_waitcnt lgkmcnt(0)
	v_mfma_f32_16x16x32_bf16 v[132:135], v[52:55], v[172:175], v[132:135]
	v_mfma_f32_16x16x32_bf16 v[72:75], v[158:161], v[172:175], v[72:75]
	v_mfma_f32_16x16x32_bf16 v[124:127], v[52:55], v[180:183], v[124:127]
	v_mfma_f32_16x16x32_bf16 v[68:71], v[158:161], v[180:183], v[68:71]
	v_mfma_f32_16x16x32_bf16 v[104:107], v[52:55], v[188:191], v[104:107]
	v_mfma_f32_16x16x32_bf16 v[32:35], v[158:161], v[188:191], v[32:35]
	v_mfma_f32_16x16x32_bf16 v[100:103], v[52:55], v[196:199], v[100:103]
	v_mfma_f32_16x16x32_bf16 v[24:27], v[158:161], v[196:199], v[24:27]
	v_mfma_f32_16x16x32_bf16 v[132:135], v[112:115], v[176:179], v[132:135]
	v_mfma_f32_16x16x32_bf16 v[72:75], v[168:171], v[176:179], v[72:75]
	v_mfma_f32_16x16x32_bf16 v[124:127], v[112:115], v[184:187], v[124:127]
	v_mfma_f32_16x16x32_bf16 v[68:71], v[168:171], v[184:187], v[68:71]
	v_mfma_f32_16x16x32_bf16 v[104:107], v[112:115], v[192:195], v[104:107]
	v_mfma_f32_16x16x32_bf16 v[32:35], v[168:171], v[192:195], v[32:35]
	v_mfma_f32_16x16x32_bf16 v[100:103], v[112:115], v[200:203], v[100:103]
	v_mfma_f32_16x16x32_bf16 v[24:27], v[168:171], v[200:203], v[24:27]
	s_setprio 0
	s_barrier
	s_add_i32 s38, 0, 0x1c000
	s_add_i32 s30, s62, s42
	v_add_u32_e32 v165, s38, v167
	v_lshl_add_u64 v[162:163], v[162:163], 0, s[6:7]
	s_mov_b32 m0, s30
	ds_read_b128 v[204:207], v165
	ds_read_b128 v[208:211], v165 offset:1024
	ds_read_b128 v[212:215], v165 offset:2048
	ds_read_b128 v[216:219], v165 offset:3072
	global_load_lds_dwordx4 v[162:163], off
	v_lshl_add_u64 v[162:163], v[220:221], 0, s[6:7]
	s_add_i32 m0, s30, 0x2000
	s_nop 0
	global_load_lds_dwordx4 v[162:163], off
	s_barrier
	s_waitcnt lgkmcnt(0)
	s_setprio 1
	s_waitcnt lgkmcnt(0)
	v_mfma_f32_16x16x32_bf16 v[120:123], v[204:207], v[172:175], v[120:123]
	v_mfma_f32_16x16x32_bf16 v[64:67], v[212:215], v[172:175], v[64:67]
	v_mfma_f32_16x16x32_bf16 v[116:119], v[204:207], v[180:183], v[116:119]
	v_mfma_f32_16x16x32_bf16 v[60:63], v[212:215], v[180:183], v[60:63]
	v_mfma_f32_16x16x32_bf16 v[96:99], v[204:207], v[188:191], v[96:99]
	v_mfma_f32_16x16x32_bf16 v[28:31], v[212:215], v[188:191], v[28:31]
	v_mfma_f32_16x16x32_bf16 v[92:95], v[204:207], v[196:199], v[92:95]
	v_mfma_f32_16x16x32_bf16 v[20:23], v[212:215], v[196:199], v[20:23]
	v_mfma_f32_16x16x32_bf16 v[120:123], v[208:211], v[176:179], v[120:123]
	v_mfma_f32_16x16x32_bf16 v[64:67], v[216:219], v[176:179], v[64:67]
	v_mfma_f32_16x16x32_bf16 v[116:119], v[208:211], v[184:187], v[116:119]
	v_mfma_f32_16x16x32_bf16 v[60:63], v[216:219], v[184:187], v[60:63]
	v_mfma_f32_16x16x32_bf16 v[96:99], v[208:211], v[192:195], v[96:99]
	v_mfma_f32_16x16x32_bf16 v[28:31], v[216:219], v[192:195], v[28:31]
	v_mfma_f32_16x16x32_bf16 v[92:95], v[208:211], v[200:203], v[92:95]
	v_mfma_f32_16x16x32_bf16 v[20:23], v[216:219], v[200:203], v[20:23]
	s_setprio 0
	s_mov_b32 m0, s50
	v_lshl_add_u64 v[162:163], v[222:223], 0, s[6:7]
	s_barrier
	ds_read_b128 v[172:175], v236 offset:49152
	ds_read_b128 v[176:179], v236 offset:50176
	ds_read_b128 v[180:183], v236 offset:51200
	ds_read_b128 v[184:187], v236 offset:52224
	ds_read_b128 v[188:191], v236 offset:53248
	ds_read_b128 v[192:195], v236 offset:54272
	ds_read_b128 v[196:199], v236 offset:55296
	ds_read_b128 v[200:203], v236 offset:56320
	global_load_lds_dwordx4 v[162:163], off
	v_lshl_add_u64 v[162:163], v[224:225], 0, s[6:7]
	s_mov_b32 m0, s51
	s_nop 0
	global_load_lds_dwordx4 v[162:163], off
	s_barrier
; __device__ __forceinline__ unsigned pk2(float lo, float hi) { return f2bf(lo) | (f2bf(hi) << 16); }
; #define PG8_STAGE(bufoff, gbase, voff) do { _Pragma("unroll") for (int _i = 0; _i < 2; ++_i) \
;         __builtin_amdgcn_global_load_lds((const unsigned*)((const char*)(gbase) + (voff)[_i]), (LAS unsigned*)(lds + (bufoff) + ldsw + _i * 8192), 16, 0, 0); } while (0)
; #define PG8_WAIT_V(n) asm volatile("s_waitcnt vmcnt(" #n ")" ::: "memory")
; #define PG8_BAR __builtin_amdgcn_s_barrier()
; template <class PT, class Epi>
; __device__ __forceinline__ void gemm_phase_once(LAS unsigned char* lds, const PT& S, const Epi& E, bool epi_on) {
;     ...
;             PG8_BAR; PG8_WAIT_L(0); PG8_MMA(1, 0, At, B0); PG8_BAR; PG8_SCHED;
;             PG8_STAGE(PG8_SB(1, 1), b3 + hstepB, voffB);
;             PG8_WAIT_V(6); PG8_BAR; PG8_MMA(1, 1, At, B1); PG8_BAR;
;     __device__ __forceinline__ void operator()(const f32x4 (&acc)[2][2][4][2], const pg8::Unit& u, int wr, int wc, int fr, int fq) const {
;         const int ch0 = 128 * u.pn + 32 * wc + 8 * fq, tok0 = 256 * u.pm + 128 * wr + 8 * fr;
;         const f32x4 r0 = *(const f32x4*)(RS + tok0), r1 = *(const f32x4*)(RS + tok0 + 4);
;         bf16* hb = HALO + ((size_t)((u.pm * 44 + u.pn) * 2 + wr) * 4) * 256 + 32 * wc + 8 * fq;
; #pragma unroll
;         for (int n = 0; n < 2; ++n) {
;             float g[8][4], v[8][4];
; #pragma unroll
;             for (int e = 0; e < 8; ++e) { const float rs = (e < 4) ? r0[e & 3] : r1[e & 3];
; #pragma unroll
;                 for (int jj = 0; jj < 4; ++jj) { g[e][jj] = acc[e >> 2][0][e & 3][n][jj] * rs; v[e][jj] = acc[e >> 2][1][e & 3][n][jj] * rs; } }
;             if (fr == 0) {
; #pragma unroll
;                 for (int q = 0; q < 2; ++q) { v2u a, b; a.x = pk2(g[q][0], g[q][1]); a.y = pk2(g[q][2], g[q][3]); b.x = pk2(v[q][0], v[q][1]); b.y = pk2(v[q][2], v[q][3]);
;                     *(v2u*)(hb + (size_t)q * 256 + 4 * n) = a; *(v2u*)(hb + (size_t)q * 256 + 128 + 4 * n) = b; } }
;             if (fr == 15) {
; #pragma unroll
;                 for (int q = 0; q < 2; ++q) { v2u a, b; a.x = pk2(g[6 + q][0], g[6 + q][1]); a.y = pk2(g[6 + q][2], g[6 + q][3]); b.x = pk2(v[6 + q][0], v[6 + q][1]); b.y = pk2(v[6 + q][2], v[6 + q][3]);
;                     *(v2u*)(hb + (size_t)(2 + q) * 256 + 4 * n) = a; *(v2u*)(hb + (size_t)(2 + q) * 256 + 128 + 4 * n) = b; } }
	s_waitcnt lgkmcnt(0)
	s_setprio 1
	s_waitcnt lgkmcnt(0)
	v_mfma_f32_16x16x32_bf16 v[88:91], v[52:55], v[172:175], v[88:91]
	v_mfma_f32_16x16x32_bf16 v[84:87], v[52:55], v[180:183], v[84:87]
	v_mfma_f32_16x16x32_bf16 v[136:139], v[52:55], v[188:191], v[136:139]
	v_mfma_f32_16x16x32_bf16 v[36:39], v[52:55], v[196:199], v[36:39]
	v_mfma_f32_16x16x32_bf16 v[88:91], v[112:115], v[176:179], v[88:91]
	v_mfma_f32_16x16x32_bf16 v[16:19], v[158:161], v[172:175], v[16:19]
	v_mfma_f32_16x16x32_bf16 v[84:87], v[112:115], v[184:187], v[84:87]
	v_mfma_f32_16x16x32_bf16 v[8:11], v[158:161], v[180:183], v[8:11]
	v_mfma_f32_16x16x32_bf16 v[136:139], v[112:115], v[192:195], v[136:139]
	v_mfma_f32_16x16x32_bf16 v[56:59], v[158:161], v[188:191], v[56:59]
	v_mfma_f32_16x16x32_bf16 v[112:115], v[112:115], v[200:203], v[36:39]
	v_mfma_f32_16x16x32_bf16 v[36:39], v[158:161], v[196:199], v[40:43]
	v_mfma_f32_16x16x32_bf16 v[16:19], v[168:171], v[176:179], v[16:19]
	v_mfma_f32_16x16x32_bf16 v[8:11], v[168:171], v[184:187], v[8:11]
	v_mfma_f32_16x16x32_bf16 v[56:59], v[168:171], v[192:195], v[56:59]
	v_mfma_f32_16x16x32_bf16 v[52:55], v[168:171], v[200:203], v[36:39]
	s_setprio 0
	s_barrier
	s_add_u32 s30, s36, 0x80080
	s_addc_u32 s31, s37, 0
	s_add_i32 s36, s38, s42
	v_lshl_add_u64 v[36:37], s[30:31], 0, v[146:147]
	s_mov_b32 m0, s36
	s_nop 0
	global_load_lds_dwordx4 v[36:37], off
	v_lshl_add_u64 v[36:37], s[30:31], 0, v[140:141]
	s_add_i32 m0, s36, 0x2000
	s_nop 0
	global_load_lds_dwordx4 v[36:37], off
	s_waitcnt vmcnt(6)
	s_barrier
	s_setprio 1
	v_mfma_f32_16x16x32_bf16 v[36:39], v[204:207], v[172:175], v[80:83]
	v_mfma_f32_16x16x32_bf16 v[80:83], v[208:211], v[176:179], v[36:39]
	v_mfma_f32_16x16x32_bf16 v[36:39], v[204:207], v[180:183], v[76:79]
	v_mfma_f32_16x16x32_bf16 v[76:79], v[208:211], v[184:187], v[36:39]
	v_mfma_f32_16x16x32_bf16 v[36:39], v[204:207], v[188:191], v[128:131]
	v_mfma_f32_16x16x32_bf16 v[128:131], v[208:211], v[192:195], v[36:39]
	v_mfma_f32_16x16x32_bf16 v[36:39], v[212:215], v[188:191], v[48:51]
	v_mfma_f32_16x16x32_bf16 v[48:51], v[216:219], v[192:195], v[36:39]
	v_mfma_f32_16x16x32_bf16 v[36:39], v[204:207], v[196:199], v[108:111]
	v_mfma_f32_16x16x32_bf16 v[12:15], v[212:215], v[172:175], v[12:15]
	v_mfma_f32_16x16x32_bf16 v[4:7], v[212:215], v[180:183], v[4:7]
	v_mfma_f32_16x16x32_bf16 v[108:111], v[208:211], v[200:203], v[36:39]
	v_mfma_f32_16x16x32_bf16 v[36:39], v[212:215], v[196:199], v[44:47]
	v_mfma_f32_16x16x32_bf16 v[12:15], v[216:219], v[176:179], v[12:15]
	v_mfma_f32_16x16x32_bf16 v[4:7], v[216:219], v[184:187], v[4:7]
	v_mfma_f32_16x16x32_bf16 v[44:47], v[216:219], v[200:203], v[36:39]
	s_setprio 0
	s_add_i32 s61, s61, 2
	s_add_u32 s59, s59, 0x100
	s_addc_u32 s60, s60, 0
	s_cmp_lt_u32 s61, 30
	s_mov_b64 s[30:31], s[34:35]
	s_barrier
	s_cbranch_scc1 .LBB0_1253
	v_lshl_add_u32 v160, s28, 8, v233
	v_ashrrev_i32_e32 v161, 31, v160
	v_lshl_add_u64 v[40:41], v[160:161], 2, s[90:91]
	global_load_dwordx4 v[36:39], v[40:41], off offset:16
	s_nop 0
	global_load_dwordx4 v[40:43], v[40:41], off
	s_mul_i32 s21, s28, 44
	s_add_i32 s21, s21, s57
	s_lshl_b32 s21, s21, 1
	s_add_i32 s28, s21, s41
	s_ashr_i32 s29, s28, 31
	v_mov_b32_e32 v162, v136
	v_mov_b32_e32 v163, v138
	s_lshl_b64 s[28:29], s[28:29], 11
	v_mov_b32_e32 v138, v137
	v_lshl_add_u64 v[158:159], v[148:149], 0, s[28:29]
	v_cmp_lt_i32_e32 vcc, 14, v3
	s_mov_b64 s[28:29], 0
	s_waitcnt vmcnt(0)
	v_pk_mul_f32 v[168:169], v[162:163], v[38:39] op_sel_hi:[1,0]
	v_mov_b32_e32 v162, v128
	v_mov_b32_e32 v163, v130
	v_mov_b32_e32 v130, v129
	v_pk_mul_f32 v[162:163], v[162:163], v[38:39] op_sel_hi:[1,0]
	v_pk_mul_f32 v[136:137], v[138:139], v[38:39] op_sel_hi:[1,0]
	v_pk_mul_f32 v[130:131], v[130:131], v[38:39] op_sel_hi:[1,0]
	s_and_saveexec_b64 s[30:31], vcc
	s_xor_b64 s[30:31], exec, s[30:31]
	s_cbranch_execz .LBB0_1256
	v_and_b32_sdwa v138, v137, v238 dst_sel:DWORD dst_unused:UNUSED_PAD src0_sel:WORD_1 src1_sel:DWORD
	v_and_b32_sdwa v139, v136, v238 dst_sel:DWORD dst_unused:UNUSED_PAD src0_sel:WORD_1 src1_sel:DWORD
	v_and_b32_sdwa v128, v169, v238 dst_sel:DWORD dst_unused:UNUSED_PAD src0_sel:WORD_1 src1_sel:DWORD
	v_and_b32_sdwa v129, v168, v238 dst_sel:DWORD dst_unused:UNUSED_PAD src0_sel:WORD_1 src1_sel:DWORD
	v_add3_u32 v138, v137, v138, s55
	v_add3_u32 v139, v136, v139, s55
	v_add3_u32 v129, v168, v129, s55
	v_add3_u32 v128, v169, v128, s55
	v_and_b32_e32 v138, 0xffff0000, v138
	v_and_b32_e32 v161, 0xffff0000, v139
	v_or_b32_sdwa v139, v138, v128 dst_sel:DWORD dst_unused:UNUSED_PAD src0_sel:DWORD src1_sel:WORD_1
	v_or_b32_sdwa v138, v161, v129 dst_sel:DWORD dst_unused:UNUSED_PAD src0_sel:DWORD src1_sel:WORD_1
	v_and_b32_sdwa v129, v162, v238 dst_sel:DWORD dst_unused:UNUSED_PAD src0_sel:WORD_1 src1_sel:DWORD
	v_add3_u32 v161, v162, v129, s55
	s_nop 0
	v_and_b32_sdwa v165, v130, v238 dst_sel:DWORD dst_unused:UNUSED_PAD src0_sel:WORD_1 src1_sel:DWORD
	s_nop 1
	v_add3_u32 v165, v130, v165, s55
	s_nop 1
	v_and_b32_e32 v165, 0xffff0000, v165
	s_mov_b64 s[28:29], exec
	v_cvt_pk_bf16_f32 v129, v163, v131
	v_or_b32_sdwa v128, v165, v161 dst_sel:DWORD dst_unused:UNUSED_PAD src0_sel:DWORD src1_sel:WORD_1
	global_store_dwordx2 v[158:159], v[138:139], off offset:1024
; __device__ __forceinline__ unsigned pk2(float lo, float hi) { return f2bf(lo) | (f2bf(hi) << 16); }
;     __device__ __forceinline__ void operator()(const f32x4 (&acc)[2][2][4][2], const pg8::Unit& u, int wr, int wc, int fr, int fq) const {
;     ...
;             for (int e = 0; e < 8; ++e) { const float rs = (e < 4) ? r0[e & 3] : r1[e & 3];
; #pragma unroll
;                 for (int jj = 0; jj < 4; ++jj) { g[e][jj] = acc[e >> 2][0][e & 3][n][jj] * rs; v[e][jj] = acc[e >> 2][1][e & 3][n][jj] * rs; } }
;             if (fr == 0) {
; #pragma unroll
;                 for (int q = 0; q < 2; ++q) { v2u a, b; a.x = pk2(g[q][0], g[q][1]); a.y = pk2(g[q][2], g[q][3]); b.x = pk2(v[q][0], v[q][1]); b.y = pk2(v[q][2], v[q][3]);
;                     *(v2u*)(hb + (size_t)q * 256 + 4 * n) = a; *(v2u*)(hb + (size_t)q * 256 + 128 + 4 * n) = b; } }
.LBB0_1256:
	s_or_saveexec_b64 s[30:31], s[30:31]
	v_mov_b32_e32 v138, v132
	v_mov_b32_e32 v139, v134
	v_pk_mul_f32 v[196:197], v[138:139], v[40:41] op_sel_hi:[1,0]
	v_mov_b32_e32 v138, v120
	v_mov_b32_e32 v139, v122
	v_mov_b32_e32 v122, v121
	v_mov_b32_e32 v120, v124
	v_mov_b32_e32 v121, v126
	v_pk_mul_f32 v[188:189], v[120:121], v[40:41] op_sel:[0,1]
	v_mov_b32_e32 v120, v116
	v_mov_b32_e32 v121, v118
	v_mov_b32_e32 v118, v117
	v_mov_b32_e32 v116, v112
	v_mov_b32_e32 v117, v114
	v_mov_b32_e32 v112, v39
	v_pk_mul_f32 v[176:177], v[116:117], v[112:113] op_sel_hi:[1,0]
	v_mov_b32_e32 v116, v108
	v_mov_b32_e32 v117, v110
	v_mov_b32_e32 v114, v113
	v_mov_b32_e32 v110, v109
	v_mov_b32_e32 v134, v133
	v_mov_b32_e32 v126, v125
	v_pk_mul_f32 v[172:173], v[116:117], v[112:113] op_sel_hi:[1,0]
	v_pk_mul_f32 v[178:179], v[114:115], v[112:113] op_sel_hi:[1,0]
	v_pk_mul_f32 v[174:175], v[110:111], v[112:113] op_sel_hi:[1,0]
	v_pk_mul_f32 v[194:195], v[138:139], v[40:41] op_sel_hi:[1,0]
	v_pk_mul_f32 v[198:199], v[134:135], v[40:41] op_sel_hi:[1,0]
	v_pk_mul_f32 v[192:193], v[122:123], v[40:41] op_sel_hi:[1,0]
	v_pk_mul_f32 v[186:187], v[120:121], v[40:41] op_sel:[0,1]
	v_pk_mul_f32 v[190:191], v[126:127], v[40:41] op_sel:[0,1]
	v_pk_mul_f32 v[184:185], v[118:119], v[40:41] op_sel:[0,1]
	v_mov_b64_e32 v[116:117], 0x500
	v_mov_b64_e32 v[110:111], 0x600
	v_mov_b64_e32 v[108:109], 0x700
	v_mov_b64_e32 v[120:121], v[176:177]
	v_mov_b64_e32 v[118:119], v[178:179]
	v_mov_b64_e32 v[112:113], v[172:173]
	v_mov_b64_e32 v[114:115], v[174:175]
	s_xor_b64 exec, exec, s[30:31]
	s_cbranch_execz .LBB0_1260
	v_cmp_eq_u32_e32 vcc, 0, v3
	s_mov_b64 s[36:37], s[28:29]
	s_and_saveexec_b64 s[34:35], vcc
	s_cbranch_execz .LBB0_1259
	v_and_b32_sdwa v109, v196, v238 dst_sel:DWORD dst_unused:UNUSED_PAD src0_sel:WORD_1 src1_sel:DWORD
	v_add3_u32 v110, v196, v109, s55
	s_nop 0
	v_and_b32_sdwa v111, v198, v238 dst_sel:DWORD dst_unused:UNUSED_PAD src0_sel:WORD_1 src1_sel:DWORD
	s_nop 1
	v_add3_u32 v111, v198, v111, s55
	s_nop 1
	v_and_b32_e32 v111, 0xffff0000, v111
	v_and_b32_sdwa v112, v193, v238 dst_sel:DWORD dst_unused:UNUSED_PAD src0_sel:WORD_1 src1_sel:DWORD
	v_and_b32_sdwa v113, v192, v238 dst_sel:DWORD dst_unused:UNUSED_PAD src0_sel:WORD_1 src1_sel:DWORD
	v_cvt_pk_bf16_f32 v109, v197, v199
	v_or_b32_sdwa v108, v111, v110 dst_sel:DWORD dst_unused:UNUSED_PAD src0_sel:DWORD src1_sel:WORD_1
	v_and_b32_sdwa v110, v195, v238 dst_sel:DWORD dst_unused:UNUSED_PAD src0_sel:WORD_1 src1_sel:DWORD
	v_and_b32_sdwa v111, v194, v238 dst_sel:DWORD dst_unused:UNUSED_PAD src0_sel:WORD_1 src1_sel:DWORD
	v_add3_u32 v112, v193, v112, s55
	v_add3_u32 v113, v192, v113, s55
	v_add3_u32 v111, v194, v111, s55
	v_add3_u32 v110, v195, v110, s55
	v_and_b32_e32 v112, 0xffff0000, v112
	v_and_b32_e32 v113, 0xffff0000, v113
	v_or_b32_sdwa v129, v112, v110 dst_sel:DWORD dst_unused:UNUSED_PAD src0_sel:DWORD src1_sel:WORD_1
	v_or_b32_sdwa v128, v113, v111 dst_sel:DWORD dst_unused:UNUSED_PAD src0_sel:DWORD src1_sel:WORD_1
	s_or_b64 s[36:37], s[28:29], exec
	global_store_dwordx2 v[158:159], v[108:109], off

; __device__ __forceinline__ unsigned pk2(float lo, float hi) { return f2bf(lo) | (f2bf(hi) << 16); }
; __device__ __forceinline__ float dpp_shr1(float x) { return __builtin_bit_cast(float, __builtin_amdgcn_update_dpp(0, __builtin_bit_cast(int, x), 0x111, 0xf, 0xf, true)); }
;     __device__ __forceinline__ void operator()(const f32x4 (&acc)[2][2][4][2], const pg8::Unit& u, int wr, int wc, int fr, int fq) const {
;     ...
;             for (int e = 0; e < 8; ++e) { const float rs = (e < 4) ? r0[e & 3] : r1[e & 3];
; #pragma unroll
;                 for (int jj = 0; jj < 4; ++jj) { g[e][jj] = acc[e >> 2][0][e & 3][n][jj] * rs; v[e][jj] = acc[e >> 2][1][e & 3][n][jj] * rs; } }
;             if (fr == 0) {
; #pragma unroll
;                 for (int q = 0; q < 2; ++q) { v2u a, b; a.x = pk2(g[q][0], g[q][1]); a.y = pk2(g[q][2], g[q][3]); b.x = pk2(v[q][0], v[q][1]); b.y = pk2(v[q][2], v[q][3]);
;                     *(v2u*)(hb + (size_t)q * 256 + 4 * n) = a; *(v2u*)(hb + (size_t)q * 256 + 128 + 4 * n) = b; } }
;             if (fr == 15) {
; #pragma unroll
;                 for (int q = 0; q < 2; ++q) { v2u a, b; a.x = pk2(g[6 + q][0], g[6 + q][1]); a.y = pk2(g[6 + q][2], g[6 + q][3]); b.x = pk2(v[6 + q][0], v[6 + q][1]); b.y = pk2(v[6 + q][2], v[6 + q][3]);
;                     *(v2u*)(hb + (size_t)(2 + q) * 256 + 4 * n) = a; *(v2u*)(hb + (size_t)(2 + q) * 256 + 128 + 4 * n) = b; } }
;             const int cc = ch0 + 4 * n;
;             const f32x4 wg0 = *(CF4)(cw + cc), wg1 = *(CF4)(cw + FF2 + cc), wg2 = *(CF4)(cw + 2 * FF2 + cc), wv0 = *(CF4)(cw + FFH + cc), wv1 = *(CF4)(cw + FF2 + FFH + cc), wv2 = *(CF4)(cw + 2 * FF2 + FFH + cc);
;             const f32x4 bg = *(CF4)(cb + cc), bv = *(CF4)(cb + FFH + cc);
; #pragma unroll
;             for (int jj = 0; jj < 4; ++jj) {
;                 float g2 = dpp_shr1(g[6][jj]), g1 = dpp_shr1(g[7][jj]), v2 = dpp_shr1(v[6][jj]), v1 = dpp_shr1(v[7][jj]);
.LBB0_1260:
	s_or_b64 exec, exec, s[30:31]
	s_and_saveexec_b64 s[30:31], s[28:29]
	s_cbranch_execz .LBB0_1262
	v_lshl_add_u64 v[116:117], v[158:159], 0, v[116:117]
	global_store_dwordx2 v[116:117], v[128:129], off
	v_and_b32_sdwa v116, v121, v238 dst_sel:DWORD dst_unused:UNUSED_PAD src0_sel:WORD_1 src1_sel:DWORD
	v_and_b32_sdwa v117, v120, v238 dst_sel:DWORD dst_unused:UNUSED_PAD src0_sel:WORD_1 src1_sel:DWORD
	v_add3_u32 v120, v120, v117, s55
	v_add3_u32 v116, v121, v116, s55
	v_and_b32_sdwa v117, v119, v238 dst_sel:DWORD dst_unused:UNUSED_PAD src0_sel:WORD_1 src1_sel:DWORD
	v_and_b32_sdwa v121, v118, v238 dst_sel:DWORD dst_unused:UNUSED_PAD src0_sel:WORD_1 src1_sel:DWORD
	v_add3_u32 v117, v119, v117, s55
	v_add3_u32 v118, v118, v121, s55
	v_and_b32_e32 v117, 0xffff0000, v117
	v_and_b32_e32 v118, 0xffff0000, v118
	v_or_b32_sdwa v117, v117, v116 dst_sel:DWORD dst_unused:UNUSED_PAD src0_sel:DWORD src1_sel:WORD_1
	v_or_b32_sdwa v116, v118, v120 dst_sel:DWORD dst_unused:UNUSED_PAD src0_sel:DWORD src1_sel:WORD_1
	s_nop 7
	s_nop 1
	v_cvt_pk_bf16_f32 v113, v113, v115
	v_cvt_pk_bf16_f32 v112, v112, v114
	v_lshl_add_u64 v[110:111], v[158:159], 0, v[110:111]
	v_lshl_add_u64 v[108:109], v[158:159], 0, v[108:109]
	global_store_dwordx2 v[110:111], v[116:117], off
	global_store_dwordx2 v[108:109], v[112:113], off
.LBB0_1262:
	s_or_b64 exec, exec, s[30:31]
	v_lshl_or_b32 v132, s57, 7, v234
	v_ashrrev_i32_e32 v133, 31, v132
	v_readlane_b32 s60, v253, 2
	v_lshlrev_b64 v[200:201], 2, v[132:133]
	v_readlane_b32 s61, v253, 3
	v_readlane_b32 s62, v253, 4
	v_readlane_b32 s63, v253, 5
	v_lshl_add_u64 v[138:139], s[60:61], 0, v[200:201]
	global_load_dwordx4 v[108:111], v[138:139], off
	v_lshl_add_u64 v[134:135], s[62:63], 0, v[200:201]
	global_load_dwordx4 v[116:119], v[134:135], off
	v_lshl_add_u64 v[112:113], s[8:9], 0, v[200:201]
	global_load_dwordx4 v[120:123], v[112:113], off
	v_lshl_add_u64 v[112:113], s[10:11], 0, v[200:201]
	global_load_dwordx4 v[124:127], v[112:113], off
	v_mov_b32_e32 v112, v104
	v_mov_b32_e32 v113, v106
	v_pk_mul_f32 v[228:229], v[112:113], v[42:43] op_sel_hi:[1,0]
	v_mov_b32_e32 v112, v96
	v_mov_b32_e32 v113, v98
	v_mov_b32_e32 v98, v97
	v_lshl_add_u64 v[96:97], s[12:13], 0, v[200:201]
	v_pk_mul_f32 v[222:223], v[98:99], v[42:43] op_sel_hi:[1,0]
	global_load_dwordx4 v[96:99], v[96:97], off
	v_pk_mul_f32 v[224:225], v[112:113], v[42:43] op_sel_hi:[1,0]
	v_mov_b32_e32 v106, v105
	v_mov_b32_e32 v112, v100
	v_mov_b32_e32 v113, v102
	v_mov_b32_e32 v166, v43
	v_lshl_add_u64 v[104:105], s[18:19], 0, v[200:201]
	v_pk_mul_f32 v[226:227], v[106:107], v[42:43] op_sel_hi:[1,0]
	global_load_dwordx4 v[104:107], v[104:105], off
	v_pk_mul_f32 v[218:219], v[112:113], v[166:167] op_sel_hi:[1,0]
	v_lshl_add_u64 v[112:113], s[14:15], 0, v[200:201]
	global_load_dwordx4 v[112:115], v[112:113], off
	v_mov_b32_e32 v102, v101
	v_lshl_add_u64 v[100:101], s[16:17], 0, v[200:201]
	v_pk_mul_f32 v[220:221], v[102:103], v[166:167] op_sel_hi:[1,0]
	global_load_dwordx4 v[100:103], v[100:101], off
	v_mov_b32_e32 v203, v94
	v_mov_b32_e32 v94, v93
	v_mov_b32_e32 v170, v36
	v_mov_b32_e32 v171, v37
	v_pk_mul_f32 v[212:213], v[94:95], v[166:167] op_sel_hi:[1,0]
	v_mov_b32_e32 v94, v88
	v_mov_b32_e32 v95, v90
	v_pk_mul_f32 v[208:209], v[94:95], v[170:171] op_sel_hi:[1,0]
	v_mov_b32_e32 v94, v80
	v_mov_b32_e32 v95, v82
	v_mov_b32_e32 v82, v81
	v_mov_b32_e32 v80, v84
	v_mov_b32_e32 v81, v86
	v_mov_b32_e32 v90, v89
	v_pk_mul_f32 v[88:89], v[80:81], v[170:171] op_sel:[0,1]
	v_mov_b32_e32 v81, v78
	v_mov_b32_e32 v86, v85
	v_mov_b32_e32 v78, v77
	v_mov_b32_e32 v202, v92
	v_pk_mul_f32 v[200:201], v[94:95], v[170:171] op_sel_hi:[1,0]
	v_mov_b32_e32 v80, v76
	v_pk_mul_f32 v[84:85], v[86:87], v[170:171] op_sel:[0,1]
	v_pk_mul_f32 v[76:77], v[78:79], v[170:171] op_sel:[0,1]
	v_mov_b32_dpp v78, v168 row_shr:1 row_mask:0xf bank_mask:0xf bound_ctrl:1
	v_mov_b32_dpp v79, v169 row_shr:1 row_mask:0xf bank_mask:0xf bound_ctrl:1
	v_pk_mul_f32 v[214:215], v[202:203], v[166:167] op_sel_hi:[1,0]
	v_pk_mul_f32 v[206:207], v[90:91], v[170:171] op_sel_hi:[1,0]
	v_pk_mul_f32 v[90:91], v[82:83], v[170:171] op_sel_hi:[1,0]
	v_pk_mul_f32 v[82:83], v[80:81], v[170:171] op_sel:[0,1]
	v_mov_b32_dpp v80, v176 row_shr:1 row_mask:0xf bank_mask:0xf bound_ctrl:1
	v_mov_b32_dpp v81, v177 row_shr:1 row_mask:0xf bank_mask:0xf bound_ctrl:1
	v_mov_b32_dpp v210, v136 row_shr:1 row_mask:0xf bank_mask:0xf bound_ctrl:1
	v_mov_b32_dpp v211, v137 row_shr:1 row_mask:0xf bank_mask:0xf bound_ctrl:1
	v_mov_b32_dpp v242, v178 row_shr:1 row_mask:0xf bank_mask:0xf bound_ctrl:1
	v_mov_b32_dpp v243, v179 row_shr:1 row_mask:0xf bank_mask:0xf bound_ctrl:1
	v_mov_b32_dpp v170, v162 row_shr:1 row_mask:0xf bank_mask:0xf bound_ctrl:1
	v_mov_b32_dpp v171, v163 row_shr:1 row_mask:0xf bank_mask:0xf bound_ctrl:1
	v_mov_b32_dpp v240, v172 row_shr:1 row_mask:0xf bank_mask:0xf bound_ctrl:1
	v_mov_b32_dpp v241, v173 row_shr:1 row_mask:0xf bank_mask:0xf bound_ctrl:1
	v_mov_b32_dpp v216, v130 row_shr:1 row_mask:0xf bank_mask:0xf bound_ctrl:1
	v_mov_b32_dpp v217, v131 row_shr:1 row_mask:0xf bank_mask:0xf bound_ctrl:1
	v_mov_b32_dpp v244, v174 row_shr:1 row_mask:0xf bank_mask:0xf bound_ctrl:1
	v_mov_b32_dpp v245, v175 row_shr:1 row_mask:0xf bank_mask:0xf bound_ctrl:1
	v_mov_b32_e32 v180, v40
	v_mov_b32_e32 v181, v40
	v_mov_b32_e32 v40, v41
	v_mov_b32_e32 v182, v38
	v_mov_b32_e32 v183, v38
	v_mov_b32_e32 v38, v39
	s_waitcnt vmcnt(0)
; __device__ __forceinline__ unsigned pk2(float lo, float hi) { return f2bf(lo) | (f2bf(hi) << 16); }
; __device__ __forceinline__ float silu_fast(float x) { return x * __builtin_amdgcn_rcpf(1.f + __builtin_amdgcn_exp2f(-1.4426950408889634f * x)); }
; __device__ __forceinline__ float dpp_shr1(float x) { return __builtin_bit_cast(float, __builtin_amdgcn_update_dpp(0, __builtin_bit_cast(int, x), 0x111, 0xf, 0xf, true)); }
;     __device__ __forceinline__ void operator()(const f32x4 (&acc)[2][2][4][2], const pg8::Unit& u, int wr, int wc, int fr, int fq) const {
;     ...
;             for (int jj = 0; jj < 4; ++jj) {
;                 float g2 = dpp_shr1(g[6][jj]), g1 = dpp_shr1(g[7][jj]), v2 = dpp_shr1(v[6][jj]), v1 = dpp_shr1(v[7][jj]);
; #pragma unroll
;                 for (int e = 0; e < 8; ++e) { const float g0 = g[e][jj], v0 = v[e][jj];
;                     const float cg = bg[jj] + wg0[jj] * g2 + wg1[jj] * g1 + wg2[jj] * g0, cv = bv[jj] + wv0[jj] * v2 + wv1[jj] * v1 + wv2[jj] * v0;
;                     g[e][jj] = silu_fast(cg) * cv; g2 = g1; g1 = g0; v2 = v1; v1 = v0; } }
; #pragma unroll
;             for (int e = 0; e < 8; ++e) { v2u w; w.x = pk2(g[e][0], g[e][1]); w.y = pk2(g[e][2], g[e][3]); *(v2u*)(ACT + (size_t)(tok0 + e) * FFH + cc) = w; }
	v_mov_b32_e32 v86, v108
	v_mov_b32_e32 v87, v110
	v_mov_b32_e32 v94, v116
	v_mov_b32_e32 v95, v118
	v_pk_fma_f32 v[78:79], v[86:87], v[78:79], v[94:95]
	v_mov_b32_e32 v202, v120
	v_mov_b32_e32 v203, v122
	v_pk_fma_f32 v[78:79], v[202:203], v[80:81], v[78:79]
	v_mov_b32_e32 v204, v124
	v_mov_b32_e32 v205, v126
	v_pk_fma_f32 v[78:79], v[196:197], v[204:205], v[78:79]
	v_mov_b32_e32 v110, v109
	v_mul_f32_e32 v108, 0xbfb8aa3b, v78
	v_mov_b32_e32 v118, v117
	v_exp_f32_e32 v116, v108
	v_pk_fma_f32 v[108:109], v[110:111], v[210:211], v[118:119]
	v_mov_b32_e32 v122, v121
	v_pk_fma_f32 v[108:109], v[122:123], v[242:243], v[108:109]
	v_mov_b32_e32 v126, v125
	v_pk_fma_f32 v[108:109], v[198:199], v[126:127], v[108:109]
	v_add_f32_e32 v116, 1.0, v116
	v_mul_f32_e32 v117, 0xbfb8aa3b, v108
	v_exp_f32_e32 v117, v117
	v_rcp_f32_e32 v246, v116
	v_mov_b32_e32 v120, v104
	v_mov_b32_e32 v121, v106
	v_add_f32_e32 v116, 1.0, v117
	v_rcp_f32_e32 v248, v116
	v_mov_b32_e32 v116, v96
	v_mul_f32_e32 v96, 0xbfb8aa3b, v79
	v_exp_f32_e32 v96, v96
	v_mov_b32_e32 v117, v98
	v_pk_fma_f32 v[124:125], v[116:117], v[170:171], v[120:121]
	v_mov_b32_e32 v210, v112
	v_add_f32_e32 v96, 1.0, v96
	v_mov_b32_e32 v211, v114
	v_rcp_f32_e32 v247, v96
	v_mul_f32_e32 v96, 0xbfb8aa3b, v109
	v_pk_fma_f32 v[170:171], v[210:211], v[240:241], v[124:125]
	v_mov_b32_e32 v124, v100
	v_exp_f32_e32 v100, v96
	v_mov_b32_e32 v98, v97
	v_mov_b32_e32 v106, v105
	v_mov_b32_e32 v125, v102
	v_add_f32_e32 v100, 1.0, v100
	v_rcp_f32_e32 v249, v100
	v_pk_fma_f32 v[96:97], v[98:99], v[216:217], v[106:107]
	v_mov_b32_e32 v114, v113
	v_pk_fma_f32 v[170:171], v[194:195], v[124:125], v[170:171]
	v_pk_mul_f32 v[78:79], v[78:79], v[246:247]
	v_pk_fma_f32 v[96:97], v[114:115], v[244:245], v[96:97]
	v_mov_b32_e32 v102, v101
	v_pk_mul_f32 v[78:79], v[170:171], v[78:79]
	v_pk_fma_f32 v[96:97], v[192:193], v[102:103], v[96:97]
	v_pk_mul_f32 v[100:101], v[108:109], v[248:249]
	v_pk_fma_f32 v[80:81], v[86:87], v[80:81], v[94:95]
	v_pk_mul_f32 v[96:97], v[96:97], v[100:101]
	s_nop 7
	s_nop 1
	v_mov_b64_e32 v[112:113], s[78:79]
	v_pk_fma_f32 v[80:81], v[196:197], v[202:203], v[80:81]
	v_cvt_pk_bf16_f32 v79, v79, v97
	v_cvt_pk_bf16_f32 v78, v78, v96
	v_mad_i64_i32 v[96:97], s[28:29], v160, s56, v[112:113]
	v_lshlrev_b64 v[216:217], 1, v[132:133]
	v_pk_fma_f32 v[80:81], v[188:189], v[204:205], v[80:81]
	v_lshl_add_u64 v[170:171], v[96:97], 0, v[216:217]
	v_mul_f32_e32 v96, 0xbfb8aa3b, v80
	v_exp_f32_e32 v100, v96
	v_pk_fma_f32 v[96:97], v[110:111], v[242:243], v[118:119]
	global_store_dwordx2 v[170:171], v[78:79], off
	v_pk_fma_f32 v[96:97], v[198:199], v[122:123], v[96:97]
	v_add_f32_e32 v78, 1.0, v100
	v_pk_fma_f32 v[96:97], v[190:191], v[126:127], v[96:97]
	v_mul_f32_e32 v100, 0xbfb8aa3b, v81
	v_mul_f32_e32 v101, 0xbfb8aa3b, v96
	v_exp_f32_e32 v101, v101
	v_rcp_f32_e32 v78, v78
	v_pk_fma_f32 v[104:105], v[116:117], v[240:241], v[120:121]
	v_mov_b32_e32 v128, v42
	v_add_f32_e32 v79, 1.0, v101
	v_exp_f32_e32 v101, v100
	v_rcp_f32_e32 v100, v79
	v_pk_fma_f32 v[104:105], v[194:195], v[210:211], v[104:105]
	v_mov_b32_e32 v129, v42
	v_add_f32_e32 v79, 1.0, v101
	v_mul_f32_e32 v101, 0xbfb8aa3b, v97
	v_rcp_f32_e32 v79, v79
	v_exp_f32_e32 v101, v101
	v_pk_fma_f32 v[104:105], v[186:187], v[124:125], v[104:105]
	v_mov_b32_e32 v42, v43
	v_pk_mul_f32 v[78:79], v[80:81], v[78:79]
	v_add_f32_e32 v80, 1.0, v101
	v_rcp_f32_e32 v101, v80
	v_pk_fma_f32 v[80:81], v[98:99], v[244:245], v[106:107]
	v_pk_mul_f32 v[78:79], v[104:105], v[78:79]
	v_pk_fma_f32 v[80:81], v[192:193], v[114:115], v[80:81]
	v_pk_mul_f32 v[96:97], v[96:97], v[100:101]
	v_pk_fma_f32 v[80:81], v[184:185], v[102:103], v[80:81]
	v_pk_fma_f32 v[104:105], v[194:195], v[116:117], v[120:121]
	v_pk_mul_f32 v[80:81], v[80:81], v[96:97]
	s_nop 7
	s_nop 1
	v_cvt_pk_bf16_f32 v78, v78, v80
	v_or_b32_e32 v80, 1, v160
	v_cvt_pk_bf16_f32 v79, v79, v81
	v_mad_i64_i32 v[80:81], s[28:29], v80, s56, v[112:113]
	v_lshl_add_u64 v[108:109], v[80:81], 0, v[216:217]
	v_pk_fma_f32 v[80:81], v[196:197], v[86:87], v[94:95]
	global_store_dwordx2 v[108:109], v[78:79], off
	v_pk_fma_f32 v[80:81], v[188:189], v[202:203], v[80:81]
	v_pk_fma_f32 v[104:105], v[186:187], v[210:211], v[104:105]
	v_pk_fma_f32 v[80:81], v[228:229], v[204:205], v[80:81]
	v_pk_fma_f32 v[104:105], v[224:225], v[124:125], v[104:105]
	v_mul_f32_e32 v96, 0xbfb8aa3b, v80
	v_exp_f32_e32 v100, v96
	v_pk_fma_f32 v[96:97], v[198:199], v[110:111], v[118:119]
	v_pk_fma_f32 v[186:187], v[186:187], v[116:117], v[120:121]
	v_pk_fma_f32 v[96:97], v[190:191], v[122:123], v[96:97]
	v_add_f32_e32 v78, 1.0, v100
	v_pk_fma_f32 v[96:97], v[226:227], v[126:127], v[96:97]
	v_mul_f32_e32 v100, 0xbfb8aa3b, v81
	v_mul_f32_e32 v101, 0xbfb8aa3b, v96
	v_exp_f32_e32 v101, v101
	v_rcp_f32_e32 v78, v78
	v_pk_fma_f32 v[186:187], v[224:225], v[210:211], v[186:187]
	v_mov_b32_e32 v92, v36
	v_add_f32_e32 v79, 1.0, v101
	v_exp_f32_e32 v101, v100
	v_rcp_f32_e32 v100, v79
	v_pk_fma_f32 v[186:187], v[214:215], v[124:125], v[186:187]
	v_mov_b32_e32 v93, v36
	v_add_f32_e32 v79, 1.0, v101
	v_mul_f32_e32 v101, 0xbfb8aa3b, v97
	v_rcp_f32_e32 v79, v79
	v_exp_f32_e32 v101, v101
	v_mov_b32_e32 v36, v37
	v_cmp_gt_i32_e32 vcc, 15, v3
	v_pk_mul_f32 v[78:79], v[80:81], v[78:79]
	v_add_f32_e32 v80, 1.0, v101
	v_rcp_f32_e32 v101, v80
	v_pk_fma_f32 v[80:81], v[192:193], v[98:99], v[106:107]
	v_pk_mul_f32 v[78:79], v[104:105], v[78:79]
	v_pk_fma_f32 v[80:81], v[184:185], v[114:115], v[80:81]
	v_pk_mul_f32 v[96:97], v[96:97], v[100:101]
	v_pk_fma_f32 v[80:81], v[222:223], v[102:103], v[80:81]
	s_mov_b64 s[30:31], -1
	v_pk_mul_f32 v[80:81], v[80:81], v[96:97]
	s_nop 7
	s_nop 1
; __device__ __forceinline__ unsigned pk2(float lo, float hi) { return f2bf(lo) | (f2bf(hi) << 16); }
; __device__ __forceinline__ float silu_fast(float x) { return x * __builtin_amdgcn_rcpf(1.f + __builtin_amdgcn_exp2f(-1.4426950408889634f * x)); }
; __device__ __forceinline__ float dpp_shr1(float x) { return __builtin_bit_cast(float, __builtin_amdgcn_update_dpp(0, __builtin_bit_cast(int, x), 0x111, 0xf, 0xf, true)); }
;     __device__ __forceinline__ void operator()(const f32x4 (&acc)[2][2][4][2], const pg8::Unit& u, int wr, int wc, int fr, int fq) const {
;     ...
;             const int cc = ch0 + 4 * n;
;             const f32x4 wg0 = *(CF4)(cw + cc), wg1 = *(CF4)(cw + FF2 + cc), wg2 = *(CF4)(cw + 2 * FF2 + cc), wv0 = *(CF4)(cw + FFH + cc), wv1 = *(CF4)(cw + FF2 + FFH + cc), wv2 = *(CF4)(cw + 2 * FF2 + FFH + cc);
;             const f32x4 bg = *(CF4)(cb + cc), bv = *(CF4)(cb + FFH + cc);
; #pragma unroll
;             for (int jj = 0; jj < 4; ++jj) {
;                 float g2 = dpp_shr1(g[6][jj]), g1 = dpp_shr1(g[7][jj]), v2 = dpp_shr1(v[6][jj]), v1 = dpp_shr1(v[7][jj]);
; #pragma unroll
;                 for (int e = 0; e < 8; ++e) { const float g0 = g[e][jj], v0 = v[e][jj];
;                     const float cg = bg[jj] + wg0[jj] * g2 + wg1[jj] * g1 + wg2[jj] * g0, cv = bv[jj] + wv0[jj] * v2 + wv1[jj] * v1 + wv2[jj] * v0;
;                     g[e][jj] = silu_fast(cg) * cv; g2 = g1; g1 = g0; v2 = v1; v1 = v0; } }
; #pragma unroll
;             for (int e = 0; e < 8; ++e) { v2u w; w.x = pk2(g[e][0], g[e][1]); w.y = pk2(g[e][2], g[e][3]); *(v2u*)(ACT + (size_t)(tok0 + e) * FFH + cc) = w; }
	v_cvt_pk_bf16_f32 v78, v78, v80
	v_or_b32_e32 v80, 2, v160
	v_cvt_pk_bf16_f32 v79, v79, v81
	v_mad_i64_i32 v[80:81], s[28:29], v80, s56, v[112:113]
	v_lshl_add_u64 v[104:105], v[80:81], 0, v[216:217]
	v_pk_fma_f32 v[80:81], v[188:189], v[86:87], v[94:95]
	global_store_dwordx2 v[104:105], v[78:79], off
	v_pk_fma_f32 v[80:81], v[228:229], v[202:203], v[80:81]
	v_pk_fma_f32 v[188:189], v[214:215], v[116:117], v[120:121]
	v_pk_fma_f32 v[80:81], v[218:219], v[204:205], v[80:81]
	v_pk_fma_f32 v[188:189], v[200:201], v[210:211], v[188:189]
	v_mul_f32_e32 v96, 0xbfb8aa3b, v80
	v_exp_f32_e32 v100, v96
	v_pk_fma_f32 v[96:97], v[190:191], v[110:111], v[118:119]
	v_pk_fma_f32 v[188:189], v[82:83], v[124:125], v[188:189]
	v_pk_fma_f32 v[96:97], v[226:227], v[122:123], v[96:97]
	v_add_f32_e32 v78, 1.0, v100
	v_pk_fma_f32 v[96:97], v[220:221], v[126:127], v[96:97]
	v_mul_f32_e32 v100, 0xbfb8aa3b, v81
	v_mul_f32_e32 v101, 0xbfb8aa3b, v96
	v_exp_f32_e32 v101, v101
	v_rcp_f32_e32 v78, v78
	v_pk_fma_f32 v[190:191], v[200:201], v[116:117], v[120:121]
	v_readlane_b32 s64, v253, 6
	v_add_f32_e32 v79, 1.0, v101
	v_exp_f32_e32 v101, v100
	v_rcp_f32_e32 v100, v79
	v_pk_fma_f32 v[190:191], v[82:83], v[210:211], v[190:191]
	v_pk_fma_f32 v[82:83], v[82:83], v[116:117], v[120:121]
	v_add_f32_e32 v79, 1.0, v101
	v_mul_f32_e32 v101, 0xbfb8aa3b, v97
	v_rcp_f32_e32 v79, v79
	v_exp_f32_e32 v101, v101
	v_pk_fma_f32 v[190:191], v[162:163], v[124:125], v[190:191]
	v_pk_fma_f32 v[82:83], v[162:163], v[210:211], v[82:83]
	v_pk_mul_f32 v[78:79], v[80:81], v[78:79]
	v_add_f32_e32 v80, 1.0, v101
	v_rcp_f32_e32 v101, v80
	v_pk_fma_f32 v[80:81], v[184:185], v[98:99], v[106:107]
	v_pk_mul_f32 v[78:79], v[186:187], v[78:79]
	v_pk_fma_f32 v[80:81], v[222:223], v[114:115], v[80:81]
	v_pk_mul_f32 v[96:97], v[96:97], v[100:101]
	v_pk_fma_f32 v[80:81], v[212:213], v[102:103], v[80:81]
	v_pk_fma_f32 v[186:187], v[224:225], v[116:117], v[120:121]
	v_pk_mul_f32 v[80:81], v[80:81], v[96:97]
	s_nop 7
	s_nop 1
	v_cvt_pk_bf16_f32 v78, v78, v80
	v_or_b32_e32 v80, 3, v160
	v_cvt_pk_bf16_f32 v79, v79, v81
	v_mad_i64_i32 v[80:81], s[28:29], v80, s56, v[112:113]
	v_lshl_add_u64 v[100:101], v[80:81], 0, v[216:217]
	v_pk_fma_f32 v[80:81], v[228:229], v[86:87], v[94:95]
	global_store_dwordx2 v[100:101], v[78:79], off
	v_pk_fma_f32 v[80:81], v[218:219], v[202:203], v[80:81]
	v_pk_fma_f32 v[186:187], v[214:215], v[210:211], v[186:187]
	v_pk_fma_f32 v[80:81], v[208:209], v[204:205], v[80:81]
	v_pk_fma_f32 v[186:187], v[200:201], v[124:125], v[186:187]
	v_mul_f32_e32 v96, 0xbfb8aa3b, v80
	v_exp_f32_e32 v133, v96
	v_pk_fma_f32 v[96:97], v[226:227], v[110:111], v[118:119]
	v_pk_fma_f32 v[82:83], v[172:173], v[124:125], v[82:83]
	v_pk_fma_f32 v[96:97], v[220:221], v[122:123], v[96:97]
	v_add_f32_e32 v78, 1.0, v133
	v_pk_fma_f32 v[96:97], v[206:207], v[126:127], v[96:97]
	v_mul_f32_e32 v133, 0xbfb8aa3b, v81
	v_mul_f32_e32 v161, 0xbfb8aa3b, v96
	v_exp_f32_e32 v161, v161
	v_exp_f32_e32 v133, v133
	v_rcp_f32_e32 v78, v78
	v_readlane_b32 s65, v253, 7
	v_add_f32_e32 v79, 1.0, v161
	v_rcp_f32_e32 v184, v79
	v_add_f32_e32 v79, 1.0, v133
	v_mul_f32_e32 v133, 0xbfb8aa3b, v97
	v_rcp_f32_e32 v79, v79
	v_exp_f32_e32 v133, v133
	v_readlane_b32 s66, v253, 8
	v_readlane_b32 s67, v253, 9
	v_pk_mul_f32 v[78:79], v[80:81], v[78:79]
	v_add_f32_e32 v80, 1.0, v133
	v_rcp_f32_e32 v185, v80
	v_pk_fma_f32 v[80:81], v[222:223], v[98:99], v[106:107]
	v_pk_mul_f32 v[78:79], v[186:187], v[78:79]
	v_pk_fma_f32 v[80:81], v[212:213], v[114:115], v[80:81]
	v_pk_mul_f32 v[96:97], v[96:97], v[184:185]
	v_pk_fma_f32 v[80:81], v[90:91], v[102:103], v[80:81]
	v_pk_fma_f32 v[184:185], v[220:221], v[110:111], v[118:119]
	v_pk_mul_f32 v[80:81], v[80:81], v[96:97]
	s_nop 7
	s_nop 1
	v_cvt_pk_bf16_f32 v78, v78, v80
	v_or_b32_e32 v80, 4, v160
	v_cvt_pk_bf16_f32 v79, v79, v81
	v_mad_i64_i32 v[80:81], s[28:29], v80, s56, v[112:113]
	v_lshl_add_u64 v[96:97], v[80:81], 0, v[216:217]
	v_pk_fma_f32 v[80:81], v[218:219], v[86:87], v[94:95]
	v_pk_fma_f32 v[184:185], v[206:207], v[122:123], v[184:185]
	v_pk_fma_f32 v[80:81], v[208:209], v[202:203], v[80:81]
	v_pk_fma_f32 v[184:185], v[84:85], v[126:127], v[184:185]
	v_pk_fma_f32 v[80:81], v[88:89], v[204:205], v[80:81]
	v_mul_f32_e32 v161, 0xbfb8aa3b, v184
	v_mul_f32_e32 v133, 0xbfb8aa3b, v80
	v_exp_f32_e32 v133, v133
	v_exp_f32_e32 v161, v161
	global_store_dwordx2 v[96:97], v[78:79], off
	v_add_f32_e32 v78, 1.0, v133
	v_mul_f32_e32 v133, 0xbfb8aa3b, v81
	v_exp_f32_e32 v133, v133
	v_add_f32_e32 v79, 1.0, v161
	v_rcp_f32_e32 v186, v79
	v_rcp_f32_e32 v78, v78
	v_add_f32_e32 v79, 1.0, v133
	v_mul_f32_e32 v133, 0xbfb8aa3b, v185
	v_rcp_f32_e32 v79, v79
	v_exp_f32_e32 v133, v133
	v_pk_mul_f32 v[78:79], v[80:81], v[78:79]
	v_add_f32_e32 v80, 1.0, v133
	v_rcp_f32_e32 v187, v80
	v_pk_fma_f32 v[80:81], v[212:213], v[98:99], v[106:107]
	v_pk_mul_f32 v[78:79], v[188:189], v[78:79]
	v_pk_fma_f32 v[80:81], v[90:91], v[114:115], v[80:81]
	v_pk_mul_f32 v[184:185], v[184:185], v[186:187]
	v_pk_fma_f32 v[80:81], v[76:77], v[102:103], v[80:81]
	v_and_b32_sdwa v133, v79, v238 dst_sel:DWORD dst_unused:UNUSED_PAD src0_sel:WORD_1 src1_sel:DWORD
	v_pk_mul_f32 v[80:81], v[80:81], v[184:185]
	v_pk_fma_f32 v[184:185], v[208:209], v[86:87], v[94:95]
	s_nop 0
	v_pk_fma_f32 v[184:185], v[88:89], v[202:203], v[184:185]
	s_nop 0
	v_add3_u32 v79, v79, v133, s55
	v_and_b32_sdwa v133, v81, v238 dst_sel:DWORD dst_unused:UNUSED_PAD src0_sel:WORD_1 src1_sel:DWORD
	s_nop 0
	v_pk_fma_f32 v[184:185], v[168:169], v[204:205], v[184:185]
	v_add3_u32 v81, v81, v133, s55
	s_nop 0
	v_mul_f32_e32 v133, 0xbfb8aa3b, v184
	s_nop 0
	v_exp_f32_e32 v133, v133
; __device__ __forceinline__ unsigned pk2(float lo, float hi) { return f2bf(lo) | (f2bf(hi) << 16); }
; __device__ __forceinline__ float silu_fast(float x) { return x * __builtin_amdgcn_rcpf(1.f + __builtin_amdgcn_exp2f(-1.4426950408889634f * x)); }
; __device__ __forceinline__ float dpp_shr1(float x) { return __builtin_bit_cast(float, __builtin_amdgcn_update_dpp(0, __builtin_bit_cast(int, x), 0x111, 0xf, 0xf, true)); }
;     __device__ __forceinline__ void operator()(const f32x4 (&acc)[2][2][4][2], const pg8::Unit& u, int wr, int wc, int fr, int fq) const {
;     ...
;             for (int e = 0; e < 8; ++e) { const float rs = (e < 4) ? r0[e & 3] : r1[e & 3];
; #pragma unroll
;                 for (int jj = 0; jj < 4; ++jj) { g[e][jj] = acc[e >> 2][0][e & 3][n][jj] * rs; v[e][jj] = acc[e >> 2][1][e & 3][n][jj] * rs; } }
;             if (fr == 0) {
; #pragma unroll
;                 for (int q = 0; q < 2; ++q) { v2u a, b; a.x = pk2(g[q][0], g[q][1]); a.y = pk2(g[q][2], g[q][3]); b.x = pk2(v[q][0], v[q][1]); b.y = pk2(v[q][2], v[q][3]);
;                     *(v2u*)(hb + (size_t)q * 256 + 4 * n) = a; *(v2u*)(hb + (size_t)q * 256 + 128 + 4 * n) = b; } }
;     ...
;             for (int jj = 0; jj < 4; ++jj) {
;                 float g2 = dpp_shr1(g[6][jj]), g1 = dpp_shr1(g[7][jj]), v2 = dpp_shr1(v[6][jj]), v1 = dpp_shr1(v[7][jj]);
; #pragma unroll
;                 for (int e = 0; e < 8; ++e) { const float g0 = g[e][jj], v0 = v[e][jj];
;                     const float cg = bg[jj] + wg0[jj] * g2 + wg1[jj] * g1 + wg2[jj] * g0, cv = bv[jj] + wv0[jj] * v2 + wv1[jj] * v1 + wv2[jj] * v0;
;                     g[e][jj] = silu_fast(cg) * cv; g2 = g1; g1 = g0; v2 = v1; v1 = v0; } }
; #pragma unroll
;             for (int e = 0; e < 8; ++e) { v2u w; w.x = pk2(g[e][0], g[e][1]); w.y = pk2(g[e][2], g[e][3]); *(v2u*)(ACT + (size_t)(tok0 + e) * FFH + cc) = w; }
	v_pk_fma_f32 v[186:187], v[206:207], v[110:111], v[118:119]
	v_and_b32_e32 v81, 0xffff0000, v81
	v_cvt_pk_bf16_f32 v78, v78, v80
	v_or_b32_e32 v80, 5, v160
	v_pk_fma_f32 v[186:187], v[84:85], v[122:123], v[186:187]
	v_or_b32_sdwa v79, v81, v79 dst_sel:DWORD dst_unused:UNUSED_PAD src0_sel:DWORD src1_sel:WORD_1
	v_mad_i64_i32 v[80:81], s[28:29], v80, s56, v[112:113]
	v_pk_fma_f32 v[186:187], v[136:137], v[126:127], v[186:187]
	v_lshl_add_u64 v[80:81], v[80:81], 0, v[216:217]
	v_mul_f32_e32 v161, 0xbfb8aa3b, v186
	v_exp_f32_e32 v161, v161
	global_store_dwordx2 v[80:81], v[78:79], off
	v_add_f32_e32 v78, 1.0, v133
	v_mul_f32_e32 v133, 0xbfb8aa3b, v185
	v_exp_f32_e32 v133, v133
	v_add_f32_e32 v79, 1.0, v161
	v_rcp_f32_e32 v188, v79
	v_rcp_f32_e32 v78, v78
	v_add_f32_e32 v79, 1.0, v133
	v_mul_f32_e32 v133, 0xbfb8aa3b, v187
	v_exp_f32_e32 v133, v133
	v_rcp_f32_e32 v79, v79
	v_pk_fma_f32 v[90:91], v[90:91], v[98:99], v[106:107]
	v_pk_fma_f32 v[84:85], v[84:85], v[110:111], v[118:119]
	v_add_f32_e32 v133, 1.0, v133
	v_rcp_f32_e32 v189, v133
	v_pk_mul_f32 v[78:79], v[184:185], v[78:79]
	v_pk_fma_f32 v[90:91], v[76:77], v[114:115], v[90:91]
	v_pk_mul_f32 v[78:79], v[190:191], v[78:79]
	v_pk_fma_f32 v[90:91], v[130:131], v[102:103], v[90:91]
	v_pk_mul_f32 v[184:185], v[186:187], v[188:189]
	v_and_b32_sdwa v161, v78, v238 dst_sel:DWORD dst_unused:UNUSED_PAD src0_sel:WORD_1 src1_sel:DWORD
	v_pk_mul_f32 v[90:91], v[90:91], v[184:185]
	s_nop 0
	v_add3_u32 v78, v78, v161, s55
	v_and_b32_sdwa v161, v90, v238 dst_sel:DWORD dst_unused:UNUSED_PAD src0_sel:WORD_1 src1_sel:DWORD
	s_nop 1
	v_add3_u32 v90, v90, v161, s55
	s_nop 0
	v_and_b32_e32 v90, 0xffff0000, v90
	s_nop 0
	v_or_b32_sdwa v90, v90, v78 dst_sel:DWORD dst_unused:UNUSED_PAD src0_sel:DWORD src1_sel:WORD_1
	v_or_b32_e32 v78, 6, v160
	v_pk_fma_f32 v[86:87], v[88:89], v[86:87], v[94:95]
	v_pk_fma_f32 v[84:85], v[136:137], v[122:123], v[84:85]
	v_cvt_pk_bf16_f32 v91, v79, v91
	v_mad_i64_i32 v[78:79], s[28:29], v78, s56, v[112:113]
	v_pk_fma_f32 v[86:87], v[168:169], v[202:203], v[86:87]
	v_pk_fma_f32 v[84:85], v[178:179], v[126:127], v[84:85]
	v_lshl_add_u64 v[78:79], v[78:79], 0, v[216:217]
	v_pk_fma_f32 v[86:87], v[176:177], v[204:205], v[86:87]
	v_mul_f32_e32 v89, 0xbfb8aa3b, v84
	v_mul_f32_e32 v88, 0xbfb8aa3b, v86
	v_exp_f32_e32 v89, v89
	global_store_dwordx2 v[78:79], v[90:91], off
	v_mul_f32_e32 v90, 0xbfb8aa3b, v87
	v_exp_f32_e32 v88, v88
	v_exp_f32_e32 v91, v90
	v_add_f32_e32 v89, 1.0, v89
	v_rcp_f32_e32 v90, v89
	v_add_f32_e32 v88, 1.0, v88
	v_add_f32_e32 v89, 1.0, v91
	v_rcp_f32_e32 v88, v88
	v_rcp_f32_e32 v89, v89
	v_mul_f32_e32 v91, 0xbfb8aa3b, v85
	v_exp_f32_e32 v91, v91
	v_pk_fma_f32 v[76:77], v[76:77], v[98:99], v[106:107]
	v_pk_mul_f32 v[86:87], v[86:87], v[88:89]
	v_pk_fma_f32 v[76:77], v[130:131], v[114:115], v[76:77]
	v_pk_mul_f32 v[82:83], v[82:83], v[86:87]
	v_add_f32_e32 v86, 1.0, v91
	v_rcp_f32_e32 v91, v86
	v_pk_fma_f32 v[76:77], v[174:175], v[102:103], v[76:77]
	v_pk_mul_f32 v[84:85], v[84:85], v[90:91]
	s_nop 0
	v_pk_mul_f32 v[76:77], v[76:77], v[84:85]
	s_nop 7
	s_nop 1
	v_cvt_pk_bf16_f32 v82, v82, v76
	v_or_b32_e32 v76, 7, v160
	v_cvt_pk_bf16_f32 v83, v83, v77
	v_mad_i64_i32 v[76:77], s[28:29], v76, s56, v[112:113]
	v_lshl_add_u64 v[76:77], v[76:77], 0, v[216:217]
	global_store_dwordx2 v[76:77], v[82:83], off
	v_mov_b32_e32 v82, v72
	v_mov_b32_e32 v83, v74
	v_pk_mul_f32 v[126:127], v[82:83], v[180:181]
	v_mov_b32_e32 v82, v64
	v_mov_b32_e32 v83, v66
	v_mov_b32_e32 v66, v65
	v_mov_b32_e32 v64, v68
	v_mov_b32_e32 v65, v70
	v_pk_mul_f32 v[112:113], v[64:65], v[40:41]
	v_mov_b32_e32 v64, v60
	v_mov_b32_e32 v65, v62
	v_mov_b32_e32 v70, v69
	v_mov_b32_e32 v62, v61
	v_pk_mul_f32 v[114:115], v[64:65], v[40:41]
	v_pk_mul_f32 v[116:117], v[70:71], v[40:41]
	v_pk_mul_f32 v[118:119], v[62:63], v[40:41]
	v_mov_b32_e32 v40, v56
	v_mov_b32_e32 v41, v58
	v_pk_mul_f32 v[88:89], v[40:41], v[182:183]
	v_mov_b32_e32 v40, v48
	v_mov_b32_e32 v41, v50
	v_pk_mul_f32 v[122:123], v[82:83], v[180:181]
	v_pk_mul_f32 v[82:83], v[40:41], v[182:183]
	v_mov_b32_e32 v40, v52
	v_mov_b32_e32 v41, v54
	v_mov_b32_e32 v74, v73
	v_mov_b32_e32 v58, v57
	v_mov_b32_e32 v50, v49
	v_pk_mul_f32 v[94:95], v[40:41], v[38:39]
	v_mov_b32_e32 v40, v44
	v_mov_b32_e32 v41, v46
	v_mov_b32_e32 v54, v53
	v_mov_b32_e32 v46, v45
	v_pk_mul_f32 v[124:125], v[74:75], v[180:181]
	v_pk_mul_f32 v[86:87], v[58:59], v[182:183]
	v_pk_mul_f32 v[72:73], v[50:51], v[182:183]
	v_pk_mul_f32 v[84:85], v[40:41], v[38:39]
	v_pk_mul_f32 v[90:91], v[54:55], v[38:39]
	v_pk_mul_f32 v[74:75], v[46:47], v[38:39]
	v_pk_mul_f32 v[120:121], v[66:67], v[180:181]
	v_mov_b64_e32 v[44:45], 0x408
	v_mov_b64_e32 v[46:47], 0x508
	v_mov_b64_e32 v[38:39], 0x608
	v_mov_b64_e32 v[40:41], 0x708
	v_mov_b64_e32 v[54:55], v[94:95]
	v_mov_b64_e32 v[52:53], v[90:91]
	v_mov_b64_e32 v[50:51], v[84:85]
	v_mov_b64_e32 v[48:49], v[74:75]
	v_mov_b64_e32 v[62:63], v[88:89]
	v_mov_b64_e32 v[60:61], v[86:87]
	v_mov_b64_e32 v[58:59], v[82:83]
	v_mov_b64_e32 v[56:57], v[72:73]
	s_and_saveexec_b64 s[28:29], vcc
	s_cbranch_execz .LBB0_1266
	v_cmp_eq_u32_e32 vcc, 0, v3
	s_mov_b64 s[30:31], 0
	v_mov_b64_e32 v[44:45], 0x408
	v_mov_b64_e32 v[46:47], 0x508
	v_mov_b64_e32 v[38:39], 0x608
	v_mov_b64_e32 v[40:41], 0x708
	s_and_saveexec_b64 s[34:35], vcc
	s_mov_b64 s[30:31], exec
	v_mov_b64_e32 v[44:45], 8
	v_mov_b64_e32 v[46:47], 0x108
	v_mov_b64_e32 v[38:39], 0x208
	v_mov_b64_e32 v[40:41], 0x308
	s_or_b64 exec, exec, s[34:35]
	s_orn2_b64 s[30:31], s[30:31], exec
	v_mov_b64_e32 v[54:55], v[112:113]
	v_mov_b64_e32 v[52:53], v[116:117]
	v_mov_b64_e32 v[50:51], v[114:115]
	v_mov_b64_e32 v[48:49], v[118:119]
	v_mov_b64_e32 v[62:63], v[126:127]
	v_mov_b64_e32 v[60:61], v[124:125]
	v_mov_b64_e32 v[58:59], v[122:123]
	v_mov_b64_e32 v[56:57], v[120:121]
; __device__ __forceinline__ unsigned pk2(float lo, float hi) { return f2bf(lo) | (f2bf(hi) << 16); }
;     __device__ __forceinline__ void operator()(const f32x4 (&acc)[2][2][4][2], const pg8::Unit& u, int wr, int wc, int fr, int fq) const {
;     ...
;             if (fr == 0) {
; #pragma unroll
;                 for (int q = 0; q < 2; ++q) { v2u a, b; a.x = pk2(g[q][0], g[q][1]); a.y = pk2(g[q][2], g[q][3]); b.x = pk2(v[q][0], v[q][1]); b.y = pk2(v[q][2], v[q][3]);
;                     *(v2u*)(hb + (size_t)q * 256 + 4 * n) = a; *(v2u*)(hb + (size_t)q * 256 + 128 + 4 * n) = b; } }
;             if (fr == 15) {
; #pragma unroll
;                 for (int q = 0; q < 2; ++q) { v2u a, b; a.x = pk2(g[6 + q][0], g[6 + q][1]); a.y = pk2(g[6 + q][2], g[6 + q][3]); b.x = pk2(v[6 + q][0], v[6 + q][1]); b.y = pk2(v[6 + q][2], v[6 + q][3]);
;                     *(v2u*)(hb + (size_t)(2 + q) * 256 + 4 * n) = a; *(v2u*)(hb + (size_t)(2 + q) * 256 + 128 + 4 * n) = b; } }
.LBB0_1266:
	s_or_b64 exec, exec, s[28:29]
	s_and_saveexec_b64 s[28:29], s[30:31]
	s_cbranch_execz .LBB0_1249
	s_nop 7
	s_nop 1
	v_cvt_pk_bf16_f32 v61, v63, v61
	v_cvt_pk_bf16_f32 v60, v62, v60
	s_nop 7
	s_nop 1
	v_lshl_add_u64 v[44:45], v[158:159], 0, v[44:45]
	v_cvt_pk_bf16_f32 v57, v59, v57
	v_cvt_pk_bf16_f32 v56, v58, v56
	global_store_dwordx2 v[44:45], v[60:61], off
	v_lshl_add_u64 v[44:45], v[158:159], 0, v[46:47]
	global_store_dwordx2 v[44:45], v[56:57], off
	v_and_b32_sdwa v45, v54, v238 dst_sel:DWORD dst_unused:UNUSED_PAD src0_sel:WORD_1 src1_sel:DWORD
	v_add3_u32 v46, v54, v45, s55
	s_nop 0
	v_and_b32_sdwa v47, v52, v238 dst_sel:DWORD dst_unused:UNUSED_PAD src0_sel:WORD_1 src1_sel:DWORD
	s_nop 1
	v_add3_u32 v47, v52, v47, s55
	s_nop 1
	v_and_b32_e32 v47, 0xffff0000, v47
	v_cvt_pk_bf16_f32 v45, v55, v53
	v_or_b32_sdwa v44, v47, v46 dst_sel:DWORD dst_unused:UNUSED_PAD src0_sel:DWORD src1_sel:WORD_1
	v_and_b32_sdwa v46, v51, v238 dst_sel:DWORD dst_unused:UNUSED_PAD src0_sel:WORD_1 src1_sel:DWORD
	v_and_b32_sdwa v47, v50, v238 dst_sel:DWORD dst_unused:UNUSED_PAD src0_sel:WORD_1 src1_sel:DWORD
	v_add3_u32 v50, v50, v47, s55
	v_add3_u32 v46, v51, v46, s55
	v_and_b32_sdwa v47, v49, v238 dst_sel:DWORD dst_unused:UNUSED_PAD src0_sel:WORD_1 src1_sel:DWORD
	v_and_b32_sdwa v51, v48, v238 dst_sel:DWORD dst_unused:UNUSED_PAD src0_sel:WORD_1 src1_sel:DWORD
	v_add3_u32 v47, v49, v47, s55
	v_add3_u32 v48, v48, v51, s55
	v_and_b32_e32 v47, 0xffff0000, v47
	v_and_b32_e32 v48, 0xffff0000, v48
	v_lshl_add_u64 v[38:39], v[158:159], 0, v[38:39]
	v_or_b32_sdwa v47, v47, v46 dst_sel:DWORD dst_unused:UNUSED_PAD src0_sel:DWORD src1_sel:WORD_1
	v_or_b32_sdwa v46, v48, v50 dst_sel:DWORD dst_unused:UNUSED_PAD src0_sel:DWORD src1_sel:WORD_1
	global_store_dwordx2 v[38:39], v[44:45], off
	v_lshl_add_u64 v[38:39], v[158:159], 0, v[40:41]
	global_store_dwordx2 v[38:39], v[46:47], off
	s_branch .LBB0_1249

; __device__ __forceinline__ unsigned pk2(float lo, float hi) { return f2bf(lo) | (f2bf(hi) << 16); }
; __device__ __forceinline__ void rms_row_bf16(const Ctx& c, const float* xrow, const float* gain, bf16* orow, float* copy) {
;     const f32x4* xr = (const f32x4*)xrow + c.lane; f32x4 v[8]; float s = 0.f;
; #pragma unroll
;     for (int j = 0; j < 8; ++j) { v[j] = xr[64 * j]; s += (v[j].x * v[j].x + v[j].y * v[j].y) + (v[j].z * v[j].z + v[j].w * v[j].w); }
;     const float rs = rsqrtf(wave_sum(s) * (1.f / DM) + EPS);
;     if (copy) {
; #pragma unroll
;         for (int j = 0; j < 8; ++j) ((f32x4*)copy + c.lane)[64 * j] = v[j]; }
;     const f32x4* gr = (const f32x4*)gain + c.lane; v2u* o8 = (v2u*)orow + c.lane;
; #pragma unroll
;     for (int j = 0; j < 8; ++j) { const f32x4 g = gr[64 * j]; v2u o; o.x = pk2(v[j].x * rs * g.x, v[j].y * rs * g.y); o.y = pk2(v[j].z * rs * g.z, v[j].w * rs * g.w); o8[64 * j] = o; }
.LBB0_1590:
	global_load_dwordx4 v[32:35], v[46:47], off offset:-4096
	global_load_dwordx4 v[28:31], v[46:47], off offset:-3072
	global_load_dwordx4 v[24:27], v[46:47], off offset:-2048
	global_load_dwordx4 v[20:23], v[46:47], off offset:-1024
	global_load_dwordx4 v[12:15], v[46:47], off
	global_load_dwordx4 v[16:19], v[46:47], off offset:1024
	s_add_i32 s2, s2, s86
	s_cmpk_lt_i32 s2, 0x400
	s_waitcnt vmcnt(0)
	v_mov_b32_e32 v6, v33
	v_mov_b32_e32 v7, v29
	v_mov_b32_e32 v4, v32
	v_mov_b32_e32 v5, v28
	v_pk_mul_f32 v[6:7], v[6:7], v[6:7]
	v_mov_b32_e32 v8, v35
	v_mov_b32_e32 v9, v31
	v_pk_fma_f32 v[4:5], v[4:5], v[4:5], v[6:7]
	v_mov_b32_e32 v6, v34
	v_mov_b32_e32 v7, v30
	v_pk_mul_f32 v[8:9], v[8:9], v[8:9]
	s_nop 0
	v_pk_fma_f32 v[6:7], v[6:7], v[6:7], v[8:9]
	v_pk_mul_f32 v[8:9], v[24:25], v[24:25]
	v_pk_add_f32 v[4:5], v[4:5], v[6:7]
	v_pk_mul_f32 v[6:7], v[26:27], v[26:27]
	v_pk_add_f32 v[4:5], v[4:5], v[4:5] op_sel:[0,1] op_sel_hi:[1,0]
	v_pk_mov_b32 v[10:11], v[8:9], v[6:7] op_sel:[1,0]
	v_mov_b32_e32 v9, v7
	v_pk_add_f32 v[6:7], v[10:11], v[8:9]
	v_mul_f32_e32 v8, v12, v12
	v_mul_f32_e32 v9, v13, v13
	v_pk_add_f32 v[6:7], v[6:7], v[6:7] op_sel:[0,1] op_sel_hi:[1,0]
	v_mov_b32_e32 v5, v8
	v_mov_b32_e32 v7, v9
	v_pk_add_f32 v[4:5], v[4:5], v[6:7]
	v_mul_f32_e32 v6, v21, v21
	v_mul_f32_e32 v8, v23, v23
	v_mul_f32_e32 v10, v14, v14
	v_mul_f32_e32 v11, v15, v15
	v_pk_fma_f32 v[6:7], v[20:21], v[20:21], v[6:7] op_sel_hi:[1,1,0]
	v_pk_fma_f32 v[8:9], v[22:23], v[22:23], v[8:9] op_sel_hi:[1,1,0]
	v_mov_b32_e32 v7, v10
	v_mov_b32_e32 v9, v11
	v_pk_add_f32 v[6:7], v[6:7], v[8:9]
	s_nop 0
	v_pk_add_f32 v[52:53], v[4:5], v[6:7]
	v_pk_mul_f32 v[4:5], v[18:19], v[18:19]
	v_pk_mul_f32 v[6:7], v[16:17], v[16:17]
	v_pk_add_f32 v[52:53], v[52:53], v[52:53] op_sel:[0,1] op_sel_hi:[1,0]
	v_pk_mov_b32 v[8:9], v[6:7], v[4:5] op_sel:[1,0]
	v_mov_b32_e32 v7, v5
	v_pk_add_f32 v[60:61], v[8:9], v[6:7]
	global_load_dwordx4 v[8:11], v[46:47], off offset:2048
	global_load_dwordx4 v[4:7], v[46:47], off offset:3072
	v_pk_add_f32 v[60:61], v[60:61], v[60:61] op_sel:[0,1] op_sel_hi:[1,0]
	v_lshl_add_u64 v[46:47], v[46:47], 0, s[6:7]
	s_waitcnt vmcnt(0)
	v_mul_f32_e32 v50, v4, v4
	v_mul_f32_e32 v62, v5, v5
	v_mov_b32_e32 v53, v50
	v_mov_b32_e32 v61, v62
	v_mul_f32_e32 v50, v9, v9
	v_mul_f32_e32 v63, v6, v6
	v_pk_add_f32 v[52:53], v[52:53], v[60:61]
	v_pk_fma_f32 v[60:61], v[8:9], v[8:9], v[50:51] op_sel_hi:[1,1,0]
	v_mul_f32_e32 v50, v11, v11
	v_mul_f32_e32 v64, v7, v7
	v_mov_b32_e32 v61, v63
	v_pk_fma_f32 v[62:63], v[10:11], v[10:11], v[50:51] op_sel_hi:[1,1,0]
	s_nop 0
	v_mov_b32_e32 v63, v64
	v_pk_add_f32 v[60:61], v[60:61], v[62:63]
	s_nop 0
	v_pk_add_f32 v[52:53], v[52:53], v[60:61]
	global_load_dwordx4 v[60:63], v[36:37], off
	v_add_f32_e32 v50, v52, v53
	ds_bpermute_b32 v52, v3, v50
	v_mov_b32_e32 v53, v34
	v_mov_b32_e32 v34, v33
	s_waitcnt lgkmcnt(0)
	v_add_f32_e32 v50, v50, v52
	ds_bpermute_b32 v52, v51, v50
	s_waitcnt lgkmcnt(0)
	v_add_f32_e32 v50, v50, v52
	ds_bpermute_b32 v52, v54, v50
	s_waitcnt lgkmcnt(0)
	v_add_f32_e32 v50, v50, v52
	ds_bpermute_b32 v52, v55, v50
	s_waitcnt lgkmcnt(0)
	v_add_f32_e32 v50, v50, v52
	ds_bpermute_b32 v52, v56, v50
	s_waitcnt lgkmcnt(0)
	v_add_f32_e32 v50, v50, v52
	ds_bpermute_b32 v52, v57, v50
	s_waitcnt lgkmcnt(0)
	v_add_f32_e32 v50, v50, v52
	v_fmamk_f32 v50, v50, 0x3a000000, v58
	v_cmp_gt_f32_e32 vcc, s10, v50
	v_mul_f32_e32 v52, 0x4b800000, v50
	s_waitcnt vmcnt(0)
	v_mov_b32_e32 v64, v60
	v_cndmask_b32_e32 v50, v50, v52, vcc
	v_rsq_f32_e32 v50, v50
	v_mov_b32_e32 v65, v62
	v_mov_b32_e32 v62, v61
	v_mul_f32_e32 v52, 0x45800000, v50
	v_cndmask_b32_e32 v50, v50, v52, vcc
	v_mov_b32_e32 v52, v32
	v_pk_mul_f32 v[52:53], v[52:53], v[50:51] op_sel_hi:[1,0]
	v_pk_mul_f32 v[32:33], v[34:35], v[50:51] op_sel_hi:[1,0]
	v_pk_mul_f32 v[52:53], v[64:65], v[52:53]
	v_pk_mul_f32 v[32:33], v[62:63], v[32:33]
	v_and_b32_sdwa v34, v53, v59 dst_sel:DWORD dst_unused:UNUSED_PAD src0_sel:WORD_1 src1_sel:DWORD
	v_and_b32_sdwa v35, v52, v59 dst_sel:DWORD dst_unused:UNUSED_PAD src0_sel:WORD_1 src1_sel:DWORD
	v_add3_u32 v35, v52, v35, s3
	v_add3_u32 v34, v53, v34, s3
	v_and_b32_sdwa v52, v33, v59 dst_sel:DWORD dst_unused:UNUSED_PAD src0_sel:WORD_1 src1_sel:DWORD
	v_and_b32_sdwa v53, v32, v59 dst_sel:DWORD dst_unused:UNUSED_PAD src0_sel:WORD_1 src1_sel:DWORD
	v_add3_u32 v33, v33, v52, s3
	v_add3_u32 v32, v32, v53, s3
	v_and_b32_e32 v33, 0xffff0000, v33
	v_and_b32_e32 v32, 0xffff0000, v32
	v_or_b32_sdwa v33, v33, v34 dst_sel:DWORD dst_unused:UNUSED_PAD src0_sel:DWORD src1_sel:WORD_1
	v_or_b32_sdwa v32, v32, v35 dst_sel:DWORD dst_unused:UNUSED_PAD src0_sel:DWORD src1_sel:WORD_1
	global_store_dwordx2 v[48:49], v[32:33], off
	global_load_dwordx4 v[32:35], v[36:37], off offset:1024
	v_mov_b32_e32 v53, v30
	v_mov_b32_e32 v30, v29
	v_mov_b32_e32 v52, v28
	v_pk_mul_f32 v[28:29], v[30:31], v[50:51] op_sel_hi:[1,0]
	v_pk_mul_f32 v[52:53], v[52:53], v[50:51] op_sel_hi:[1,0]
	s_waitcnt vmcnt(0)
; __device__ __forceinline__ unsigned pk2(float lo, float hi) { return f2bf(lo) | (f2bf(hi) << 16); }
; __device__ __forceinline__ void rms_row_bf16(const Ctx& c, const float* xrow, const float* gain, bf16* orow, float* copy) {
;     ...
;     const f32x4* gr = (const f32x4*)gain + c.lane; v2u* o8 = (v2u*)orow + c.lane;
; #pragma unroll
;     for (int j = 0; j < 8; ++j) { const f32x4 g = gr[64 * j]; v2u o; o.x = pk2(v[j].x * rs * g.x, v[j].y * rs * g.y); o.y = pk2(v[j].z * rs * g.z, v[j].w * rs * g.w); o8[64 * j] = o; }
	v_mov_b32_e32 v61, v34
	v_mov_b32_e32 v34, v33
	v_mov_b32_e32 v60, v32
	v_pk_mul_f32 v[28:29], v[34:35], v[28:29]
	v_pk_mul_f32 v[52:53], v[60:61], v[52:53]
	s_nop 7
	s_nop 1
	v_cvt_pk_bf16_f32 v29, v53, v29
	v_cvt_pk_bf16_f32 v28, v52, v28
	global_store_dwordx2 v[48:49], v[28:29], off offset:512
	global_load_dwordx4 v[28:31], v[36:37], off offset:2048
	v_mov_b32_e32 v33, v26
	v_mov_b32_e32 v26, v25
	v_mov_b32_e32 v32, v24
	v_pk_mul_f32 v[24:25], v[26:27], v[50:51] op_sel_hi:[1,0]
	v_pk_mul_f32 v[32:33], v[32:33], v[50:51] op_sel_hi:[1,0]
	s_waitcnt vmcnt(0)
	v_mov_b32_e32 v35, v30
	v_mov_b32_e32 v30, v29
	v_mov_b32_e32 v34, v28
	v_pk_mul_f32 v[24:25], v[30:31], v[24:25]
	v_pk_mul_f32 v[32:33], v[34:35], v[32:33]
	s_nop 7
	s_nop 1
	v_cvt_pk_bf16_f32 v25, v33, v25
	v_cvt_pk_bf16_f32 v24, v32, v24
	global_store_dwordx2 v[48:49], v[24:25], off offset:1024
	global_load_dwordx4 v[24:27], v[36:37], off offset:3072
	v_mov_b32_e32 v29, v22
	v_mov_b32_e32 v22, v21
	v_mov_b32_e32 v28, v20
	v_pk_mul_f32 v[20:21], v[22:23], v[50:51] op_sel_hi:[1,0]
	v_pk_mul_f32 v[28:29], v[28:29], v[50:51] op_sel_hi:[1,0]
	s_waitcnt vmcnt(0)
	v_mov_b32_e32 v31, v26
	v_mov_b32_e32 v26, v25
	v_mov_b32_e32 v30, v24
	v_pk_mul_f32 v[20:21], v[26:27], v[20:21]
	v_pk_mul_f32 v[28:29], v[30:31], v[28:29]
	s_nop 7
	s_nop 1
	v_cvt_pk_bf16_f32 v21, v29, v21
	v_cvt_pk_bf16_f32 v20, v28, v20
	global_store_dwordx2 v[48:49], v[20:21], off offset:1536
	global_load_dwordx4 v[20:23], v[38:39], off
	v_mov_b32_e32 v25, v14
	v_mov_b32_e32 v14, v13
	v_mov_b32_e32 v24, v12
	v_pk_mul_f32 v[12:13], v[14:15], v[50:51] op_sel_hi:[1,0]
	v_pk_mul_f32 v[24:25], v[24:25], v[50:51] op_sel_hi:[1,0]
	s_waitcnt vmcnt(0)
	v_mov_b32_e32 v27, v22
	v_mov_b32_e32 v22, v21
	v_mov_b32_e32 v26, v20
	v_pk_mul_f32 v[12:13], v[22:23], v[12:13]
	v_pk_mul_f32 v[24:25], v[26:27], v[24:25]
	s_nop 7
	s_nop 1
	v_cvt_pk_bf16_f32 v13, v25, v13
	v_cvt_pk_bf16_f32 v12, v24, v12
	global_store_dwordx2 v[48:49], v[12:13], off offset:2048
	global_load_dwordx4 v[12:15], v[40:41], off
	v_mov_b32_e32 v21, v18
	v_mov_b32_e32 v18, v17
	v_mov_b32_e32 v20, v16
	v_pk_mul_f32 v[16:17], v[18:19], v[50:51] op_sel_hi:[1,0]
	v_pk_mul_f32 v[20:21], v[20:21], v[50:51] op_sel_hi:[1,0]
	s_waitcnt vmcnt(0)
	v_mov_b32_e32 v23, v14
	v_mov_b32_e32 v14, v13
	v_mov_b32_e32 v22, v12
	v_pk_mul_f32 v[12:13], v[14:15], v[16:17]
	v_pk_mul_f32 v[20:21], v[22:23], v[20:21]
	s_nop 7
	s_nop 1
	v_cvt_pk_bf16_f32 v13, v21, v13
	v_cvt_pk_bf16_f32 v12, v20, v12
	global_store_dwordx2 v[48:49], v[12:13], off offset:2560
	global_load_dwordx4 v[12:15], v[42:43], off
	v_mov_b32_e32 v17, v10
	v_mov_b32_e32 v10, v9
	v_mov_b32_e32 v16, v8
	v_pk_mul_f32 v[8:9], v[10:11], v[50:51] op_sel_hi:[1,0]
	v_pk_mul_f32 v[16:17], v[16:17], v[50:51] op_sel_hi:[1,0]
	s_waitcnt vmcnt(0)
	v_mov_b32_e32 v19, v14
	v_mov_b32_e32 v14, v13
	v_mov_b32_e32 v18, v12
	v_pk_mul_f32 v[8:9], v[8:9], v[14:15]
	v_pk_mul_f32 v[16:17], v[16:17], v[18:19]
	s_nop 7
	s_nop 1
	v_cvt_pk_bf16_f32 v9, v17, v9
	v_cvt_pk_bf16_f32 v8, v16, v8
	global_store_dwordx2 v[48:49], v[8:9], off offset:3072
	global_load_dwordx4 v[8:11], v[44:45], off
	v_mov_b32_e32 v13, v6
	v_mov_b32_e32 v6, v5
	v_mov_b32_e32 v12, v4
	v_pk_mul_f32 v[4:5], v[6:7], v[50:51] op_sel_hi:[1,0]
	v_pk_mul_f32 v[12:13], v[12:13], v[50:51] op_sel_hi:[1,0]
	s_waitcnt vmcnt(0)
	v_mov_b32_e32 v15, v10
	v_mov_b32_e32 v10, v9
	v_mov_b32_e32 v14, v8
	v_pk_mul_f32 v[4:5], v[4:5], v[10:11]
	v_pk_mul_f32 v[12:13], v[12:13], v[14:15]
	v_and_b32_sdwa v8, v5, v59 dst_sel:DWORD dst_unused:UNUSED_PAD src0_sel:WORD_1 src1_sel:DWORD
	v_and_b32_sdwa v9, v4, v59 dst_sel:DWORD dst_unused:UNUSED_PAD src0_sel:WORD_1 src1_sel:DWORD
	v_and_b32_sdwa v6, v13, v59 dst_sel:DWORD dst_unused:UNUSED_PAD src0_sel:WORD_1 src1_sel:DWORD
	v_and_b32_sdwa v7, v12, v59 dst_sel:DWORD dst_unused:UNUSED_PAD src0_sel:WORD_1 src1_sel:DWORD
	v_add3_u32 v5, v5, v8, s3
	v_add3_u32 v4, v4, v9, s3
	v_add3_u32 v7, v12, v7, s3
	v_add3_u32 v6, v13, v6, s3
	v_and_b32_e32 v5, 0xffff0000, v5
	v_and_b32_e32 v4, 0xffff0000, v4
	v_or_b32_sdwa v5, v5, v6 dst_sel:DWORD dst_unused:UNUSED_PAD src0_sel:DWORD src1_sel:WORD_1
	v_or_b32_sdwa v4, v4, v7 dst_sel:DWORD dst_unused:UNUSED_PAD src0_sel:DWORD src1_sel:WORD_1
	global_store_dwordx2 v[48:49], v[4:5], off offset:3584
	v_lshl_add_u64 v[48:49], v[48:49], 0, s[8:9]
	s_cbranch_scc1 .LBB0_1590

; __device__ __forceinline__ float silu_fast(float x) { return x * __builtin_amdgcn_rcpf(1.f + __builtin_amdgcn_exp2f(-1.4426950408889634f * x)); }
; __device__ __forceinline__ float dpp_shr1(float x) { return __builtin_bit_cast(float, __builtin_amdgcn_update_dpp(0, __builtin_bit_cast(int, x), 0x111, 0xf, 0xf, true)); }
;     __device__ __forceinline__ void operator()(const f32x4 (&acc)[2][2][4][2], const pg8::Unit& u, int wr, int wc, int fr, int fq) const {
;     ...
;             const int cc = ch0 + 4 * n;
;             const f32x4 wg0 = *(CF4)(cw + cc), wg1 = *(CF4)(cw + FF2 + cc), wg2 = *(CF4)(cw + 2 * FF2 + cc), wv0 = *(CF4)(cw + FFH + cc), wv1 = *(CF4)(cw + FF2 + FFH + cc), wv2 = *(CF4)(cw + 2 * FF2 + FFH + cc);
;             const f32x4 bg = *(CF4)(cb + cc), bv = *(CF4)(cb + FFH + cc);
; #pragma unroll
;             for (int jj = 0; jj < 4; ++jj) {
;                 float g2 = dpp_shr1(g[6][jj]), g1 = dpp_shr1(g[7][jj]), v2 = dpp_shr1(v[6][jj]), v1 = dpp_shr1(v[7][jj]);
; #pragma unroll
;                 for (int e = 0; e < 8; ++e) { const float g0 = g[e][jj], v0 = v[e][jj];
;                     const float cg = bg[jj] + wg0[jj] * g2 + wg1[jj] * g1 + wg2[jj] * g0, cv = bv[jj] + wv0[jj] * v2 + wv1[jj] * v1 + wv2[jj] * v0;
;                     g[e][jj] = silu_fast(cg) * cv; g2 = g1; g1 = g0; v2 = v1; v1 = v0; } }
.LBB0_2979:
	s_or_b64 exec, exec, s[36:37]
	v_or_b32_e32 v38, 4, v132
	v_ashrrev_i32_e32 v39, 31, v38
	v_lshlrev_b64 v[64:65], 2, v[38:39]
	v_lshl_add_u64 v[38:39], s[8:9], 0, v[64:65]
	v_lshl_add_u64 v[44:45], s[20:21], 0, v[64:65]
	v_lshl_add_u64 v[66:67], s[10:11], 0, v[64:65]
	global_load_dwordx4 v[52:55], v[38:39], off
	v_lshl_add_u64 v[48:49], s[22:23], 0, v[64:65]
	global_load_dwordx4 v[44:47], v[44:45], off
	v_lshl_add_u64 v[38:39], s[14:15], 0, v[64:65]
	global_load_dwordx4 v[68:71], v[66:67], off
	global_load_dwordx4 v[56:59], v[38:39], off
	v_mov_b32_dpp v106, v88 row_shr:1 row_mask:0xf bank_mask:0xf bound_ctrl:1
	global_load_dwordx4 v[48:51], v[48:49], off
	v_lshl_add_u64 v[38:39], s[16:17], 0, v[64:65]
	global_load_dwordx4 v[60:63], v[38:39], off
	v_lshl_add_u64 v[38:39], s[18:19], 0, v[64:65]
	global_load_dwordx4 v[38:41], v[38:39], off
	v_lshl_add_u64 v[64:65], s[24:25], 0, v[64:65]
	global_load_dwordx4 v[64:67], v[64:65], off
	v_mov_b32_dpp v107, v89 row_shr:1 row_mask:0xf bank_mask:0xf bound_ctrl:1
	v_mov_b32_dpp v138, v94 row_shr:1 row_mask:0xf bank_mask:0xf bound_ctrl:1
	v_mov_b32_dpp v139, v95 row_shr:1 row_mask:0xf bank_mask:0xf bound_ctrl:1
	v_mov_b32_dpp v160, v86 row_shr:1 row_mask:0xf bank_mask:0xf bound_ctrl:1
	v_mov_b32_dpp v161, v87 row_shr:1 row_mask:0xf bank_mask:0xf bound_ctrl:1
	v_mov_b32_dpp v136, v90 row_shr:1 row_mask:0xf bank_mask:0xf bound_ctrl:1
	v_mov_b32_dpp v137, v91 row_shr:1 row_mask:0xf bank_mask:0xf bound_ctrl:1
	v_mov_b32_dpp v158, v82 row_shr:1 row_mask:0xf bank_mask:0xf bound_ctrl:1
	v_mov_b32_dpp v162, v72 row_shr:1 row_mask:0xf bank_mask:0xf bound_ctrl:1
	v_mov_b32_dpp v159, v83 row_shr:1 row_mask:0xf bank_mask:0xf bound_ctrl:1
	v_mov_b32_dpp v163, v73 row_shr:1 row_mask:0xf bank_mask:0xf bound_ctrl:1
	v_mov_b32_dpp v134, v84 row_shr:1 row_mask:0xf bank_mask:0xf bound_ctrl:1
	v_mov_b32_dpp v132, v74 row_shr:1 row_mask:0xf bank_mask:0xf bound_ctrl:1
	v_mov_b32_dpp v135, v85 row_shr:1 row_mask:0xf bank_mask:0xf bound_ctrl:1
	v_mov_b32_dpp v133, v75 row_shr:1 row_mask:0xf bank_mask:0xf bound_ctrl:1
	s_andn2_b64 vcc, exec, s[0:1]
	s_mov_b32 s63, s26
	s_mov_b32 s36, s28
	s_mov_b64 s[40:41], s[34:35]
	s_mov_b64 s[38:39], s[30:31]
	s_waitcnt vmcnt(0)
	v_mov_b32_e32 v98, v52
	v_mov_b32_e32 v99, v54
	v_mov_b32_e32 v54, v53
	v_mov_b32_e32 v102, v68
	v_mov_b32_e32 v103, v70
	v_pk_fma_f32 v[110:111], v[98:99], v[106:107], v[102:103]
	v_mov_b32_e32 v106, v56
	v_mov_b32_e32 v107, v58
	v_pk_fma_f32 v[168:169], v[106:107], v[138:139], v[110:111]
	v_mov_b32_e32 v110, v60
	v_mov_b32_e32 v111, v62
	v_pk_fma_f32 v[168:169], v[130:131], v[110:111], v[168:169]
	v_mov_b32_e32 v70, v69
	v_mul_f32_e32 v52, 0xbfb8aa3b, v168
	v_exp_f32_e32 v52, v52
	v_mov_b32_e32 v58, v57
	v_mov_b32_e32 v62, v61
	v_mov_b32_e32 v60, v44
	v_add_f32_e32 v52, 1.0, v52
	v_rcp_f32_e32 v170, v52
	v_pk_fma_f32 v[52:53], v[54:55], v[160:161], v[70:71]
	v_mov_b32_e32 v56, v64
	v_pk_fma_f32 v[52:53], v[58:59], v[136:137], v[52:53]
	v_mov_b32_e32 v57, v66
	v_pk_fma_f32 v[160:161], v[126:127], v[62:63], v[52:53]
	v_mov_b32_e32 v53, v40
	v_mul_f32_e32 v52, 0xbfb8aa3b, v160
	v_exp_f32_e32 v52, v52
	v_mul_f32_e32 v44, 0xbfb8aa3b, v161
	v_exp_f32_e32 v44, v44
	v_mov_b32_e32 v40, v39
	v_add_f32_e32 v52, 1.0, v52
	v_rcp_f32_e32 v172, v52
	v_mov_b32_e32 v52, v38
	v_mul_f32_e32 v38, 0xbfb8aa3b, v169
	v_exp_f32_e32 v38, v38
	v_add_f32_e32 v44, 1.0, v44
	v_rcp_f32_e32 v173, v44
	v_mov_b32_e32 v66, v65
	v_add_f32_e32 v38, 1.0, v38
	v_pk_fma_f32 v[68:69], v[52:53], v[158:159], v[56:57]
	v_mov_b32_e32 v61, v46
	v_rcp_f32_e32 v171, v38
	v_pk_fma_f32 v[38:39], v[40:41], v[162:163], v[66:67]
	v_mov_b32_e32 v46, v45
	v_pk_fma_f32 v[158:159], v[60:61], v[134:135], v[68:69]
	v_mov_b32_e32 v69, v50
	v_pk_fma_f32 v[38:39], v[46:47], v[132:133], v[38:39]
	v_mov_b32_e32 v50, v49
	v_pk_fma_f32 v[38:39], v[122:123], v[50:51], v[38:39]
	v_pk_mul_f32 v[44:45], v[160:161], v[172:173]
	v_mov_b32_e32 v68, v48
	v_pk_mul_f32 v[38:39], v[38:39], v[44:45]
	v_pk_fma_f32 v[158:159], v[124:125], v[68:69], v[158:159]
	v_pk_mul_f32 v[168:169], v[168:169], v[170:171]
	v_and_b32_sdwa v48, v39, v234 dst_sel:DWORD dst_unused:UNUSED_PAD src0_sel:WORD_1 src1_sel:DWORD
	v_and_b32_sdwa v49, v38, v234 dst_sel:DWORD dst_unused:UNUSED_PAD src0_sel:WORD_1 src1_sel:DWORD
	v_pk_mul_f32 v[158:159], v[158:159], v[168:169]
	v_add3_u32 v39, v39, v48, s61
	v_add3_u32 v38, v38, v49, s61
	v_pk_fma_f32 v[48:49], v[54:55], v[136:137], v[70:71]
	v_and_b32_sdwa v45, v158, v234 dst_sel:DWORD dst_unused:UNUSED_PAD src0_sel:WORD_1 src1_sel:DWORD
	v_pk_fma_f32 v[48:49], v[126:127], v[58:59], v[48:49]
	v_add3_u32 v45, v158, v45, s61
	v_and_b32_e32 v38, 0xffff0000, v38
	v_pk_fma_f32 v[48:49], v[118:119], v[62:63], v[48:49]
	v_and_b32_sdwa v44, v159, v234 dst_sel:DWORD dst_unused:UNUSED_PAD src0_sel:WORD_1 src1_sel:DWORD
	v_or_b32_sdwa v38, v38, v45 dst_sel:DWORD dst_unused:UNUSED_PAD src0_sel:DWORD src1_sel:WORD_1
	v_mul_f32_e32 v45, 0xbfb8aa3b, v48
	v_add3_u32 v44, v159, v44, s61
	v_and_b32_e32 v39, 0xffff0000, v39
	v_exp_f32_e32 v45, v45
	v_or_b32_sdwa v39, v39, v44 dst_sel:DWORD dst_unused:UNUSED_PAD src0_sel:DWORD src1_sel:WORD_1
	global_store_dwordx2 v[112:113], v[38:39], off offset:8
	v_pk_fma_f32 v[38:39], v[98:99], v[138:139], v[102:103]
	v_add_f32_e32 v45, 1.0, v45
	v_pk_fma_f32 v[38:39], v[130:131], v[106:107], v[38:39]
	v_rcp_f32_e32 v64, v45
	v_pk_fma_f32 v[38:39], v[114:115], v[110:111], v[38:39]
	v_mul_f32_e32 v65, 0xbfb8aa3b, v49
	v_mul_f32_e32 v44, 0xbfb8aa3b, v38
	v_mul_f32_e32 v45, 0xbfb8aa3b, v39
	v_exp_f32_e32 v44, v44
	v_exp_f32_e32 v45, v45
	v_exp_f32_e32 v65, v65
; __device__ __forceinline__ unsigned pk2(float lo, float hi) { return f2bf(lo) | (f2bf(hi) << 16); }
; __device__ __forceinline__ float silu_fast(float x) { return x * __builtin_amdgcn_rcpf(1.f + __builtin_amdgcn_exp2f(-1.4426950408889634f * x)); }
; __device__ __forceinline__ float dpp_shr1(float x) { return __builtin_bit_cast(float, __builtin_amdgcn_update_dpp(0, __builtin_bit_cast(int, x), 0x111, 0xf, 0xf, true)); }
;     __device__ __forceinline__ void operator()(const f32x4 (&acc)[2][2][4][2], const pg8::Unit& u, int wr, int wc, int fr, int fq) const {
;     ...
;             for (int jj = 0; jj < 4; ++jj) {
;                 float g2 = dpp_shr1(g[6][jj]), g1 = dpp_shr1(g[7][jj]), v2 = dpp_shr1(v[6][jj]), v1 = dpp_shr1(v[7][jj]);
; #pragma unroll
;                 for (int e = 0; e < 8; ++e) { const float g0 = g[e][jj], v0 = v[e][jj];
;                     const float cg = bg[jj] + wg0[jj] * g2 + wg1[jj] * g1 + wg2[jj] * g0, cv = bv[jj] + wv0[jj] * v2 + wv1[jj] * v1 + wv2[jj] * v0;
;                     g[e][jj] = silu_fast(cg) * cv; g2 = g1; g1 = g0; v2 = v1; v1 = v0; } }
; #pragma unroll
;             for (int e = 0; e < 8; ++e) { v2u w; w.x = pk2(g[e][0], g[e][1]); w.y = pk2(g[e][2], g[e][3]); *(v2u*)(ACT + (size_t)(tok0 + e) * FFH + cc) = w; }
	v_pk_fma_f32 v[112:113], v[52:53], v[134:135], v[56:57]
	v_add_f32_e32 v44, 1.0, v44
	v_add_f32_e32 v45, 1.0, v45
	v_rcp_f32_e32 v44, v44
	v_rcp_f32_e32 v45, v45
	v_add_f32_e32 v65, 1.0, v65
	v_rcp_f32_e32 v65, v65
	v_pk_fma_f32 v[112:113], v[124:125], v[60:61], v[112:113]
	v_pk_mul_f32 v[38:39], v[38:39], v[44:45]
	v_pk_fma_f32 v[44:45], v[40:41], v[132:133], v[66:67]
	v_pk_fma_f32 v[112:113], v[116:117], v[68:69], v[112:113]
	v_pk_fma_f32 v[44:45], v[122:123], v[46:47], v[44:45]
	v_pk_mul_f32 v[38:39], v[112:113], v[38:39]
	v_pk_fma_f32 v[44:45], v[120:121], v[50:51], v[44:45]
	v_pk_mul_f32 v[48:49], v[48:49], v[64:65]
	s_nop 0
	v_pk_mul_f32 v[44:45], v[44:45], v[48:49]
	s_nop 7
	s_nop 1
	v_cvt_pk_bf16_f32 v39, v39, v45
	v_cvt_pk_bf16_f32 v38, v38, v44
	v_mov_b32_e32 v44, v33
	v_mov_b32_e32 v45, v35
	v_mov_b32_e32 v33, v34
	v_pk_fma_f32 v[34:35], v[126:127], v[54:55], v[70:71]
	v_pk_mul_f32 v[44:45], v[44:45], v[128:129]
	v_pk_fma_f32 v[34:35], v[118:119], v[58:59], v[34:35]
	global_store_dwordx2 v[108:109], v[38:39], off offset:8
	v_pk_fma_f32 v[34:35], v[44:45], v[62:63], v[34:35]
	v_mov_b32_e32 v39, v31
	v_mul_f32_e32 v31, 0xbfb8aa3b, v34
	v_exp_f32_e32 v31, v31
	v_mov_b32_e32 v38, v29
	v_mov_b32_e32 v29, v30
	v_pk_mul_f32 v[48:49], v[28:29], v[128:129]
	v_pk_fma_f32 v[28:29], v[130:131], v[98:99], v[102:103]
	v_pk_mul_f32 v[32:33], v[32:33], v[128:129]
	v_pk_fma_f32 v[28:29], v[114:115], v[106:107], v[28:29]
	v_add_f32_e32 v31, 1.0, v31
	v_pk_fma_f32 v[28:29], v[32:33], v[110:111], v[28:29]
	v_rcp_f32_e32 v64, v31
	v_mul_f32_e32 v30, 0xbfb8aa3b, v28
	v_mul_f32_e32 v31, 0xbfb8aa3b, v29
	v_exp_f32_e32 v30, v30
	v_exp_f32_e32 v31, v31
	v_mul_f32_e32 v65, 0xbfb8aa3b, v35
	v_exp_f32_e32 v65, v65
	v_add_f32_e32 v30, 1.0, v30
	v_add_f32_e32 v31, 1.0, v31
	v_rcp_f32_e32 v30, v30
	v_rcp_f32_e32 v31, v31
	v_add_f32_e32 v65, 1.0, v65
	v_rcp_f32_e32 v65, v65
	v_pk_fma_f32 v[108:109], v[124:125], v[52:53], v[56:57]
	v_pk_mul_f32 v[28:29], v[28:29], v[30:31]
	v_pk_fma_f32 v[108:109], v[116:117], v[60:61], v[108:109]
	v_pk_fma_f32 v[30:31], v[122:123], v[40:41], v[66:67]
	v_pk_mul_f32 v[38:39], v[38:39], v[128:129]
	v_pk_fma_f32 v[108:109], v[48:49], v[68:69], v[108:109]
	v_pk_fma_f32 v[30:31], v[120:121], v[46:47], v[30:31]
	v_pk_mul_f32 v[28:29], v[108:109], v[28:29]
	v_pk_fma_f32 v[30:31], v[38:39], v[50:51], v[30:31]
	v_pk_mul_f32 v[34:35], v[34:35], v[64:65]
	s_nop 0
	v_pk_mul_f32 v[30:31], v[30:31], v[34:35]
	s_nop 7
	s_nop 1
	v_cvt_pk_bf16_f32 v29, v29, v31
	v_cvt_pk_bf16_f32 v28, v28, v30
	v_mov_b32_e32 v30, v25
	v_mov_b32_e32 v31, v27
	v_pk_fma_f32 v[34:35], v[118:119], v[54:55], v[70:71]
	v_pk_mul_f32 v[30:31], v[30:31], v[42:43]
	v_pk_fma_f32 v[34:35], v[44:45], v[58:59], v[34:35]
	v_mov_b32_e32 v25, v26
	v_pk_fma_f32 v[34:35], v[30:31], v[62:63], v[34:35]
	global_store_dwordx2 v[104:105], v[28:29], off offset:8
	v_mul_f32_e32 v65, 0xbfb8aa3b, v34
	v_exp_f32_e32 v65, v65
	v_mov_b32_e32 v28, v21
	v_mov_b32_e32 v29, v23
	v_mov_b32_e32 v21, v22
	v_pk_mul_f32 v[22:23], v[24:25], v[42:43]
	v_pk_fma_f32 v[24:25], v[114:115], v[98:99], v[102:103]
	v_add_f32_e32 v65, 1.0, v65
	v_pk_fma_f32 v[24:25], v[32:33], v[106:107], v[24:25]
	v_rcp_f32_e32 v104, v65
	v_pk_fma_f32 v[24:25], v[22:23], v[110:111], v[24:25]
	v_pk_fma_f32 v[26:27], v[116:117], v[52:53], v[56:57]
	v_mul_f32_e32 v64, 0xbfb8aa3b, v24
	v_mul_f32_e32 v65, 0xbfb8aa3b, v25
	v_exp_f32_e32 v64, v64
	v_exp_f32_e32 v65, v65
	v_pk_mul_f32 v[20:21], v[20:21], v[42:43]
	v_pk_fma_f32 v[26:27], v[48:49], v[60:61], v[26:27]
	v_add_f32_e32 v64, 1.0, v64
	v_add_f32_e32 v65, 1.0, v65
	v_rcp_f32_e32 v64, v64
	v_rcp_f32_e32 v65, v65
	v_pk_mul_f32 v[28:29], v[28:29], v[42:43]
	v_pk_fma_f32 v[42:43], v[120:121], v[40:41], v[66:67]
	v_pk_fma_f32 v[26:27], v[20:21], v[68:69], v[26:27]
	v_pk_mul_f32 v[24:25], v[24:25], v[64:65]
	s_nop 0
	v_pk_mul_f32 v[24:25], v[26:27], v[24:25]
	v_pk_fma_f32 v[26:27], v[38:39], v[46:47], v[42:43]
	v_mul_f32_e32 v42, 0xbfb8aa3b, v35
	v_exp_f32_e32 v42, v42
	v_pk_fma_f32 v[26:27], v[28:29], v[50:51], v[26:27]
	v_add_f32_e32 v42, 1.0, v42
	v_rcp_f32_e32 v105, v42
	s_nop 0
	v_pk_mul_f32 v[34:35], v[34:35], v[104:105]
	s_nop 0
	v_pk_mul_f32 v[26:27], v[26:27], v[34:35]
	s_nop 7
	s_nop 1
	v_cvt_pk_bf16_f32 v25, v25, v27
	v_cvt_pk_bf16_f32 v24, v24, v26
	v_mov_b32_e32 v26, v17
	v_mov_b32_e32 v27, v19
	v_mov_b32_e32 v17, v18
	v_pk_fma_f32 v[18:19], v[44:45], v[54:55], v[70:71]
	v_pk_mul_f32 v[26:27], v[26:27], v[92:93]
	v_pk_fma_f32 v[18:19], v[30:31], v[58:59], v[18:19]
	global_store_dwordx2 v[100:101], v[24:25], off offset:8
	v_mov_b32_e32 v24, v13
	v_mov_b32_e32 v13, v14
	v_pk_fma_f32 v[18:19], v[26:27], v[62:63], v[18:19]
	v_pk_mul_f32 v[34:35], v[12:13], v[92:93]
	v_pk_fma_f32 v[12:13], v[32:33], v[98:99], v[102:103]
	v_pk_fma_f32 v[32:33], v[38:39], v[40:41], v[66:67]
	v_mul_f32_e32 v39, 0xbfb8aa3b, v18
	v_exp_f32_e32 v39, v39
	v_pk_mul_f32 v[16:17], v[16:17], v[92:93]
	v_pk_fma_f32 v[12:13], v[22:23], v[106:107], v[12:13]
	v_mov_b32_e32 v25, v15
	v_pk_fma_f32 v[12:13], v[16:17], v[110:111], v[12:13]
	v_add_f32_e32 v39, 1.0, v39
	v_mul_f32_e32 v38, 0xbfb8aa3b, v12
	v_rcp_f32_e32 v42, v39
	v_mul_f32_e32 v39, 0xbfb8aa3b, v13
	v_exp_f32_e32 v38, v38
	v_exp_f32_e32 v39, v39
	v_pk_fma_f32 v[14:15], v[48:49], v[52:53], v[56:57]
	v_pk_mul_f32 v[24:25], v[24:25], v[92:93]
	v_add_f32_e32 v38, 1.0, v38
	v_add_f32_e32 v39, 1.0, v39
	v_rcp_f32_e32 v38, v38
	v_rcp_f32_e32 v39, v39
	v_pk_fma_f32 v[14:15], v[20:21], v[60:61], v[14:15]
	v_pk_mul_f32 v[12:13], v[12:13], v[38:39]
	v_pk_fma_f32 v[14:15], v[34:35], v[68:69], v[14:15]
	s_nop 0
; __device__ __forceinline__ unsigned pk2(float lo, float hi) { return f2bf(lo) | (f2bf(hi) << 16); }
; __device__ __forceinline__ float silu_fast(float x) { return x * __builtin_amdgcn_rcpf(1.f + __builtin_amdgcn_exp2f(-1.4426950408889634f * x)); }
; __device__ __forceinline__ float dpp_shr1(float x) { return __builtin_bit_cast(float, __builtin_amdgcn_update_dpp(0, __builtin_bit_cast(int, x), 0x111, 0xf, 0xf, true)); }
;     __device__ __forceinline__ void operator()(const f32x4 (&acc)[2][2][4][2], const pg8::Unit& u, int wr, int wc, int fr, int fq) const {
;     ...
;             for (int jj = 0; jj < 4; ++jj) {
;                 float g2 = dpp_shr1(g[6][jj]), g1 = dpp_shr1(g[7][jj]), v2 = dpp_shr1(v[6][jj]), v1 = dpp_shr1(v[7][jj]);
; #pragma unroll
;                 for (int e = 0; e < 8; ++e) { const float g0 = g[e][jj], v0 = v[e][jj];
;                     const float cg = bg[jj] + wg0[jj] * g2 + wg1[jj] * g1 + wg2[jj] * g0, cv = bv[jj] + wv0[jj] * v2 + wv1[jj] * v1 + wv2[jj] * v0;
;                     g[e][jj] = silu_fast(cg) * cv; g2 = g1; g1 = g0; v2 = v1; v1 = v0; } }
; #pragma unroll
;             for (int e = 0; e < 8; ++e) { v2u w; w.x = pk2(g[e][0], g[e][1]); w.y = pk2(g[e][2], g[e][3]); *(v2u*)(ACT + (size_t)(tok0 + e) * FFH + cc) = w; }
	v_pk_mul_f32 v[12:13], v[14:15], v[12:13]
	v_pk_fma_f32 v[14:15], v[28:29], v[46:47], v[32:33]
	v_mul_f32_e32 v32, 0xbfb8aa3b, v19
	v_exp_f32_e32 v32, v32
	v_pk_fma_f32 v[14:15], v[24:25], v[50:51], v[14:15]
	v_add_f32_e32 v32, 1.0, v32
	v_rcp_f32_e32 v43, v32
	s_nop 0
	v_pk_mul_f32 v[18:19], v[18:19], v[42:43]
	s_nop 0
	v_pk_mul_f32 v[14:15], v[14:15], v[18:19]
	s_nop 7
	s_nop 1
	v_cvt_pk_bf16_f32 v13, v13, v15
	v_cvt_pk_bf16_f32 v12, v12, v14
	v_mov_b32_e32 v14, v9
	v_mov_b32_e32 v15, v11
	v_pk_fma_f32 v[18:19], v[30:31], v[54:55], v[70:71]
	v_pk_mul_f32 v[14:15], v[14:15], v[36:37]
	v_pk_fma_f32 v[18:19], v[26:27], v[58:59], v[18:19]
	v_mov_b32_e32 v9, v10
	v_pk_fma_f32 v[18:19], v[14:15], v[62:63], v[18:19]
	global_store_dwordx2 v[96:97], v[12:13], off offset:8
	v_mov_b32_e32 v12, v5
	v_mov_b32_e32 v13, v7
	v_mov_b32_e32 v5, v6
	v_pk_mul_f32 v[6:7], v[8:9], v[36:37]
	v_pk_fma_f32 v[8:9], v[22:23], v[98:99], v[102:103]
	v_mul_f32_e32 v23, 0xbfb8aa3b, v18
	v_exp_f32_e32 v23, v23
	v_pk_fma_f32 v[8:9], v[16:17], v[106:107], v[8:9]
	v_pk_fma_f32 v[10:11], v[20:21], v[52:53], v[56:57]
	v_pk_fma_f32 v[8:9], v[6:7], v[110:111], v[8:9]
	v_add_f32_e32 v23, 1.0, v23
	v_pk_fma_f32 v[20:21], v[28:29], v[40:41], v[66:67]
	v_mul_f32_e32 v22, 0xbfb8aa3b, v8
	v_rcp_f32_e32 v28, v23
	v_mul_f32_e32 v23, 0xbfb8aa3b, v9
	v_exp_f32_e32 v22, v22
	v_exp_f32_e32 v23, v23
	v_pk_mul_f32 v[4:5], v[4:5], v[36:37]
	v_pk_fma_f32 v[10:11], v[34:35], v[60:61], v[10:11]
	v_add_f32_e32 v22, 1.0, v22
	v_add_f32_e32 v23, 1.0, v23
	v_rcp_f32_e32 v22, v22
	v_rcp_f32_e32 v23, v23
	v_pk_fma_f32 v[10:11], v[4:5], v[68:69], v[10:11]
	v_pk_mul_f32 v[12:13], v[12:13], v[36:37]
	v_pk_mul_f32 v[8:9], v[8:9], v[22:23]
	s_nop 0
	v_pk_mul_f32 v[8:9], v[10:11], v[8:9]
	v_pk_fma_f32 v[10:11], v[24:25], v[46:47], v[20:21]
	v_mul_f32_e32 v20, 0xbfb8aa3b, v19
	v_exp_f32_e32 v20, v20
	v_pk_fma_f32 v[10:11], v[12:13], v[50:51], v[10:11]
	v_add_f32_e32 v20, 1.0, v20
	v_rcp_f32_e32 v29, v20
	s_nop 0
	v_pk_mul_f32 v[18:19], v[18:19], v[28:29]
	s_nop 0
	v_pk_mul_f32 v[10:11], v[10:11], v[18:19]
	s_nop 7
	s_nop 1
	v_cvt_pk_bf16_f32 v9, v9, v11
	v_cvt_pk_bf16_f32 v8, v8, v10
	global_store_dwordx2 v[80:81], v[8:9], off offset:8
	v_pk_fma_f32 v[8:9], v[16:17], v[98:99], v[102:103]
	v_pk_fma_f32 v[16:17], v[26:27], v[54:55], v[70:71]
	v_pk_fma_f32 v[8:9], v[6:7], v[106:107], v[8:9]
	v_pk_fma_f32 v[16:17], v[14:15], v[58:59], v[16:17]
	v_pk_fma_f32 v[8:9], v[88:89], v[110:111], v[8:9]
	v_pk_fma_f32 v[16:17], v[86:87], v[62:63], v[16:17]
	v_mul_f32_e32 v20, 0xbfb8aa3b, v8
	v_mul_f32_e32 v21, 0xbfb8aa3b, v16
	v_exp_f32_e32 v21, v21
	v_exp_f32_e32 v20, v20
	v_pk_fma_f32 v[10:11], v[34:35], v[52:53], v[56:57]
	v_pk_fma_f32 v[18:19], v[24:25], v[40:41], v[66:67]
	v_add_f32_e32 v21, 1.0, v21
	v_rcp_f32_e32 v22, v21
	v_mul_f32_e32 v21, 0xbfb8aa3b, v9
	v_exp_f32_e32 v21, v21
	v_add_f32_e32 v20, 1.0, v20
	v_rcp_f32_e32 v20, v20
	v_pk_fma_f32 v[10:11], v[4:5], v[60:61], v[10:11]
	v_add_f32_e32 v21, 1.0, v21
	v_rcp_f32_e32 v21, v21
	v_pk_fma_f32 v[10:11], v[82:83], v[68:69], v[10:11]
	v_pk_fma_f32 v[6:7], v[6:7], v[98:99], v[102:103]
	v_pk_fma_f32 v[4:5], v[4:5], v[52:53], v[56:57]
	v_pk_mul_f32 v[8:9], v[8:9], v[20:21]
	v_pk_fma_f32 v[6:7], v[88:89], v[106:107], v[6:7]
	v_pk_mul_f32 v[8:9], v[10:11], v[8:9]
	v_pk_fma_f32 v[10:11], v[12:13], v[46:47], v[18:19]
	v_mul_f32_e32 v18, 0xbfb8aa3b, v17
	v_exp_f32_e32 v18, v18
	v_pk_fma_f32 v[10:11], v[72:73], v[50:51], v[10:11]
	v_pk_fma_f32 v[6:7], v[94:95], v[110:111], v[6:7]
	v_pk_fma_f32 v[4:5], v[82:83], v[60:61], v[4:5]
	v_add_f32_e32 v18, 1.0, v18
	v_rcp_f32_e32 v23, v18
	v_pk_fma_f32 v[4:5], v[84:85], v[68:69], v[4:5]
	v_pk_mul_f32 v[16:17], v[16:17], v[22:23]
	s_nop 0
	v_pk_mul_f32 v[10:11], v[10:11], v[16:17]
	s_nop 7
	s_nop 1
	v_cvt_pk_bf16_f32 v9, v9, v11
	v_cvt_pk_bf16_f32 v8, v8, v10
	v_pk_fma_f32 v[10:11], v[14:15], v[54:55], v[70:71]
	global_store_dwordx2 v[78:79], v[8:9], off offset:8
	v_pk_fma_f32 v[10:11], v[86:87], v[58:59], v[10:11]
	v_mul_f32_e32 v8, 0xbfb8aa3b, v6
	v_pk_fma_f32 v[10:11], v[90:91], v[62:63], v[10:11]
	v_exp_f32_e32 v8, v8
	v_mul_f32_e32 v9, 0xbfb8aa3b, v10
	v_exp_f32_e32 v9, v9
	v_add_f32_e32 v8, 1.0, v8
	v_rcp_f32_e32 v8, v8
	v_add_f32_e32 v9, 1.0, v9
	v_rcp_f32_e32 v14, v9
	v_mul_f32_e32 v9, 0xbfb8aa3b, v7
	v_exp_f32_e32 v9, v9
	s_nop 0
	v_add_f32_e32 v9, 1.0, v9
	v_rcp_f32_e32 v9, v9
	s_nop 0
	v_pk_mul_f32 v[6:7], v[6:7], v[8:9]
	v_mul_f32_e32 v8, 0xbfb8aa3b, v11
	v_exp_f32_e32 v8, v8
	v_pk_mul_f32 v[4:5], v[4:5], v[6:7]
	v_pk_fma_f32 v[6:7], v[12:13], v[40:41], v[66:67]
	v_add_f32_e32 v8, 1.0, v8
	v_rcp_f32_e32 v15, v8
	v_pk_fma_f32 v[6:7], v[72:73], v[46:47], v[6:7]
	v_pk_mul_f32 v[8:9], v[10:11], v[14:15]
	v_pk_fma_f32 v[6:7], v[74:75], v[50:51], v[6:7]
	s_nop 0
	v_pk_mul_f32 v[6:7], v[6:7], v[8:9]
	v_and_b32_sdwa v8, v5, v234 dst_sel:DWORD dst_unused:UNUSED_PAD src0_sel:WORD_1 src1_sel:DWORD
	v_and_b32_sdwa v9, v4, v234 dst_sel:DWORD dst_unused:UNUSED_PAD src0_sel:WORD_1 src1_sel:DWORD
	v_add3_u32 v4, v4, v9, s61
	v_add3_u32 v5, v5, v8, s61
	v_and_b32_sdwa v8, v7, v234 dst_sel:DWORD dst_unused:UNUSED_PAD src0_sel:WORD_1 src1_sel:DWORD
	v_and_b32_sdwa v9, v6, v234 dst_sel:DWORD dst_unused:UNUSED_PAD src0_sel:WORD_1 src1_sel:DWORD
	v_add3_u32 v7, v7, v8, s61
	v_add3_u32 v6, v6, v9, s61
	v_and_b32_e32 v7, 0xffff0000, v7
	v_and_b32_e32 v6, 0xffff0000, v6
	v_or_b32_sdwa v5, v7, v5 dst_sel:DWORD dst_unused:UNUSED_PAD src0_sel:DWORD src1_sel:WORD_1
	v_or_b32_sdwa v4, v6, v4 dst_sel:DWORD dst_unused:UNUSED_PAD src0_sel:DWORD src1_sel:WORD_1
	global_store_dwordx2 v[76:77], v[4:5], off offset:8
	s_cbranch_vccz .LBB0_2998

; #define PG8_STAGE(bufoff, gbase, voff) do { _Pragma("unroll") for (int _i = 0; _i < 2; ++_i) \
;         __builtin_amdgcn_global_load_lds((const unsigned*)((const char*)(gbase) + (voff)[_i]), (LAS unsigned*)(lds + (bufoff) + ldsw + _i * 8192), 16, 0, 0); } while (0)
; #define PG8_LDA(dst, b, h) do { _Pragma("unroll") for (int m = 0; m < 4; ++m) _Pragma("unroll") for (int k = 0; k < 2; ++k) dst[m][k] = *(const LAS bf16x8*)(lds + PG8_SA(b, h) + aoff + m * 2048 + k * 1024); } while (0)
; #define PG8_LDB(dst, b, h) do { _Pragma("unroll") for (int n = 0; n < 2; ++n) _Pragma("unroll") for (int k = 0; k < 2; ++k) dst[n][k] = *(const LAS bf16x8*)(lds + PG8_SB(b, h) + boff + n * 2048 + k * 1024); } while (0)
; #define PG8_MMA(ai, bj, At, Bt) do { __builtin_amdgcn_s_setprio(1); _Pragma("unroll") for (int m = 0; m < 4; ++m) _Pragma("unroll") for (int n = 0; n < 2; ++n) _Pragma("unroll") for (int k = 0; k < 2; ++k) \
;         acc[ai][bj][m][n] = __builtin_amdgcn_mfma_f32_16x16x32_bf16(Bt[n][k], At[m][k], acc[ai][bj][m][n], 0, 0, 0); __builtin_amdgcn_s_setprio(0); } while (0)
; #define PG8_WAIT_V(n) asm volatile("s_waitcnt vmcnt(" #n ")" ::: "memory")
; #define PG8_WAIT_L(n) asm volatile("s_waitcnt lgkmcnt(" #n ")" ::: "memory")
; #define PG8_BAR __builtin_amdgcn_s_barrier()
; #define PG8_SCHED __builtin_amdgcn_sched_barrier(0)
; template <class PT, class Epi>
; __device__ __forceinline__ void gemm_phase_once(LAS unsigned char* lds, const PT& S, const Epi& E, bool epi_on) {
;     ...
;             PG8_LDB(B0, 0, 0); PG8_SCHED; PG8_LDA(At, 0, 0); PG8_STAGE(PG8_SA(1, 1), a1 + hstepA, voffA);
;             PG8_WAIT_L(8); PG8_BAR; PG8_WAIT_L(0); PG8_MMA(0, 0, At, B0); PG8_BAR; PG8_SCHED;
;             PG8_LDB(B1, 0, 1); PG8_STAGE(PG8_SB(0, 0), b2, voffB);
;             PG8_BAR; PG8_WAIT_L(0); PG8_MMA(0, 1, At, B1); PG8_BAR;
;             PG8_LDA(At, 0, 1); PG8_STAGE(PG8_SA(0, 0), a2, voffA);
;             PG8_BAR; PG8_WAIT_L(0); PG8_MMA(1, 0, At, B0); PG8_BAR; PG8_SCHED;
;             PG8_STAGE(PG8_SB(0, 1), b2 + hstepB, voffB);
;             PG8_WAIT_V(6); PG8_BAR; PG8_MMA(1, 1, At, B1); PG8_BAR;
.LBB0_2983:
	ds_read_b128 v[36:39], v228
	ds_read_b128 v[40:43], v228 offset:1024
	ds_read_b128 v[158:161], v228 offset:2048
	ds_read_b128 v[168:171], v228 offset:3072
	s_add_u32 s40, s38, 0x100
	s_addc_u32 s41, s39, 0
	s_cmp_eq_u32 s67, 28
	s_cselect_b32 s45, s29, s41
	s_cselect_b32 s44, s37, s40
	s_cselect_b32 s43, s27, s66
	s_cselect_b32 s42, s64, s65
	v_lshl_add_u64 v[162:163], s[38:39], 0, v[150:151]
	s_add_i32 m0, s51, 0xc000
	ds_read_b128 v[172:175], v229
	ds_read_b128 v[176:179], v229 offset:1024
	ds_read_b128 v[180:183], v229 offset:2048
	ds_read_b128 v[184:187], v229 offset:3072
	ds_read_b128 v[188:191], v229 offset:4096
	ds_read_b128 v[192:195], v229 offset:5120
	ds_read_b128 v[196:199], v229 offset:6144
	ds_read_b128 v[200:203], v229 offset:7168
	global_load_lds_dwordx4 v[162:163], off
	v_lshl_add_u64 v[162:163], s[38:39], 0, v[152:153]
	s_add_i32 m0, s51, 0xe000
	s_nop 0
	global_load_lds_dwordx4 v[162:163], off
	s_waitcnt lgkmcnt(8)
	s_barrier
	s_waitcnt lgkmcnt(0)
	s_setprio 1
	s_waitcnt lgkmcnt(0)
	v_mfma_f32_16x16x32_bf16 v[132:135], v[36:39], v[172:175], v[132:135]
	v_mfma_f32_16x16x32_bf16 v[72:75], v[158:161], v[172:175], v[72:75]
	v_mfma_f32_16x16x32_bf16 v[124:127], v[36:39], v[180:183], v[124:127]
	v_mfma_f32_16x16x32_bf16 v[68:71], v[158:161], v[180:183], v[68:71]
	v_mfma_f32_16x16x32_bf16 v[104:107], v[36:39], v[188:191], v[104:107]
	v_mfma_f32_16x16x32_bf16 v[32:35], v[158:161], v[188:191], v[32:35]
	v_mfma_f32_16x16x32_bf16 v[100:103], v[36:39], v[196:199], v[100:103]
	v_mfma_f32_16x16x32_bf16 v[24:27], v[158:161], v[196:199], v[24:27]
	v_mfma_f32_16x16x32_bf16 v[132:135], v[40:43], v[176:179], v[132:135]
	v_mfma_f32_16x16x32_bf16 v[72:75], v[168:171], v[176:179], v[72:75]
	v_mfma_f32_16x16x32_bf16 v[124:127], v[40:43], v[184:187], v[124:127]
	v_mfma_f32_16x16x32_bf16 v[68:71], v[168:171], v[184:187], v[68:71]
	v_mfma_f32_16x16x32_bf16 v[104:107], v[40:43], v[192:195], v[104:107]
	v_mfma_f32_16x16x32_bf16 v[32:35], v[168:171], v[192:195], v[32:35]
	v_mfma_f32_16x16x32_bf16 v[100:103], v[40:43], v[200:203], v[100:103]
	v_mfma_f32_16x16x32_bf16 v[24:27], v[168:171], v[200:203], v[24:27]
	s_setprio 0
	s_barrier
	s_add_i32 s38, s59, s48
	v_lshl_add_u64 v[162:163], s[42:43], 0, v[146:147]
	s_mov_b32 m0, s38
	ds_read_b128 v[204:207], v233
	ds_read_b128 v[208:211], v233 offset:1024
	ds_read_b128 v[212:215], v233 offset:2048
	ds_read_b128 v[216:219], v233 offset:3072
	global_load_lds_dwordx4 v[162:163], off
	v_lshl_add_u64 v[220:221], s[42:43], 0, v[140:141]
	s_add_i32 m0, s38, 0x2000
	s_nop 0
	global_load_lds_dwordx4 v[220:221], off
	s_barrier
	s_waitcnt lgkmcnt(0)
	s_setprio 1
	s_waitcnt lgkmcnt(0)
	v_mfma_f32_16x16x32_bf16 v[120:123], v[204:207], v[172:175], v[120:123]
	v_mfma_f32_16x16x32_bf16 v[64:67], v[212:215], v[172:175], v[64:67]
	v_mfma_f32_16x16x32_bf16 v[116:119], v[204:207], v[180:183], v[116:119]
	v_mfma_f32_16x16x32_bf16 v[60:63], v[212:215], v[180:183], v[60:63]
	v_mfma_f32_16x16x32_bf16 v[96:99], v[204:207], v[188:191], v[96:99]
	v_mfma_f32_16x16x32_bf16 v[28:31], v[212:215], v[188:191], v[28:31]
	v_mfma_f32_16x16x32_bf16 v[92:95], v[204:207], v[196:199], v[92:95]
	v_mfma_f32_16x16x32_bf16 v[20:23], v[212:215], v[196:199], v[20:23]
	v_mfma_f32_16x16x32_bf16 v[120:123], v[208:211], v[176:179], v[120:123]
	v_mfma_f32_16x16x32_bf16 v[64:67], v[216:219], v[176:179], v[64:67]
	v_mfma_f32_16x16x32_bf16 v[116:119], v[208:211], v[184:187], v[116:119]
	v_mfma_f32_16x16x32_bf16 v[60:63], v[216:219], v[184:187], v[60:63]
	v_mfma_f32_16x16x32_bf16 v[96:99], v[208:211], v[192:195], v[96:99]
	v_mfma_f32_16x16x32_bf16 v[28:31], v[216:219], v[192:195], v[28:31]
	v_mfma_f32_16x16x32_bf16 v[92:95], v[208:211], v[200:203], v[92:95]
	v_mfma_f32_16x16x32_bf16 v[20:23], v[216:219], v[200:203], v[20:23]
	s_setprio 0
	s_mov_b32 m0, s51
	v_lshl_add_u64 v[222:223], s[44:45], 0, v[142:143]
	s_barrier
	ds_read_b128 v[172:175], v229 offset:16384
	ds_read_b128 v[176:179], v229 offset:17408
	ds_read_b128 v[180:183], v229 offset:18432
	ds_read_b128 v[184:187], v229 offset:19456
	ds_read_b128 v[188:191], v229 offset:20480
	ds_read_b128 v[192:195], v229 offset:21504
	ds_read_b128 v[196:199], v229 offset:22528
	ds_read_b128 v[200:203], v229 offset:23552
	global_load_lds_dwordx4 v[222:223], off
	v_lshl_add_u64 v[224:225], s[44:45], 0, v[144:145]
	s_mov_b32 m0, s52
	s_nop 0
	global_load_lds_dwordx4 v[224:225], off
	s_barrier
	s_waitcnt lgkmcnt(0)
	s_setprio 1
	s_waitcnt lgkmcnt(0)
	v_mfma_f32_16x16x32_bf16 v[88:91], v[36:39], v[172:175], v[88:91]
	v_mfma_f32_16x16x32_bf16 v[16:19], v[158:161], v[172:175], v[16:19]
	v_mfma_f32_16x16x32_bf16 v[84:87], v[36:39], v[180:183], v[84:87]
	v_mfma_f32_16x16x32_bf16 v[8:11], v[158:161], v[180:183], v[8:11]
	v_mfma_f32_16x16x32_bf16 v[136:139], v[36:39], v[188:191], v[136:139]
	v_mfma_f32_16x16x32_bf16 v[56:59], v[158:161], v[188:191], v[56:59]
	v_mfma_f32_16x16x32_bf16 v[36:39], v[36:39], v[196:199], v[112:115]
	v_mfma_f32_16x16x32_bf16 v[88:91], v[40:43], v[176:179], v[88:91]
	v_mfma_f32_16x16x32_bf16 v[16:19], v[168:171], v[176:179], v[16:19]
	v_mfma_f32_16x16x32_bf16 v[84:87], v[40:43], v[184:187], v[84:87]
	v_mfma_f32_16x16x32_bf16 v[8:11], v[168:171], v[184:187], v[8:11]
	v_mfma_f32_16x16x32_bf16 v[136:139], v[40:43], v[192:195], v[136:139]
	v_mfma_f32_16x16x32_bf16 v[56:59], v[168:171], v[192:195], v[56:59]
	v_mfma_f32_16x16x32_bf16 v[36:39], v[40:43], v[200:203], v[36:39]
	v_mfma_f32_16x16x32_bf16 v[40:43], v[158:161], v[196:199], v[52:55]
	v_mfma_f32_16x16x32_bf16 v[40:43], v[168:171], v[200:203], v[40:43]
	s_setprio 0
	s_barrier
; #define PG8_STAGE(bufoff, gbase, voff) do { _Pragma("unroll") for (int _i = 0; _i < 2; ++_i) \
;         __builtin_amdgcn_global_load_lds((const unsigned*)((const char*)(gbase) + (voff)[_i]), (LAS unsigned*)(lds + (bufoff) + ldsw + _i * 8192), 16, 0, 0); } while (0)
; #define PG8_LDA(dst, b, h) do { _Pragma("unroll") for (int m = 0; m < 4; ++m) _Pragma("unroll") for (int k = 0; k < 2; ++k) dst[m][k] = *(const LAS bf16x8*)(lds + PG8_SA(b, h) + aoff + m * 2048 + k * 1024); } while (0)
; #define PG8_LDB(dst, b, h) do { _Pragma("unroll") for (int n = 0; n < 2; ++n) _Pragma("unroll") for (int k = 0; k < 2; ++k) dst[n][k] = *(const LAS bf16x8*)(lds + PG8_SB(b, h) + boff + n * 2048 + k * 1024); } while (0)
; #define PG8_MMA(ai, bj, At, Bt) do { __builtin_amdgcn_s_setprio(1); _Pragma("unroll") for (int m = 0; m < 4; ++m) _Pragma("unroll") for (int n = 0; n < 2; ++n) _Pragma("unroll") for (int k = 0; k < 2; ++k) \
;         acc[ai][bj][m][n] = __builtin_amdgcn_mfma_f32_16x16x32_bf16(Bt[n][k], At[m][k], acc[ai][bj][m][n], 0, 0, 0); __builtin_amdgcn_s_setprio(0); } while (0)
; #define PG8_WAIT_V(n) asm volatile("s_waitcnt vmcnt(" #n ")" ::: "memory")
; #define PG8_WAIT_L(n) asm volatile("s_waitcnt lgkmcnt(" #n ")" ::: "memory")
; #define PG8_BAR __builtin_amdgcn_s_barrier()
; #define PG8_SCHED __builtin_amdgcn_sched_barrier(0)
; template <class PT, class Epi>
; __device__ __forceinline__ void gemm_phase_once(LAS unsigned char* lds, const PT& S, const Epi& E, bool epi_on) {
;     ...
;             PG8_WAIT_V(6); PG8_BAR; PG8_MMA(1, 1, At, B1); PG8_BAR;
;             PG8_LDB(B0, 1, 0); PG8_SCHED; PG8_LDA(At, 1, 0); PG8_STAGE(PG8_SA(0, 1), a2 + hstepA, voffA);
;             PG8_WAIT_L(8); PG8_BAR; PG8_WAIT_L(0); PG8_MMA(0, 0, At, B0); PG8_BAR; PG8_SCHED;
;             PG8_LDB(B1, 1, 1); PG8_STAGE(PG8_SB(1, 0), b3, voffB);
;             PG8_BAR; PG8_WAIT_L(0); PG8_MMA(0, 1, At, B1); PG8_BAR;
;             PG8_LDA(At, 1, 1); PG8_STAGE(PG8_SA(1, 0), a3, voffA);
;             PG8_BAR; PG8_WAIT_L(0); PG8_MMA(1, 0, At, B0); PG8_BAR; PG8_SCHED;
	s_add_u32 s38, s42, 0x80000
	s_addc_u32 s39, s43, 0
	s_add_i32 s68, s60, s48
	v_lshl_add_u64 v[52:53], s[38:39], 0, v[146:147]
	s_mov_b32 m0, s68
	s_nop 0
	global_load_lds_dwordx4 v[52:53], off
	v_lshl_add_u64 v[52:53], s[38:39], 0, v[140:141]
	s_add_i32 m0, s68, 0x2000
	s_nop 0
	global_load_lds_dwordx4 v[52:53], off
	s_waitcnt vmcnt(6)
	s_barrier
	s_setprio 1
	v_mfma_f32_16x16x32_bf16 v[52:55], v[204:207], v[172:175], v[80:83]
	v_mfma_f32_16x16x32_bf16 v[80:83], v[208:211], v[176:179], v[52:55]
	v_mfma_f32_16x16x32_bf16 v[52:55], v[204:207], v[180:183], v[76:79]
	v_mfma_f32_16x16x32_bf16 v[76:79], v[208:211], v[184:187], v[52:55]
	v_mfma_f32_16x16x32_bf16 v[52:55], v[204:207], v[188:191], v[128:131]
	v_mfma_f32_16x16x32_bf16 v[12:15], v[212:215], v[172:175], v[12:15]
	v_mfma_f32_16x16x32_bf16 v[4:7], v[212:215], v[180:183], v[4:7]
	v_mfma_f32_16x16x32_bf16 v[128:131], v[208:211], v[192:195], v[52:55]
	v_mfma_f32_16x16x32_bf16 v[48:51], v[212:215], v[188:191], v[48:51]
	v_mfma_f32_16x16x32_bf16 v[52:55], v[204:207], v[196:199], v[108:111]
	v_mfma_f32_16x16x32_bf16 v[44:47], v[212:215], v[196:199], v[44:47]
	v_mfma_f32_16x16x32_bf16 v[12:15], v[216:219], v[176:179], v[12:15]
	v_mfma_f32_16x16x32_bf16 v[4:7], v[216:219], v[184:187], v[4:7]
	v_mfma_f32_16x16x32_bf16 v[48:51], v[216:219], v[192:195], v[48:51]
	v_mfma_f32_16x16x32_bf16 v[108:111], v[208:211], v[200:203], v[52:55]
	v_mfma_f32_16x16x32_bf16 v[44:47], v[216:219], v[200:203], v[44:47]
	s_setprio 0
	s_add_i32 s68, 0, 0x18000
	v_add_u32_e32 v165, s68, v167
	s_barrier
	ds_read_b128 v[52:55], v165
	ds_read_b128 v[112:115], v165 offset:1024
	ds_read_b128 v[158:161], v165 offset:2048
	ds_read_b128 v[168:171], v165 offset:3072
	s_add_u32 s38, s44, 0x4000
	s_addc_u32 s39, s45, 0
	s_mov_b32 m0, s53
	v_lshl_add_u64 v[204:205], s[38:39], 0, v[142:143]
	ds_read_b128 v[172:175], v229 offset:32768
	ds_read_b128 v[176:179], v229 offset:33792
	ds_read_b128 v[180:183], v229 offset:34816
	ds_read_b128 v[184:187], v229 offset:35840
	ds_read_b128 v[188:191], v229 offset:36864
	ds_read_b128 v[192:195], v229 offset:37888
	ds_read_b128 v[196:199], v229 offset:38912
	ds_read_b128 v[200:203], v229 offset:39936
	global_load_lds_dwordx4 v[204:205], off
	v_lshl_add_u64 v[204:205], s[38:39], 0, v[144:145]
	s_mov_b32 m0, s54
	s_nop 0
	global_load_lds_dwordx4 v[204:205], off
	s_waitcnt lgkmcnt(8)
	s_barrier
	s_waitcnt lgkmcnt(0)
	s_setprio 1
	s_waitcnt lgkmcnt(0)
	v_mfma_f32_16x16x32_bf16 v[132:135], v[52:55], v[172:175], v[132:135]
	v_mfma_f32_16x16x32_bf16 v[72:75], v[158:161], v[172:175], v[72:75]
	v_mfma_f32_16x16x32_bf16 v[124:127], v[52:55], v[180:183], v[124:127]
	v_mfma_f32_16x16x32_bf16 v[68:71], v[158:161], v[180:183], v[68:71]
	v_mfma_f32_16x16x32_bf16 v[104:107], v[52:55], v[188:191], v[104:107]
	v_mfma_f32_16x16x32_bf16 v[32:35], v[158:161], v[188:191], v[32:35]
	v_mfma_f32_16x16x32_bf16 v[100:103], v[52:55], v[196:199], v[100:103]
	v_mfma_f32_16x16x32_bf16 v[24:27], v[158:161], v[196:199], v[24:27]
	v_mfma_f32_16x16x32_bf16 v[132:135], v[112:115], v[176:179], v[132:135]
	v_mfma_f32_16x16x32_bf16 v[72:75], v[168:171], v[176:179], v[72:75]
	v_mfma_f32_16x16x32_bf16 v[124:127], v[112:115], v[184:187], v[124:127]
	v_mfma_f32_16x16x32_bf16 v[68:71], v[168:171], v[184:187], v[68:71]
	v_mfma_f32_16x16x32_bf16 v[104:107], v[112:115], v[192:195], v[104:107]
	v_mfma_f32_16x16x32_bf16 v[32:35], v[168:171], v[192:195], v[32:35]
	v_mfma_f32_16x16x32_bf16 v[100:103], v[112:115], v[200:203], v[100:103]
	v_mfma_f32_16x16x32_bf16 v[24:27], v[168:171], v[200:203], v[24:27]
	s_setprio 0
	s_barrier
	s_add_i32 s44, 0, 0x1c000
	s_add_i32 s38, s68, s48
	v_add_u32_e32 v165, s44, v167
	v_lshl_add_u64 v[162:163], v[162:163], 0, s[12:13]
	s_mov_b32 m0, s38
	ds_read_b128 v[204:207], v165
	ds_read_b128 v[208:211], v165 offset:1024
	ds_read_b128 v[212:215], v165 offset:2048
	ds_read_b128 v[216:219], v165 offset:3072
	global_load_lds_dwordx4 v[162:163], off
	v_lshl_add_u64 v[162:163], v[220:221], 0, s[12:13]
	s_add_i32 m0, s38, 0x2000
	s_nop 0
	global_load_lds_dwordx4 v[162:163], off
	s_barrier
	s_waitcnt lgkmcnt(0)
	s_setprio 1
	s_waitcnt lgkmcnt(0)
	v_mfma_f32_16x16x32_bf16 v[120:123], v[204:207], v[172:175], v[120:123]
	v_mfma_f32_16x16x32_bf16 v[64:67], v[212:215], v[172:175], v[64:67]
	v_mfma_f32_16x16x32_bf16 v[116:119], v[204:207], v[180:183], v[116:119]
	v_mfma_f32_16x16x32_bf16 v[60:63], v[212:215], v[180:183], v[60:63]
	v_mfma_f32_16x16x32_bf16 v[96:99], v[204:207], v[188:191], v[96:99]
	v_mfma_f32_16x16x32_bf16 v[28:31], v[212:215], v[188:191], v[28:31]
	v_mfma_f32_16x16x32_bf16 v[92:95], v[204:207], v[196:199], v[92:95]
	v_mfma_f32_16x16x32_bf16 v[20:23], v[212:215], v[196:199], v[20:23]
	v_mfma_f32_16x16x32_bf16 v[120:123], v[208:211], v[176:179], v[120:123]
	v_mfma_f32_16x16x32_bf16 v[64:67], v[216:219], v[176:179], v[64:67]
	v_mfma_f32_16x16x32_bf16 v[116:119], v[208:211], v[184:187], v[116:119]
	v_mfma_f32_16x16x32_bf16 v[60:63], v[216:219], v[184:187], v[60:63]
	v_mfma_f32_16x16x32_bf16 v[96:99], v[208:211], v[192:195], v[96:99]
	v_mfma_f32_16x16x32_bf16 v[28:31], v[216:219], v[192:195], v[28:31]
	v_mfma_f32_16x16x32_bf16 v[92:95], v[208:211], v[200:203], v[92:95]
	v_mfma_f32_16x16x32_bf16 v[20:23], v[216:219], v[200:203], v[20:23]
	s_setprio 0
	s_mov_b32 m0, s56
	v_lshl_add_u64 v[162:163], v[222:223], 0, s[12:13]
	s_barrier
	ds_read_b128 v[172:175], v229 offset:49152
	ds_read_b128 v[176:179], v229 offset:50176
	ds_read_b128 v[180:183], v229 offset:51200
	ds_read_b128 v[184:187], v229 offset:52224
	ds_read_b128 v[188:191], v229 offset:53248
	ds_read_b128 v[192:195], v229 offset:54272
	ds_read_b128 v[196:199], v229 offset:55296
	ds_read_b128 v[200:203], v229 offset:56320
	global_load_lds_dwordx4 v[162:163], off
	v_lshl_add_u64 v[162:163], v[224:225], 0, s[12:13]
	s_mov_b32 m0, s57
	s_nop 0
	global_load_lds_dwordx4 v[162:163], off
	s_barrier
; __device__ __forceinline__ unsigned pk2(float lo, float hi) { return f2bf(lo) | (f2bf(hi) << 16); }
; #define PG8_STAGE(bufoff, gbase, voff) do { _Pragma("unroll") for (int _i = 0; _i < 2; ++_i) \
;         __builtin_amdgcn_global_load_lds((const unsigned*)((const char*)(gbase) + (voff)[_i]), (LAS unsigned*)(lds + (bufoff) + ldsw + _i * 8192), 16, 0, 0); } while (0)
; #define PG8_WAIT_V(n) asm volatile("s_waitcnt vmcnt(" #n ")" ::: "memory")
; #define PG8_BAR __builtin_amdgcn_s_barrier()
; template <class PT, class Epi>
; __device__ __forceinline__ void gemm_phase_once(LAS unsigned char* lds, const PT& S, const Epi& E, bool epi_on) {
;     ...
;             PG8_BAR; PG8_WAIT_L(0); PG8_MMA(1, 0, At, B0); PG8_BAR; PG8_SCHED;
;             PG8_STAGE(PG8_SB(1, 1), b3 + hstepB, voffB);
;             PG8_WAIT_V(6); PG8_BAR; PG8_MMA(1, 1, At, B1); PG8_BAR;
;     __device__ __forceinline__ void operator()(const f32x4 (&acc)[2][2][4][2], const pg8::Unit& u, int wr, int wc, int fr, int fq) const {
;         const int ch0 = 128 * u.pn + 32 * wc + 8 * fq, tok0 = 256 * u.pm + 128 * wr + 8 * fr;
;         const f32x4 r0 = *(const f32x4*)(RS + tok0), r1 = *(const f32x4*)(RS + tok0 + 4);
;         bf16* hb = HALO + ((size_t)((u.pm * 44 + u.pn) * 2 + wr) * 4) * 256 + 32 * wc + 8 * fq;
; #pragma unroll
;         for (int n = 0; n < 2; ++n) {
;             float g[8][4], v[8][4];
; #pragma unroll
;             for (int e = 0; e < 8; ++e) { const float rs = (e < 4) ? r0[e & 3] : r1[e & 3];
; #pragma unroll
;                 for (int jj = 0; jj < 4; ++jj) { g[e][jj] = acc[e >> 2][0][e & 3][n][jj] * rs; v[e][jj] = acc[e >> 2][1][e & 3][n][jj] * rs; } }
;             if (fr == 0) {
; #pragma unroll
;                 for (int q = 0; q < 2; ++q) { v2u a, b; a.x = pk2(g[q][0], g[q][1]); a.y = pk2(g[q][2], g[q][3]); b.x = pk2(v[q][0], v[q][1]); b.y = pk2(v[q][2], v[q][3]);
;                     *(v2u*)(hb + (size_t)q * 256 + 4 * n) = a; *(v2u*)(hb + (size_t)q * 256 + 128 + 4 * n) = b; } }
;             if (fr == 15) {
; #pragma unroll
;                 for (int q = 0; q < 2; ++q) { v2u a, b; a.x = pk2(g[6 + q][0], g[6 + q][1]); a.y = pk2(g[6 + q][2], g[6 + q][3]); b.x = pk2(v[6 + q][0], v[6 + q][1]); b.y = pk2(v[6 + q][2], v[6 + q][3]);
;                     *(v2u*)(hb + (size_t)(2 + q) * 256 + 4 * n) = a; *(v2u*)(hb + (size_t)(2 + q) * 256 + 128 + 4 * n) = b; } }
	s_waitcnt lgkmcnt(0)
	s_setprio 1
	s_waitcnt lgkmcnt(0)
	v_mfma_f32_16x16x32_bf16 v[88:91], v[52:55], v[172:175], v[88:91]
	v_mfma_f32_16x16x32_bf16 v[84:87], v[52:55], v[180:183], v[84:87]
	v_mfma_f32_16x16x32_bf16 v[136:139], v[52:55], v[188:191], v[136:139]
	v_mfma_f32_16x16x32_bf16 v[36:39], v[52:55], v[196:199], v[36:39]
	v_mfma_f32_16x16x32_bf16 v[88:91], v[112:115], v[176:179], v[88:91]
	v_mfma_f32_16x16x32_bf16 v[16:19], v[158:161], v[172:175], v[16:19]
	v_mfma_f32_16x16x32_bf16 v[84:87], v[112:115], v[184:187], v[84:87]
	v_mfma_f32_16x16x32_bf16 v[8:11], v[158:161], v[180:183], v[8:11]
	v_mfma_f32_16x16x32_bf16 v[136:139], v[112:115], v[192:195], v[136:139]
	v_mfma_f32_16x16x32_bf16 v[56:59], v[158:161], v[188:191], v[56:59]
	v_mfma_f32_16x16x32_bf16 v[112:115], v[112:115], v[200:203], v[36:39]
	v_mfma_f32_16x16x32_bf16 v[36:39], v[158:161], v[196:199], v[40:43]
	v_mfma_f32_16x16x32_bf16 v[16:19], v[168:171], v[176:179], v[16:19]
	v_mfma_f32_16x16x32_bf16 v[8:11], v[168:171], v[184:187], v[8:11]
	v_mfma_f32_16x16x32_bf16 v[56:59], v[168:171], v[192:195], v[56:59]
	v_mfma_f32_16x16x32_bf16 v[52:55], v[168:171], v[200:203], v[36:39]
	s_setprio 0
	s_barrier
	s_add_u32 s38, s42, 0x80080
	s_addc_u32 s39, s43, 0
	s_add_i32 s42, s44, s48
	v_lshl_add_u64 v[36:37], s[38:39], 0, v[146:147]
	s_mov_b32 m0, s42
	s_nop 0
	global_load_lds_dwordx4 v[36:37], off
	v_lshl_add_u64 v[36:37], s[38:39], 0, v[140:141]
	s_add_i32 m0, s42, 0x2000
	s_nop 0
	global_load_lds_dwordx4 v[36:37], off
	s_waitcnt vmcnt(6)
	s_barrier
	s_setprio 1
	v_mfma_f32_16x16x32_bf16 v[36:39], v[204:207], v[172:175], v[80:83]
	v_mfma_f32_16x16x32_bf16 v[80:83], v[208:211], v[176:179], v[36:39]
	v_mfma_f32_16x16x32_bf16 v[36:39], v[204:207], v[180:183], v[76:79]
	v_mfma_f32_16x16x32_bf16 v[76:79], v[208:211], v[184:187], v[36:39]
	v_mfma_f32_16x16x32_bf16 v[36:39], v[204:207], v[188:191], v[128:131]
	v_mfma_f32_16x16x32_bf16 v[128:131], v[208:211], v[192:195], v[36:39]
	v_mfma_f32_16x16x32_bf16 v[36:39], v[212:215], v[188:191], v[48:51]
	v_mfma_f32_16x16x32_bf16 v[48:51], v[216:219], v[192:195], v[36:39]
	v_mfma_f32_16x16x32_bf16 v[36:39], v[204:207], v[196:199], v[108:111]
	v_mfma_f32_16x16x32_bf16 v[12:15], v[212:215], v[172:175], v[12:15]
	v_mfma_f32_16x16x32_bf16 v[4:7], v[212:215], v[180:183], v[4:7]
	v_mfma_f32_16x16x32_bf16 v[108:111], v[208:211], v[200:203], v[36:39]
	v_mfma_f32_16x16x32_bf16 v[36:39], v[212:215], v[196:199], v[44:47]
	v_mfma_f32_16x16x32_bf16 v[12:15], v[216:219], v[176:179], v[12:15]
	v_mfma_f32_16x16x32_bf16 v[4:7], v[216:219], v[184:187], v[4:7]
	v_mfma_f32_16x16x32_bf16 v[44:47], v[216:219], v[200:203], v[36:39]
	s_setprio 0
	s_add_i32 s67, s67, 2
	s_add_u32 s65, s65, 0x100
	s_addc_u32 s66, s66, 0
	s_cmp_lt_u32 s67, 30
	s_mov_b64 s[38:39], s[40:41]
	s_barrier
	s_cbranch_scc1 .LBB0_2983
	v_lshl_add_u32 v160, s36, 8, v226
	v_ashrrev_i32_e32 v161, 31, v160
	v_lshl_add_u64 v[40:41], v[160:161], 2, s[90:91]
	global_load_dwordx4 v[36:39], v[40:41], off offset:16
	s_nop 0
	global_load_dwordx4 v[40:43], v[40:41], off
	s_mul_i32 s27, s36, 44
	s_add_i32 s27, s27, s63
	s_lshl_b32 s27, s27, 1
	s_add_i32 s36, s27, s47
	s_ashr_i32 s37, s36, 31
	v_mov_b32_e32 v162, v136
	v_mov_b32_e32 v163, v138
	s_lshl_b64 s[36:37], s[36:37], 11
	v_mov_b32_e32 v138, v137
	v_lshl_add_u64 v[158:159], v[148:149], 0, s[36:37]
	v_cmp_lt_i32_e32 vcc, 14, v3
	s_mov_b64 s[36:37], 0
	s_waitcnt vmcnt(0)
	v_pk_mul_f32 v[168:169], v[162:163], v[38:39] op_sel_hi:[1,0]
	v_mov_b32_e32 v162, v128
	v_mov_b32_e32 v163, v130
	v_mov_b32_e32 v130, v129
	v_pk_mul_f32 v[162:163], v[162:163], v[38:39] op_sel_hi:[1,0]
	v_pk_mul_f32 v[136:137], v[138:139], v[38:39] op_sel_hi:[1,0]
	v_pk_mul_f32 v[130:131], v[130:131], v[38:39] op_sel_hi:[1,0]
	s_and_saveexec_b64 s[38:39], vcc
	s_xor_b64 s[38:39], exec, s[38:39]
	s_cbranch_execz .LBB0_2986
	v_and_b32_sdwa v138, v137, v234 dst_sel:DWORD dst_unused:UNUSED_PAD src0_sel:WORD_1 src1_sel:DWORD
	v_and_b32_sdwa v139, v136, v234 dst_sel:DWORD dst_unused:UNUSED_PAD src0_sel:WORD_1 src1_sel:DWORD
	v_and_b32_sdwa v128, v169, v234 dst_sel:DWORD dst_unused:UNUSED_PAD src0_sel:WORD_1 src1_sel:DWORD
	v_and_b32_sdwa v129, v168, v234 dst_sel:DWORD dst_unused:UNUSED_PAD src0_sel:WORD_1 src1_sel:DWORD
	v_add3_u32 v138, v137, v138, s61
	v_add3_u32 v139, v136, v139, s61
	v_add3_u32 v129, v168, v129, s61
	v_add3_u32 v128, v169, v128, s61
	v_and_b32_e32 v138, 0xffff0000, v138
	v_and_b32_e32 v161, 0xffff0000, v139
	v_or_b32_sdwa v139, v138, v128 dst_sel:DWORD dst_unused:UNUSED_PAD src0_sel:DWORD src1_sel:WORD_1
	v_or_b32_sdwa v138, v161, v129 dst_sel:DWORD dst_unused:UNUSED_PAD src0_sel:DWORD src1_sel:WORD_1
	v_and_b32_sdwa v129, v162, v234 dst_sel:DWORD dst_unused:UNUSED_PAD src0_sel:WORD_1 src1_sel:DWORD
	v_add3_u32 v161, v162, v129, s61
	s_nop 0
	v_and_b32_sdwa v165, v130, v234 dst_sel:DWORD dst_unused:UNUSED_PAD src0_sel:WORD_1 src1_sel:DWORD
	s_nop 1
	v_add3_u32 v165, v130, v165, s61
	s_nop 1
	v_and_b32_e32 v165, 0xffff0000, v165
	s_mov_b64 s[36:37], exec
	v_cvt_pk_bf16_f32 v129, v163, v131
	v_or_b32_sdwa v128, v165, v161 dst_sel:DWORD dst_unused:UNUSED_PAD src0_sel:DWORD src1_sel:WORD_1
	global_store_dwordx2 v[158:159], v[138:139], off offset:1024
; __device__ __forceinline__ unsigned pk2(float lo, float hi) { return f2bf(lo) | (f2bf(hi) << 16); }
;     __device__ __forceinline__ void operator()(const f32x4 (&acc)[2][2][4][2], const pg8::Unit& u, int wr, int wc, int fr, int fq) const {
;     ...
;             float g[8][4], v[8][4];
; #pragma unroll
;             for (int e = 0; e < 8; ++e) { const float rs = (e < 4) ? r0[e & 3] : r1[e & 3];
; #pragma unroll
;                 for (int jj = 0; jj < 4; ++jj) { g[e][jj] = acc[e >> 2][0][e & 3][n][jj] * rs; v[e][jj] = acc[e >> 2][1][e & 3][n][jj] * rs; } }
;             if (fr == 0) {
; #pragma unroll
;                 for (int q = 0; q < 2; ++q) { v2u a, b; a.x = pk2(g[q][0], g[q][1]); a.y = pk2(g[q][2], g[q][3]); b.x = pk2(v[q][0], v[q][1]); b.y = pk2(v[q][2], v[q][3]);
;                     *(v2u*)(hb + (size_t)q * 256 + 4 * n) = a; *(v2u*)(hb + (size_t)q * 256 + 128 + 4 * n) = b; } }
.LBB0_2986:
	s_or_saveexec_b64 s[38:39], s[38:39]
	v_mov_b32_e32 v138, v132
	v_mov_b32_e32 v139, v134
	v_pk_mul_f32 v[190:191], v[138:139], v[40:41] op_sel_hi:[1,0]
	v_mov_b32_e32 v138, v120
	v_mov_b32_e32 v139, v122
	v_mov_b32_e32 v122, v121
	v_mov_b32_e32 v120, v124
	v_mov_b32_e32 v121, v126
	v_pk_mul_f32 v[182:183], v[120:121], v[40:41] op_sel:[0,1]
	v_mov_b32_e32 v120, v116
	v_mov_b32_e32 v121, v118
	v_mov_b32_e32 v118, v117
	v_mov_b32_e32 v116, v112
	v_mov_b32_e32 v117, v114
	v_mov_b32_e32 v112, v39
	v_mov_b32_e32 v134, v133
	v_pk_mul_f32 v[170:171], v[116:117], v[112:113] op_sel_hi:[1,0]
	v_mov_b32_e32 v116, v108
	v_mov_b32_e32 v117, v110
	v_mov_b32_e32 v114, v113
	v_mov_b32_e32 v110, v109
	v_pk_mul_f32 v[188:189], v[138:139], v[40:41] op_sel_hi:[1,0]
	v_pk_mul_f32 v[192:193], v[134:135], v[40:41] op_sel_hi:[1,0]
	v_mov_b32_e32 v126, v125
	v_pk_mul_f32 v[134:135], v[116:117], v[112:113] op_sel_hi:[1,0]
	v_pk_mul_f32 v[172:173], v[114:115], v[112:113] op_sel_hi:[1,0]
	v_pk_mul_f32 v[138:139], v[110:111], v[112:113] op_sel_hi:[1,0]
	v_pk_mul_f32 v[186:187], v[122:123], v[40:41] op_sel_hi:[1,0]
	v_pk_mul_f32 v[180:181], v[120:121], v[40:41] op_sel:[0,1]
	v_pk_mul_f32 v[184:185], v[126:127], v[40:41] op_sel:[0,1]
	v_pk_mul_f32 v[178:179], v[118:119], v[40:41] op_sel:[0,1]
	v_mov_b64_e32 v[116:117], 0x500
	v_mov_b64_e32 v[110:111], 0x600
	v_mov_b64_e32 v[108:109], 0x700
	v_mov_b64_e32 v[120:121], v[170:171]
	v_mov_b64_e32 v[118:119], v[172:173]
	v_mov_b64_e32 v[112:113], v[134:135]
	v_mov_b64_e32 v[114:115], v[138:139]
	s_xor_b64 exec, exec, s[38:39]
	s_cbranch_execz .LBB0_2990
	v_cmp_eq_u32_e32 vcc, 0, v3
	s_mov_b64 s[42:43], s[36:37]
	s_and_saveexec_b64 s[40:41], vcc
	s_cbranch_execz .LBB0_2989
	v_and_b32_sdwa v109, v190, v234 dst_sel:DWORD dst_unused:UNUSED_PAD src0_sel:WORD_1 src1_sel:DWORD
	v_add3_u32 v110, v190, v109, s61
	s_nop 0
	v_and_b32_sdwa v111, v192, v234 dst_sel:DWORD dst_unused:UNUSED_PAD src0_sel:WORD_1 src1_sel:DWORD
	s_nop 1
	v_add3_u32 v111, v192, v111, s61
	s_nop 1
	v_and_b32_e32 v111, 0xffff0000, v111
	v_and_b32_sdwa v112, v187, v234 dst_sel:DWORD dst_unused:UNUSED_PAD src0_sel:WORD_1 src1_sel:DWORD
	v_and_b32_sdwa v113, v186, v234 dst_sel:DWORD dst_unused:UNUSED_PAD src0_sel:WORD_1 src1_sel:DWORD
	v_cvt_pk_bf16_f32 v109, v191, v193
	v_or_b32_sdwa v108, v111, v110 dst_sel:DWORD dst_unused:UNUSED_PAD src0_sel:DWORD src1_sel:WORD_1
	v_and_b32_sdwa v110, v189, v234 dst_sel:DWORD dst_unused:UNUSED_PAD src0_sel:WORD_1 src1_sel:DWORD
	v_and_b32_sdwa v111, v188, v234 dst_sel:DWORD dst_unused:UNUSED_PAD src0_sel:WORD_1 src1_sel:DWORD
	v_add3_u32 v112, v187, v112, s61
	v_add3_u32 v113, v186, v113, s61
	v_add3_u32 v111, v188, v111, s61
	v_add3_u32 v110, v189, v110, s61
	v_and_b32_e32 v112, 0xffff0000, v112
	v_and_b32_e32 v113, 0xffff0000, v113
	v_or_b32_sdwa v129, v112, v110 dst_sel:DWORD dst_unused:UNUSED_PAD src0_sel:DWORD src1_sel:WORD_1
	v_or_b32_sdwa v128, v113, v111 dst_sel:DWORD dst_unused:UNUSED_PAD src0_sel:DWORD src1_sel:WORD_1
	s_or_b64 s[42:43], s[36:37], exec
	global_store_dwordx2 v[158:159], v[108:109], off

; __device__ __forceinline__ unsigned pk2(float lo, float hi) { return f2bf(lo) | (f2bf(hi) << 16); }
; __device__ __forceinline__ float dpp_shr1(float x) { return __builtin_bit_cast(float, __builtin_amdgcn_update_dpp(0, __builtin_bit_cast(int, x), 0x111, 0xf, 0xf, true)); }
;     __device__ __forceinline__ void operator()(const f32x4 (&acc)[2][2][4][2], const pg8::Unit& u, int wr, int wc, int fr, int fq) const {
;     ...
;             if (fr == 15) {
; #pragma unroll
;                 for (int q = 0; q < 2; ++q) { v2u a, b; a.x = pk2(g[6 + q][0], g[6 + q][1]); a.y = pk2(g[6 + q][2], g[6 + q][3]); b.x = pk2(v[6 + q][0], v[6 + q][1]); b.y = pk2(v[6 + q][2], v[6 + q][3]);
;                     *(v2u*)(hb + (size_t)(2 + q) * 256 + 4 * n) = a; *(v2u*)(hb + (size_t)(2 + q) * 256 + 128 + 4 * n) = b; } }
;             const int cc = ch0 + 4 * n;
;             const f32x4 wg0 = *(CF4)(cw + cc), wg1 = *(CF4)(cw + FF2 + cc), wg2 = *(CF4)(cw + 2 * FF2 + cc), wv0 = *(CF4)(cw + FFH + cc), wv1 = *(CF4)(cw + FF2 + FFH + cc), wv2 = *(CF4)(cw + 2 * FF2 + FFH + cc);
;             const f32x4 bg = *(CF4)(cb + cc), bv = *(CF4)(cb + FFH + cc);
; #pragma unroll
;             for (int jj = 0; jj < 4; ++jj) {
;                 float g2 = dpp_shr1(g[6][jj]), g1 = dpp_shr1(g[7][jj]), v2 = dpp_shr1(v[6][jj]), v1 = dpp_shr1(v[7][jj]);
.LBB0_2990:
	s_or_b64 exec, exec, s[38:39]
	s_and_saveexec_b64 s[38:39], s[36:37]
	s_cbranch_execz .LBB0_2992
	v_lshl_add_u64 v[116:117], v[158:159], 0, v[116:117]
	global_store_dwordx2 v[116:117], v[128:129], off
	v_and_b32_sdwa v116, v121, v234 dst_sel:DWORD dst_unused:UNUSED_PAD src0_sel:WORD_1 src1_sel:DWORD
	v_and_b32_sdwa v117, v120, v234 dst_sel:DWORD dst_unused:UNUSED_PAD src0_sel:WORD_1 src1_sel:DWORD
	v_add3_u32 v120, v120, v117, s61
	v_add3_u32 v116, v121, v116, s61
	v_and_b32_sdwa v117, v119, v234 dst_sel:DWORD dst_unused:UNUSED_PAD src0_sel:WORD_1 src1_sel:DWORD
	v_and_b32_sdwa v121, v118, v234 dst_sel:DWORD dst_unused:UNUSED_PAD src0_sel:WORD_1 src1_sel:DWORD
	v_add3_u32 v117, v119, v117, s61
	v_add3_u32 v118, v118, v121, s61
	v_and_b32_e32 v117, 0xffff0000, v117
	v_and_b32_e32 v118, 0xffff0000, v118
	v_or_b32_sdwa v117, v117, v116 dst_sel:DWORD dst_unused:UNUSED_PAD src0_sel:DWORD src1_sel:WORD_1
	v_or_b32_sdwa v116, v118, v120 dst_sel:DWORD dst_unused:UNUSED_PAD src0_sel:DWORD src1_sel:WORD_1
	s_nop 7
	s_nop 1
	v_cvt_pk_bf16_f32 v113, v113, v115
	v_cvt_pk_bf16_f32 v112, v112, v114
	v_lshl_add_u64 v[110:111], v[158:159], 0, v[110:111]
	v_lshl_add_u64 v[108:109], v[158:159], 0, v[108:109]
	global_store_dwordx2 v[110:111], v[116:117], off
	global_store_dwordx2 v[108:109], v[112:113], off
.LBB0_2992:
	s_or_b64 exec, exec, s[38:39]
	v_lshl_or_b32 v132, s63, 7, v227
	v_ashrrev_i32_e32 v133, 31, v132
	v_lshlrev_b64 v[194:195], 2, v[132:133]
	v_lshl_add_u64 v[108:109], s[8:9], 0, v[194:195]
	v_lshl_add_u64 v[112:113], s[10:11], 0, v[194:195]
	global_load_dwordx4 v[108:111], v[108:109], off
	v_mov_b32_e32 v166, v43
	global_load_dwordx4 v[116:119], v[112:113], off
	v_lshl_add_u64 v[112:113], s[14:15], 0, v[194:195]
	global_load_dwordx4 v[120:123], v[112:113], off
	v_lshl_add_u64 v[112:113], s[16:17], 0, v[194:195]
	global_load_dwordx4 v[124:127], v[112:113], off
	v_mov_b32_e32 v112, v104
	v_mov_b32_e32 v113, v106
	v_pk_mul_f32 v[224:225], v[112:113], v[42:43] op_sel_hi:[1,0]
	v_mov_b32_e32 v112, v96
	v_mov_b32_e32 v113, v98
	v_mov_b32_e32 v98, v97
	v_lshl_add_u64 v[96:97], s[18:19], 0, v[194:195]
	v_pk_mul_f32 v[218:219], v[98:99], v[42:43] op_sel_hi:[1,0]
	global_load_dwordx4 v[96:99], v[96:97], off
	v_pk_mul_f32 v[220:221], v[112:113], v[42:43] op_sel_hi:[1,0]
	v_mov_b32_e32 v106, v105
	v_mov_b32_e32 v112, v100
	v_mov_b32_e32 v113, v102
	v_lshl_add_u64 v[104:105], s[24:25], 0, v[194:195]
	v_pk_mul_f32 v[222:223], v[106:107], v[42:43] op_sel_hi:[1,0]
	global_load_dwordx4 v[104:107], v[104:105], off
	v_pk_mul_f32 v[214:215], v[112:113], v[166:167] op_sel_hi:[1,0]
	v_lshl_add_u64 v[112:113], s[20:21], 0, v[194:195]
	global_load_dwordx4 v[112:115], v[112:113], off
	v_mov_b32_e32 v102, v101
	v_lshl_add_u64 v[100:101], s[22:23], 0, v[194:195]
	v_pk_mul_f32 v[216:217], v[102:103], v[166:167] op_sel_hi:[1,0]
	global_load_dwordx4 v[100:103], v[100:101], off
	v_mov_b32_e32 v199, v94
	v_mov_b32_e32 v94, v93
	v_mov_b32_e32 v196, v36
	v_mov_b32_e32 v197, v37
	v_pk_mul_f32 v[206:207], v[94:95], v[166:167] op_sel_hi:[1,0]
	v_mov_b32_e32 v94, v88
	v_mov_b32_e32 v95, v90
	v_pk_mul_f32 v[202:203], v[94:95], v[196:197] op_sel_hi:[1,0]
	v_mov_b32_e32 v94, v80
	v_mov_b32_e32 v95, v82
	v_mov_b32_e32 v82, v81
	v_mov_b32_e32 v80, v84
	v_mov_b32_e32 v81, v86
	v_mov_b32_e32 v90, v89
	v_pk_mul_f32 v[88:89], v[80:81], v[196:197] op_sel:[0,1]
	v_mov_b32_e32 v81, v78
	v_mov_b32_e32 v86, v85
	v_mov_b32_e32 v78, v77
	v_pk_mul_f32 v[194:195], v[94:95], v[196:197] op_sel_hi:[1,0]
	v_mov_b32_e32 v80, v76
	v_pk_mul_f32 v[84:85], v[86:87], v[196:197] op_sel:[0,1]
	v_pk_mul_f32 v[76:77], v[78:79], v[196:197] op_sel:[0,1]
	v_mov_b32_dpp v78, v168 row_shr:1 row_mask:0xf bank_mask:0xf bound_ctrl:1
	v_mov_b32_dpp v79, v169 row_shr:1 row_mask:0xf bank_mask:0xf bound_ctrl:1
	v_mov_b32_e32 v198, v92
	v_pk_mul_f32 v[200:201], v[90:91], v[196:197] op_sel_hi:[1,0]
	v_pk_mul_f32 v[90:91], v[82:83], v[196:197] op_sel_hi:[1,0]
	v_pk_mul_f32 v[82:83], v[80:81], v[196:197] op_sel:[0,1]
	v_mov_b32_dpp v80, v170 row_shr:1 row_mask:0xf bank_mask:0xf bound_ctrl:1
	v_mov_b32_dpp v81, v171 row_shr:1 row_mask:0xf bank_mask:0xf bound_ctrl:1
	v_pk_mul_f32 v[208:209], v[198:199], v[166:167] op_sel_hi:[1,0]
	v_mov_b32_dpp v210, v136 row_shr:1 row_mask:0xf bank_mask:0xf bound_ctrl:1
	v_mov_b32_dpp v211, v137 row_shr:1 row_mask:0xf bank_mask:0xf bound_ctrl:1
	v_mov_b32_dpp v238, v172 row_shr:1 row_mask:0xf bank_mask:0xf bound_ctrl:1
	v_mov_b32_dpp v239, v173 row_shr:1 row_mask:0xf bank_mask:0xf bound_ctrl:1
	v_mov_b32_dpp v204, v162 row_shr:1 row_mask:0xf bank_mask:0xf bound_ctrl:1
	v_mov_b32_dpp v205, v163 row_shr:1 row_mask:0xf bank_mask:0xf bound_ctrl:1
	v_mov_b32_dpp v236, v134 row_shr:1 row_mask:0xf bank_mask:0xf bound_ctrl:1
	v_mov_b32_dpp v237, v135 row_shr:1 row_mask:0xf bank_mask:0xf bound_ctrl:1
	v_mov_b32_dpp v212, v130 row_shr:1 row_mask:0xf bank_mask:0xf bound_ctrl:1
	v_mov_b32_dpp v213, v131 row_shr:1 row_mask:0xf bank_mask:0xf bound_ctrl:1
	v_mov_b32_dpp v240, v138 row_shr:1 row_mask:0xf bank_mask:0xf bound_ctrl:1
	v_mov_b32_dpp v241, v139 row_shr:1 row_mask:0xf bank_mask:0xf bound_ctrl:1
	v_mov_b32_e32 v174, v40
	v_mov_b32_e32 v175, v40
	v_mov_b32_e32 v40, v41
	v_mov_b32_e32 v176, v38
	v_mov_b32_e32 v177, v38
	v_mov_b32_e32 v38, v39
	v_mov_b32_e32 v128, v42
	s_waitcnt vmcnt(0)
; __device__ __forceinline__ unsigned pk2(float lo, float hi) { return f2bf(lo) | (f2bf(hi) << 16); }
; __device__ __forceinline__ float silu_fast(float x) { return x * __builtin_amdgcn_rcpf(1.f + __builtin_amdgcn_exp2f(-1.4426950408889634f * x)); }
; __device__ __forceinline__ float dpp_shr1(float x) { return __builtin_bit_cast(float, __builtin_amdgcn_update_dpp(0, __builtin_bit_cast(int, x), 0x111, 0xf, 0xf, true)); }
;     __device__ __forceinline__ void operator()(const f32x4 (&acc)[2][2][4][2], const pg8::Unit& u, int wr, int wc, int fr, int fq) const {
;     ...
;             for (int jj = 0; jj < 4; ++jj) {
;                 float g2 = dpp_shr1(g[6][jj]), g1 = dpp_shr1(g[7][jj]), v2 = dpp_shr1(v[6][jj]), v1 = dpp_shr1(v[7][jj]);
; #pragma unroll
;                 for (int e = 0; e < 8; ++e) { const float g0 = g[e][jj], v0 = v[e][jj];
;                     const float cg = bg[jj] + wg0[jj] * g2 + wg1[jj] * g1 + wg2[jj] * g0, cv = bv[jj] + wv0[jj] * v2 + wv1[jj] * v1 + wv2[jj] * v0;
;                     g[e][jj] = silu_fast(cg) * cv; g2 = g1; g1 = g0; v2 = v1; v1 = v0; } }
; #pragma unroll
;             for (int e = 0; e < 8; ++e) { v2u w; w.x = pk2(g[e][0], g[e][1]); w.y = pk2(g[e][2], g[e][3]); *(v2u*)(ACT + (size_t)(tok0 + e) * FFH + cc) = w; }
	v_mov_b32_e32 v86, v108
	v_mov_b32_e32 v87, v110
	v_mov_b32_e32 v94, v116
	v_mov_b32_e32 v95, v118
	v_pk_fma_f32 v[78:79], v[86:87], v[78:79], v[94:95]
	v_mov_b32_e32 v196, v120
	v_mov_b32_e32 v197, v122
	v_pk_fma_f32 v[78:79], v[196:197], v[80:81], v[78:79]
	v_mov_b32_e32 v198, v124
	v_mov_b32_e32 v199, v126
	v_pk_fma_f32 v[78:79], v[190:191], v[198:199], v[78:79]
	v_mov_b32_e32 v110, v109
	v_mul_f32_e32 v108, 0xbfb8aa3b, v78
	v_mov_b32_e32 v118, v117
	v_exp_f32_e32 v116, v108
	v_pk_fma_f32 v[108:109], v[110:111], v[210:211], v[118:119]
	v_mov_b32_e32 v122, v121
	v_pk_fma_f32 v[108:109], v[122:123], v[238:239], v[108:109]
	v_mov_b32_e32 v126, v125
	v_pk_fma_f32 v[108:109], v[192:193], v[126:127], v[108:109]
	v_add_f32_e32 v116, 1.0, v116
	v_mul_f32_e32 v117, 0xbfb8aa3b, v108
	v_exp_f32_e32 v117, v117
	v_rcp_f32_e32 v210, v116
	v_mov_b32_e32 v120, v104
	v_mov_b32_e32 v121, v106
	v_add_f32_e32 v116, 1.0, v117
	v_rcp_f32_e32 v242, v116
	v_mov_b32_e32 v116, v96
	v_mul_f32_e32 v96, 0xbfb8aa3b, v79
	v_exp_f32_e32 v96, v96
	v_mov_b32_e32 v117, v98
	v_pk_fma_f32 v[124:125], v[116:117], v[204:205], v[120:121]
	v_mov_b32_e32 v204, v112
	v_add_f32_e32 v96, 1.0, v96
	v_mov_b32_e32 v205, v114
	v_rcp_f32_e32 v211, v96
	v_mul_f32_e32 v96, 0xbfb8aa3b, v109
	v_pk_fma_f32 v[244:245], v[204:205], v[236:237], v[124:125]
	v_mov_b32_e32 v124, v100
	v_exp_f32_e32 v100, v96
	v_mov_b32_e32 v98, v97
	v_mov_b32_e32 v106, v105
	v_mov_b32_e32 v125, v102
	v_add_f32_e32 v100, 1.0, v100
	v_rcp_f32_e32 v243, v100
	v_pk_fma_f32 v[96:97], v[98:99], v[212:213], v[106:107]
	v_mov_b32_e32 v114, v113
	v_pk_fma_f32 v[244:245], v[188:189], v[124:125], v[244:245]
	v_pk_mul_f32 v[78:79], v[78:79], v[210:211]
	v_pk_fma_f32 v[96:97], v[114:115], v[240:241], v[96:97]
	v_mov_b32_e32 v102, v101
	v_pk_mul_f32 v[78:79], v[244:245], v[78:79]
	v_pk_fma_f32 v[96:97], v[186:187], v[102:103], v[96:97]
	v_pk_mul_f32 v[100:101], v[108:109], v[242:243]
	v_pk_fma_f32 v[80:81], v[86:87], v[80:81], v[94:95]
	v_pk_mul_f32 v[96:97], v[96:97], v[100:101]
	s_nop 7
	s_nop 1
	v_mov_b64_e32 v[210:211], s[78:79]
	v_pk_fma_f32 v[80:81], v[190:191], v[196:197], v[80:81]
	v_cvt_pk_bf16_f32 v79, v79, v97
	v_cvt_pk_bf16_f32 v78, v78, v96
	v_mad_i64_i32 v[96:97], s[36:37], v160, s62, v[210:211]
	v_lshlrev_b64 v[212:213], 1, v[132:133]
	v_pk_fma_f32 v[80:81], v[182:183], v[198:199], v[80:81]
	v_lshl_add_u64 v[112:113], v[96:97], 0, v[212:213]
	v_mul_f32_e32 v96, 0xbfb8aa3b, v80
	v_exp_f32_e32 v100, v96
	v_pk_fma_f32 v[96:97], v[110:111], v[238:239], v[118:119]
	global_store_dwordx2 v[112:113], v[78:79], off
	v_pk_fma_f32 v[96:97], v[192:193], v[122:123], v[96:97]
	v_add_f32_e32 v78, 1.0, v100
	v_pk_fma_f32 v[96:97], v[184:185], v[126:127], v[96:97]
	v_mul_f32_e32 v100, 0xbfb8aa3b, v81
	v_mul_f32_e32 v101, 0xbfb8aa3b, v96
	v_exp_f32_e32 v101, v101
	v_rcp_f32_e32 v78, v78
	v_pk_fma_f32 v[104:105], v[116:117], v[236:237], v[120:121]
	v_mov_b32_e32 v129, v42
	v_add_f32_e32 v79, 1.0, v101
	v_exp_f32_e32 v101, v100
	v_rcp_f32_e32 v100, v79
	v_pk_fma_f32 v[104:105], v[188:189], v[204:205], v[104:105]
	v_mov_b32_e32 v42, v43
	v_add_f32_e32 v79, 1.0, v101
	v_mul_f32_e32 v101, 0xbfb8aa3b, v97
	v_rcp_f32_e32 v79, v79
	v_exp_f32_e32 v101, v101
	v_pk_fma_f32 v[104:105], v[180:181], v[124:125], v[104:105]
	v_mov_b32_e32 v92, v36
	v_pk_mul_f32 v[78:79], v[80:81], v[78:79]
	v_add_f32_e32 v80, 1.0, v101
	v_rcp_f32_e32 v101, v80
	v_pk_fma_f32 v[80:81], v[98:99], v[240:241], v[106:107]
	v_pk_mul_f32 v[78:79], v[104:105], v[78:79]
	v_pk_fma_f32 v[80:81], v[186:187], v[114:115], v[80:81]
	v_pk_mul_f32 v[96:97], v[96:97], v[100:101]
	v_pk_fma_f32 v[80:81], v[178:179], v[102:103], v[80:81]
	v_pk_fma_f32 v[104:105], v[188:189], v[116:117], v[120:121]
	v_pk_mul_f32 v[80:81], v[80:81], v[96:97]
	s_nop 7
	s_nop 1
	v_cvt_pk_bf16_f32 v78, v78, v80
	v_or_b32_e32 v80, 1, v160
	v_cvt_pk_bf16_f32 v79, v79, v81
	v_mad_i64_i32 v[80:81], s[36:37], v80, s62, v[210:211]
	v_lshl_add_u64 v[108:109], v[80:81], 0, v[212:213]
	v_pk_fma_f32 v[80:81], v[190:191], v[86:87], v[94:95]
	global_store_dwordx2 v[108:109], v[78:79], off
	v_pk_fma_f32 v[80:81], v[182:183], v[196:197], v[80:81]
	v_pk_fma_f32 v[104:105], v[180:181], v[204:205], v[104:105]
	v_pk_fma_f32 v[80:81], v[224:225], v[198:199], v[80:81]
	v_pk_fma_f32 v[104:105], v[220:221], v[124:125], v[104:105]
	v_mul_f32_e32 v96, 0xbfb8aa3b, v80
	v_exp_f32_e32 v100, v96
	v_pk_fma_f32 v[96:97], v[192:193], v[110:111], v[118:119]
	v_pk_fma_f32 v[180:181], v[180:181], v[116:117], v[120:121]
	v_pk_fma_f32 v[96:97], v[184:185], v[122:123], v[96:97]
	v_add_f32_e32 v78, 1.0, v100
	v_pk_fma_f32 v[96:97], v[222:223], v[126:127], v[96:97]
	v_mul_f32_e32 v100, 0xbfb8aa3b, v81
	v_mul_f32_e32 v101, 0xbfb8aa3b, v96
	v_exp_f32_e32 v101, v101
	v_rcp_f32_e32 v78, v78
	v_pk_fma_f32 v[180:181], v[220:221], v[204:205], v[180:181]
	v_mov_b32_e32 v93, v36
	v_add_f32_e32 v79, 1.0, v101
	v_exp_f32_e32 v101, v100
	v_rcp_f32_e32 v100, v79
	v_pk_fma_f32 v[180:181], v[208:209], v[124:125], v[180:181]
	v_mov_b32_e32 v36, v37
	v_add_f32_e32 v79, 1.0, v101
	v_mul_f32_e32 v101, 0xbfb8aa3b, v97
	v_rcp_f32_e32 v79, v79
	v_exp_f32_e32 v101, v101
	v_cmp_gt_i32_e32 vcc, 15, v3
	s_mov_b64 s[38:39], -1
	v_pk_mul_f32 v[78:79], v[80:81], v[78:79]
	v_add_f32_e32 v80, 1.0, v101
	v_rcp_f32_e32 v101, v80
	v_pk_fma_f32 v[80:81], v[186:187], v[98:99], v[106:107]
	v_pk_mul_f32 v[78:79], v[104:105], v[78:79]
	v_pk_fma_f32 v[80:81], v[178:179], v[114:115], v[80:81]
	v_pk_mul_f32 v[96:97], v[96:97], v[100:101]
	v_pk_fma_f32 v[80:81], v[218:219], v[102:103], v[80:81]
	s_nop 0
	v_pk_mul_f32 v[80:81], v[80:81], v[96:97]
	s_nop 7
	s_nop 1
; __device__ __forceinline__ unsigned pk2(float lo, float hi) { return f2bf(lo) | (f2bf(hi) << 16); }
; __device__ __forceinline__ float silu_fast(float x) { return x * __builtin_amdgcn_rcpf(1.f + __builtin_amdgcn_exp2f(-1.4426950408889634f * x)); }
; __device__ __forceinline__ float dpp_shr1(float x) { return __builtin_bit_cast(float, __builtin_amdgcn_update_dpp(0, __builtin_bit_cast(int, x), 0x111, 0xf, 0xf, true)); }
;     __device__ __forceinline__ void operator()(const f32x4 (&acc)[2][2][4][2], const pg8::Unit& u, int wr, int wc, int fr, int fq) const {
;     ...
;             for (int jj = 0; jj < 4; ++jj) {
;                 float g2 = dpp_shr1(g[6][jj]), g1 = dpp_shr1(g[7][jj]), v2 = dpp_shr1(v[6][jj]), v1 = dpp_shr1(v[7][jj]);
; #pragma unroll
;                 for (int e = 0; e < 8; ++e) { const float g0 = g[e][jj], v0 = v[e][jj];
;                     const float cg = bg[jj] + wg0[jj] * g2 + wg1[jj] * g1 + wg2[jj] * g0, cv = bv[jj] + wv0[jj] * v2 + wv1[jj] * v1 + wv2[jj] * v0;
;                     g[e][jj] = silu_fast(cg) * cv; g2 = g1; g1 = g0; v2 = v1; v1 = v0; } }
; #pragma unroll
;             for (int e = 0; e < 8; ++e) { v2u w; w.x = pk2(g[e][0], g[e][1]); w.y = pk2(g[e][2], g[e][3]); *(v2u*)(ACT + (size_t)(tok0 + e) * FFH + cc) = w; }
	v_cvt_pk_bf16_f32 v78, v78, v80
	v_or_b32_e32 v80, 2, v160
	v_cvt_pk_bf16_f32 v79, v79, v81
	v_mad_i64_i32 v[80:81], s[36:37], v80, s62, v[210:211]
	v_lshl_add_u64 v[104:105], v[80:81], 0, v[212:213]
	v_pk_fma_f32 v[80:81], v[182:183], v[86:87], v[94:95]
	global_store_dwordx2 v[104:105], v[78:79], off
	v_pk_fma_f32 v[80:81], v[224:225], v[196:197], v[80:81]
	v_pk_fma_f32 v[182:183], v[208:209], v[116:117], v[120:121]
	v_pk_fma_f32 v[80:81], v[214:215], v[198:199], v[80:81]
	v_pk_fma_f32 v[182:183], v[194:195], v[204:205], v[182:183]
	v_mul_f32_e32 v96, 0xbfb8aa3b, v80
	v_exp_f32_e32 v100, v96
	v_pk_fma_f32 v[96:97], v[184:185], v[110:111], v[118:119]
	v_pk_fma_f32 v[182:183], v[82:83], v[124:125], v[182:183]
	v_pk_fma_f32 v[96:97], v[222:223], v[122:123], v[96:97]
	v_add_f32_e32 v78, 1.0, v100
	v_pk_fma_f32 v[96:97], v[216:217], v[126:127], v[96:97]
	v_mul_f32_e32 v100, 0xbfb8aa3b, v81
	v_mul_f32_e32 v101, 0xbfb8aa3b, v96
	v_exp_f32_e32 v101, v101
	v_rcp_f32_e32 v78, v78
	v_pk_fma_f32 v[184:185], v[194:195], v[116:117], v[120:121]
	v_add_f32_e32 v79, 1.0, v101
	v_exp_f32_e32 v101, v100
	v_rcp_f32_e32 v100, v79
	v_pk_fma_f32 v[184:185], v[82:83], v[204:205], v[184:185]
	v_pk_fma_f32 v[82:83], v[82:83], v[116:117], v[120:121]
	v_add_f32_e32 v79, 1.0, v101
	v_mul_f32_e32 v101, 0xbfb8aa3b, v97
	v_rcp_f32_e32 v79, v79
	v_exp_f32_e32 v101, v101
	v_pk_fma_f32 v[184:185], v[162:163], v[124:125], v[184:185]
	v_pk_fma_f32 v[82:83], v[162:163], v[204:205], v[82:83]
	v_pk_mul_f32 v[78:79], v[80:81], v[78:79]
	v_add_f32_e32 v80, 1.0, v101
	v_rcp_f32_e32 v101, v80
	v_pk_fma_f32 v[80:81], v[178:179], v[98:99], v[106:107]
	v_pk_mul_f32 v[78:79], v[180:181], v[78:79]
	v_pk_fma_f32 v[80:81], v[218:219], v[114:115], v[80:81]
	v_pk_mul_f32 v[96:97], v[96:97], v[100:101]
	v_pk_fma_f32 v[80:81], v[206:207], v[102:103], v[80:81]
	v_pk_fma_f32 v[180:181], v[220:221], v[116:117], v[120:121]
	v_pk_mul_f32 v[80:81], v[80:81], v[96:97]
	s_nop 7
	s_nop 1
	v_cvt_pk_bf16_f32 v78, v78, v80
	v_or_b32_e32 v80, 3, v160
	v_cvt_pk_bf16_f32 v79, v79, v81
	v_mad_i64_i32 v[80:81], s[36:37], v80, s62, v[210:211]
	v_lshl_add_u64 v[100:101], v[80:81], 0, v[212:213]
	v_pk_fma_f32 v[80:81], v[224:225], v[86:87], v[94:95]
	global_store_dwordx2 v[100:101], v[78:79], off
	v_pk_fma_f32 v[80:81], v[214:215], v[196:197], v[80:81]
	v_pk_fma_f32 v[180:181], v[208:209], v[204:205], v[180:181]
	v_pk_fma_f32 v[80:81], v[202:203], v[198:199], v[80:81]
	v_pk_fma_f32 v[180:181], v[194:195], v[124:125], v[180:181]
	v_mul_f32_e32 v96, 0xbfb8aa3b, v80
	v_exp_f32_e32 v133, v96
	v_pk_fma_f32 v[96:97], v[222:223], v[110:111], v[118:119]
	v_pk_fma_f32 v[82:83], v[134:135], v[124:125], v[82:83]
	v_pk_fma_f32 v[96:97], v[216:217], v[122:123], v[96:97]
	v_add_f32_e32 v78, 1.0, v133
	v_pk_fma_f32 v[96:97], v[200:201], v[126:127], v[96:97]
	v_mul_f32_e32 v133, 0xbfb8aa3b, v81
	v_mul_f32_e32 v161, 0xbfb8aa3b, v96
	v_exp_f32_e32 v161, v161
	v_exp_f32_e32 v133, v133
	v_rcp_f32_e32 v78, v78
	v_add_f32_e32 v79, 1.0, v161
	v_rcp_f32_e32 v178, v79
	v_add_f32_e32 v79, 1.0, v133
	v_mul_f32_e32 v133, 0xbfb8aa3b, v97
	v_rcp_f32_e32 v79, v79
	v_exp_f32_e32 v133, v133
	v_pk_mul_f32 v[78:79], v[80:81], v[78:79]
	v_add_f32_e32 v80, 1.0, v133
	v_rcp_f32_e32 v179, v80
	v_pk_fma_f32 v[80:81], v[218:219], v[98:99], v[106:107]
	v_pk_mul_f32 v[78:79], v[180:181], v[78:79]
	v_pk_fma_f32 v[80:81], v[206:207], v[114:115], v[80:81]
	v_pk_mul_f32 v[96:97], v[96:97], v[178:179]
	v_pk_fma_f32 v[80:81], v[90:91], v[102:103], v[80:81]
	v_pk_fma_f32 v[178:179], v[216:217], v[110:111], v[118:119]
	v_pk_mul_f32 v[80:81], v[80:81], v[96:97]
	s_nop 7
	s_nop 1
	v_cvt_pk_bf16_f32 v78, v78, v80
	v_or_b32_e32 v80, 4, v160
	v_cvt_pk_bf16_f32 v79, v79, v81
	v_mad_i64_i32 v[80:81], s[36:37], v80, s62, v[210:211]
	v_lshl_add_u64 v[96:97], v[80:81], 0, v[212:213]
	v_pk_fma_f32 v[80:81], v[214:215], v[86:87], v[94:95]
	v_pk_fma_f32 v[178:179], v[200:201], v[122:123], v[178:179]
	v_pk_fma_f32 v[80:81], v[202:203], v[196:197], v[80:81]
	v_pk_fma_f32 v[178:179], v[84:85], v[126:127], v[178:179]
	v_pk_fma_f32 v[80:81], v[88:89], v[198:199], v[80:81]
	v_mul_f32_e32 v161, 0xbfb8aa3b, v178
	v_mul_f32_e32 v133, 0xbfb8aa3b, v80
	v_exp_f32_e32 v133, v133
	v_exp_f32_e32 v161, v161
	global_store_dwordx2 v[96:97], v[78:79], off
	v_add_f32_e32 v78, 1.0, v133
	v_mul_f32_e32 v133, 0xbfb8aa3b, v81
	v_exp_f32_e32 v133, v133
	v_add_f32_e32 v79, 1.0, v161
	v_rcp_f32_e32 v180, v79
	v_rcp_f32_e32 v78, v78
	v_add_f32_e32 v79, 1.0, v133
	v_mul_f32_e32 v133, 0xbfb8aa3b, v179
	v_rcp_f32_e32 v79, v79
	v_exp_f32_e32 v133, v133
	v_pk_mul_f32 v[78:79], v[80:81], v[78:79]
	v_add_f32_e32 v80, 1.0, v133
	v_rcp_f32_e32 v181, v80
	v_pk_fma_f32 v[80:81], v[206:207], v[98:99], v[106:107]
	v_pk_mul_f32 v[78:79], v[182:183], v[78:79]
	v_pk_fma_f32 v[80:81], v[90:91], v[114:115], v[80:81]
	v_pk_mul_f32 v[178:179], v[178:179], v[180:181]
	v_pk_fma_f32 v[80:81], v[76:77], v[102:103], v[80:81]
	v_and_b32_sdwa v133, v79, v234 dst_sel:DWORD dst_unused:UNUSED_PAD src0_sel:WORD_1 src1_sel:DWORD
	v_pk_mul_f32 v[80:81], v[80:81], v[178:179]
	v_pk_fma_f32 v[178:179], v[202:203], v[86:87], v[94:95]
	s_nop 0
	v_pk_fma_f32 v[178:179], v[88:89], v[196:197], v[178:179]
	s_nop 0
	v_add3_u32 v79, v79, v133, s61
	v_and_b32_sdwa v133, v81, v234 dst_sel:DWORD dst_unused:UNUSED_PAD src0_sel:WORD_1 src1_sel:DWORD
	s_nop 0
	v_pk_fma_f32 v[178:179], v[168:169], v[198:199], v[178:179]
	v_add3_u32 v81, v81, v133, s61
	s_nop 0
	v_mul_f32_e32 v133, 0xbfb8aa3b, v178
	s_nop 0
	v_exp_f32_e32 v133, v133
	v_pk_fma_f32 v[180:181], v[200:201], v[110:111], v[118:119]
	v_and_b32_e32 v81, 0xffff0000, v81
	v_cvt_pk_bf16_f32 v78, v78, v80
; __device__ __forceinline__ unsigned pk2(float lo, float hi) { return f2bf(lo) | (f2bf(hi) << 16); }
; __device__ __forceinline__ float silu_fast(float x) { return x * __builtin_amdgcn_rcpf(1.f + __builtin_amdgcn_exp2f(-1.4426950408889634f * x)); }
; __device__ __forceinline__ float dpp_shr1(float x) { return __builtin_bit_cast(float, __builtin_amdgcn_update_dpp(0, __builtin_bit_cast(int, x), 0x111, 0xf, 0xf, true)); }
;     __device__ __forceinline__ void operator()(const f32x4 (&acc)[2][2][4][2], const pg8::Unit& u, int wr, int wc, int fr, int fq) const {
;     ...
;             for (int e = 0; e < 8; ++e) { const float rs = (e < 4) ? r0[e & 3] : r1[e & 3];
; #pragma unroll
;                 for (int jj = 0; jj < 4; ++jj) { g[e][jj] = acc[e >> 2][0][e & 3][n][jj] * rs; v[e][jj] = acc[e >> 2][1][e & 3][n][jj] * rs; } }
;             if (fr == 0) {
; #pragma unroll
;                 for (int q = 0; q < 2; ++q) { v2u a, b; a.x = pk2(g[q][0], g[q][1]); a.y = pk2(g[q][2], g[q][3]); b.x = pk2(v[q][0], v[q][1]); b.y = pk2(v[q][2], v[q][3]);
;                     *(v2u*)(hb + (size_t)q * 256 + 4 * n) = a; *(v2u*)(hb + (size_t)q * 256 + 128 + 4 * n) = b; } }
;     ...
;             for (int jj = 0; jj < 4; ++jj) {
;                 float g2 = dpp_shr1(g[6][jj]), g1 = dpp_shr1(g[7][jj]), v2 = dpp_shr1(v[6][jj]), v1 = dpp_shr1(v[7][jj]);
; #pragma unroll
;                 for (int e = 0; e < 8; ++e) { const float g0 = g[e][jj], v0 = v[e][jj];
;                     const float cg = bg[jj] + wg0[jj] * g2 + wg1[jj] * g1 + wg2[jj] * g0, cv = bv[jj] + wv0[jj] * v2 + wv1[jj] * v1 + wv2[jj] * v0;
;                     g[e][jj] = silu_fast(cg) * cv; g2 = g1; g1 = g0; v2 = v1; v1 = v0; } }
; #pragma unroll
;             for (int e = 0; e < 8; ++e) { v2u w; w.x = pk2(g[e][0], g[e][1]); w.y = pk2(g[e][2], g[e][3]); *(v2u*)(ACT + (size_t)(tok0 + e) * FFH + cc) = w; }
	v_or_b32_e32 v80, 5, v160
	v_pk_fma_f32 v[180:181], v[84:85], v[122:123], v[180:181]
	v_or_b32_sdwa v79, v81, v79 dst_sel:DWORD dst_unused:UNUSED_PAD src0_sel:DWORD src1_sel:WORD_1
	v_mad_i64_i32 v[80:81], s[36:37], v80, s62, v[210:211]
	v_pk_fma_f32 v[180:181], v[136:137], v[126:127], v[180:181]
	v_lshl_add_u64 v[80:81], v[80:81], 0, v[212:213]
	v_mul_f32_e32 v161, 0xbfb8aa3b, v180
	v_exp_f32_e32 v161, v161
	global_store_dwordx2 v[80:81], v[78:79], off
	v_add_f32_e32 v78, 1.0, v133
	v_mul_f32_e32 v133, 0xbfb8aa3b, v179
	v_exp_f32_e32 v133, v133
	v_add_f32_e32 v79, 1.0, v161
	v_rcp_f32_e32 v182, v79
	v_rcp_f32_e32 v78, v78
	v_add_f32_e32 v79, 1.0, v133
	v_mul_f32_e32 v133, 0xbfb8aa3b, v181
	v_exp_f32_e32 v133, v133
	v_rcp_f32_e32 v79, v79
	v_pk_fma_f32 v[90:91], v[90:91], v[98:99], v[106:107]
	v_pk_fma_f32 v[84:85], v[84:85], v[110:111], v[118:119]
	v_add_f32_e32 v133, 1.0, v133
	v_rcp_f32_e32 v183, v133
	v_pk_mul_f32 v[78:79], v[178:179], v[78:79]
	v_pk_fma_f32 v[90:91], v[76:77], v[114:115], v[90:91]
	v_pk_mul_f32 v[78:79], v[184:185], v[78:79]
	v_pk_fma_f32 v[90:91], v[130:131], v[102:103], v[90:91]
	v_pk_mul_f32 v[178:179], v[180:181], v[182:183]
	v_and_b32_sdwa v161, v78, v234 dst_sel:DWORD dst_unused:UNUSED_PAD src0_sel:WORD_1 src1_sel:DWORD
	v_pk_mul_f32 v[90:91], v[90:91], v[178:179]
	s_nop 0
	v_add3_u32 v78, v78, v161, s61
	v_and_b32_sdwa v161, v90, v234 dst_sel:DWORD dst_unused:UNUSED_PAD src0_sel:WORD_1 src1_sel:DWORD
	s_nop 1
	v_add3_u32 v90, v90, v161, s61
	s_nop 0
	v_and_b32_e32 v90, 0xffff0000, v90
	s_nop 0
	v_or_b32_sdwa v90, v90, v78 dst_sel:DWORD dst_unused:UNUSED_PAD src0_sel:DWORD src1_sel:WORD_1
	v_or_b32_e32 v78, 6, v160
	v_pk_fma_f32 v[86:87], v[88:89], v[86:87], v[94:95]
	v_pk_fma_f32 v[84:85], v[136:137], v[122:123], v[84:85]
	v_cvt_pk_bf16_f32 v91, v79, v91
	v_mad_i64_i32 v[78:79], s[36:37], v78, s62, v[210:211]
	v_pk_fma_f32 v[86:87], v[168:169], v[196:197], v[86:87]
	v_pk_fma_f32 v[84:85], v[172:173], v[126:127], v[84:85]
	v_lshl_add_u64 v[78:79], v[78:79], 0, v[212:213]
	v_pk_fma_f32 v[86:87], v[170:171], v[198:199], v[86:87]
	v_mul_f32_e32 v89, 0xbfb8aa3b, v84
	v_mul_f32_e32 v88, 0xbfb8aa3b, v86
	v_exp_f32_e32 v89, v89
	global_store_dwordx2 v[78:79], v[90:91], off
	v_mul_f32_e32 v90, 0xbfb8aa3b, v87
	v_exp_f32_e32 v88, v88
	v_exp_f32_e32 v91, v90
	v_add_f32_e32 v89, 1.0, v89
	v_rcp_f32_e32 v90, v89
	v_add_f32_e32 v88, 1.0, v88
	v_add_f32_e32 v89, 1.0, v91
	v_rcp_f32_e32 v88, v88
	v_rcp_f32_e32 v89, v89
	v_mul_f32_e32 v91, 0xbfb8aa3b, v85
	v_exp_f32_e32 v91, v91
	v_pk_fma_f32 v[76:77], v[76:77], v[98:99], v[106:107]
	v_pk_mul_f32 v[86:87], v[86:87], v[88:89]
	v_pk_fma_f32 v[76:77], v[130:131], v[114:115], v[76:77]
	v_pk_mul_f32 v[82:83], v[82:83], v[86:87]
	v_add_f32_e32 v86, 1.0, v91
	v_rcp_f32_e32 v91, v86
	v_pk_fma_f32 v[76:77], v[138:139], v[102:103], v[76:77]
	v_pk_mul_f32 v[84:85], v[84:85], v[90:91]
	s_nop 0
	v_pk_mul_f32 v[76:77], v[76:77], v[84:85]
	s_nop 7
	s_nop 1
	v_cvt_pk_bf16_f32 v82, v82, v76
	v_or_b32_e32 v76, 7, v160
	v_cvt_pk_bf16_f32 v83, v83, v77
	v_mad_i64_i32 v[76:77], s[36:37], v76, s62, v[210:211]
	v_lshl_add_u64 v[76:77], v[76:77], 0, v[212:213]
	global_store_dwordx2 v[76:77], v[82:83], off
	v_mov_b32_e32 v82, v72
	v_mov_b32_e32 v83, v74
	v_pk_mul_f32 v[130:131], v[82:83], v[174:175]
	v_mov_b32_e32 v82, v64
	v_mov_b32_e32 v83, v66
	v_mov_b32_e32 v66, v65
	v_mov_b32_e32 v64, v68
	v_mov_b32_e32 v65, v70
	v_pk_mul_f32 v[114:115], v[64:65], v[40:41]
	v_mov_b32_e32 v64, v60
	v_mov_b32_e32 v65, v62
	v_mov_b32_e32 v70, v69
	v_mov_b32_e32 v62, v61
	v_pk_mul_f32 v[116:117], v[64:65], v[40:41]
	v_pk_mul_f32 v[118:119], v[70:71], v[40:41]
	v_pk_mul_f32 v[120:121], v[62:63], v[40:41]
	v_mov_b32_e32 v40, v56
	v_mov_b32_e32 v41, v58
	v_pk_mul_f32 v[88:89], v[40:41], v[176:177]
	v_mov_b32_e32 v40, v48
	v_mov_b32_e32 v41, v50
	v_pk_mul_f32 v[124:125], v[82:83], v[174:175]
	v_pk_mul_f32 v[82:83], v[40:41], v[176:177]
	v_mov_b32_e32 v40, v52
	v_mov_b32_e32 v41, v54
	v_mov_b32_e32 v74, v73
	v_mov_b32_e32 v58, v57
	v_mov_b32_e32 v50, v49
	v_pk_mul_f32 v[94:95], v[40:41], v[38:39]
	v_mov_b32_e32 v40, v44
	v_mov_b32_e32 v41, v46
	v_mov_b32_e32 v54, v53
	v_mov_b32_e32 v46, v45
	v_pk_mul_f32 v[126:127], v[74:75], v[174:175]
	v_pk_mul_f32 v[86:87], v[58:59], v[176:177]
	v_pk_mul_f32 v[72:73], v[50:51], v[176:177]
	v_pk_mul_f32 v[84:85], v[40:41], v[38:39]
	v_pk_mul_f32 v[90:91], v[54:55], v[38:39]
	v_pk_mul_f32 v[74:75], v[46:47], v[38:39]
	v_pk_mul_f32 v[122:123], v[66:67], v[174:175]
	v_mov_b64_e32 v[44:45], 0x408
	v_mov_b64_e32 v[46:47], 0x508
	v_mov_b64_e32 v[38:39], 0x608
	v_mov_b64_e32 v[40:41], 0x708
	v_mov_b64_e32 v[54:55], v[94:95]
	v_mov_b64_e32 v[52:53], v[90:91]
	v_mov_b64_e32 v[50:51], v[84:85]
	v_mov_b64_e32 v[48:49], v[74:75]
	v_mov_b64_e32 v[62:63], v[88:89]
	v_mov_b64_e32 v[60:61], v[86:87]
	v_mov_b64_e32 v[58:59], v[82:83]
	v_mov_b64_e32 v[56:57], v[72:73]
	s_and_saveexec_b64 s[36:37], vcc
	s_cbranch_execz .LBB0_2996
	v_cmp_eq_u32_e32 vcc, 0, v3
	s_mov_b64 s[38:39], 0
	v_mov_b64_e32 v[44:45], 0x408
	v_mov_b64_e32 v[46:47], 0x508
	v_mov_b64_e32 v[38:39], 0x608
	v_mov_b64_e32 v[40:41], 0x708
	s_and_saveexec_b64 s[40:41], vcc
	s_mov_b64 s[38:39], exec
	v_mov_b64_e32 v[44:45], 8
	v_mov_b64_e32 v[46:47], 0x108
	v_mov_b64_e32 v[38:39], 0x208
	v_mov_b64_e32 v[40:41], 0x308
	s_or_b64 exec, exec, s[40:41]
	s_orn2_b64 s[38:39], s[38:39], exec
	v_mov_b64_e32 v[54:55], v[114:115]
	v_mov_b64_e32 v[52:53], v[118:119]
	v_mov_b64_e32 v[50:51], v[116:117]
	v_mov_b64_e32 v[48:49], v[120:121]
	v_mov_b64_e32 v[62:63], v[130:131]
	v_mov_b64_e32 v[60:61], v[126:127]
	v_mov_b64_e32 v[58:59], v[124:125]
	v_mov_b64_e32 v[56:57], v[122:123]
; __device__ __forceinline__ unsigned pk2(float lo, float hi) { return f2bf(lo) | (f2bf(hi) << 16); }
;     __device__ __forceinline__ void operator()(const f32x4 (&acc)[2][2][4][2], const pg8::Unit& u, int wr, int wc, int fr, int fq) const {
;     ...
;             if (fr == 0) {
; #pragma unroll
;                 for (int q = 0; q < 2; ++q) { v2u a, b; a.x = pk2(g[q][0], g[q][1]); a.y = pk2(g[q][2], g[q][3]); b.x = pk2(v[q][0], v[q][1]); b.y = pk2(v[q][2], v[q][3]);
;                     *(v2u*)(hb + (size_t)q * 256 + 4 * n) = a; *(v2u*)(hb + (size_t)q * 256 + 128 + 4 * n) = b; } }
;             if (fr == 15) {
; #pragma unroll
;                 for (int q = 0; q < 2; ++q) { v2u a, b; a.x = pk2(g[6 + q][0], g[6 + q][1]); a.y = pk2(g[6 + q][2], g[6 + q][3]); b.x = pk2(v[6 + q][0], v[6 + q][1]); b.y = pk2(v[6 + q][2], v[6 + q][3]);
;                     *(v2u*)(hb + (size_t)(2 + q) * 256 + 4 * n) = a; *(v2u*)(hb + (size_t)(2 + q) * 256 + 128 + 4 * n) = b; } }
.LBB0_2996:
	s_or_b64 exec, exec, s[36:37]
	s_and_saveexec_b64 s[36:37], s[38:39]
	s_cbranch_execz .LBB0_2979
	s_nop 7
	s_nop 1
	v_cvt_pk_bf16_f32 v61, v63, v61
	v_cvt_pk_bf16_f32 v60, v62, v60
	s_nop 7
	s_nop 1
	v_lshl_add_u64 v[44:45], v[158:159], 0, v[44:45]
	v_cvt_pk_bf16_f32 v57, v59, v57
	v_cvt_pk_bf16_f32 v56, v58, v56
	global_store_dwordx2 v[44:45], v[60:61], off
	v_lshl_add_u64 v[44:45], v[158:159], 0, v[46:47]
	global_store_dwordx2 v[44:45], v[56:57], off
	v_and_b32_sdwa v45, v54, v234 dst_sel:DWORD dst_unused:UNUSED_PAD src0_sel:WORD_1 src1_sel:DWORD
	v_add3_u32 v46, v54, v45, s61
	s_nop 0
	v_and_b32_sdwa v47, v52, v234 dst_sel:DWORD dst_unused:UNUSED_PAD src0_sel:WORD_1 src1_sel:DWORD
	s_nop 1
	v_add3_u32 v47, v52, v47, s61
	s_nop 1
	v_and_b32_e32 v47, 0xffff0000, v47
	v_cvt_pk_bf16_f32 v45, v55, v53
	v_or_b32_sdwa v44, v47, v46 dst_sel:DWORD dst_unused:UNUSED_PAD src0_sel:DWORD src1_sel:WORD_1
	v_and_b32_sdwa v46, v51, v234 dst_sel:DWORD dst_unused:UNUSED_PAD src0_sel:WORD_1 src1_sel:DWORD
	v_and_b32_sdwa v47, v50, v234 dst_sel:DWORD dst_unused:UNUSED_PAD src0_sel:WORD_1 src1_sel:DWORD
	v_add3_u32 v50, v50, v47, s61
	v_add3_u32 v46, v51, v46, s61
	v_and_b32_sdwa v47, v49, v234 dst_sel:DWORD dst_unused:UNUSED_PAD src0_sel:WORD_1 src1_sel:DWORD
	v_and_b32_sdwa v51, v48, v234 dst_sel:DWORD dst_unused:UNUSED_PAD src0_sel:WORD_1 src1_sel:DWORD
	v_add3_u32 v47, v49, v47, s61
	v_add3_u32 v48, v48, v51, s61
	v_and_b32_e32 v47, 0xffff0000, v47
	v_and_b32_e32 v48, 0xffff0000, v48
	v_lshl_add_u64 v[38:39], v[158:159], 0, v[38:39]
	v_or_b32_sdwa v47, v47, v46 dst_sel:DWORD dst_unused:UNUSED_PAD src0_sel:DWORD src1_sel:WORD_1
	v_or_b32_sdwa v46, v48, v50 dst_sel:DWORD dst_unused:UNUSED_PAD src0_sel:DWORD src1_sel:WORD_1
	global_store_dwordx2 v[38:39], v[44:45], off
	v_lshl_add_u64 v[38:39], v[158:159], 0, v[40:41]
	global_store_dwordx2 v[38:39], v[46:47], off
	s_branch .LBB0_2979

; __device__ __forceinline__ unsigned pk2(float lo, float hi) { return f2bf(lo) | (f2bf(hi) << 16); }
; __device__ __forceinline__ void rms_row_bf16(const Ctx& c, const float* xrow, const float* gain, bf16* orow, float* copy) {
;     const f32x4* xr = (const f32x4*)xrow + c.lane; f32x4 v[8]; float s = 0.f;
; #pragma unroll
;     for (int j = 0; j < 8; ++j) { v[j] = xr[64 * j]; s += (v[j].x * v[j].x + v[j].y * v[j].y) + (v[j].z * v[j].z + v[j].w * v[j].w); }
;     const float rs = rsqrtf(wave_sum(s) * (1.f / DM) + EPS);
;     if (copy) {
; #pragma unroll
;         for (int j = 0; j < 8; ++j) ((f32x4*)copy + c.lane)[64 * j] = v[j]; }
;     const f32x4* gr = (const f32x4*)gain + c.lane; v2u* o8 = (v2u*)orow + c.lane;
; #pragma unroll
;     for (int j = 0; j < 8; ++j) { const f32x4 g = gr[64 * j]; v2u o; o.x = pk2(v[j].x * rs * g.x, v[j].y * rs * g.y); o.y = pk2(v[j].z * rs * g.z, v[j].w * rs * g.w); o8[64 * j] = o; }
.LBB0_3314:
	global_load_dwordx4 v[32:35], v[46:47], off offset:-4096
	global_load_dwordx4 v[28:31], v[46:47], off offset:-3072
	global_load_dwordx4 v[24:27], v[46:47], off offset:-2048
	global_load_dwordx4 v[20:23], v[46:47], off offset:-1024
	global_load_dwordx4 v[12:15], v[46:47], off
	global_load_dwordx4 v[16:19], v[46:47], off offset:1024
	s_add_i32 s6, s6, s86
	s_cmpk_lt_i32 s6, 0x400
	s_waitcnt vmcnt(0)
	v_mov_b32_e32 v6, v33
	v_mov_b32_e32 v7, v29
	v_mov_b32_e32 v4, v32
	v_mov_b32_e32 v5, v28
	v_pk_mul_f32 v[6:7], v[6:7], v[6:7]
	v_mov_b32_e32 v8, v35
	v_mov_b32_e32 v9, v31
	v_pk_fma_f32 v[4:5], v[4:5], v[4:5], v[6:7]
	v_mov_b32_e32 v6, v34
	v_mov_b32_e32 v7, v30
	v_pk_mul_f32 v[8:9], v[8:9], v[8:9]
	s_nop 0
	v_pk_fma_f32 v[6:7], v[6:7], v[6:7], v[8:9]
	v_pk_mul_f32 v[8:9], v[24:25], v[24:25]
	v_pk_add_f32 v[4:5], v[4:5], v[6:7]
	v_pk_mul_f32 v[6:7], v[26:27], v[26:27]
	v_pk_add_f32 v[4:5], v[4:5], v[4:5] op_sel:[0,1] op_sel_hi:[1,0]
	v_pk_mov_b32 v[10:11], v[8:9], v[6:7] op_sel:[1,0]
	v_mov_b32_e32 v9, v7
	v_pk_add_f32 v[6:7], v[10:11], v[8:9]
	v_mul_f32_e32 v8, v12, v12
	v_mul_f32_e32 v9, v13, v13
	v_pk_add_f32 v[6:7], v[6:7], v[6:7] op_sel:[0,1] op_sel_hi:[1,0]
	v_mov_b32_e32 v5, v8
	v_mov_b32_e32 v7, v9
	v_pk_add_f32 v[4:5], v[4:5], v[6:7]
	v_mul_f32_e32 v6, v21, v21
	v_mul_f32_e32 v8, v23, v23
	v_mul_f32_e32 v10, v14, v14
	v_mul_f32_e32 v11, v15, v15
	v_pk_fma_f32 v[6:7], v[20:21], v[20:21], v[6:7] op_sel_hi:[1,1,0]
	v_pk_fma_f32 v[8:9], v[22:23], v[22:23], v[8:9] op_sel_hi:[1,1,0]
	v_mov_b32_e32 v7, v10
	v_mov_b32_e32 v9, v11
	v_pk_add_f32 v[6:7], v[6:7], v[8:9]
	s_nop 0
	v_pk_add_f32 v[52:53], v[4:5], v[6:7]
	v_pk_mul_f32 v[4:5], v[18:19], v[18:19]
	v_pk_mul_f32 v[6:7], v[16:17], v[16:17]
	v_pk_add_f32 v[52:53], v[52:53], v[52:53] op_sel:[0,1] op_sel_hi:[1,0]
	v_pk_mov_b32 v[8:9], v[6:7], v[4:5] op_sel:[1,0]
	v_mov_b32_e32 v7, v5
	v_pk_add_f32 v[60:61], v[8:9], v[6:7]
	global_load_dwordx4 v[8:11], v[46:47], off offset:2048
	global_load_dwordx4 v[4:7], v[46:47], off offset:3072
	v_pk_add_f32 v[60:61], v[60:61], v[60:61] op_sel:[0,1] op_sel_hi:[1,0]
	v_lshl_add_u64 v[46:47], v[46:47], 0, s[8:9]
	s_waitcnt vmcnt(0)
	v_mul_f32_e32 v50, v4, v4
	v_mul_f32_e32 v62, v5, v5
	v_mov_b32_e32 v53, v50
	v_mov_b32_e32 v61, v62
	v_mul_f32_e32 v50, v9, v9
	v_mul_f32_e32 v63, v6, v6
	v_pk_add_f32 v[52:53], v[52:53], v[60:61]
	v_pk_fma_f32 v[60:61], v[8:9], v[8:9], v[50:51] op_sel_hi:[1,1,0]
	v_mul_f32_e32 v50, v11, v11
	v_mul_f32_e32 v64, v7, v7
	v_mov_b32_e32 v61, v63
	v_pk_fma_f32 v[62:63], v[10:11], v[10:11], v[50:51] op_sel_hi:[1,1,0]
	s_nop 0
	v_mov_b32_e32 v63, v64
	v_pk_add_f32 v[60:61], v[60:61], v[62:63]
	s_nop 0
	v_pk_add_f32 v[52:53], v[52:53], v[60:61]
	global_load_dwordx4 v[60:63], v[36:37], off
	v_add_f32_e32 v50, v52, v53
	ds_bpermute_b32 v52, v3, v50
	v_mov_b32_e32 v53, v34
	v_mov_b32_e32 v34, v33
	s_waitcnt lgkmcnt(0)
	v_add_f32_e32 v50, v50, v52
	ds_bpermute_b32 v52, v51, v50
	s_waitcnt lgkmcnt(0)
	v_add_f32_e32 v50, v50, v52
	ds_bpermute_b32 v52, v54, v50
	s_waitcnt lgkmcnt(0)
	v_add_f32_e32 v50, v50, v52
	ds_bpermute_b32 v52, v55, v50
	s_waitcnt lgkmcnt(0)
	v_add_f32_e32 v50, v50, v52
	ds_bpermute_b32 v52, v56, v50
	s_waitcnt lgkmcnt(0)
	v_add_f32_e32 v50, v50, v52
	ds_bpermute_b32 v52, v57, v50
	s_waitcnt lgkmcnt(0)
	v_add_f32_e32 v50, v50, v52
	v_fmamk_f32 v50, v50, 0x3a000000, v58
	v_cmp_gt_f32_e32 vcc, s12, v50
	v_mul_f32_e32 v52, 0x4b800000, v50
	s_waitcnt vmcnt(0)
	v_mov_b32_e32 v64, v60
	v_cndmask_b32_e32 v50, v50, v52, vcc
	v_rsq_f32_e32 v50, v50
	v_mov_b32_e32 v65, v62
	v_mov_b32_e32 v62, v61
	v_mul_f32_e32 v52, 0x45800000, v50
	v_cndmask_b32_e32 v50, v50, v52, vcc
	v_mov_b32_e32 v52, v32
	v_pk_mul_f32 v[52:53], v[52:53], v[50:51] op_sel_hi:[1,0]
	v_pk_mul_f32 v[32:33], v[34:35], v[50:51] op_sel_hi:[1,0]
	v_pk_mul_f32 v[52:53], v[64:65], v[52:53]
	v_pk_mul_f32 v[32:33], v[62:63], v[32:33]
	v_and_b32_sdwa v34, v53, v59 dst_sel:DWORD dst_unused:UNUSED_PAD src0_sel:WORD_1 src1_sel:DWORD
	v_and_b32_sdwa v35, v52, v59 dst_sel:DWORD dst_unused:UNUSED_PAD src0_sel:WORD_1 src1_sel:DWORD
	v_add3_u32 v35, v52, v35, s7
	v_add3_u32 v34, v53, v34, s7
	v_and_b32_sdwa v52, v33, v59 dst_sel:DWORD dst_unused:UNUSED_PAD src0_sel:WORD_1 src1_sel:DWORD
	v_and_b32_sdwa v53, v32, v59 dst_sel:DWORD dst_unused:UNUSED_PAD src0_sel:WORD_1 src1_sel:DWORD
	v_add3_u32 v33, v33, v52, s7
	v_add3_u32 v32, v32, v53, s7
	v_and_b32_e32 v33, 0xffff0000, v33
	v_and_b32_e32 v32, 0xffff0000, v32
	v_or_b32_sdwa v33, v33, v34 dst_sel:DWORD dst_unused:UNUSED_PAD src0_sel:DWORD src1_sel:WORD_1
	v_or_b32_sdwa v32, v32, v35 dst_sel:DWORD dst_unused:UNUSED_PAD src0_sel:DWORD src1_sel:WORD_1
	global_store_dwordx2 v[48:49], v[32:33], off
	global_load_dwordx4 v[32:35], v[36:37], off offset:1024
	v_mov_b32_e32 v53, v30
	v_mov_b32_e32 v30, v29
	v_mov_b32_e32 v52, v28
	v_pk_mul_f32 v[28:29], v[30:31], v[50:51] op_sel_hi:[1,0]
	v_pk_mul_f32 v[52:53], v[52:53], v[50:51] op_sel_hi:[1,0]
	s_waitcnt vmcnt(0)
; __device__ __forceinline__ unsigned pk2(float lo, float hi) { return f2bf(lo) | (f2bf(hi) << 16); }
; __device__ __forceinline__ void rms_row_bf16(const Ctx& c, const float* xrow, const float* gain, bf16* orow, float* copy) {
;     ...
;     const f32x4* gr = (const f32x4*)gain + c.lane; v2u* o8 = (v2u*)orow + c.lane;
; #pragma unroll
;     for (int j = 0; j < 8; ++j) { const f32x4 g = gr[64 * j]; v2u o; o.x = pk2(v[j].x * rs * g.x, v[j].y * rs * g.y); o.y = pk2(v[j].z * rs * g.z, v[j].w * rs * g.w); o8[64 * j] = o; }
	v_mov_b32_e32 v61, v34
	v_mov_b32_e32 v34, v33
	v_mov_b32_e32 v60, v32
	v_pk_mul_f32 v[28:29], v[34:35], v[28:29]
	v_pk_mul_f32 v[52:53], v[60:61], v[52:53]
	s_nop 7
	s_nop 1
	v_cvt_pk_bf16_f32 v29, v53, v29
	v_cvt_pk_bf16_f32 v28, v52, v28
	global_store_dwordx2 v[48:49], v[28:29], off offset:512
	global_load_dwordx4 v[28:31], v[36:37], off offset:2048
	v_mov_b32_e32 v33, v26
	v_mov_b32_e32 v26, v25
	v_mov_b32_e32 v32, v24
	v_pk_mul_f32 v[24:25], v[26:27], v[50:51] op_sel_hi:[1,0]
	v_pk_mul_f32 v[32:33], v[32:33], v[50:51] op_sel_hi:[1,0]
	s_waitcnt vmcnt(0)
	v_mov_b32_e32 v35, v30
	v_mov_b32_e32 v30, v29
	v_mov_b32_e32 v34, v28
	v_pk_mul_f32 v[24:25], v[30:31], v[24:25]
	v_pk_mul_f32 v[32:33], v[34:35], v[32:33]
	s_nop 7
	s_nop 1
	v_cvt_pk_bf16_f32 v25, v33, v25
	v_cvt_pk_bf16_f32 v24, v32, v24
	global_store_dwordx2 v[48:49], v[24:25], off offset:1024
	global_load_dwordx4 v[24:27], v[36:37], off offset:3072
	v_mov_b32_e32 v29, v22
	v_mov_b32_e32 v22, v21
	v_mov_b32_e32 v28, v20
	v_pk_mul_f32 v[20:21], v[22:23], v[50:51] op_sel_hi:[1,0]
	v_pk_mul_f32 v[28:29], v[28:29], v[50:51] op_sel_hi:[1,0]
	s_waitcnt vmcnt(0)
	v_mov_b32_e32 v31, v26
	v_mov_b32_e32 v26, v25
	v_mov_b32_e32 v30, v24
	v_pk_mul_f32 v[20:21], v[26:27], v[20:21]
	v_pk_mul_f32 v[28:29], v[30:31], v[28:29]
	s_nop 7
	s_nop 1
	v_cvt_pk_bf16_f32 v21, v29, v21
	v_cvt_pk_bf16_f32 v20, v28, v20
	global_store_dwordx2 v[48:49], v[20:21], off offset:1536
	global_load_dwordx4 v[20:23], v[38:39], off
	v_mov_b32_e32 v25, v14
	v_mov_b32_e32 v14, v13
	v_mov_b32_e32 v24, v12
	v_pk_mul_f32 v[12:13], v[14:15], v[50:51] op_sel_hi:[1,0]
	v_pk_mul_f32 v[24:25], v[24:25], v[50:51] op_sel_hi:[1,0]
	s_waitcnt vmcnt(0)
	v_mov_b32_e32 v27, v22
	v_mov_b32_e32 v22, v21
	v_mov_b32_e32 v26, v20
	v_pk_mul_f32 v[12:13], v[22:23], v[12:13]
	v_pk_mul_f32 v[24:25], v[26:27], v[24:25]
	s_nop 7
	s_nop 1
	v_cvt_pk_bf16_f32 v13, v25, v13
	v_cvt_pk_bf16_f32 v12, v24, v12
	global_store_dwordx2 v[48:49], v[12:13], off offset:2048
	global_load_dwordx4 v[12:15], v[40:41], off
	v_mov_b32_e32 v21, v18
	v_mov_b32_e32 v18, v17
	v_mov_b32_e32 v20, v16
	v_pk_mul_f32 v[16:17], v[18:19], v[50:51] op_sel_hi:[1,0]
	v_pk_mul_f32 v[20:21], v[20:21], v[50:51] op_sel_hi:[1,0]
	s_waitcnt vmcnt(0)
	v_mov_b32_e32 v23, v14
	v_mov_b32_e32 v14, v13
	v_mov_b32_e32 v22, v12
	v_pk_mul_f32 v[12:13], v[14:15], v[16:17]
	v_pk_mul_f32 v[20:21], v[22:23], v[20:21]
	s_nop 7
	s_nop 1
	v_cvt_pk_bf16_f32 v13, v21, v13
	v_cvt_pk_bf16_f32 v12, v20, v12
	global_store_dwordx2 v[48:49], v[12:13], off offset:2560
	global_load_dwordx4 v[12:15], v[42:43], off
	v_mov_b32_e32 v17, v10
	v_mov_b32_e32 v10, v9
	v_mov_b32_e32 v16, v8
	v_pk_mul_f32 v[8:9], v[10:11], v[50:51] op_sel_hi:[1,0]
	v_pk_mul_f32 v[16:17], v[16:17], v[50:51] op_sel_hi:[1,0]
	s_waitcnt vmcnt(0)
	v_mov_b32_e32 v19, v14
	v_mov_b32_e32 v14, v13
	v_mov_b32_e32 v18, v12
	v_pk_mul_f32 v[8:9], v[8:9], v[14:15]
	v_pk_mul_f32 v[16:17], v[16:17], v[18:19]
	s_nop 7
	s_nop 1
	v_cvt_pk_bf16_f32 v9, v17, v9
	v_cvt_pk_bf16_f32 v8, v16, v8
	global_store_dwordx2 v[48:49], v[8:9], off offset:3072
	global_load_dwordx4 v[8:11], v[44:45], off
	v_mov_b32_e32 v13, v6
	v_mov_b32_e32 v6, v5
	v_mov_b32_e32 v12, v4
	v_pk_mul_f32 v[4:5], v[6:7], v[50:51] op_sel_hi:[1,0]
	v_pk_mul_f32 v[12:13], v[12:13], v[50:51] op_sel_hi:[1,0]
	s_waitcnt vmcnt(0)
	v_mov_b32_e32 v15, v10
	v_mov_b32_e32 v10, v9
	v_mov_b32_e32 v14, v8
	v_pk_mul_f32 v[4:5], v[4:5], v[10:11]
	v_pk_mul_f32 v[12:13], v[12:13], v[14:15]
	v_and_b32_sdwa v8, v5, v59 dst_sel:DWORD dst_unused:UNUSED_PAD src0_sel:WORD_1 src1_sel:DWORD
	v_and_b32_sdwa v9, v4, v59 dst_sel:DWORD dst_unused:UNUSED_PAD src0_sel:WORD_1 src1_sel:DWORD
	v_and_b32_sdwa v6, v13, v59 dst_sel:DWORD dst_unused:UNUSED_PAD src0_sel:WORD_1 src1_sel:DWORD
	v_and_b32_sdwa v7, v12, v59 dst_sel:DWORD dst_unused:UNUSED_PAD src0_sel:WORD_1 src1_sel:DWORD
	v_add3_u32 v5, v5, v8, s7
	v_add3_u32 v4, v4, v9, s7
	v_add3_u32 v7, v12, v7, s7
	v_add3_u32 v6, v13, v6, s7
	v_and_b32_e32 v5, 0xffff0000, v5
	v_and_b32_e32 v4, 0xffff0000, v4
	v_or_b32_sdwa v5, v5, v6 dst_sel:DWORD dst_unused:UNUSED_PAD src0_sel:DWORD src1_sel:WORD_1
	v_or_b32_sdwa v4, v4, v7 dst_sel:DWORD dst_unused:UNUSED_PAD src0_sel:DWORD src1_sel:WORD_1
	global_store_dwordx2 v[48:49], v[4:5], off offset:3584
	v_lshl_add_u64 v[48:49], v[48:49], 0, s[10:11]
	s_cbranch_scc1 .LBB0_3314

; #define LAS __attribute__((address_space(3)))
; __device__ __forceinline__ unsigned pk2(float lo, float hi) { return f2bf(lo) | (f2bf(hi) << 16); }
; __device__ __forceinline__ void sgu_spatial_mfma(const Ctx& c, const bf16* P, const float* Wsp, const float* bsp, bf16* ACT) {
;     ...
;             for (int dt = 0; dt < 16; ++dt) {
;                 f32x4 acc = (f32x4){0.f, 0.f, 0.f, 0.f};
; #pragma unroll
;                 for (int ks = 0; ks < 4; ++ks) if (ks < nks) {
;                     const s16x4 a0 = __builtin_amdgcn_ds_read_tr16_b64_v4i16((LAS s16x4*)(vb + ks * 32 * RS + dt * 32)), a1 = __builtin_amdgcn_ds_read_tr16_b64_v4i16((LAS s16x4*)(vb + ks * 32 * RS + 4 * RS + dt * 32));
;                     bf16x8 af; af[0] = a0[0]; af[1] = a0[1]; af[2] = a0[2]; af[3] = a0[3]; af[4] = a1[0]; af[5] = a1[1]; af[6] = a1[2]; af[7] = a1[3];
;                     acc = __builtin_amdgcn_mfma_f32_16x16x32_bf16(af, Wf[ks], acc, 0, 0, 0); }
;                 const size_t col = (size_t)g * 512 + 256 * half + 16 * dt + 4 * lg;
;                 const v2u uu = uv[dt];
;                 v2u o; o.x = pk2(bflo(uu.x) * (acc[0] + bb), bfhi(uu.x) * (acc[1] + bb)); o.y = pk2(bflo(uu.y) * (acc[2] + bb), bfhi(uu.y) * (acc[3] + bb));
;                 *(v2u*)(ACT + (row0 + t) * 4096 + col) = o;
.LBB0_3591:
	v_mov_b32_e32 v57, v56
	s_nop 6
	v_mov_b32_e32 v117, v22
	v_mov_b32_e32 v22, v21
	s_waitcnt vmcnt(15)
	v_lshlrev_b32_e32 v115, 16, v89
	v_lshlrev_b32_e32 v114, 16, v88
	v_mov_b32_e32 v116, v20
	v_and_b32_e32 v89, 0xffff0000, v89
	v_and_b32_e32 v88, 0xffff0000, v88
	v_pk_add_f32 v[20:21], v[56:57], v[22:23]
	v_pk_add_f32 v[116:117], v[56:57], v[116:117]
	v_pk_mul_f32 v[20:21], v[20:21], v[88:89]
	v_pk_mul_f32 v[114:115], v[116:117], v[114:115]
	s_nop 7
	s_nop 1
	v_cvt_pk_bf16_f32 v21, v115, v21
	v_cvt_pk_bf16_f32 v20, v114, v20
	global_store_dwordx2 v[60:61], v[20:21], off offset:32
	ds_read_b64_tr_b16 v[20:21], v90 offset:64
	ds_read_b64_tr_b16 v[22:23], v90 offset:2176
	s_waitcnt lgkmcnt(0)
	v_mfma_f32_16x16x32_bf16 v[20:23], v[20:23], v[16:19], 0
	s_and_b64 vcc, exec, s[70:71]
	s_cbranch_vccz .LBB0_3650
	s_and_b64 vcc, exec, s[68:69]
	s_cbranch_vccz .LBB0_3651

; #define LAS __attribute__((address_space(3)))
; __device__ __forceinline__ unsigned pk2(float lo, float hi) { return f2bf(lo) | (f2bf(hi) << 16); }
; __device__ __forceinline__ void sgu_spatial_mfma(const Ctx& c, const bf16* P, const float* Wsp, const float* bsp, bf16* ACT) {
;     ...
;             for (int dt = 0; dt < 16; ++dt) {
;                 f32x4 acc = (f32x4){0.f, 0.f, 0.f, 0.f};
; #pragma unroll
;                 for (int ks = 0; ks < 4; ++ks) if (ks < nks) {
;                     const s16x4 a0 = __builtin_amdgcn_ds_read_tr16_b64_v4i16((LAS s16x4*)(vb + ks * 32 * RS + dt * 32)), a1 = __builtin_amdgcn_ds_read_tr16_b64_v4i16((LAS s16x4*)(vb + ks * 32 * RS + 4 * RS + dt * 32));
;                     bf16x8 af; af[0] = a0[0]; af[1] = a0[1]; af[2] = a0[2]; af[3] = a0[3]; af[4] = a1[0]; af[5] = a1[1]; af[6] = a1[2]; af[7] = a1[3];
;                     acc = __builtin_amdgcn_mfma_f32_16x16x32_bf16(af, Wf[ks], acc, 0, 0, 0); }
;                 const size_t col = (size_t)g * 512 + 256 * half + 16 * dt + 4 * lg;
;                 const v2u uu = uv[dt];
;                 v2u o; o.x = pk2(bflo(uu.x) * (acc[0] + bb), bfhi(uu.x) * (acc[1] + bb)); o.y = pk2(bflo(uu.y) * (acc[2] + bb), bfhi(uu.y) * (acc[3] + bb));
;                 *(v2u*)(ACT + (row0 + t) * 4096 + col) = o;
.LBB0_3595:
	s_nop 7
	v_mov_b32_e32 v115, v22
	v_mov_b32_e32 v22, v21
	s_waitcnt vmcnt(15)
	v_lshlrev_b32_e32 v89, 16, v87
	v_lshlrev_b32_e32 v88, 16, v86
	v_mov_b32_e32 v114, v20
	v_and_b32_e32 v87, 0xffff0000, v87
	v_and_b32_e32 v86, 0xffff0000, v86
	v_pk_add_f32 v[20:21], v[56:57], v[22:23]
	v_pk_add_f32 v[114:115], v[56:57], v[114:115]
	v_pk_mul_f32 v[20:21], v[20:21], v[86:87]
	v_pk_mul_f32 v[88:89], v[114:115], v[88:89]
	s_nop 7
	s_nop 1
	v_cvt_pk_bf16_f32 v21, v89, v21
	v_cvt_pk_bf16_f32 v20, v88, v20
	global_store_dwordx2 v[60:61], v[20:21], off offset:64
	ds_read_b64_tr_b16 v[20:21], v90 offset:96
	ds_read_b64_tr_b16 v[22:23], v90 offset:2208
	s_waitcnt lgkmcnt(0)
	v_mfma_f32_16x16x32_bf16 v[20:23], v[20:23], v[16:19], 0
	s_and_b64 vcc, exec, s[70:71]
	s_cbranch_vccz .LBB0_3652
	s_and_b64 vcc, exec, s[68:69]
	s_cbranch_vccz .LBB0_3653

; #define LAS __attribute__((address_space(3)))
; __device__ __forceinline__ unsigned pk2(float lo, float hi) { return f2bf(lo) | (f2bf(hi) << 16); }
; __device__ __forceinline__ void sgu_spatial_mfma(const Ctx& c, const bf16* P, const float* Wsp, const float* bsp, bf16* ACT) {
;     ...
;             for (int dt = 0; dt < 16; ++dt) {
;                 f32x4 acc = (f32x4){0.f, 0.f, 0.f, 0.f};
; #pragma unroll
;                 for (int ks = 0; ks < 4; ++ks) if (ks < nks) {
;                     const s16x4 a0 = __builtin_amdgcn_ds_read_tr16_b64_v4i16((LAS s16x4*)(vb + ks * 32 * RS + dt * 32)), a1 = __builtin_amdgcn_ds_read_tr16_b64_v4i16((LAS s16x4*)(vb + ks * 32 * RS + 4 * RS + dt * 32));
;                     bf16x8 af; af[0] = a0[0]; af[1] = a0[1]; af[2] = a0[2]; af[3] = a0[3]; af[4] = a1[0]; af[5] = a1[1]; af[6] = a1[2]; af[7] = a1[3];
;                     acc = __builtin_amdgcn_mfma_f32_16x16x32_bf16(af, Wf[ks], acc, 0, 0, 0); }
;                 const size_t col = (size_t)g * 512 + 256 * half + 16 * dt + 4 * lg;
;                 const v2u uu = uv[dt];
;                 v2u o; o.x = pk2(bflo(uu.x) * (acc[0] + bb), bfhi(uu.x) * (acc[1] + bb)); o.y = pk2(bflo(uu.y) * (acc[2] + bb), bfhi(uu.y) * (acc[3] + bb));
;                 *(v2u*)(ACT + (row0 + t) * 4096 + col) = o;
.LBB0_3599:
	s_nop 7
	v_mov_b32_e32 v89, v22
	v_mov_b32_e32 v22, v21
	s_waitcnt vmcnt(15)
	v_lshlrev_b32_e32 v87, 16, v85
	v_lshlrev_b32_e32 v86, 16, v84
	v_mov_b32_e32 v88, v20
	v_and_b32_e32 v85, 0xffff0000, v85
	v_and_b32_e32 v84, 0xffff0000, v84
	v_pk_add_f32 v[20:21], v[56:57], v[22:23]
	v_pk_add_f32 v[88:89], v[56:57], v[88:89]
	v_pk_mul_f32 v[20:21], v[20:21], v[84:85]
	v_pk_mul_f32 v[86:87], v[88:89], v[86:87]
	s_nop 7
	s_nop 1
	v_cvt_pk_bf16_f32 v21, v87, v21
	v_cvt_pk_bf16_f32 v20, v86, v20
	global_store_dwordx2 v[60:61], v[20:21], off offset:96
	ds_read_b64_tr_b16 v[20:21], v90 offset:128
	ds_read_b64_tr_b16 v[22:23], v90 offset:2240
	s_waitcnt lgkmcnt(0)
	v_mfma_f32_16x16x32_bf16 v[20:23], v[20:23], v[16:19], 0
	s_and_b64 vcc, exec, s[70:71]
	s_cbranch_vccz .LBB0_3654
	s_and_b64 vcc, exec, s[68:69]
	s_cbranch_vccz .LBB0_3655

; #define LAS __attribute__((address_space(3)))
; __device__ __forceinline__ unsigned pk2(float lo, float hi) { return f2bf(lo) | (f2bf(hi) << 16); }
; __device__ __forceinline__ void sgu_spatial_mfma(const Ctx& c, const bf16* P, const float* Wsp, const float* bsp, bf16* ACT) {
;     ...
;             for (int dt = 0; dt < 16; ++dt) {
;                 f32x4 acc = (f32x4){0.f, 0.f, 0.f, 0.f};
; #pragma unroll
;                 for (int ks = 0; ks < 4; ++ks) if (ks < nks) {
;                     const s16x4 a0 = __builtin_amdgcn_ds_read_tr16_b64_v4i16((LAS s16x4*)(vb + ks * 32 * RS + dt * 32)), a1 = __builtin_amdgcn_ds_read_tr16_b64_v4i16((LAS s16x4*)(vb + ks * 32 * RS + 4 * RS + dt * 32));
;                     bf16x8 af; af[0] = a0[0]; af[1] = a0[1]; af[2] = a0[2]; af[3] = a0[3]; af[4] = a1[0]; af[5] = a1[1]; af[6] = a1[2]; af[7] = a1[3];
;                     acc = __builtin_amdgcn_mfma_f32_16x16x32_bf16(af, Wf[ks], acc, 0, 0, 0); }
;                 const size_t col = (size_t)g * 512 + 256 * half + 16 * dt + 4 * lg;
;                 const v2u uu = uv[dt];
;                 v2u o; o.x = pk2(bflo(uu.x) * (acc[0] + bb), bfhi(uu.x) * (acc[1] + bb)); o.y = pk2(bflo(uu.y) * (acc[2] + bb), bfhi(uu.y) * (acc[3] + bb));
;                 *(v2u*)(ACT + (row0 + t) * 4096 + col) = o;
.LBB0_3603:
	s_nop 7
	v_mov_b32_e32 v87, v22
	v_mov_b32_e32 v22, v21
	s_waitcnt vmcnt(15)
	v_lshlrev_b32_e32 v85, 16, v83
	v_lshlrev_b32_e32 v84, 16, v82
	v_mov_b32_e32 v86, v20
	v_and_b32_e32 v83, 0xffff0000, v83
	v_and_b32_e32 v82, 0xffff0000, v82
	v_pk_add_f32 v[20:21], v[56:57], v[22:23]
	v_pk_add_f32 v[86:87], v[56:57], v[86:87]
	v_pk_mul_f32 v[20:21], v[20:21], v[82:83]
	v_pk_mul_f32 v[84:85], v[86:87], v[84:85]
	s_nop 7
	s_nop 1
	v_cvt_pk_bf16_f32 v21, v85, v21
	v_cvt_pk_bf16_f32 v20, v84, v20
	global_store_dwordx2 v[60:61], v[20:21], off offset:128
	ds_read_b64_tr_b16 v[20:21], v90 offset:160
	ds_read_b64_tr_b16 v[22:23], v90 offset:2272
	s_waitcnt lgkmcnt(0)
	v_mfma_f32_16x16x32_bf16 v[20:23], v[20:23], v[16:19], 0
	s_and_b64 vcc, exec, s[70:71]
	s_cbranch_vccz .LBB0_3656
	s_and_b64 vcc, exec, s[68:69]
	s_cbranch_vccz .LBB0_3657

; #define LAS __attribute__((address_space(3)))
; __device__ __forceinline__ unsigned pk2(float lo, float hi) { return f2bf(lo) | (f2bf(hi) << 16); }
; __device__ __forceinline__ void sgu_spatial_mfma(const Ctx& c, const bf16* P, const float* Wsp, const float* bsp, bf16* ACT) {
;     ...
;             for (int dt = 0; dt < 16; ++dt) {
;                 f32x4 acc = (f32x4){0.f, 0.f, 0.f, 0.f};
; #pragma unroll
;                 for (int ks = 0; ks < 4; ++ks) if (ks < nks) {
;                     const s16x4 a0 = __builtin_amdgcn_ds_read_tr16_b64_v4i16((LAS s16x4*)(vb + ks * 32 * RS + dt * 32)), a1 = __builtin_amdgcn_ds_read_tr16_b64_v4i16((LAS s16x4*)(vb + ks * 32 * RS + 4 * RS + dt * 32));
;                     bf16x8 af; af[0] = a0[0]; af[1] = a0[1]; af[2] = a0[2]; af[3] = a0[3]; af[4] = a1[0]; af[5] = a1[1]; af[6] = a1[2]; af[7] = a1[3];
;                     acc = __builtin_amdgcn_mfma_f32_16x16x32_bf16(af, Wf[ks], acc, 0, 0, 0); }
;                 const size_t col = (size_t)g * 512 + 256 * half + 16 * dt + 4 * lg;
;                 const v2u uu = uv[dt];
;                 v2u o; o.x = pk2(bflo(uu.x) * (acc[0] + bb), bfhi(uu.x) * (acc[1] + bb)); o.y = pk2(bflo(uu.y) * (acc[2] + bb), bfhi(uu.y) * (acc[3] + bb));
;                 *(v2u*)(ACT + (row0 + t) * 4096 + col) = o;
.LBB0_3607:
	s_nop 7
	v_mov_b32_e32 v85, v22
	v_mov_b32_e32 v22, v21
	s_waitcnt vmcnt(15)
	v_lshlrev_b32_e32 v83, 16, v81
	v_lshlrev_b32_e32 v82, 16, v80
	v_mov_b32_e32 v84, v20
	v_and_b32_e32 v81, 0xffff0000, v81
	v_and_b32_e32 v80, 0xffff0000, v80
	v_pk_add_f32 v[20:21], v[56:57], v[22:23]
	v_pk_add_f32 v[84:85], v[56:57], v[84:85]
	v_pk_mul_f32 v[20:21], v[20:21], v[80:81]
	v_pk_mul_f32 v[82:83], v[84:85], v[82:83]
	s_nop 7
	s_nop 1
	v_cvt_pk_bf16_f32 v21, v83, v21
	v_cvt_pk_bf16_f32 v20, v82, v20
	global_store_dwordx2 v[60:61], v[20:21], off offset:160
	ds_read_b64_tr_b16 v[20:21], v90 offset:192
	ds_read_b64_tr_b16 v[22:23], v90 offset:2304
	s_waitcnt lgkmcnt(0)
	v_mfma_f32_16x16x32_bf16 v[20:23], v[20:23], v[16:19], 0
	s_and_b64 vcc, exec, s[70:71]
	s_cbranch_vccz .LBB0_3658
	s_and_b64 vcc, exec, s[68:69]
	s_cbranch_vccz .LBB0_3659

; #define LAS __attribute__((address_space(3)))
; __device__ __forceinline__ unsigned pk2(float lo, float hi) { return f2bf(lo) | (f2bf(hi) << 16); }
; __device__ __forceinline__ void sgu_spatial_mfma(const Ctx& c, const bf16* P, const float* Wsp, const float* bsp, bf16* ACT) {
;     ...
;             for (int dt = 0; dt < 16; ++dt) {
;                 f32x4 acc = (f32x4){0.f, 0.f, 0.f, 0.f};
; #pragma unroll
;                 for (int ks = 0; ks < 4; ++ks) if (ks < nks) {
;                     const s16x4 a0 = __builtin_amdgcn_ds_read_tr16_b64_v4i16((LAS s16x4*)(vb + ks * 32 * RS + dt * 32)), a1 = __builtin_amdgcn_ds_read_tr16_b64_v4i16((LAS s16x4*)(vb + ks * 32 * RS + 4 * RS + dt * 32));
;                     bf16x8 af; af[0] = a0[0]; af[1] = a0[1]; af[2] = a0[2]; af[3] = a0[3]; af[4] = a1[0]; af[5] = a1[1]; af[6] = a1[2]; af[7] = a1[3];
;                     acc = __builtin_amdgcn_mfma_f32_16x16x32_bf16(af, Wf[ks], acc, 0, 0, 0); }
;                 const size_t col = (size_t)g * 512 + 256 * half + 16 * dt + 4 * lg;
;                 const v2u uu = uv[dt];
;                 v2u o; o.x = pk2(bflo(uu.x) * (acc[0] + bb), bfhi(uu.x) * (acc[1] + bb)); o.y = pk2(bflo(uu.y) * (acc[2] + bb), bfhi(uu.y) * (acc[3] + bb));
;                 *(v2u*)(ACT + (row0 + t) * 4096 + col) = o;
.LBB0_3611:
	s_nop 7
	v_mov_b32_e32 v83, v22
	v_mov_b32_e32 v22, v21
	s_waitcnt vmcnt(15)
	v_lshlrev_b32_e32 v81, 16, v79
	v_lshlrev_b32_e32 v80, 16, v78
	v_mov_b32_e32 v82, v20
	v_and_b32_e32 v79, 0xffff0000, v79
	v_and_b32_e32 v78, 0xffff0000, v78
	v_pk_add_f32 v[20:21], v[56:57], v[22:23]
	v_pk_add_f32 v[82:83], v[56:57], v[82:83]
	v_pk_mul_f32 v[20:21], v[20:21], v[78:79]
	v_pk_mul_f32 v[80:81], v[82:83], v[80:81]
	s_nop 7
	s_nop 1
	v_cvt_pk_bf16_f32 v21, v81, v21
	v_cvt_pk_bf16_f32 v20, v80, v20
	global_store_dwordx2 v[60:61], v[20:21], off offset:192
	ds_read_b64_tr_b16 v[20:21], v90 offset:224
	ds_read_b64_tr_b16 v[22:23], v90 offset:2336
	s_waitcnt lgkmcnt(0)
	v_mfma_f32_16x16x32_bf16 v[20:23], v[20:23], v[16:19], 0
	s_and_b64 vcc, exec, s[70:71]
	s_cbranch_vccz .LBB0_3660
	s_and_b64 vcc, exec, s[68:69]
	s_cbranch_vccz .LBB0_3661

; #define LAS __attribute__((address_space(3)))
; __device__ __forceinline__ unsigned pk2(float lo, float hi) { return f2bf(lo) | (f2bf(hi) << 16); }
; __device__ __forceinline__ void sgu_spatial_mfma(const Ctx& c, const bf16* P, const float* Wsp, const float* bsp, bf16* ACT) {
;     ...
;             for (int dt = 0; dt < 16; ++dt) {
;                 f32x4 acc = (f32x4){0.f, 0.f, 0.f, 0.f};
; #pragma unroll
;                 for (int ks = 0; ks < 4; ++ks) if (ks < nks) {
;                     const s16x4 a0 = __builtin_amdgcn_ds_read_tr16_b64_v4i16((LAS s16x4*)(vb + ks * 32 * RS + dt * 32)), a1 = __builtin_amdgcn_ds_read_tr16_b64_v4i16((LAS s16x4*)(vb + ks * 32 * RS + 4 * RS + dt * 32));
;                     bf16x8 af; af[0] = a0[0]; af[1] = a0[1]; af[2] = a0[2]; af[3] = a0[3]; af[4] = a1[0]; af[5] = a1[1]; af[6] = a1[2]; af[7] = a1[3];
;                     acc = __builtin_amdgcn_mfma_f32_16x16x32_bf16(af, Wf[ks], acc, 0, 0, 0); }
;                 const size_t col = (size_t)g * 512 + 256 * half + 16 * dt + 4 * lg;
;                 const v2u uu = uv[dt];
;                 v2u o; o.x = pk2(bflo(uu.x) * (acc[0] + bb), bfhi(uu.x) * (acc[1] + bb)); o.y = pk2(bflo(uu.y) * (acc[2] + bb), bfhi(uu.y) * (acc[3] + bb));
;                 *(v2u*)(ACT + (row0 + t) * 4096 + col) = o;
.LBB0_3615:
	s_nop 7
	v_mov_b32_e32 v81, v22
	v_mov_b32_e32 v22, v21
	s_waitcnt vmcnt(15)
	v_lshlrev_b32_e32 v79, 16, v77
	v_lshlrev_b32_e32 v78, 16, v76
	v_mov_b32_e32 v80, v20
	v_and_b32_e32 v77, 0xffff0000, v77
	v_and_b32_e32 v76, 0xffff0000, v76
	v_pk_add_f32 v[20:21], v[56:57], v[22:23]
	v_pk_add_f32 v[80:81], v[56:57], v[80:81]
	v_pk_mul_f32 v[20:21], v[20:21], v[76:77]
	v_pk_mul_f32 v[78:79], v[80:81], v[78:79]
	s_nop 7
	s_nop 1
	v_cvt_pk_bf16_f32 v21, v79, v21
	v_cvt_pk_bf16_f32 v20, v78, v20
	global_store_dwordx2 v[60:61], v[20:21], off offset:224
	ds_read_b64_tr_b16 v[20:21], v90 offset:256
	ds_read_b64_tr_b16 v[22:23], v90 offset:2368
	s_waitcnt lgkmcnt(0)
	v_mfma_f32_16x16x32_bf16 v[20:23], v[20:23], v[16:19], 0
	s_and_b64 vcc, exec, s[70:71]
	s_cbranch_vccz .LBB0_3662
	s_and_b64 vcc, exec, s[68:69]
	s_cbranch_vccz .LBB0_3663

; #define LAS __attribute__((address_space(3)))
; __device__ __forceinline__ unsigned pk2(float lo, float hi) { return f2bf(lo) | (f2bf(hi) << 16); }
; __device__ __forceinline__ void sgu_spatial_mfma(const Ctx& c, const bf16* P, const float* Wsp, const float* bsp, bf16* ACT) {
;     ...
;             for (int dt = 0; dt < 16; ++dt) {
;                 f32x4 acc = (f32x4){0.f, 0.f, 0.f, 0.f};
; #pragma unroll
;                 for (int ks = 0; ks < 4; ++ks) if (ks < nks) {
;                     const s16x4 a0 = __builtin_amdgcn_ds_read_tr16_b64_v4i16((LAS s16x4*)(vb + ks * 32 * RS + dt * 32)), a1 = __builtin_amdgcn_ds_read_tr16_b64_v4i16((LAS s16x4*)(vb + ks * 32 * RS + 4 * RS + dt * 32));
;                     bf16x8 af; af[0] = a0[0]; af[1] = a0[1]; af[2] = a0[2]; af[3] = a0[3]; af[4] = a1[0]; af[5] = a1[1]; af[6] = a1[2]; af[7] = a1[3];
;                     acc = __builtin_amdgcn_mfma_f32_16x16x32_bf16(af, Wf[ks], acc, 0, 0, 0); }
;                 const size_t col = (size_t)g * 512 + 256 * half + 16 * dt + 4 * lg;
;                 const v2u uu = uv[dt];
;                 v2u o; o.x = pk2(bflo(uu.x) * (acc[0] + bb), bfhi(uu.x) * (acc[1] + bb)); o.y = pk2(bflo(uu.y) * (acc[2] + bb), bfhi(uu.y) * (acc[3] + bb));
;                 *(v2u*)(ACT + (row0 + t) * 4096 + col) = o;
.LBB0_3619:
	s_nop 7
	v_mov_b32_e32 v79, v22
	v_mov_b32_e32 v22, v21
	s_waitcnt vmcnt(15)
	v_lshlrev_b32_e32 v77, 16, v75
	v_lshlrev_b32_e32 v76, 16, v74
	v_mov_b32_e32 v78, v20
	v_and_b32_e32 v75, 0xffff0000, v75
	v_and_b32_e32 v74, 0xffff0000, v74
	v_pk_add_f32 v[20:21], v[56:57], v[22:23]
	v_pk_add_f32 v[78:79], v[56:57], v[78:79]
	v_pk_mul_f32 v[20:21], v[20:21], v[74:75]
	v_pk_mul_f32 v[76:77], v[78:79], v[76:77]
	s_nop 7
	s_nop 1
	v_cvt_pk_bf16_f32 v21, v77, v21
	v_cvt_pk_bf16_f32 v20, v76, v20
	global_store_dwordx2 v[60:61], v[20:21], off offset:256
	ds_read_b64_tr_b16 v[20:21], v90 offset:288
	ds_read_b64_tr_b16 v[22:23], v90 offset:2400
	s_waitcnt lgkmcnt(0)
	v_mfma_f32_16x16x32_bf16 v[20:23], v[20:23], v[16:19], 0
	s_and_b64 vcc, exec, s[70:71]
	s_cbranch_vccz .LBB0_3664
	s_and_b64 vcc, exec, s[68:69]
	s_cbranch_vccz .LBB0_3665

; #define LAS __attribute__((address_space(3)))
; __device__ __forceinline__ unsigned pk2(float lo, float hi) { return f2bf(lo) | (f2bf(hi) << 16); }
; __device__ __forceinline__ void sgu_spatial_mfma(const Ctx& c, const bf16* P, const float* Wsp, const float* bsp, bf16* ACT) {
;     ...
;             for (int dt = 0; dt < 16; ++dt) {
;                 f32x4 acc = (f32x4){0.f, 0.f, 0.f, 0.f};
; #pragma unroll
;                 for (int ks = 0; ks < 4; ++ks) if (ks < nks) {
;                     const s16x4 a0 = __builtin_amdgcn_ds_read_tr16_b64_v4i16((LAS s16x4*)(vb + ks * 32 * RS + dt * 32)), a1 = __builtin_amdgcn_ds_read_tr16_b64_v4i16((LAS s16x4*)(vb + ks * 32 * RS + 4 * RS + dt * 32));
;                     bf16x8 af; af[0] = a0[0]; af[1] = a0[1]; af[2] = a0[2]; af[3] = a0[3]; af[4] = a1[0]; af[5] = a1[1]; af[6] = a1[2]; af[7] = a1[3];
;                     acc = __builtin_amdgcn_mfma_f32_16x16x32_bf16(af, Wf[ks], acc, 0, 0, 0); }
;                 const size_t col = (size_t)g * 512 + 256 * half + 16 * dt + 4 * lg;
;                 const v2u uu = uv[dt];
;                 v2u o; o.x = pk2(bflo(uu.x) * (acc[0] + bb), bfhi(uu.x) * (acc[1] + bb)); o.y = pk2(bflo(uu.y) * (acc[2] + bb), bfhi(uu.y) * (acc[3] + bb));
;                 *(v2u*)(ACT + (row0 + t) * 4096 + col) = o;
.LBB0_3623:
	s_nop 7
	v_mov_b32_e32 v77, v22
	v_mov_b32_e32 v22, v21
	s_waitcnt vmcnt(15)
	v_lshlrev_b32_e32 v75, 16, v73
	v_lshlrev_b32_e32 v74, 16, v72
	v_mov_b32_e32 v76, v20
	v_and_b32_e32 v73, 0xffff0000, v73
	v_and_b32_e32 v72, 0xffff0000, v72
	v_pk_add_f32 v[20:21], v[56:57], v[22:23]
	v_pk_add_f32 v[76:77], v[56:57], v[76:77]
	v_pk_mul_f32 v[20:21], v[20:21], v[72:73]
	v_pk_mul_f32 v[74:75], v[76:77], v[74:75]
	s_nop 7
	s_nop 1
	v_cvt_pk_bf16_f32 v21, v75, v21
	v_cvt_pk_bf16_f32 v20, v74, v20
	global_store_dwordx2 v[60:61], v[20:21], off offset:288
	ds_read_b64_tr_b16 v[20:21], v90 offset:320
	ds_read_b64_tr_b16 v[22:23], v90 offset:2432
	s_waitcnt lgkmcnt(0)
	v_mfma_f32_16x16x32_bf16 v[20:23], v[20:23], v[16:19], 0
	s_and_b64 vcc, exec, s[70:71]
	s_cbranch_vccz .LBB0_3666
	s_and_b64 vcc, exec, s[68:69]
	s_cbranch_vccz .LBB0_3667

; #define LAS __attribute__((address_space(3)))
; __device__ __forceinline__ unsigned pk2(float lo, float hi) { return f2bf(lo) | (f2bf(hi) << 16); }
; __device__ __forceinline__ void sgu_spatial_mfma(const Ctx& c, const bf16* P, const float* Wsp, const float* bsp, bf16* ACT) {
;     ...
;             for (int dt = 0; dt < 16; ++dt) {
;                 f32x4 acc = (f32x4){0.f, 0.f, 0.f, 0.f};
; #pragma unroll
;                 for (int ks = 0; ks < 4; ++ks) if (ks < nks) {
;                     const s16x4 a0 = __builtin_amdgcn_ds_read_tr16_b64_v4i16((LAS s16x4*)(vb + ks * 32 * RS + dt * 32)), a1 = __builtin_amdgcn_ds_read_tr16_b64_v4i16((LAS s16x4*)(vb + ks * 32 * RS + 4 * RS + dt * 32));
;                     bf16x8 af; af[0] = a0[0]; af[1] = a0[1]; af[2] = a0[2]; af[3] = a0[3]; af[4] = a1[0]; af[5] = a1[1]; af[6] = a1[2]; af[7] = a1[3];
;                     acc = __builtin_amdgcn_mfma_f32_16x16x32_bf16(af, Wf[ks], acc, 0, 0, 0); }
;                 const size_t col = (size_t)g * 512 + 256 * half + 16 * dt + 4 * lg;
;                 const v2u uu = uv[dt];
;                 v2u o; o.x = pk2(bflo(uu.x) * (acc[0] + bb), bfhi(uu.x) * (acc[1] + bb)); o.y = pk2(bflo(uu.y) * (acc[2] + bb), bfhi(uu.y) * (acc[3] + bb));
;                 *(v2u*)(ACT + (row0 + t) * 4096 + col) = o;
.LBB0_3627:
	s_nop 7
	v_mov_b32_e32 v75, v22
	v_mov_b32_e32 v22, v21
	s_waitcnt vmcnt(15)
	v_lshlrev_b32_e32 v73, 16, v71
	v_lshlrev_b32_e32 v72, 16, v70
	v_mov_b32_e32 v74, v20
	v_and_b32_e32 v71, 0xffff0000, v71
	v_and_b32_e32 v70, 0xffff0000, v70
	v_pk_add_f32 v[20:21], v[56:57], v[22:23]
	v_pk_add_f32 v[74:75], v[56:57], v[74:75]
	v_pk_mul_f32 v[20:21], v[20:21], v[70:71]
	v_pk_mul_f32 v[72:73], v[74:75], v[72:73]
	s_nop 7
	s_nop 1
	v_cvt_pk_bf16_f32 v21, v73, v21
	v_cvt_pk_bf16_f32 v20, v72, v20
	global_store_dwordx2 v[60:61], v[20:21], off offset:320
	ds_read_b64_tr_b16 v[20:21], v90 offset:352
	ds_read_b64_tr_b16 v[22:23], v90 offset:2464
	s_waitcnt lgkmcnt(0)
	v_mfma_f32_16x16x32_bf16 v[20:23], v[20:23], v[16:19], 0
	s_and_b64 vcc, exec, s[70:71]
	s_cbranch_vccz .LBB0_3668
	s_and_b64 vcc, exec, s[68:69]
	s_cbranch_vccz .LBB0_3669

; #define LAS __attribute__((address_space(3)))
; __device__ __forceinline__ unsigned pk2(float lo, float hi) { return f2bf(lo) | (f2bf(hi) << 16); }
; __device__ __forceinline__ void sgu_spatial_mfma(const Ctx& c, const bf16* P, const float* Wsp, const float* bsp, bf16* ACT) {
;     ...
;             for (int dt = 0; dt < 16; ++dt) {
;                 f32x4 acc = (f32x4){0.f, 0.f, 0.f, 0.f};
; #pragma unroll
;                 for (int ks = 0; ks < 4; ++ks) if (ks < nks) {
;                     const s16x4 a0 = __builtin_amdgcn_ds_read_tr16_b64_v4i16((LAS s16x4*)(vb + ks * 32 * RS + dt * 32)), a1 = __builtin_amdgcn_ds_read_tr16_b64_v4i16((LAS s16x4*)(vb + ks * 32 * RS + 4 * RS + dt * 32));
;                     bf16x8 af; af[0] = a0[0]; af[1] = a0[1]; af[2] = a0[2]; af[3] = a0[3]; af[4] = a1[0]; af[5] = a1[1]; af[6] = a1[2]; af[7] = a1[3];
;                     acc = __builtin_amdgcn_mfma_f32_16x16x32_bf16(af, Wf[ks], acc, 0, 0, 0); }
;                 const size_t col = (size_t)g * 512 + 256 * half + 16 * dt + 4 * lg;
;                 const v2u uu = uv[dt];
;                 v2u o; o.x = pk2(bflo(uu.x) * (acc[0] + bb), bfhi(uu.x) * (acc[1] + bb)); o.y = pk2(bflo(uu.y) * (acc[2] + bb), bfhi(uu.y) * (acc[3] + bb));
;                 *(v2u*)(ACT + (row0 + t) * 4096 + col) = o;
.LBB0_3631:
	s_nop 7
	v_mov_b32_e32 v73, v22
	v_mov_b32_e32 v22, v21
	s_waitcnt vmcnt(15)
	v_lshlrev_b32_e32 v71, 16, v69
	v_lshlrev_b32_e32 v70, 16, v68
	v_mov_b32_e32 v72, v20
	v_and_b32_e32 v69, 0xffff0000, v69
	v_and_b32_e32 v68, 0xffff0000, v68
	v_pk_add_f32 v[20:21], v[56:57], v[22:23]
	v_pk_add_f32 v[72:73], v[56:57], v[72:73]
	v_pk_mul_f32 v[20:21], v[20:21], v[68:69]
	v_pk_mul_f32 v[70:71], v[72:73], v[70:71]
	s_nop 7
	s_nop 1
	v_cvt_pk_bf16_f32 v21, v71, v21
	v_cvt_pk_bf16_f32 v20, v70, v20
	global_store_dwordx2 v[60:61], v[20:21], off offset:352
	ds_read_b64_tr_b16 v[20:21], v90 offset:384
	ds_read_b64_tr_b16 v[22:23], v90 offset:2496
	s_waitcnt lgkmcnt(0)
	v_mfma_f32_16x16x32_bf16 v[20:23], v[20:23], v[16:19], 0
	s_and_b64 vcc, exec, s[70:71]
	s_cbranch_vccz .LBB0_3670
	s_and_b64 vcc, exec, s[68:69]
	s_cbranch_vccz .LBB0_3671

; #define LAS __attribute__((address_space(3)))
; __device__ __forceinline__ unsigned pk2(float lo, float hi) { return f2bf(lo) | (f2bf(hi) << 16); }
; __device__ __forceinline__ void sgu_spatial_mfma(const Ctx& c, const bf16* P, const float* Wsp, const float* bsp, bf16* ACT) {
;     ...
;             for (int dt = 0; dt < 16; ++dt) {
;                 f32x4 acc = (f32x4){0.f, 0.f, 0.f, 0.f};
; #pragma unroll
;                 for (int ks = 0; ks < 4; ++ks) if (ks < nks) {
;                     const s16x4 a0 = __builtin_amdgcn_ds_read_tr16_b64_v4i16((LAS s16x4*)(vb + ks * 32 * RS + dt * 32)), a1 = __builtin_amdgcn_ds_read_tr16_b64_v4i16((LAS s16x4*)(vb + ks * 32 * RS + 4 * RS + dt * 32));
;                     bf16x8 af; af[0] = a0[0]; af[1] = a0[1]; af[2] = a0[2]; af[3] = a0[3]; af[4] = a1[0]; af[5] = a1[1]; af[6] = a1[2]; af[7] = a1[3];
;                     acc = __builtin_amdgcn_mfma_f32_16x16x32_bf16(af, Wf[ks], acc, 0, 0, 0); }
;                 const size_t col = (size_t)g * 512 + 256 * half + 16 * dt + 4 * lg;
;                 const v2u uu = uv[dt];
;                 v2u o; o.x = pk2(bflo(uu.x) * (acc[0] + bb), bfhi(uu.x) * (acc[1] + bb)); o.y = pk2(bflo(uu.y) * (acc[2] + bb), bfhi(uu.y) * (acc[3] + bb));
;                 *(v2u*)(ACT + (row0 + t) * 4096 + col) = o;
.LBB0_3635:
	s_nop 7
	v_mov_b32_e32 v71, v22
	v_mov_b32_e32 v22, v21
	s_waitcnt vmcnt(15)
	v_lshlrev_b32_e32 v69, 16, v67
	v_lshlrev_b32_e32 v68, 16, v66
	v_mov_b32_e32 v70, v20
	v_and_b32_e32 v67, 0xffff0000, v67
	v_and_b32_e32 v66, 0xffff0000, v66
	v_pk_add_f32 v[20:21], v[56:57], v[22:23]
	v_pk_add_f32 v[70:71], v[56:57], v[70:71]
	v_pk_mul_f32 v[20:21], v[20:21], v[66:67]
	v_pk_mul_f32 v[68:69], v[70:71], v[68:69]
	s_nop 7
	s_nop 1
	v_cvt_pk_bf16_f32 v21, v69, v21
	v_cvt_pk_bf16_f32 v20, v68, v20
	global_store_dwordx2 v[60:61], v[20:21], off offset:384
	ds_read_b64_tr_b16 v[20:21], v90 offset:416
	ds_read_b64_tr_b16 v[22:23], v90 offset:2528
	s_waitcnt lgkmcnt(0)
	v_mfma_f32_16x16x32_bf16 v[20:23], v[20:23], v[16:19], 0
	s_and_b64 vcc, exec, s[70:71]
	s_cbranch_vccz .LBB0_3672
	s_and_b64 vcc, exec, s[68:69]
	s_cbranch_vccz .LBB0_3673

; #define LAS __attribute__((address_space(3)))
; __device__ __forceinline__ unsigned pk2(float lo, float hi) { return f2bf(lo) | (f2bf(hi) << 16); }
; __device__ __forceinline__ void sgu_spatial_mfma(const Ctx& c, const bf16* P, const float* Wsp, const float* bsp, bf16* ACT) {
;     ...
;             for (int dt = 0; dt < 16; ++dt) {
;                 f32x4 acc = (f32x4){0.f, 0.f, 0.f, 0.f};
; #pragma unroll
;                 for (int ks = 0; ks < 4; ++ks) if (ks < nks) {
;                     const s16x4 a0 = __builtin_amdgcn_ds_read_tr16_b64_v4i16((LAS s16x4*)(vb + ks * 32 * RS + dt * 32)), a1 = __builtin_amdgcn_ds_read_tr16_b64_v4i16((LAS s16x4*)(vb + ks * 32 * RS + 4 * RS + dt * 32));
;                     bf16x8 af; af[0] = a0[0]; af[1] = a0[1]; af[2] = a0[2]; af[3] = a0[3]; af[4] = a1[0]; af[5] = a1[1]; af[6] = a1[2]; af[7] = a1[3];
;                     acc = __builtin_amdgcn_mfma_f32_16x16x32_bf16(af, Wf[ks], acc, 0, 0, 0); }
;                 const size_t col = (size_t)g * 512 + 256 * half + 16 * dt + 4 * lg;
;                 const v2u uu = uv[dt];
;                 v2u o; o.x = pk2(bflo(uu.x) * (acc[0] + bb), bfhi(uu.x) * (acc[1] + bb)); o.y = pk2(bflo(uu.y) * (acc[2] + bb), bfhi(uu.y) * (acc[3] + bb));
;                 *(v2u*)(ACT + (row0 + t) * 4096 + col) = o;
.LBB0_3639:
	s_nop 7
	v_mov_b32_e32 v69, v22
	v_mov_b32_e32 v22, v21
	s_waitcnt vmcnt(15)
	v_lshlrev_b32_e32 v67, 16, v65
	v_lshlrev_b32_e32 v66, 16, v64
	v_mov_b32_e32 v68, v20
	v_and_b32_e32 v65, 0xffff0000, v65
	v_and_b32_e32 v64, 0xffff0000, v64
	v_pk_add_f32 v[20:21], v[56:57], v[22:23]
	v_pk_add_f32 v[68:69], v[56:57], v[68:69]
	v_pk_mul_f32 v[20:21], v[20:21], v[64:65]
	v_pk_mul_f32 v[66:67], v[68:69], v[66:67]
	s_nop 7
	s_nop 1
	v_cvt_pk_bf16_f32 v21, v67, v21
	v_cvt_pk_bf16_f32 v20, v66, v20
	global_store_dwordx2 v[60:61], v[20:21], off offset:416
	ds_read_b64_tr_b16 v[20:21], v90 offset:448
	ds_read_b64_tr_b16 v[22:23], v90 offset:2560
	s_waitcnt lgkmcnt(0)
	v_mfma_f32_16x16x32_bf16 v[20:23], v[20:23], v[16:19], 0
	s_and_b64 vcc, exec, s[70:71]
	s_cbranch_vccz .LBB0_3674
	s_and_b64 vcc, exec, s[68:69]
	s_cbranch_vccz .LBB0_3675

; #define LAS __attribute__((address_space(3)))
; __device__ __forceinline__ unsigned pk2(float lo, float hi) { return f2bf(lo) | (f2bf(hi) << 16); }
; __device__ __forceinline__ void sgu_spatial_mfma(const Ctx& c, const bf16* P, const float* Wsp, const float* bsp, bf16* ACT) {
;     ...
;             for (int dt = 0; dt < 16; ++dt) {
;                 f32x4 acc = (f32x4){0.f, 0.f, 0.f, 0.f};
; #pragma unroll
;                 for (int ks = 0; ks < 4; ++ks) if (ks < nks) {
;                     const s16x4 a0 = __builtin_amdgcn_ds_read_tr16_b64_v4i16((LAS s16x4*)(vb + ks * 32 * RS + dt * 32)), a1 = __builtin_amdgcn_ds_read_tr16_b64_v4i16((LAS s16x4*)(vb + ks * 32 * RS + 4 * RS + dt * 32));
;                     bf16x8 af; af[0] = a0[0]; af[1] = a0[1]; af[2] = a0[2]; af[3] = a0[3]; af[4] = a1[0]; af[5] = a1[1]; af[6] = a1[2]; af[7] = a1[3];
;                     acc = __builtin_amdgcn_mfma_f32_16x16x32_bf16(af, Wf[ks], acc, 0, 0, 0); }
;                 const size_t col = (size_t)g * 512 + 256 * half + 16 * dt + 4 * lg;
;                 const v2u uu = uv[dt];
;                 v2u o; o.x = pk2(bflo(uu.x) * (acc[0] + bb), bfhi(uu.x) * (acc[1] + bb)); o.y = pk2(bflo(uu.y) * (acc[2] + bb), bfhi(uu.y) * (acc[3] + bb));
;                 *(v2u*)(ACT + (row0 + t) * 4096 + col) = o;
.LBB0_3643:
	s_nop 7
	v_mov_b32_e32 v67, v22
	v_mov_b32_e32 v22, v21
	s_waitcnt vmcnt(15)
	v_lshlrev_b32_e32 v65, 16, v63
	v_lshlrev_b32_e32 v64, 16, v62
	v_mov_b32_e32 v66, v20
	v_and_b32_e32 v63, 0xffff0000, v63
	v_and_b32_e32 v62, 0xffff0000, v62
	v_pk_add_f32 v[20:21], v[56:57], v[22:23]
	v_pk_add_f32 v[66:67], v[56:57], v[66:67]
	v_pk_mul_f32 v[20:21], v[20:21], v[62:63]
	v_pk_mul_f32 v[64:65], v[66:67], v[64:65]
	s_nop 7
	s_nop 1
	v_cvt_pk_bf16_f32 v21, v65, v21
	v_cvt_pk_bf16_f32 v20, v64, v20
	global_store_dwordx2 v[60:61], v[20:21], off offset:448
	ds_read_b64_tr_b16 v[20:21], v90 offset:480
	ds_read_b64_tr_b16 v[22:23], v90 offset:2592
	s_waitcnt lgkmcnt(0)
	v_mfma_f32_16x16x32_bf16 v[16:19], v[20:23], v[16:19], 0
	s_and_b64 vcc, exec, s[70:71]
	s_cbranch_vccz .LBB0_3676
	s_and_b64 vcc, exec, s[68:69]
	s_cbranch_vccz .LBB0_3677

; __device__ __forceinline__ unsigned pk2(float lo, float hi) { return f2bf(lo) | (f2bf(hi) << 16); }
; __device__ __forceinline__ float silu_fast(float x) { return x * __builtin_amdgcn_rcpf(1.f + __builtin_amdgcn_exp2f(-1.4426950408889634f * x)); }
; __device__ __forceinline__ float dpp_shr1(float x) { return __builtin_bit_cast(float, __builtin_amdgcn_update_dpp(0, __builtin_bit_cast(int, x), 0x111, 0xf, 0xf, true)); }
;     __device__ __forceinline__ void operator()(const f32x4 (&acc)[2][2][4][2], const pg8::Unit& u, int wr, int wc, int fr, int fq) const {
;     ...
;             const int cc = ch0 + 4 * n;
;             const f32x4 wg0 = *(CF4)(cw + cc), wg1 = *(CF4)(cw + FF2 + cc), wg2 = *(CF4)(cw + 2 * FF2 + cc), wv0 = *(CF4)(cw + FFH + cc), wv1 = *(CF4)(cw + FF2 + FFH + cc), wv2 = *(CF4)(cw + 2 * FF2 + FFH + cc);
;             const f32x4 bg = *(CF4)(cb + cc), bv = *(CF4)(cb + FFH + cc);
; #pragma unroll
;             for (int jj = 0; jj < 4; ++jj) {
;                 float g2 = dpp_shr1(g[6][jj]), g1 = dpp_shr1(g[7][jj]), v2 = dpp_shr1(v[6][jj]), v1 = dpp_shr1(v[7][jj]);
; #pragma unroll
;                 for (int e = 0; e < 8; ++e) { const float g0 = g[e][jj], v0 = v[e][jj];
;                     const float cg = bg[jj] + wg0[jj] * g2 + wg1[jj] * g1 + wg2[jj] * g0, cv = bv[jj] + wv0[jj] * v2 + wv1[jj] * v1 + wv2[jj] * v0;
;                     g[e][jj] = silu_fast(cg) * cv; g2 = g1; g1 = g0; v2 = v1; v1 = v0; } }
; #pragma unroll
;             for (int e = 0; e < 8; ++e) { v2u w; w.x = pk2(g[e][0], g[e][1]); w.y = pk2(g[e][2], g[e][3]); *(v2u*)(ACT + (size_t)(tok0 + e) * FFH + cc) = w; }
.LBB0_4346:
	s_or_b64 exec, exec, s[34:35]
	v_or_b32_e32 v38, 4, v132
	v_ashrrev_i32_e32 v39, 31, v38
	v_lshlrev_b64 v[64:65], 2, v[38:39]
	v_lshl_add_u64 v[38:39], s[6:7], 0, v[64:65]
	v_lshl_add_u64 v[44:45], s[18:19], 0, v[64:65]
	v_lshl_add_u64 v[66:67], s[8:9], 0, v[64:65]
	global_load_dwordx4 v[52:55], v[38:39], off
	v_lshl_add_u64 v[48:49], s[20:21], 0, v[64:65]
	global_load_dwordx4 v[44:47], v[44:45], off
	v_lshl_add_u64 v[38:39], s[12:13], 0, v[64:65]
	global_load_dwordx4 v[68:71], v[66:67], off
	global_load_dwordx4 v[56:59], v[38:39], off
	v_mov_b32_dpp v106, v88 row_shr:1 row_mask:0xf bank_mask:0xf bound_ctrl:1
	global_load_dwordx4 v[48:51], v[48:49], off
	v_lshl_add_u64 v[38:39], s[14:15], 0, v[64:65]
	global_load_dwordx4 v[60:63], v[38:39], off
	v_lshl_add_u64 v[38:39], s[16:17], 0, v[64:65]
	global_load_dwordx4 v[38:41], v[38:39], off
	v_lshl_add_u64 v[64:65], s[22:23], 0, v[64:65]
	global_load_dwordx4 v[64:67], v[64:65], off
	v_mov_b32_dpp v107, v89 row_shr:1 row_mask:0xf bank_mask:0xf bound_ctrl:1
	v_mov_b32_dpp v138, v94 row_shr:1 row_mask:0xf bank_mask:0xf bound_ctrl:1
	v_mov_b32_dpp v139, v95 row_shr:1 row_mask:0xf bank_mask:0xf bound_ctrl:1
	v_mov_b32_dpp v160, v86 row_shr:1 row_mask:0xf bank_mask:0xf bound_ctrl:1
	v_mov_b32_dpp v161, v87 row_shr:1 row_mask:0xf bank_mask:0xf bound_ctrl:1
	v_mov_b32_dpp v136, v90 row_shr:1 row_mask:0xf bank_mask:0xf bound_ctrl:1
	v_mov_b32_dpp v137, v91 row_shr:1 row_mask:0xf bank_mask:0xf bound_ctrl:1
	v_mov_b32_dpp v158, v82 row_shr:1 row_mask:0xf bank_mask:0xf bound_ctrl:1
	v_mov_b32_dpp v162, v72 row_shr:1 row_mask:0xf bank_mask:0xf bound_ctrl:1
	v_mov_b32_dpp v159, v83 row_shr:1 row_mask:0xf bank_mask:0xf bound_ctrl:1
	v_mov_b32_dpp v163, v73 row_shr:1 row_mask:0xf bank_mask:0xf bound_ctrl:1
	v_mov_b32_dpp v134, v84 row_shr:1 row_mask:0xf bank_mask:0xf bound_ctrl:1
	v_mov_b32_dpp v132, v74 row_shr:1 row_mask:0xf bank_mask:0xf bound_ctrl:1
	v_mov_b32_dpp v135, v85 row_shr:1 row_mask:0xf bank_mask:0xf bound_ctrl:1
	v_mov_b32_dpp v133, v75 row_shr:1 row_mask:0xf bank_mask:0xf bound_ctrl:1
	s_andn2_b64 vcc, exec, s[0:1]
	s_mov_b32 s61, s24
	s_mov_b32 s34, s26
	s_mov_b64 s[38:39], s[30:31]
	s_mov_b64 s[36:37], s[28:29]
	s_waitcnt vmcnt(0)
	v_mov_b32_e32 v98, v52
	v_mov_b32_e32 v99, v54
	v_mov_b32_e32 v54, v53
	v_mov_b32_e32 v102, v68
	v_mov_b32_e32 v103, v70
	v_pk_fma_f32 v[110:111], v[98:99], v[106:107], v[102:103]
	v_mov_b32_e32 v106, v56
	v_mov_b32_e32 v107, v58
	v_pk_fma_f32 v[168:169], v[106:107], v[138:139], v[110:111]
	v_mov_b32_e32 v110, v60
	v_mov_b32_e32 v111, v62
	v_pk_fma_f32 v[168:169], v[130:131], v[110:111], v[168:169]
	v_mov_b32_e32 v70, v69
	v_mul_f32_e32 v52, 0xbfb8aa3b, v168
	v_exp_f32_e32 v52, v52
	v_mov_b32_e32 v58, v57
	v_mov_b32_e32 v62, v61
	v_mov_b32_e32 v60, v44
	v_add_f32_e32 v52, 1.0, v52
	v_rcp_f32_e32 v170, v52
	v_pk_fma_f32 v[52:53], v[54:55], v[160:161], v[70:71]
	v_mov_b32_e32 v56, v64
	v_pk_fma_f32 v[52:53], v[58:59], v[136:137], v[52:53]
	v_mov_b32_e32 v57, v66
	v_pk_fma_f32 v[160:161], v[126:127], v[62:63], v[52:53]
	v_mov_b32_e32 v53, v40
	v_mul_f32_e32 v52, 0xbfb8aa3b, v160
	v_exp_f32_e32 v52, v52
	v_mul_f32_e32 v44, 0xbfb8aa3b, v161
	v_exp_f32_e32 v44, v44
	v_mov_b32_e32 v40, v39
	v_add_f32_e32 v52, 1.0, v52
	v_rcp_f32_e32 v172, v52
	v_mov_b32_e32 v52, v38
	v_mul_f32_e32 v38, 0xbfb8aa3b, v169
	v_exp_f32_e32 v38, v38
	v_add_f32_e32 v44, 1.0, v44
	v_rcp_f32_e32 v173, v44
	v_mov_b32_e32 v66, v65
	v_add_f32_e32 v38, 1.0, v38
	v_pk_fma_f32 v[68:69], v[52:53], v[158:159], v[56:57]
	v_mov_b32_e32 v61, v46
	v_rcp_f32_e32 v171, v38
	v_pk_fma_f32 v[38:39], v[40:41], v[162:163], v[66:67]
	v_mov_b32_e32 v46, v45
	v_pk_fma_f32 v[158:159], v[60:61], v[134:135], v[68:69]
	v_mov_b32_e32 v69, v50
	v_pk_fma_f32 v[38:39], v[46:47], v[132:133], v[38:39]
	v_mov_b32_e32 v50, v49
	v_pk_fma_f32 v[38:39], v[122:123], v[50:51], v[38:39]
	v_pk_mul_f32 v[44:45], v[160:161], v[172:173]
	v_mov_b32_e32 v68, v48
	v_pk_mul_f32 v[38:39], v[38:39], v[44:45]
	v_pk_fma_f32 v[158:159], v[124:125], v[68:69], v[158:159]
	v_pk_mul_f32 v[168:169], v[168:169], v[170:171]
	v_and_b32_sdwa v48, v39, v234 dst_sel:DWORD dst_unused:UNUSED_PAD src0_sel:WORD_1 src1_sel:DWORD
	v_and_b32_sdwa v49, v38, v234 dst_sel:DWORD dst_unused:UNUSED_PAD src0_sel:WORD_1 src1_sel:DWORD
	v_pk_mul_f32 v[158:159], v[158:159], v[168:169]
	v_add3_u32 v39, v39, v48, s59
	v_add3_u32 v38, v38, v49, s59
	v_pk_fma_f32 v[48:49], v[54:55], v[136:137], v[70:71]
	v_and_b32_sdwa v45, v158, v234 dst_sel:DWORD dst_unused:UNUSED_PAD src0_sel:WORD_1 src1_sel:DWORD
	v_pk_fma_f32 v[48:49], v[126:127], v[58:59], v[48:49]
	v_add3_u32 v45, v158, v45, s59
	v_and_b32_e32 v38, 0xffff0000, v38
	v_pk_fma_f32 v[48:49], v[118:119], v[62:63], v[48:49]
	v_and_b32_sdwa v44, v159, v234 dst_sel:DWORD dst_unused:UNUSED_PAD src0_sel:WORD_1 src1_sel:DWORD
	v_or_b32_sdwa v38, v38, v45 dst_sel:DWORD dst_unused:UNUSED_PAD src0_sel:DWORD src1_sel:WORD_1
	v_mul_f32_e32 v45, 0xbfb8aa3b, v48
	v_add3_u32 v44, v159, v44, s59
	v_and_b32_e32 v39, 0xffff0000, v39
	v_exp_f32_e32 v45, v45
	v_or_b32_sdwa v39, v39, v44 dst_sel:DWORD dst_unused:UNUSED_PAD src0_sel:DWORD src1_sel:WORD_1
	global_store_dwordx2 v[112:113], v[38:39], off offset:8
	v_pk_fma_f32 v[38:39], v[98:99], v[138:139], v[102:103]
	v_add_f32_e32 v45, 1.0, v45
	v_pk_fma_f32 v[38:39], v[130:131], v[106:107], v[38:39]
	v_rcp_f32_e32 v64, v45
	v_pk_fma_f32 v[38:39], v[114:115], v[110:111], v[38:39]
	v_mul_f32_e32 v65, 0xbfb8aa3b, v49
	v_mul_f32_e32 v44, 0xbfb8aa3b, v38
	v_mul_f32_e32 v45, 0xbfb8aa3b, v39
	v_exp_f32_e32 v44, v44
	v_exp_f32_e32 v45, v45
	v_exp_f32_e32 v65, v65
; __device__ __forceinline__ unsigned pk2(float lo, float hi) { return f2bf(lo) | (f2bf(hi) << 16); }
; __device__ __forceinline__ float silu_fast(float x) { return x * __builtin_amdgcn_rcpf(1.f + __builtin_amdgcn_exp2f(-1.4426950408889634f * x)); }
; __device__ __forceinline__ float dpp_shr1(float x) { return __builtin_bit_cast(float, __builtin_amdgcn_update_dpp(0, __builtin_bit_cast(int, x), 0x111, 0xf, 0xf, true)); }
;     __device__ __forceinline__ void operator()(const f32x4 (&acc)[2][2][4][2], const pg8::Unit& u, int wr, int wc, int fr, int fq) const {
;     ...
;             for (int jj = 0; jj < 4; ++jj) {
;                 float g2 = dpp_shr1(g[6][jj]), g1 = dpp_shr1(g[7][jj]), v2 = dpp_shr1(v[6][jj]), v1 = dpp_shr1(v[7][jj]);
; #pragma unroll
;                 for (int e = 0; e < 8; ++e) { const float g0 = g[e][jj], v0 = v[e][jj];
;                     const float cg = bg[jj] + wg0[jj] * g2 + wg1[jj] * g1 + wg2[jj] * g0, cv = bv[jj] + wv0[jj] * v2 + wv1[jj] * v1 + wv2[jj] * v0;
;                     g[e][jj] = silu_fast(cg) * cv; g2 = g1; g1 = g0; v2 = v1; v1 = v0; } }
; #pragma unroll
;             for (int e = 0; e < 8; ++e) { v2u w; w.x = pk2(g[e][0], g[e][1]); w.y = pk2(g[e][2], g[e][3]); *(v2u*)(ACT + (size_t)(tok0 + e) * FFH + cc) = w; }
	v_pk_fma_f32 v[112:113], v[52:53], v[134:135], v[56:57]
	v_add_f32_e32 v44, 1.0, v44
	v_add_f32_e32 v45, 1.0, v45
	v_rcp_f32_e32 v44, v44
	v_rcp_f32_e32 v45, v45
	v_add_f32_e32 v65, 1.0, v65
	v_rcp_f32_e32 v65, v65
	v_pk_fma_f32 v[112:113], v[124:125], v[60:61], v[112:113]
	v_pk_mul_f32 v[38:39], v[38:39], v[44:45]
	v_pk_fma_f32 v[44:45], v[40:41], v[132:133], v[66:67]
	v_pk_fma_f32 v[112:113], v[116:117], v[68:69], v[112:113]
	v_pk_fma_f32 v[44:45], v[122:123], v[46:47], v[44:45]
	v_pk_mul_f32 v[38:39], v[112:113], v[38:39]
	v_pk_fma_f32 v[44:45], v[120:121], v[50:51], v[44:45]
	v_pk_mul_f32 v[48:49], v[48:49], v[64:65]
	s_nop 0
	v_pk_mul_f32 v[44:45], v[44:45], v[48:49]
	s_nop 7
	s_nop 1
	v_cvt_pk_bf16_f32 v39, v39, v45
	v_cvt_pk_bf16_f32 v38, v38, v44
	v_mov_b32_e32 v44, v33
	v_mov_b32_e32 v45, v35
	v_mov_b32_e32 v33, v34
	v_pk_fma_f32 v[34:35], v[126:127], v[54:55], v[70:71]
	v_pk_mul_f32 v[44:45], v[44:45], v[128:129]
	v_pk_fma_f32 v[34:35], v[118:119], v[58:59], v[34:35]
	global_store_dwordx2 v[108:109], v[38:39], off offset:8
	v_pk_fma_f32 v[34:35], v[44:45], v[62:63], v[34:35]
	v_mov_b32_e32 v39, v31
	v_mul_f32_e32 v31, 0xbfb8aa3b, v34
	v_exp_f32_e32 v31, v31
	v_mov_b32_e32 v38, v29
	v_mov_b32_e32 v29, v30
	v_pk_mul_f32 v[48:49], v[28:29], v[128:129]
	v_pk_fma_f32 v[28:29], v[130:131], v[98:99], v[102:103]
	v_pk_mul_f32 v[32:33], v[32:33], v[128:129]
	v_pk_fma_f32 v[28:29], v[114:115], v[106:107], v[28:29]
	v_add_f32_e32 v31, 1.0, v31
	v_pk_fma_f32 v[28:29], v[32:33], v[110:111], v[28:29]
	v_rcp_f32_e32 v64, v31
	v_mul_f32_e32 v30, 0xbfb8aa3b, v28
	v_mul_f32_e32 v31, 0xbfb8aa3b, v29
	v_exp_f32_e32 v30, v30
	v_exp_f32_e32 v31, v31
	v_mul_f32_e32 v65, 0xbfb8aa3b, v35
	v_exp_f32_e32 v65, v65
	v_add_f32_e32 v30, 1.0, v30
	v_add_f32_e32 v31, 1.0, v31
	v_rcp_f32_e32 v30, v30
	v_rcp_f32_e32 v31, v31
	v_add_f32_e32 v65, 1.0, v65
	v_rcp_f32_e32 v65, v65
	v_pk_fma_f32 v[108:109], v[124:125], v[52:53], v[56:57]
	v_pk_mul_f32 v[28:29], v[28:29], v[30:31]
	v_pk_fma_f32 v[108:109], v[116:117], v[60:61], v[108:109]
	v_pk_fma_f32 v[30:31], v[122:123], v[40:41], v[66:67]
	v_pk_mul_f32 v[38:39], v[38:39], v[128:129]
	v_pk_fma_f32 v[108:109], v[48:49], v[68:69], v[108:109]
	v_pk_fma_f32 v[30:31], v[120:121], v[46:47], v[30:31]
	v_pk_mul_f32 v[28:29], v[108:109], v[28:29]
	v_pk_fma_f32 v[30:31], v[38:39], v[50:51], v[30:31]
	v_pk_mul_f32 v[34:35], v[34:35], v[64:65]
	s_nop 0
	v_pk_mul_f32 v[30:31], v[30:31], v[34:35]
	s_nop 7
	s_nop 1
	v_cvt_pk_bf16_f32 v29, v29, v31
	v_cvt_pk_bf16_f32 v28, v28, v30
	v_mov_b32_e32 v30, v25
	v_mov_b32_e32 v31, v27
	v_pk_fma_f32 v[34:35], v[118:119], v[54:55], v[70:71]
	v_pk_mul_f32 v[30:31], v[30:31], v[42:43]
	v_pk_fma_f32 v[34:35], v[44:45], v[58:59], v[34:35]
	v_mov_b32_e32 v25, v26
	v_pk_fma_f32 v[34:35], v[30:31], v[62:63], v[34:35]
	global_store_dwordx2 v[104:105], v[28:29], off offset:8
	v_mul_f32_e32 v65, 0xbfb8aa3b, v34
	v_exp_f32_e32 v65, v65
	v_mov_b32_e32 v28, v21
	v_mov_b32_e32 v29, v23
	v_mov_b32_e32 v21, v22
	v_pk_mul_f32 v[22:23], v[24:25], v[42:43]
	v_pk_fma_f32 v[24:25], v[114:115], v[98:99], v[102:103]
	v_add_f32_e32 v65, 1.0, v65
	v_pk_fma_f32 v[24:25], v[32:33], v[106:107], v[24:25]
	v_rcp_f32_e32 v104, v65
	v_pk_fma_f32 v[24:25], v[22:23], v[110:111], v[24:25]
	v_pk_fma_f32 v[26:27], v[116:117], v[52:53], v[56:57]
	v_mul_f32_e32 v64, 0xbfb8aa3b, v24
	v_mul_f32_e32 v65, 0xbfb8aa3b, v25
	v_exp_f32_e32 v64, v64
	v_exp_f32_e32 v65, v65
	v_pk_mul_f32 v[20:21], v[20:21], v[42:43]
	v_pk_fma_f32 v[26:27], v[48:49], v[60:61], v[26:27]
	v_add_f32_e32 v64, 1.0, v64
	v_add_f32_e32 v65, 1.0, v65
	v_rcp_f32_e32 v64, v64
	v_rcp_f32_e32 v65, v65
	v_pk_mul_f32 v[28:29], v[28:29], v[42:43]
	v_pk_fma_f32 v[42:43], v[120:121], v[40:41], v[66:67]
	v_pk_fma_f32 v[26:27], v[20:21], v[68:69], v[26:27]
	v_pk_mul_f32 v[24:25], v[24:25], v[64:65]
	s_nop 0
	v_pk_mul_f32 v[24:25], v[26:27], v[24:25]
	v_pk_fma_f32 v[26:27], v[38:39], v[46:47], v[42:43]
	v_mul_f32_e32 v42, 0xbfb8aa3b, v35
	v_exp_f32_e32 v42, v42
	v_pk_fma_f32 v[26:27], v[28:29], v[50:51], v[26:27]
	v_add_f32_e32 v42, 1.0, v42
	v_rcp_f32_e32 v105, v42
	s_nop 0
	v_pk_mul_f32 v[34:35], v[34:35], v[104:105]
	s_nop 0
	v_pk_mul_f32 v[26:27], v[26:27], v[34:35]
	s_nop 7
	s_nop 1
	v_cvt_pk_bf16_f32 v25, v25, v27
	v_cvt_pk_bf16_f32 v24, v24, v26
	v_mov_b32_e32 v26, v17
	v_mov_b32_e32 v27, v19
	v_mov_b32_e32 v17, v18
	v_pk_fma_f32 v[18:19], v[44:45], v[54:55], v[70:71]
	v_pk_mul_f32 v[26:27], v[26:27], v[92:93]
	v_pk_fma_f32 v[18:19], v[30:31], v[58:59], v[18:19]
	global_store_dwordx2 v[100:101], v[24:25], off offset:8
	v_mov_b32_e32 v24, v13
	v_mov_b32_e32 v13, v14
	v_pk_fma_f32 v[18:19], v[26:27], v[62:63], v[18:19]
	v_pk_mul_f32 v[34:35], v[12:13], v[92:93]
	v_pk_fma_f32 v[12:13], v[32:33], v[98:99], v[102:103]
	v_pk_fma_f32 v[32:33], v[38:39], v[40:41], v[66:67]
	v_mul_f32_e32 v39, 0xbfb8aa3b, v18
	v_exp_f32_e32 v39, v39
	v_pk_mul_f32 v[16:17], v[16:17], v[92:93]
	v_pk_fma_f32 v[12:13], v[22:23], v[106:107], v[12:13]
	v_mov_b32_e32 v25, v15
	v_pk_fma_f32 v[12:13], v[16:17], v[110:111], v[12:13]
	v_add_f32_e32 v39, 1.0, v39
	v_mul_f32_e32 v38, 0xbfb8aa3b, v12
	v_rcp_f32_e32 v42, v39
	v_mul_f32_e32 v39, 0xbfb8aa3b, v13
	v_exp_f32_e32 v38, v38
	v_exp_f32_e32 v39, v39
	v_pk_fma_f32 v[14:15], v[48:49], v[52:53], v[56:57]
	v_pk_mul_f32 v[24:25], v[24:25], v[92:93]
	v_add_f32_e32 v38, 1.0, v38
	v_add_f32_e32 v39, 1.0, v39
	v_rcp_f32_e32 v38, v38
	v_rcp_f32_e32 v39, v39
	v_pk_fma_f32 v[14:15], v[20:21], v[60:61], v[14:15]
	v_pk_mul_f32 v[12:13], v[12:13], v[38:39]
	v_pk_fma_f32 v[14:15], v[34:35], v[68:69], v[14:15]
	s_nop 0
; __device__ __forceinline__ unsigned pk2(float lo, float hi) { return f2bf(lo) | (f2bf(hi) << 16); }
; __device__ __forceinline__ float silu_fast(float x) { return x * __builtin_amdgcn_rcpf(1.f + __builtin_amdgcn_exp2f(-1.4426950408889634f * x)); }
; __device__ __forceinline__ float dpp_shr1(float x) { return __builtin_bit_cast(float, __builtin_amdgcn_update_dpp(0, __builtin_bit_cast(int, x), 0x111, 0xf, 0xf, true)); }
;     __device__ __forceinline__ void operator()(const f32x4 (&acc)[2][2][4][2], const pg8::Unit& u, int wr, int wc, int fr, int fq) const {
;     ...
;             for (int jj = 0; jj < 4; ++jj) {
;                 float g2 = dpp_shr1(g[6][jj]), g1 = dpp_shr1(g[7][jj]), v2 = dpp_shr1(v[6][jj]), v1 = dpp_shr1(v[7][jj]);
; #pragma unroll
;                 for (int e = 0; e < 8; ++e) { const float g0 = g[e][jj], v0 = v[e][jj];
;                     const float cg = bg[jj] + wg0[jj] * g2 + wg1[jj] * g1 + wg2[jj] * g0, cv = bv[jj] + wv0[jj] * v2 + wv1[jj] * v1 + wv2[jj] * v0;
;                     g[e][jj] = silu_fast(cg) * cv; g2 = g1; g1 = g0; v2 = v1; v1 = v0; } }
; #pragma unroll
;             for (int e = 0; e < 8; ++e) { v2u w; w.x = pk2(g[e][0], g[e][1]); w.y = pk2(g[e][2], g[e][3]); *(v2u*)(ACT + (size_t)(tok0 + e) * FFH + cc) = w; }
	v_pk_mul_f32 v[12:13], v[14:15], v[12:13]
	v_pk_fma_f32 v[14:15], v[28:29], v[46:47], v[32:33]
	v_mul_f32_e32 v32, 0xbfb8aa3b, v19
	v_exp_f32_e32 v32, v32
	v_pk_fma_f32 v[14:15], v[24:25], v[50:51], v[14:15]
	v_add_f32_e32 v32, 1.0, v32
	v_rcp_f32_e32 v43, v32
	s_nop 0
	v_pk_mul_f32 v[18:19], v[18:19], v[42:43]
	s_nop 0
	v_pk_mul_f32 v[14:15], v[14:15], v[18:19]
	s_nop 7
	s_nop 1
	v_cvt_pk_bf16_f32 v13, v13, v15
	v_cvt_pk_bf16_f32 v12, v12, v14
	v_mov_b32_e32 v14, v9
	v_mov_b32_e32 v15, v11
	v_pk_fma_f32 v[18:19], v[30:31], v[54:55], v[70:71]
	v_pk_mul_f32 v[14:15], v[14:15], v[36:37]
	v_pk_fma_f32 v[18:19], v[26:27], v[58:59], v[18:19]
	v_mov_b32_e32 v9, v10
	v_pk_fma_f32 v[18:19], v[14:15], v[62:63], v[18:19]
	global_store_dwordx2 v[96:97], v[12:13], off offset:8
	v_mov_b32_e32 v12, v5
	v_mov_b32_e32 v13, v7
	v_mov_b32_e32 v5, v6
	v_pk_mul_f32 v[6:7], v[8:9], v[36:37]
	v_pk_fma_f32 v[8:9], v[22:23], v[98:99], v[102:103]
	v_mul_f32_e32 v23, 0xbfb8aa3b, v18
	v_exp_f32_e32 v23, v23
	v_pk_fma_f32 v[8:9], v[16:17], v[106:107], v[8:9]
	v_pk_fma_f32 v[10:11], v[20:21], v[52:53], v[56:57]
	v_pk_fma_f32 v[8:9], v[6:7], v[110:111], v[8:9]
	v_add_f32_e32 v23, 1.0, v23
	v_pk_fma_f32 v[20:21], v[28:29], v[40:41], v[66:67]
	v_mul_f32_e32 v22, 0xbfb8aa3b, v8
	v_rcp_f32_e32 v28, v23
	v_mul_f32_e32 v23, 0xbfb8aa3b, v9
	v_exp_f32_e32 v22, v22
	v_exp_f32_e32 v23, v23
	v_pk_mul_f32 v[4:5], v[4:5], v[36:37]
	v_pk_fma_f32 v[10:11], v[34:35], v[60:61], v[10:11]
	v_add_f32_e32 v22, 1.0, v22
	v_add_f32_e32 v23, 1.0, v23
	v_rcp_f32_e32 v22, v22
	v_rcp_f32_e32 v23, v23
	v_pk_fma_f32 v[10:11], v[4:5], v[68:69], v[10:11]
	v_pk_mul_f32 v[12:13], v[12:13], v[36:37]
	v_pk_mul_f32 v[8:9], v[8:9], v[22:23]
	s_nop 0
	v_pk_mul_f32 v[8:9], v[10:11], v[8:9]
	v_pk_fma_f32 v[10:11], v[24:25], v[46:47], v[20:21]
	v_mul_f32_e32 v20, 0xbfb8aa3b, v19
	v_exp_f32_e32 v20, v20
	v_pk_fma_f32 v[10:11], v[12:13], v[50:51], v[10:11]
	v_add_f32_e32 v20, 1.0, v20
	v_rcp_f32_e32 v29, v20
	s_nop 0
	v_pk_mul_f32 v[18:19], v[18:19], v[28:29]
	s_nop 0
	v_pk_mul_f32 v[10:11], v[10:11], v[18:19]
	s_nop 7
	s_nop 1
	v_cvt_pk_bf16_f32 v9, v9, v11
	v_cvt_pk_bf16_f32 v8, v8, v10
	global_store_dwordx2 v[80:81], v[8:9], off offset:8
	v_pk_fma_f32 v[8:9], v[16:17], v[98:99], v[102:103]
	v_pk_fma_f32 v[16:17], v[26:27], v[54:55], v[70:71]
	v_pk_fma_f32 v[8:9], v[6:7], v[106:107], v[8:9]
	v_pk_fma_f32 v[16:17], v[14:15], v[58:59], v[16:17]
	v_pk_fma_f32 v[8:9], v[88:89], v[110:111], v[8:9]
	v_pk_fma_f32 v[16:17], v[86:87], v[62:63], v[16:17]
	v_mul_f32_e32 v20, 0xbfb8aa3b, v8
	v_mul_f32_e32 v21, 0xbfb8aa3b, v16
	v_exp_f32_e32 v21, v21
	v_exp_f32_e32 v20, v20
	v_pk_fma_f32 v[10:11], v[34:35], v[52:53], v[56:57]
	v_pk_fma_f32 v[18:19], v[24:25], v[40:41], v[66:67]
	v_add_f32_e32 v21, 1.0, v21
	v_rcp_f32_e32 v22, v21
	v_mul_f32_e32 v21, 0xbfb8aa3b, v9
	v_exp_f32_e32 v21, v21
	v_add_f32_e32 v20, 1.0, v20
	v_rcp_f32_e32 v20, v20
	v_pk_fma_f32 v[10:11], v[4:5], v[60:61], v[10:11]
	v_add_f32_e32 v21, 1.0, v21
	v_rcp_f32_e32 v21, v21
	v_pk_fma_f32 v[10:11], v[82:83], v[68:69], v[10:11]
	v_pk_fma_f32 v[6:7], v[6:7], v[98:99], v[102:103]
	v_pk_fma_f32 v[4:5], v[4:5], v[52:53], v[56:57]
	v_pk_mul_f32 v[8:9], v[8:9], v[20:21]
	v_pk_fma_f32 v[6:7], v[88:89], v[106:107], v[6:7]
	v_pk_mul_f32 v[8:9], v[10:11], v[8:9]
	v_pk_fma_f32 v[10:11], v[12:13], v[46:47], v[18:19]
	v_mul_f32_e32 v18, 0xbfb8aa3b, v17
	v_exp_f32_e32 v18, v18
	v_pk_fma_f32 v[10:11], v[72:73], v[50:51], v[10:11]
	v_pk_fma_f32 v[6:7], v[94:95], v[110:111], v[6:7]
	v_pk_fma_f32 v[4:5], v[82:83], v[60:61], v[4:5]
	v_add_f32_e32 v18, 1.0, v18
	v_rcp_f32_e32 v23, v18
	v_pk_fma_f32 v[4:5], v[84:85], v[68:69], v[4:5]
	v_pk_mul_f32 v[16:17], v[16:17], v[22:23]
	s_nop 0
	v_pk_mul_f32 v[10:11], v[10:11], v[16:17]
	s_nop 7
	s_nop 1
	v_cvt_pk_bf16_f32 v9, v9, v11
	v_cvt_pk_bf16_f32 v8, v8, v10
	v_pk_fma_f32 v[10:11], v[14:15], v[54:55], v[70:71]
	global_store_dwordx2 v[78:79], v[8:9], off offset:8
	v_pk_fma_f32 v[10:11], v[86:87], v[58:59], v[10:11]
	v_mul_f32_e32 v8, 0xbfb8aa3b, v6
	v_pk_fma_f32 v[10:11], v[90:91], v[62:63], v[10:11]
	v_exp_f32_e32 v8, v8
	v_mul_f32_e32 v9, 0xbfb8aa3b, v10
	v_exp_f32_e32 v9, v9
	v_add_f32_e32 v8, 1.0, v8
	v_rcp_f32_e32 v8, v8
	v_add_f32_e32 v9, 1.0, v9
	v_rcp_f32_e32 v14, v9
	v_mul_f32_e32 v9, 0xbfb8aa3b, v7
	v_exp_f32_e32 v9, v9
	s_nop 0
	v_add_f32_e32 v9, 1.0, v9
	v_rcp_f32_e32 v9, v9
	s_nop 0
	v_pk_mul_f32 v[6:7], v[6:7], v[8:9]
	v_mul_f32_e32 v8, 0xbfb8aa3b, v11
	v_exp_f32_e32 v8, v8
	v_pk_mul_f32 v[4:5], v[4:5], v[6:7]
	v_pk_fma_f32 v[6:7], v[12:13], v[40:41], v[66:67]
	v_add_f32_e32 v8, 1.0, v8
	v_rcp_f32_e32 v15, v8
	v_pk_fma_f32 v[6:7], v[72:73], v[46:47], v[6:7]
	v_pk_mul_f32 v[8:9], v[10:11], v[14:15]
	v_pk_fma_f32 v[6:7], v[74:75], v[50:51], v[6:7]
	s_nop 0
	v_pk_mul_f32 v[6:7], v[6:7], v[8:9]
	v_and_b32_sdwa v8, v5, v234 dst_sel:DWORD dst_unused:UNUSED_PAD src0_sel:WORD_1 src1_sel:DWORD
	v_and_b32_sdwa v9, v4, v234 dst_sel:DWORD dst_unused:UNUSED_PAD src0_sel:WORD_1 src1_sel:DWORD
	v_add3_u32 v4, v4, v9, s59
	v_add3_u32 v5, v5, v8, s59
	v_and_b32_sdwa v8, v7, v234 dst_sel:DWORD dst_unused:UNUSED_PAD src0_sel:WORD_1 src1_sel:DWORD
	v_and_b32_sdwa v9, v6, v234 dst_sel:DWORD dst_unused:UNUSED_PAD src0_sel:WORD_1 src1_sel:DWORD
	v_add3_u32 v7, v7, v8, s59
	v_add3_u32 v6, v6, v9, s59
	v_and_b32_e32 v7, 0xffff0000, v7
	v_and_b32_e32 v6, 0xffff0000, v6
	v_or_b32_sdwa v5, v7, v5 dst_sel:DWORD dst_unused:UNUSED_PAD src0_sel:DWORD src1_sel:WORD_1
	v_or_b32_sdwa v4, v6, v4 dst_sel:DWORD dst_unused:UNUSED_PAD src0_sel:DWORD src1_sel:WORD_1
	global_store_dwordx2 v[76:77], v[4:5], off offset:8
	s_cbranch_vccz .LBB0_4365

; #define PG8_STAGE(bufoff, gbase, voff) do { _Pragma("unroll") for (int _i = 0; _i < 2; ++_i) \
;         __builtin_amdgcn_global_load_lds((const unsigned*)((const char*)(gbase) + (voff)[_i]), (LAS unsigned*)(lds + (bufoff) + ldsw + _i * 8192), 16, 0, 0); } while (0)
; #define PG8_LDA(dst, b, h) do { _Pragma("unroll") for (int m = 0; m < 4; ++m) _Pragma("unroll") for (int k = 0; k < 2; ++k) dst[m][k] = *(const LAS bf16x8*)(lds + PG8_SA(b, h) + aoff + m * 2048 + k * 1024); } while (0)
; #define PG8_LDB(dst, b, h) do { _Pragma("unroll") for (int n = 0; n < 2; ++n) _Pragma("unroll") for (int k = 0; k < 2; ++k) dst[n][k] = *(const LAS bf16x8*)(lds + PG8_SB(b, h) + boff + n * 2048 + k * 1024); } while (0)
; #define PG8_MMA(ai, bj, At, Bt) do { __builtin_amdgcn_s_setprio(1); _Pragma("unroll") for (int m = 0; m < 4; ++m) _Pragma("unroll") for (int n = 0; n < 2; ++n) _Pragma("unroll") for (int k = 0; k < 2; ++k) \
;         acc[ai][bj][m][n] = __builtin_amdgcn_mfma_f32_16x16x32_bf16(Bt[n][k], At[m][k], acc[ai][bj][m][n], 0, 0, 0); __builtin_amdgcn_s_setprio(0); } while (0)
; #define PG8_WAIT_V(n) asm volatile("s_waitcnt vmcnt(" #n ")" ::: "memory")
; #define PG8_WAIT_L(n) asm volatile("s_waitcnt lgkmcnt(" #n ")" ::: "memory")
; #define PG8_BAR __builtin_amdgcn_s_barrier()
; #define PG8_SCHED __builtin_amdgcn_sched_barrier(0)
; template <class PT, class Epi>
; __device__ __forceinline__ void gemm_phase_once(LAS unsigned char* lds, const PT& S, const Epi& E, bool epi_on) {
;     ...
;             PG8_LDB(B0, 0, 0); PG8_SCHED; PG8_LDA(At, 0, 0); PG8_STAGE(PG8_SA(1, 1), a1 + hstepA, voffA);
;             PG8_WAIT_L(8); PG8_BAR; PG8_WAIT_L(0); PG8_MMA(0, 0, At, B0); PG8_BAR; PG8_SCHED;
;             PG8_LDB(B1, 0, 1); PG8_STAGE(PG8_SB(0, 0), b2, voffB);
;             PG8_BAR; PG8_WAIT_L(0); PG8_MMA(0, 1, At, B1); PG8_BAR;
;             PG8_LDA(At, 0, 1); PG8_STAGE(PG8_SA(0, 0), a2, voffA);
;             PG8_BAR; PG8_WAIT_L(0); PG8_MMA(1, 0, At, B0); PG8_BAR; PG8_SCHED;
;             PG8_STAGE(PG8_SB(0, 1), b2 + hstepB, voffB);
;             PG8_WAIT_V(6); PG8_BAR; PG8_MMA(1, 1, At, B1); PG8_BAR;
.LBB0_4350:
	ds_read_b128 v[36:39], v228
	ds_read_b128 v[40:43], v228 offset:1024
	ds_read_b128 v[158:161], v228 offset:2048
	ds_read_b128 v[168:171], v228 offset:3072
	s_add_u32 s38, s36, 0x100
	s_addc_u32 s39, s37, 0
	s_cmp_eq_u32 s65, 28
	s_cselect_b32 s43, s27, s39
	s_cselect_b32 s42, s35, s38
	s_cselect_b32 s41, s25, s64
	s_cselect_b32 s40, s62, s63
	v_lshl_add_u64 v[162:163], s[36:37], 0, v[150:151]
	s_add_i32 m0, s49, 0xc000
	ds_read_b128 v[172:175], v229
	ds_read_b128 v[176:179], v229 offset:1024
	ds_read_b128 v[180:183], v229 offset:2048
	ds_read_b128 v[184:187], v229 offset:3072
	ds_read_b128 v[188:191], v229 offset:4096
	ds_read_b128 v[192:195], v229 offset:5120
	ds_read_b128 v[196:199], v229 offset:6144
	ds_read_b128 v[200:203], v229 offset:7168
	global_load_lds_dwordx4 v[162:163], off
	v_lshl_add_u64 v[162:163], s[36:37], 0, v[152:153]
	s_add_i32 m0, s49, 0xe000
	s_nop 0
	global_load_lds_dwordx4 v[162:163], off
	s_waitcnt lgkmcnt(8)
	s_barrier
	s_waitcnt lgkmcnt(0)
	s_setprio 1
	s_waitcnt lgkmcnt(0)
	v_mfma_f32_16x16x32_bf16 v[132:135], v[36:39], v[172:175], v[132:135]
	v_mfma_f32_16x16x32_bf16 v[72:75], v[158:161], v[172:175], v[72:75]
	v_mfma_f32_16x16x32_bf16 v[124:127], v[36:39], v[180:183], v[124:127]
	v_mfma_f32_16x16x32_bf16 v[68:71], v[158:161], v[180:183], v[68:71]
	v_mfma_f32_16x16x32_bf16 v[104:107], v[36:39], v[188:191], v[104:107]
	v_mfma_f32_16x16x32_bf16 v[32:35], v[158:161], v[188:191], v[32:35]
	v_mfma_f32_16x16x32_bf16 v[100:103], v[36:39], v[196:199], v[100:103]
	v_mfma_f32_16x16x32_bf16 v[24:27], v[158:161], v[196:199], v[24:27]
	v_mfma_f32_16x16x32_bf16 v[132:135], v[40:43], v[176:179], v[132:135]
	v_mfma_f32_16x16x32_bf16 v[72:75], v[168:171], v[176:179], v[72:75]
	v_mfma_f32_16x16x32_bf16 v[124:127], v[40:43], v[184:187], v[124:127]
	v_mfma_f32_16x16x32_bf16 v[68:71], v[168:171], v[184:187], v[68:71]
	v_mfma_f32_16x16x32_bf16 v[104:107], v[40:43], v[192:195], v[104:107]
	v_mfma_f32_16x16x32_bf16 v[32:35], v[168:171], v[192:195], v[32:35]
	v_mfma_f32_16x16x32_bf16 v[100:103], v[40:43], v[200:203], v[100:103]
	v_mfma_f32_16x16x32_bf16 v[24:27], v[168:171], v[200:203], v[24:27]
	s_setprio 0
	s_barrier
	s_add_i32 s36, s57, s46
	v_lshl_add_u64 v[162:163], s[40:41], 0, v[146:147]
	s_mov_b32 m0, s36
	ds_read_b128 v[204:207], v233
	ds_read_b128 v[208:211], v233 offset:1024
	ds_read_b128 v[212:215], v233 offset:2048
	ds_read_b128 v[216:219], v233 offset:3072
	global_load_lds_dwordx4 v[162:163], off
	v_lshl_add_u64 v[220:221], s[40:41], 0, v[140:141]
	s_add_i32 m0, s36, 0x2000
	s_nop 0
	global_load_lds_dwordx4 v[220:221], off
	s_barrier
	s_waitcnt lgkmcnt(0)
	s_setprio 1
	s_waitcnt lgkmcnt(0)
	v_mfma_f32_16x16x32_bf16 v[120:123], v[204:207], v[172:175], v[120:123]
	v_mfma_f32_16x16x32_bf16 v[64:67], v[212:215], v[172:175], v[64:67]
	v_mfma_f32_16x16x32_bf16 v[116:119], v[204:207], v[180:183], v[116:119]
	v_mfma_f32_16x16x32_bf16 v[60:63], v[212:215], v[180:183], v[60:63]
	v_mfma_f32_16x16x32_bf16 v[96:99], v[204:207], v[188:191], v[96:99]
	v_mfma_f32_16x16x32_bf16 v[28:31], v[212:215], v[188:191], v[28:31]
	v_mfma_f32_16x16x32_bf16 v[92:95], v[204:207], v[196:199], v[92:95]
	v_mfma_f32_16x16x32_bf16 v[20:23], v[212:215], v[196:199], v[20:23]
	v_mfma_f32_16x16x32_bf16 v[120:123], v[208:211], v[176:179], v[120:123]
	v_mfma_f32_16x16x32_bf16 v[64:67], v[216:219], v[176:179], v[64:67]
	v_mfma_f32_16x16x32_bf16 v[116:119], v[208:211], v[184:187], v[116:119]
	v_mfma_f32_16x16x32_bf16 v[60:63], v[216:219], v[184:187], v[60:63]
	v_mfma_f32_16x16x32_bf16 v[96:99], v[208:211], v[192:195], v[96:99]
	v_mfma_f32_16x16x32_bf16 v[28:31], v[216:219], v[192:195], v[28:31]
	v_mfma_f32_16x16x32_bf16 v[92:95], v[208:211], v[200:203], v[92:95]
	v_mfma_f32_16x16x32_bf16 v[20:23], v[216:219], v[200:203], v[20:23]
	s_setprio 0
	s_mov_b32 m0, s49
	v_lshl_add_u64 v[222:223], s[42:43], 0, v[142:143]
	s_barrier
	ds_read_b128 v[172:175], v229 offset:16384
	ds_read_b128 v[176:179], v229 offset:17408
	ds_read_b128 v[180:183], v229 offset:18432
	ds_read_b128 v[184:187], v229 offset:19456
	ds_read_b128 v[188:191], v229 offset:20480
	ds_read_b128 v[192:195], v229 offset:21504
	ds_read_b128 v[196:199], v229 offset:22528
	ds_read_b128 v[200:203], v229 offset:23552
	global_load_lds_dwordx4 v[222:223], off
	v_lshl_add_u64 v[224:225], s[42:43], 0, v[144:145]
	s_mov_b32 m0, s50
	s_nop 0
	global_load_lds_dwordx4 v[224:225], off
	s_barrier
	s_waitcnt lgkmcnt(0)
	s_setprio 1
	s_waitcnt lgkmcnt(0)
	v_mfma_f32_16x16x32_bf16 v[88:91], v[36:39], v[172:175], v[88:91]
	v_mfma_f32_16x16x32_bf16 v[16:19], v[158:161], v[172:175], v[16:19]
	v_mfma_f32_16x16x32_bf16 v[84:87], v[36:39], v[180:183], v[84:87]
	v_mfma_f32_16x16x32_bf16 v[8:11], v[158:161], v[180:183], v[8:11]
	v_mfma_f32_16x16x32_bf16 v[136:139], v[36:39], v[188:191], v[136:139]
	v_mfma_f32_16x16x32_bf16 v[56:59], v[158:161], v[188:191], v[56:59]
	v_mfma_f32_16x16x32_bf16 v[36:39], v[36:39], v[196:199], v[112:115]
	v_mfma_f32_16x16x32_bf16 v[88:91], v[40:43], v[176:179], v[88:91]
	v_mfma_f32_16x16x32_bf16 v[16:19], v[168:171], v[176:179], v[16:19]
	v_mfma_f32_16x16x32_bf16 v[84:87], v[40:43], v[184:187], v[84:87]
	v_mfma_f32_16x16x32_bf16 v[8:11], v[168:171], v[184:187], v[8:11]
	v_mfma_f32_16x16x32_bf16 v[136:139], v[40:43], v[192:195], v[136:139]
	v_mfma_f32_16x16x32_bf16 v[56:59], v[168:171], v[192:195], v[56:59]
	v_mfma_f32_16x16x32_bf16 v[36:39], v[40:43], v[200:203], v[36:39]
	v_mfma_f32_16x16x32_bf16 v[40:43], v[158:161], v[196:199], v[52:55]
	v_mfma_f32_16x16x32_bf16 v[40:43], v[168:171], v[200:203], v[40:43]
	s_setprio 0
	s_barrier
; #define PG8_STAGE(bufoff, gbase, voff) do { _Pragma("unroll") for (int _i = 0; _i < 2; ++_i) \
;         __builtin_amdgcn_global_load_lds((const unsigned*)((const char*)(gbase) + (voff)[_i]), (LAS unsigned*)(lds + (bufoff) + ldsw + _i * 8192), 16, 0, 0); } while (0)
; #define PG8_LDA(dst, b, h) do { _Pragma("unroll") for (int m = 0; m < 4; ++m) _Pragma("unroll") for (int k = 0; k < 2; ++k) dst[m][k] = *(const LAS bf16x8*)(lds + PG8_SA(b, h) + aoff + m * 2048 + k * 1024); } while (0)
; #define PG8_LDB(dst, b, h) do { _Pragma("unroll") for (int n = 0; n < 2; ++n) _Pragma("unroll") for (int k = 0; k < 2; ++k) dst[n][k] = *(const LAS bf16x8*)(lds + PG8_SB(b, h) + boff + n * 2048 + k * 1024); } while (0)
; #define PG8_MMA(ai, bj, At, Bt) do { __builtin_amdgcn_s_setprio(1); _Pragma("unroll") for (int m = 0; m < 4; ++m) _Pragma("unroll") for (int n = 0; n < 2; ++n) _Pragma("unroll") for (int k = 0; k < 2; ++k) \
;         acc[ai][bj][m][n] = __builtin_amdgcn_mfma_f32_16x16x32_bf16(Bt[n][k], At[m][k], acc[ai][bj][m][n], 0, 0, 0); __builtin_amdgcn_s_setprio(0); } while (0)
; #define PG8_WAIT_V(n) asm volatile("s_waitcnt vmcnt(" #n ")" ::: "memory")
; #define PG8_WAIT_L(n) asm volatile("s_waitcnt lgkmcnt(" #n ")" ::: "memory")
; #define PG8_BAR __builtin_amdgcn_s_barrier()
; #define PG8_SCHED __builtin_amdgcn_sched_barrier(0)
; template <class PT, class Epi>
; __device__ __forceinline__ void gemm_phase_once(LAS unsigned char* lds, const PT& S, const Epi& E, bool epi_on) {
;     ...
;             PG8_STAGE(PG8_SB(0, 1), b2 + hstepB, voffB);
;             PG8_WAIT_V(6); PG8_BAR; PG8_MMA(1, 1, At, B1); PG8_BAR;
;             PG8_LDB(B0, 1, 0); PG8_SCHED; PG8_LDA(At, 1, 0); PG8_STAGE(PG8_SA(0, 1), a2 + hstepA, voffA);
;             PG8_WAIT_L(8); PG8_BAR; PG8_WAIT_L(0); PG8_MMA(0, 0, At, B0); PG8_BAR; PG8_SCHED;
;             PG8_LDB(B1, 1, 1); PG8_STAGE(PG8_SB(1, 0), b3, voffB);
;             PG8_BAR; PG8_WAIT_L(0); PG8_MMA(0, 1, At, B1); PG8_BAR;
;             PG8_LDA(At, 1, 1); PG8_STAGE(PG8_SA(1, 0), a3, voffA);
;             PG8_BAR; PG8_WAIT_L(0); PG8_MMA(1, 0, At, B0); PG8_BAR; PG8_SCHED;
	s_add_u32 s36, s40, 0x80000
	s_addc_u32 s37, s41, 0
	s_add_i32 s66, s58, s46
	v_lshl_add_u64 v[52:53], s[36:37], 0, v[146:147]
	s_mov_b32 m0, s66
	s_nop 0
	global_load_lds_dwordx4 v[52:53], off
	v_lshl_add_u64 v[52:53], s[36:37], 0, v[140:141]
	s_add_i32 m0, s66, 0x2000
	s_nop 0
	global_load_lds_dwordx4 v[52:53], off
	s_waitcnt vmcnt(6)
	s_barrier
	s_setprio 1
	v_mfma_f32_16x16x32_bf16 v[52:55], v[204:207], v[172:175], v[80:83]
	v_mfma_f32_16x16x32_bf16 v[80:83], v[208:211], v[176:179], v[52:55]
	v_mfma_f32_16x16x32_bf16 v[52:55], v[204:207], v[180:183], v[76:79]
	v_mfma_f32_16x16x32_bf16 v[76:79], v[208:211], v[184:187], v[52:55]
	v_mfma_f32_16x16x32_bf16 v[52:55], v[204:207], v[188:191], v[128:131]
	v_mfma_f32_16x16x32_bf16 v[12:15], v[212:215], v[172:175], v[12:15]
	v_mfma_f32_16x16x32_bf16 v[4:7], v[212:215], v[180:183], v[4:7]
	v_mfma_f32_16x16x32_bf16 v[128:131], v[208:211], v[192:195], v[52:55]
	v_mfma_f32_16x16x32_bf16 v[48:51], v[212:215], v[188:191], v[48:51]
	v_mfma_f32_16x16x32_bf16 v[52:55], v[204:207], v[196:199], v[108:111]
	v_mfma_f32_16x16x32_bf16 v[44:47], v[212:215], v[196:199], v[44:47]
	v_mfma_f32_16x16x32_bf16 v[12:15], v[216:219], v[176:179], v[12:15]
	v_mfma_f32_16x16x32_bf16 v[4:7], v[216:219], v[184:187], v[4:7]
	v_mfma_f32_16x16x32_bf16 v[48:51], v[216:219], v[192:195], v[48:51]
	v_mfma_f32_16x16x32_bf16 v[108:111], v[208:211], v[200:203], v[52:55]
	v_mfma_f32_16x16x32_bf16 v[44:47], v[216:219], v[200:203], v[44:47]
	s_setprio 0
	s_add_i32 s66, 0, 0x18000
	v_add_u32_e32 v165, s66, v167
	s_barrier
	ds_read_b128 v[52:55], v165
	ds_read_b128 v[112:115], v165 offset:1024
	ds_read_b128 v[158:161], v165 offset:2048
	ds_read_b128 v[168:171], v165 offset:3072
	s_add_u32 s36, s42, 0x4000
	s_addc_u32 s37, s43, 0
	s_mov_b32 m0, s51
	v_lshl_add_u64 v[204:205], s[36:37], 0, v[142:143]
	ds_read_b128 v[172:175], v229 offset:32768
	ds_read_b128 v[176:179], v229 offset:33792
	ds_read_b128 v[180:183], v229 offset:34816
	ds_read_b128 v[184:187], v229 offset:35840
	ds_read_b128 v[188:191], v229 offset:36864
	ds_read_b128 v[192:195], v229 offset:37888
	ds_read_b128 v[196:199], v229 offset:38912
	ds_read_b128 v[200:203], v229 offset:39936
	global_load_lds_dwordx4 v[204:205], off
	v_lshl_add_u64 v[204:205], s[36:37], 0, v[144:145]
	s_mov_b32 m0, s52
	s_nop 0
	global_load_lds_dwordx4 v[204:205], off
	s_waitcnt lgkmcnt(8)
	s_barrier
	s_waitcnt lgkmcnt(0)
	s_setprio 1
	s_waitcnt lgkmcnt(0)
	v_mfma_f32_16x16x32_bf16 v[132:135], v[52:55], v[172:175], v[132:135]
	v_mfma_f32_16x16x32_bf16 v[72:75], v[158:161], v[172:175], v[72:75]
	v_mfma_f32_16x16x32_bf16 v[124:127], v[52:55], v[180:183], v[124:127]
	v_mfma_f32_16x16x32_bf16 v[68:71], v[158:161], v[180:183], v[68:71]
	v_mfma_f32_16x16x32_bf16 v[104:107], v[52:55], v[188:191], v[104:107]
	v_mfma_f32_16x16x32_bf16 v[32:35], v[158:161], v[188:191], v[32:35]
	v_mfma_f32_16x16x32_bf16 v[100:103], v[52:55], v[196:199], v[100:103]
	v_mfma_f32_16x16x32_bf16 v[24:27], v[158:161], v[196:199], v[24:27]
	v_mfma_f32_16x16x32_bf16 v[132:135], v[112:115], v[176:179], v[132:135]
	v_mfma_f32_16x16x32_bf16 v[72:75], v[168:171], v[176:179], v[72:75]
	v_mfma_f32_16x16x32_bf16 v[124:127], v[112:115], v[184:187], v[124:127]
	v_mfma_f32_16x16x32_bf16 v[68:71], v[168:171], v[184:187], v[68:71]
	v_mfma_f32_16x16x32_bf16 v[104:107], v[112:115], v[192:195], v[104:107]
	v_mfma_f32_16x16x32_bf16 v[32:35], v[168:171], v[192:195], v[32:35]
	v_mfma_f32_16x16x32_bf16 v[100:103], v[112:115], v[200:203], v[100:103]
	v_mfma_f32_16x16x32_bf16 v[24:27], v[168:171], v[200:203], v[24:27]
	s_setprio 0
	s_barrier
	s_add_i32 s42, 0, 0x1c000
	s_add_i32 s36, s66, s46
	v_add_u32_e32 v165, s42, v167
	v_lshl_add_u64 v[162:163], v[162:163], 0, s[10:11]
	s_mov_b32 m0, s36
	ds_read_b128 v[204:207], v165
	ds_read_b128 v[208:211], v165 offset:1024
	ds_read_b128 v[212:215], v165 offset:2048
	ds_read_b128 v[216:219], v165 offset:3072
	global_load_lds_dwordx4 v[162:163], off
	v_lshl_add_u64 v[162:163], v[220:221], 0, s[10:11]
	s_add_i32 m0, s36, 0x2000
	s_nop 0
	global_load_lds_dwordx4 v[162:163], off
	s_barrier
	s_waitcnt lgkmcnt(0)
	s_setprio 1
	s_waitcnt lgkmcnt(0)
	v_mfma_f32_16x16x32_bf16 v[120:123], v[204:207], v[172:175], v[120:123]
	v_mfma_f32_16x16x32_bf16 v[64:67], v[212:215], v[172:175], v[64:67]
	v_mfma_f32_16x16x32_bf16 v[116:119], v[204:207], v[180:183], v[116:119]
	v_mfma_f32_16x16x32_bf16 v[60:63], v[212:215], v[180:183], v[60:63]
	v_mfma_f32_16x16x32_bf16 v[96:99], v[204:207], v[188:191], v[96:99]
	v_mfma_f32_16x16x32_bf16 v[28:31], v[212:215], v[188:191], v[28:31]
	v_mfma_f32_16x16x32_bf16 v[92:95], v[204:207], v[196:199], v[92:95]
	v_mfma_f32_16x16x32_bf16 v[20:23], v[212:215], v[196:199], v[20:23]
	v_mfma_f32_16x16x32_bf16 v[120:123], v[208:211], v[176:179], v[120:123]
	v_mfma_f32_16x16x32_bf16 v[64:67], v[216:219], v[176:179], v[64:67]
	v_mfma_f32_16x16x32_bf16 v[116:119], v[208:211], v[184:187], v[116:119]
	v_mfma_f32_16x16x32_bf16 v[60:63], v[216:219], v[184:187], v[60:63]
	v_mfma_f32_16x16x32_bf16 v[96:99], v[208:211], v[192:195], v[96:99]
	v_mfma_f32_16x16x32_bf16 v[28:31], v[216:219], v[192:195], v[28:31]
	v_mfma_f32_16x16x32_bf16 v[92:95], v[208:211], v[200:203], v[92:95]
	v_mfma_f32_16x16x32_bf16 v[20:23], v[216:219], v[200:203], v[20:23]
	s_setprio 0
	s_mov_b32 m0, s54
	v_lshl_add_u64 v[162:163], v[222:223], 0, s[10:11]
	s_barrier
	ds_read_b128 v[172:175], v229 offset:49152
	ds_read_b128 v[176:179], v229 offset:50176
	ds_read_b128 v[180:183], v229 offset:51200
	ds_read_b128 v[184:187], v229 offset:52224
	ds_read_b128 v[188:191], v229 offset:53248
	ds_read_b128 v[192:195], v229 offset:54272
	ds_read_b128 v[196:199], v229 offset:55296
	ds_read_b128 v[200:203], v229 offset:56320
	global_load_lds_dwordx4 v[162:163], off
	v_lshl_add_u64 v[162:163], v[224:225], 0, s[10:11]
	s_mov_b32 m0, s55
	s_nop 0
	global_load_lds_dwordx4 v[162:163], off
	s_barrier
; __device__ __forceinline__ unsigned pk2(float lo, float hi) { return f2bf(lo) | (f2bf(hi) << 16); }
; #define PG8_STAGE(bufoff, gbase, voff) do { _Pragma("unroll") for (int _i = 0; _i < 2; ++_i) \
;         __builtin_amdgcn_global_load_lds((const unsigned*)((const char*)(gbase) + (voff)[_i]), (LAS unsigned*)(lds + (bufoff) + ldsw + _i * 8192), 16, 0, 0); } while (0)
; #define PG8_WAIT_V(n) asm volatile("s_waitcnt vmcnt(" #n ")" ::: "memory")
; #define PG8_BAR __builtin_amdgcn_s_barrier()
; template <class PT, class Epi>
; __device__ __forceinline__ void gemm_phase_once(LAS unsigned char* lds, const PT& S, const Epi& E, bool epi_on) {
;     ...
;             PG8_BAR; PG8_WAIT_L(0); PG8_MMA(1, 0, At, B0); PG8_BAR; PG8_SCHED;
;             PG8_STAGE(PG8_SB(1, 1), b3 + hstepB, voffB);
;             PG8_WAIT_V(6); PG8_BAR; PG8_MMA(1, 1, At, B1); PG8_BAR;
;     __device__ __forceinline__ void operator()(const f32x4 (&acc)[2][2][4][2], const pg8::Unit& u, int wr, int wc, int fr, int fq) const {
;         const int ch0 = 128 * u.pn + 32 * wc + 8 * fq, tok0 = 256 * u.pm + 128 * wr + 8 * fr;
;         const f32x4 r0 = *(const f32x4*)(RS + tok0), r1 = *(const f32x4*)(RS + tok0 + 4);
;         bf16* hb = HALO + ((size_t)((u.pm * 44 + u.pn) * 2 + wr) * 4) * 256 + 32 * wc + 8 * fq;
; #pragma unroll
;         for (int n = 0; n < 2; ++n) {
;             float g[8][4], v[8][4];
; #pragma unroll
;             for (int e = 0; e < 8; ++e) { const float rs = (e < 4) ? r0[e & 3] : r1[e & 3];
; #pragma unroll
;                 for (int jj = 0; jj < 4; ++jj) { g[e][jj] = acc[e >> 2][0][e & 3][n][jj] * rs; v[e][jj] = acc[e >> 2][1][e & 3][n][jj] * rs; } }
;             if (fr == 0) {
; #pragma unroll
;                 for (int q = 0; q < 2; ++q) { v2u a, b; a.x = pk2(g[q][0], g[q][1]); a.y = pk2(g[q][2], g[q][3]); b.x = pk2(v[q][0], v[q][1]); b.y = pk2(v[q][2], v[q][3]);
;                     *(v2u*)(hb + (size_t)q * 256 + 4 * n) = a; *(v2u*)(hb + (size_t)q * 256 + 128 + 4 * n) = b; } }
;             if (fr == 15) {
; #pragma unroll
;                 for (int q = 0; q < 2; ++q) { v2u a, b; a.x = pk2(g[6 + q][0], g[6 + q][1]); a.y = pk2(g[6 + q][2], g[6 + q][3]); b.x = pk2(v[6 + q][0], v[6 + q][1]); b.y = pk2(v[6 + q][2], v[6 + q][3]);
;                     *(v2u*)(hb + (size_t)(2 + q) * 256 + 4 * n) = a; *(v2u*)(hb + (size_t)(2 + q) * 256 + 128 + 4 * n) = b; } }
	s_waitcnt lgkmcnt(0)
	s_setprio 1
	s_waitcnt lgkmcnt(0)
	v_mfma_f32_16x16x32_bf16 v[88:91], v[52:55], v[172:175], v[88:91]
	v_mfma_f32_16x16x32_bf16 v[84:87], v[52:55], v[180:183], v[84:87]
	v_mfma_f32_16x16x32_bf16 v[136:139], v[52:55], v[188:191], v[136:139]
	v_mfma_f32_16x16x32_bf16 v[36:39], v[52:55], v[196:199], v[36:39]
	v_mfma_f32_16x16x32_bf16 v[88:91], v[112:115], v[176:179], v[88:91]
	v_mfma_f32_16x16x32_bf16 v[16:19], v[158:161], v[172:175], v[16:19]
	v_mfma_f32_16x16x32_bf16 v[84:87], v[112:115], v[184:187], v[84:87]
	v_mfma_f32_16x16x32_bf16 v[8:11], v[158:161], v[180:183], v[8:11]
	v_mfma_f32_16x16x32_bf16 v[136:139], v[112:115], v[192:195], v[136:139]
	v_mfma_f32_16x16x32_bf16 v[56:59], v[158:161], v[188:191], v[56:59]
	v_mfma_f32_16x16x32_bf16 v[112:115], v[112:115], v[200:203], v[36:39]
	v_mfma_f32_16x16x32_bf16 v[36:39], v[158:161], v[196:199], v[40:43]
	v_mfma_f32_16x16x32_bf16 v[16:19], v[168:171], v[176:179], v[16:19]
	v_mfma_f32_16x16x32_bf16 v[8:11], v[168:171], v[184:187], v[8:11]
	v_mfma_f32_16x16x32_bf16 v[56:59], v[168:171], v[192:195], v[56:59]
	v_mfma_f32_16x16x32_bf16 v[52:55], v[168:171], v[200:203], v[36:39]
	s_setprio 0
	s_barrier
	s_add_u32 s36, s40, 0x80080
	s_addc_u32 s37, s41, 0
	s_add_i32 s40, s42, s46
	v_lshl_add_u64 v[36:37], s[36:37], 0, v[146:147]
	s_mov_b32 m0, s40
	s_nop 0
	global_load_lds_dwordx4 v[36:37], off
	v_lshl_add_u64 v[36:37], s[36:37], 0, v[140:141]
	s_add_i32 m0, s40, 0x2000
	s_nop 0
	global_load_lds_dwordx4 v[36:37], off
	s_waitcnt vmcnt(6)
	s_barrier
	s_setprio 1
	v_mfma_f32_16x16x32_bf16 v[36:39], v[204:207], v[172:175], v[80:83]
	v_mfma_f32_16x16x32_bf16 v[80:83], v[208:211], v[176:179], v[36:39]
	v_mfma_f32_16x16x32_bf16 v[36:39], v[204:207], v[180:183], v[76:79]
	v_mfma_f32_16x16x32_bf16 v[76:79], v[208:211], v[184:187], v[36:39]
	v_mfma_f32_16x16x32_bf16 v[36:39], v[204:207], v[188:191], v[128:131]
	v_mfma_f32_16x16x32_bf16 v[128:131], v[208:211], v[192:195], v[36:39]
	v_mfma_f32_16x16x32_bf16 v[36:39], v[212:215], v[188:191], v[48:51]
	v_mfma_f32_16x16x32_bf16 v[48:51], v[216:219], v[192:195], v[36:39]
	v_mfma_f32_16x16x32_bf16 v[36:39], v[204:207], v[196:199], v[108:111]
	v_mfma_f32_16x16x32_bf16 v[12:15], v[212:215], v[172:175], v[12:15]
	v_mfma_f32_16x16x32_bf16 v[4:7], v[212:215], v[180:183], v[4:7]
	v_mfma_f32_16x16x32_bf16 v[108:111], v[208:211], v[200:203], v[36:39]
	v_mfma_f32_16x16x32_bf16 v[36:39], v[212:215], v[196:199], v[44:47]
	v_mfma_f32_16x16x32_bf16 v[12:15], v[216:219], v[176:179], v[12:15]
	v_mfma_f32_16x16x32_bf16 v[4:7], v[216:219], v[184:187], v[4:7]
	v_mfma_f32_16x16x32_bf16 v[44:47], v[216:219], v[200:203], v[36:39]
	s_setprio 0
	s_add_i32 s65, s65, 2
	s_add_u32 s63, s63, 0x100
	s_addc_u32 s64, s64, 0
	s_cmp_lt_u32 s65, 30
	s_mov_b64 s[36:37], s[38:39]
	s_barrier
	s_cbranch_scc1 .LBB0_4350
	v_lshl_add_u32 v160, s34, 8, v226
	v_ashrrev_i32_e32 v161, 31, v160
	v_lshl_add_u64 v[40:41], v[160:161], 2, s[90:91]
	global_load_dwordx4 v[36:39], v[40:41], off offset:16
	s_nop 0
	global_load_dwordx4 v[40:43], v[40:41], off
	s_mul_i32 s25, s34, 44
	s_add_i32 s25, s25, s61
	s_lshl_b32 s25, s25, 1
	s_add_i32 s34, s25, s45
	s_ashr_i32 s35, s34, 31
	v_mov_b32_e32 v162, v136
	v_mov_b32_e32 v163, v138
	s_lshl_b64 s[34:35], s[34:35], 11
	v_mov_b32_e32 v138, v137
	v_lshl_add_u64 v[158:159], v[148:149], 0, s[34:35]
	v_cmp_lt_i32_e32 vcc, 14, v3
	s_mov_b64 s[34:35], 0
	s_waitcnt vmcnt(0)
	v_pk_mul_f32 v[168:169], v[162:163], v[38:39] op_sel_hi:[1,0]
	v_mov_b32_e32 v162, v128
	v_mov_b32_e32 v163, v130
	v_mov_b32_e32 v130, v129
	v_pk_mul_f32 v[162:163], v[162:163], v[38:39] op_sel_hi:[1,0]
	v_pk_mul_f32 v[136:137], v[138:139], v[38:39] op_sel_hi:[1,0]
	v_pk_mul_f32 v[130:131], v[130:131], v[38:39] op_sel_hi:[1,0]
	s_and_saveexec_b64 s[36:37], vcc
	s_xor_b64 s[36:37], exec, s[36:37]
	s_cbranch_execz .LBB0_4353
	v_and_b32_sdwa v138, v137, v234 dst_sel:DWORD dst_unused:UNUSED_PAD src0_sel:WORD_1 src1_sel:DWORD
	v_and_b32_sdwa v139, v136, v234 dst_sel:DWORD dst_unused:UNUSED_PAD src0_sel:WORD_1 src1_sel:DWORD
	v_and_b32_sdwa v128, v169, v234 dst_sel:DWORD dst_unused:UNUSED_PAD src0_sel:WORD_1 src1_sel:DWORD
	v_and_b32_sdwa v129, v168, v234 dst_sel:DWORD dst_unused:UNUSED_PAD src0_sel:WORD_1 src1_sel:DWORD
	v_add3_u32 v138, v137, v138, s59
	v_add3_u32 v139, v136, v139, s59
	v_add3_u32 v129, v168, v129, s59
	v_add3_u32 v128, v169, v128, s59
	v_and_b32_e32 v138, 0xffff0000, v138
	v_and_b32_e32 v161, 0xffff0000, v139
	v_or_b32_sdwa v139, v138, v128 dst_sel:DWORD dst_unused:UNUSED_PAD src0_sel:DWORD src1_sel:WORD_1
	v_or_b32_sdwa v138, v161, v129 dst_sel:DWORD dst_unused:UNUSED_PAD src0_sel:DWORD src1_sel:WORD_1
	v_and_b32_sdwa v129, v162, v234 dst_sel:DWORD dst_unused:UNUSED_PAD src0_sel:WORD_1 src1_sel:DWORD
	v_add3_u32 v161, v162, v129, s59
	s_nop 0
	v_and_b32_sdwa v165, v130, v234 dst_sel:DWORD dst_unused:UNUSED_PAD src0_sel:WORD_1 src1_sel:DWORD
	s_nop 1
	v_add3_u32 v165, v130, v165, s59
	s_nop 1
	v_and_b32_e32 v165, 0xffff0000, v165
	s_mov_b64 s[34:35], exec
	v_cvt_pk_bf16_f32 v129, v163, v131
	v_or_b32_sdwa v128, v165, v161 dst_sel:DWORD dst_unused:UNUSED_PAD src0_sel:DWORD src1_sel:WORD_1
	global_store_dwordx2 v[158:159], v[138:139], off offset:1024
; __device__ __forceinline__ unsigned pk2(float lo, float hi) { return f2bf(lo) | (f2bf(hi) << 16); }
;     __device__ __forceinline__ void operator()(const f32x4 (&acc)[2][2][4][2], const pg8::Unit& u, int wr, int wc, int fr, int fq) const {
;     ...
;             for (int e = 0; e < 8; ++e) { const float rs = (e < 4) ? r0[e & 3] : r1[e & 3];
; #pragma unroll
;                 for (int jj = 0; jj < 4; ++jj) { g[e][jj] = acc[e >> 2][0][e & 3][n][jj] * rs; v[e][jj] = acc[e >> 2][1][e & 3][n][jj] * rs; } }
;             if (fr == 0) {
; #pragma unroll
;                 for (int q = 0; q < 2; ++q) { v2u a, b; a.x = pk2(g[q][0], g[q][1]); a.y = pk2(g[q][2], g[q][3]); b.x = pk2(v[q][0], v[q][1]); b.y = pk2(v[q][2], v[q][3]);
;                     *(v2u*)(hb + (size_t)q * 256 + 4 * n) = a; *(v2u*)(hb + (size_t)q * 256 + 128 + 4 * n) = b; } }
.LBB0_4353:
	s_or_saveexec_b64 s[36:37], s[36:37]
	v_mov_b32_e32 v138, v132
	v_mov_b32_e32 v139, v134
	v_pk_mul_f32 v[190:191], v[138:139], v[40:41] op_sel_hi:[1,0]
	v_mov_b32_e32 v138, v120
	v_mov_b32_e32 v139, v122
	v_mov_b32_e32 v122, v121
	v_mov_b32_e32 v120, v124
	v_mov_b32_e32 v121, v126
	v_pk_mul_f32 v[182:183], v[120:121], v[40:41] op_sel:[0,1]
	v_mov_b32_e32 v120, v116
	v_mov_b32_e32 v121, v118
	v_mov_b32_e32 v118, v117
	v_mov_b32_e32 v116, v112
	v_mov_b32_e32 v117, v114
	v_mov_b32_e32 v112, v39
	v_mov_b32_e32 v134, v133
	v_pk_mul_f32 v[170:171], v[116:117], v[112:113] op_sel_hi:[1,0]
	v_mov_b32_e32 v116, v108
	v_mov_b32_e32 v117, v110
	v_mov_b32_e32 v114, v113
	v_mov_b32_e32 v110, v109
	v_pk_mul_f32 v[188:189], v[138:139], v[40:41] op_sel_hi:[1,0]
	v_pk_mul_f32 v[192:193], v[134:135], v[40:41] op_sel_hi:[1,0]
	v_mov_b32_e32 v126, v125
	v_pk_mul_f32 v[134:135], v[116:117], v[112:113] op_sel_hi:[1,0]
	v_pk_mul_f32 v[172:173], v[114:115], v[112:113] op_sel_hi:[1,0]
	v_pk_mul_f32 v[138:139], v[110:111], v[112:113] op_sel_hi:[1,0]
	v_pk_mul_f32 v[186:187], v[122:123], v[40:41] op_sel_hi:[1,0]
	v_pk_mul_f32 v[180:181], v[120:121], v[40:41] op_sel:[0,1]
	v_pk_mul_f32 v[184:185], v[126:127], v[40:41] op_sel:[0,1]
	v_pk_mul_f32 v[178:179], v[118:119], v[40:41] op_sel:[0,1]
	v_mov_b64_e32 v[116:117], 0x500
	v_mov_b64_e32 v[110:111], 0x600
	v_mov_b64_e32 v[108:109], 0x700
	v_mov_b64_e32 v[120:121], v[170:171]
	v_mov_b64_e32 v[118:119], v[172:173]
	v_mov_b64_e32 v[112:113], v[134:135]
	v_mov_b64_e32 v[114:115], v[138:139]
	s_xor_b64 exec, exec, s[36:37]
	s_cbranch_execz .LBB0_4357
	v_cmp_eq_u32_e32 vcc, 0, v3
	s_mov_b64 s[40:41], s[34:35]
	s_and_saveexec_b64 s[38:39], vcc
	s_cbranch_execz .LBB0_4356
	v_and_b32_sdwa v109, v190, v234 dst_sel:DWORD dst_unused:UNUSED_PAD src0_sel:WORD_1 src1_sel:DWORD
	v_add3_u32 v110, v190, v109, s59
	s_nop 0
	v_and_b32_sdwa v111, v192, v234 dst_sel:DWORD dst_unused:UNUSED_PAD src0_sel:WORD_1 src1_sel:DWORD
	s_nop 1
	v_add3_u32 v111, v192, v111, s59
	s_nop 1
	v_and_b32_e32 v111, 0xffff0000, v111
	v_and_b32_sdwa v112, v187, v234 dst_sel:DWORD dst_unused:UNUSED_PAD src0_sel:WORD_1 src1_sel:DWORD
	v_and_b32_sdwa v113, v186, v234 dst_sel:DWORD dst_unused:UNUSED_PAD src0_sel:WORD_1 src1_sel:DWORD
	v_cvt_pk_bf16_f32 v109, v191, v193
	v_or_b32_sdwa v108, v111, v110 dst_sel:DWORD dst_unused:UNUSED_PAD src0_sel:DWORD src1_sel:WORD_1
	v_and_b32_sdwa v110, v189, v234 dst_sel:DWORD dst_unused:UNUSED_PAD src0_sel:WORD_1 src1_sel:DWORD
	v_and_b32_sdwa v111, v188, v234 dst_sel:DWORD dst_unused:UNUSED_PAD src0_sel:WORD_1 src1_sel:DWORD
	v_add3_u32 v112, v187, v112, s59
	v_add3_u32 v113, v186, v113, s59
	v_add3_u32 v111, v188, v111, s59
	v_add3_u32 v110, v189, v110, s59
	v_and_b32_e32 v112, 0xffff0000, v112
	v_and_b32_e32 v113, 0xffff0000, v113
	v_or_b32_sdwa v129, v112, v110 dst_sel:DWORD dst_unused:UNUSED_PAD src0_sel:DWORD src1_sel:WORD_1
	v_or_b32_sdwa v128, v113, v111 dst_sel:DWORD dst_unused:UNUSED_PAD src0_sel:DWORD src1_sel:WORD_1
	s_or_b64 s[40:41], s[34:35], exec
	global_store_dwordx2 v[158:159], v[108:109], off

; __device__ __forceinline__ unsigned pk2(float lo, float hi) { return f2bf(lo) | (f2bf(hi) << 16); }
; __device__ __forceinline__ float dpp_shr1(float x) { return __builtin_bit_cast(float, __builtin_amdgcn_update_dpp(0, __builtin_bit_cast(int, x), 0x111, 0xf, 0xf, true)); }
;     __device__ __forceinline__ void operator()(const f32x4 (&acc)[2][2][4][2], const pg8::Unit& u, int wr, int wc, int fr, int fq) const {
;     ...
;             if (fr == 0) {
; #pragma unroll
;                 for (int q = 0; q < 2; ++q) { v2u a, b; a.x = pk2(g[q][0], g[q][1]); a.y = pk2(g[q][2], g[q][3]); b.x = pk2(v[q][0], v[q][1]); b.y = pk2(v[q][2], v[q][3]);
;                     *(v2u*)(hb + (size_t)q * 256 + 4 * n) = a; *(v2u*)(hb + (size_t)q * 256 + 128 + 4 * n) = b; } }
;             if (fr == 15) {
; #pragma unroll
;                 for (int q = 0; q < 2; ++q) { v2u a, b; a.x = pk2(g[6 + q][0], g[6 + q][1]); a.y = pk2(g[6 + q][2], g[6 + q][3]); b.x = pk2(v[6 + q][0], v[6 + q][1]); b.y = pk2(v[6 + q][2], v[6 + q][3]);
;                     *(v2u*)(hb + (size_t)(2 + q) * 256 + 4 * n) = a; *(v2u*)(hb + (size_t)(2 + q) * 256 + 128 + 4 * n) = b; } }
;             const int cc = ch0 + 4 * n;
;             const f32x4 wg0 = *(CF4)(cw + cc), wg1 = *(CF4)(cw + FF2 + cc), wg2 = *(CF4)(cw + 2 * FF2 + cc), wv0 = *(CF4)(cw + FFH + cc), wv1 = *(CF4)(cw + FF2 + FFH + cc), wv2 = *(CF4)(cw + 2 * FF2 + FFH + cc);
;             const f32x4 bg = *(CF4)(cb + cc), bv = *(CF4)(cb + FFH + cc);
; #pragma unroll
;             for (int jj = 0; jj < 4; ++jj) {
;                 float g2 = dpp_shr1(g[6][jj]), g1 = dpp_shr1(g[7][jj]), v2 = dpp_shr1(v[6][jj]), v1 = dpp_shr1(v[7][jj]);
.LBB0_4357:
	s_or_b64 exec, exec, s[36:37]
	s_and_saveexec_b64 s[36:37], s[34:35]
	s_cbranch_execz .LBB0_4359
	v_lshl_add_u64 v[116:117], v[158:159], 0, v[116:117]
	global_store_dwordx2 v[116:117], v[128:129], off
	v_and_b32_sdwa v116, v121, v234 dst_sel:DWORD dst_unused:UNUSED_PAD src0_sel:WORD_1 src1_sel:DWORD
	v_and_b32_sdwa v117, v120, v234 dst_sel:DWORD dst_unused:UNUSED_PAD src0_sel:WORD_1 src1_sel:DWORD
	v_add3_u32 v120, v120, v117, s59
	v_add3_u32 v116, v121, v116, s59
	v_and_b32_sdwa v117, v119, v234 dst_sel:DWORD dst_unused:UNUSED_PAD src0_sel:WORD_1 src1_sel:DWORD
	v_and_b32_sdwa v121, v118, v234 dst_sel:DWORD dst_unused:UNUSED_PAD src0_sel:WORD_1 src1_sel:DWORD
	v_add3_u32 v117, v119, v117, s59
	v_add3_u32 v118, v118, v121, s59
	v_and_b32_e32 v117, 0xffff0000, v117
	v_and_b32_e32 v118, 0xffff0000, v118
	v_or_b32_sdwa v117, v117, v116 dst_sel:DWORD dst_unused:UNUSED_PAD src0_sel:DWORD src1_sel:WORD_1
	v_or_b32_sdwa v116, v118, v120 dst_sel:DWORD dst_unused:UNUSED_PAD src0_sel:DWORD src1_sel:WORD_1
	s_nop 7
	s_nop 1
	v_cvt_pk_bf16_f32 v113, v113, v115
	v_cvt_pk_bf16_f32 v112, v112, v114
	v_lshl_add_u64 v[110:111], v[158:159], 0, v[110:111]
	v_lshl_add_u64 v[108:109], v[158:159], 0, v[108:109]
	global_store_dwordx2 v[110:111], v[116:117], off
	global_store_dwordx2 v[108:109], v[112:113], off
.LBB0_4359:
	s_or_b64 exec, exec, s[36:37]
	v_lshl_or_b32 v132, s61, 7, v227
	v_ashrrev_i32_e32 v133, 31, v132
	v_lshlrev_b64 v[194:195], 2, v[132:133]
	v_lshl_add_u64 v[108:109], s[6:7], 0, v[194:195]
	v_lshl_add_u64 v[112:113], s[8:9], 0, v[194:195]
	global_load_dwordx4 v[108:111], v[108:109], off
	v_mov_b32_e32 v166, v43
	global_load_dwordx4 v[116:119], v[112:113], off
	v_lshl_add_u64 v[112:113], s[12:13], 0, v[194:195]
	global_load_dwordx4 v[120:123], v[112:113], off
	v_lshl_add_u64 v[112:113], s[14:15], 0, v[194:195]
	global_load_dwordx4 v[124:127], v[112:113], off
	v_mov_b32_e32 v112, v104
	v_mov_b32_e32 v113, v106
	v_pk_mul_f32 v[224:225], v[112:113], v[42:43] op_sel_hi:[1,0]
	v_mov_b32_e32 v112, v96
	v_mov_b32_e32 v113, v98
	v_mov_b32_e32 v98, v97
	v_lshl_add_u64 v[96:97], s[16:17], 0, v[194:195]
	v_pk_mul_f32 v[218:219], v[98:99], v[42:43] op_sel_hi:[1,0]
	global_load_dwordx4 v[96:99], v[96:97], off
	v_pk_mul_f32 v[220:221], v[112:113], v[42:43] op_sel_hi:[1,0]
	v_mov_b32_e32 v106, v105
	v_mov_b32_e32 v112, v100
	v_mov_b32_e32 v113, v102
	v_lshl_add_u64 v[104:105], s[22:23], 0, v[194:195]
	v_pk_mul_f32 v[222:223], v[106:107], v[42:43] op_sel_hi:[1,0]
	global_load_dwordx4 v[104:107], v[104:105], off
	v_pk_mul_f32 v[214:215], v[112:113], v[166:167] op_sel_hi:[1,0]
	v_lshl_add_u64 v[112:113], s[18:19], 0, v[194:195]
	global_load_dwordx4 v[112:115], v[112:113], off
	v_mov_b32_e32 v102, v101
	v_lshl_add_u64 v[100:101], s[20:21], 0, v[194:195]
	v_pk_mul_f32 v[216:217], v[102:103], v[166:167] op_sel_hi:[1,0]
	global_load_dwordx4 v[100:103], v[100:101], off
	v_mov_b32_e32 v199, v94
	v_mov_b32_e32 v94, v93
	v_mov_b32_e32 v196, v36
	v_mov_b32_e32 v197, v37
	v_pk_mul_f32 v[206:207], v[94:95], v[166:167] op_sel_hi:[1,0]
	v_mov_b32_e32 v94, v88
	v_mov_b32_e32 v95, v90
	v_pk_mul_f32 v[202:203], v[94:95], v[196:197] op_sel_hi:[1,0]
	v_mov_b32_e32 v94, v80
	v_mov_b32_e32 v95, v82
	v_mov_b32_e32 v82, v81
	v_mov_b32_e32 v80, v84
	v_mov_b32_e32 v81, v86
	v_mov_b32_e32 v90, v89
	v_pk_mul_f32 v[88:89], v[80:81], v[196:197] op_sel:[0,1]
	v_mov_b32_e32 v81, v78
	v_mov_b32_e32 v86, v85
	v_mov_b32_e32 v78, v77
	v_pk_mul_f32 v[194:195], v[94:95], v[196:197] op_sel_hi:[1,0]
	v_mov_b32_e32 v80, v76
	v_pk_mul_f32 v[84:85], v[86:87], v[196:197] op_sel:[0,1]
	v_pk_mul_f32 v[76:77], v[78:79], v[196:197] op_sel:[0,1]
	v_mov_b32_dpp v78, v168 row_shr:1 row_mask:0xf bank_mask:0xf bound_ctrl:1
	v_mov_b32_dpp v79, v169 row_shr:1 row_mask:0xf bank_mask:0xf bound_ctrl:1
	v_mov_b32_e32 v198, v92
	v_pk_mul_f32 v[200:201], v[90:91], v[196:197] op_sel_hi:[1,0]
	v_pk_mul_f32 v[90:91], v[82:83], v[196:197] op_sel_hi:[1,0]
	v_pk_mul_f32 v[82:83], v[80:81], v[196:197] op_sel:[0,1]
	v_mov_b32_dpp v80, v170 row_shr:1 row_mask:0xf bank_mask:0xf bound_ctrl:1
	v_mov_b32_dpp v81, v171 row_shr:1 row_mask:0xf bank_mask:0xf bound_ctrl:1
	v_pk_mul_f32 v[208:209], v[198:199], v[166:167] op_sel_hi:[1,0]
	v_mov_b32_dpp v210, v136 row_shr:1 row_mask:0xf bank_mask:0xf bound_ctrl:1
	v_mov_b32_dpp v211, v137 row_shr:1 row_mask:0xf bank_mask:0xf bound_ctrl:1
	v_mov_b32_dpp v238, v172 row_shr:1 row_mask:0xf bank_mask:0xf bound_ctrl:1
	v_mov_b32_dpp v239, v173 row_shr:1 row_mask:0xf bank_mask:0xf bound_ctrl:1
	v_mov_b32_dpp v204, v162 row_shr:1 row_mask:0xf bank_mask:0xf bound_ctrl:1
	v_mov_b32_dpp v205, v163 row_shr:1 row_mask:0xf bank_mask:0xf bound_ctrl:1
	v_mov_b32_dpp v236, v134 row_shr:1 row_mask:0xf bank_mask:0xf bound_ctrl:1
	v_mov_b32_dpp v237, v135 row_shr:1 row_mask:0xf bank_mask:0xf bound_ctrl:1
	v_mov_b32_dpp v212, v130 row_shr:1 row_mask:0xf bank_mask:0xf bound_ctrl:1
	v_mov_b32_dpp v213, v131 row_shr:1 row_mask:0xf bank_mask:0xf bound_ctrl:1
	v_mov_b32_dpp v240, v138 row_shr:1 row_mask:0xf bank_mask:0xf bound_ctrl:1
	v_mov_b32_dpp v241, v139 row_shr:1 row_mask:0xf bank_mask:0xf bound_ctrl:1
	v_mov_b32_e32 v174, v40
	v_mov_b32_e32 v175, v40
	v_mov_b32_e32 v40, v41
	v_mov_b32_e32 v176, v38
	v_mov_b32_e32 v177, v38
	v_mov_b32_e32 v38, v39
	v_mov_b32_e32 v128, v42
	s_waitcnt vmcnt(0)
; __device__ __forceinline__ unsigned pk2(float lo, float hi) { return f2bf(lo) | (f2bf(hi) << 16); }
; __device__ __forceinline__ float silu_fast(float x) { return x * __builtin_amdgcn_rcpf(1.f + __builtin_amdgcn_exp2f(-1.4426950408889634f * x)); }
; __device__ __forceinline__ float dpp_shr1(float x) { return __builtin_bit_cast(float, __builtin_amdgcn_update_dpp(0, __builtin_bit_cast(int, x), 0x111, 0xf, 0xf, true)); }
;     __device__ __forceinline__ void operator()(const f32x4 (&acc)[2][2][4][2], const pg8::Unit& u, int wr, int wc, int fr, int fq) const {
;     ...
;             const int cc = ch0 + 4 * n;
;             const f32x4 wg0 = *(CF4)(cw + cc), wg1 = *(CF4)(cw + FF2 + cc), wg2 = *(CF4)(cw + 2 * FF2 + cc), wv0 = *(CF4)(cw + FFH + cc), wv1 = *(CF4)(cw + FF2 + FFH + cc), wv2 = *(CF4)(cw + 2 * FF2 + FFH + cc);
;             const f32x4 bg = *(CF4)(cb + cc), bv = *(CF4)(cb + FFH + cc);
; #pragma unroll
;             for (int jj = 0; jj < 4; ++jj) {
;                 float g2 = dpp_shr1(g[6][jj]), g1 = dpp_shr1(g[7][jj]), v2 = dpp_shr1(v[6][jj]), v1 = dpp_shr1(v[7][jj]);
; #pragma unroll
;                 for (int e = 0; e < 8; ++e) { const float g0 = g[e][jj], v0 = v[e][jj];
;                     const float cg = bg[jj] + wg0[jj] * g2 + wg1[jj] * g1 + wg2[jj] * g0, cv = bv[jj] + wv0[jj] * v2 + wv1[jj] * v1 + wv2[jj] * v0;
;                     g[e][jj] = silu_fast(cg) * cv; g2 = g1; g1 = g0; v2 = v1; v1 = v0; } }
; #pragma unroll
;             for (int e = 0; e < 8; ++e) { v2u w; w.x = pk2(g[e][0], g[e][1]); w.y = pk2(g[e][2], g[e][3]); *(v2u*)(ACT + (size_t)(tok0 + e) * FFH + cc) = w; }
	v_mov_b32_e32 v86, v108
	v_mov_b32_e32 v87, v110
	v_mov_b32_e32 v94, v116
	v_mov_b32_e32 v95, v118
	v_pk_fma_f32 v[78:79], v[86:87], v[78:79], v[94:95]
	v_mov_b32_e32 v196, v120
	v_mov_b32_e32 v197, v122
	v_pk_fma_f32 v[78:79], v[196:197], v[80:81], v[78:79]
	v_mov_b32_e32 v198, v124
	v_mov_b32_e32 v199, v126
	v_pk_fma_f32 v[78:79], v[190:191], v[198:199], v[78:79]
	v_mov_b32_e32 v110, v109
	v_mul_f32_e32 v108, 0xbfb8aa3b, v78
	v_mov_b32_e32 v118, v117
	v_exp_f32_e32 v116, v108
	v_pk_fma_f32 v[108:109], v[110:111], v[210:211], v[118:119]
	v_mov_b32_e32 v122, v121
	v_pk_fma_f32 v[108:109], v[122:123], v[238:239], v[108:109]
	v_mov_b32_e32 v126, v125
	v_pk_fma_f32 v[108:109], v[192:193], v[126:127], v[108:109]
	v_add_f32_e32 v116, 1.0, v116
	v_mul_f32_e32 v117, 0xbfb8aa3b, v108
	v_exp_f32_e32 v117, v117
	v_rcp_f32_e32 v210, v116
	v_mov_b32_e32 v120, v104
	v_mov_b32_e32 v121, v106
	v_add_f32_e32 v116, 1.0, v117
	v_rcp_f32_e32 v242, v116
	v_mov_b32_e32 v116, v96
	v_mul_f32_e32 v96, 0xbfb8aa3b, v79
	v_exp_f32_e32 v96, v96
	v_mov_b32_e32 v117, v98
	v_pk_fma_f32 v[124:125], v[116:117], v[204:205], v[120:121]
	v_mov_b32_e32 v204, v112
	v_add_f32_e32 v96, 1.0, v96
	v_mov_b32_e32 v205, v114
	v_rcp_f32_e32 v211, v96
	v_mul_f32_e32 v96, 0xbfb8aa3b, v109
	v_pk_fma_f32 v[244:245], v[204:205], v[236:237], v[124:125]
	v_mov_b32_e32 v124, v100
	v_exp_f32_e32 v100, v96
	v_mov_b32_e32 v98, v97
	v_mov_b32_e32 v106, v105
	v_mov_b32_e32 v125, v102
	v_add_f32_e32 v100, 1.0, v100
	v_rcp_f32_e32 v243, v100
	v_pk_fma_f32 v[96:97], v[98:99], v[212:213], v[106:107]
	v_mov_b32_e32 v114, v113
	v_pk_fma_f32 v[244:245], v[188:189], v[124:125], v[244:245]
	v_pk_mul_f32 v[78:79], v[78:79], v[210:211]
	v_pk_fma_f32 v[96:97], v[114:115], v[240:241], v[96:97]
	v_mov_b32_e32 v102, v101
	v_pk_mul_f32 v[78:79], v[244:245], v[78:79]
	v_pk_fma_f32 v[96:97], v[186:187], v[102:103], v[96:97]
	v_pk_mul_f32 v[100:101], v[108:109], v[242:243]
	v_pk_fma_f32 v[80:81], v[86:87], v[80:81], v[94:95]
	v_pk_mul_f32 v[96:97], v[96:97], v[100:101]
	s_nop 7
	s_nop 1
	v_mov_b64_e32 v[210:211], s[78:79]
	v_pk_fma_f32 v[80:81], v[190:191], v[196:197], v[80:81]
	v_cvt_pk_bf16_f32 v79, v79, v97
	v_cvt_pk_bf16_f32 v78, v78, v96
	v_mad_i64_i32 v[96:97], s[34:35], v160, s60, v[210:211]
	v_lshlrev_b64 v[212:213], 1, v[132:133]
	v_pk_fma_f32 v[80:81], v[182:183], v[198:199], v[80:81]
	v_lshl_add_u64 v[112:113], v[96:97], 0, v[212:213]
	v_mul_f32_e32 v96, 0xbfb8aa3b, v80
	v_exp_f32_e32 v100, v96
	v_pk_fma_f32 v[96:97], v[110:111], v[238:239], v[118:119]
	global_store_dwordx2 v[112:113], v[78:79], off
	v_pk_fma_f32 v[96:97], v[192:193], v[122:123], v[96:97]
	v_add_f32_e32 v78, 1.0, v100
	v_pk_fma_f32 v[96:97], v[184:185], v[126:127], v[96:97]
	v_mul_f32_e32 v100, 0xbfb8aa3b, v81
	v_mul_f32_e32 v101, 0xbfb8aa3b, v96
	v_exp_f32_e32 v101, v101
	v_rcp_f32_e32 v78, v78
	v_pk_fma_f32 v[104:105], v[116:117], v[236:237], v[120:121]
	v_mov_b32_e32 v129, v42
	v_add_f32_e32 v79, 1.0, v101
	v_exp_f32_e32 v101, v100
	v_rcp_f32_e32 v100, v79
	v_pk_fma_f32 v[104:105], v[188:189], v[204:205], v[104:105]
	v_mov_b32_e32 v42, v43
	v_add_f32_e32 v79, 1.0, v101
	v_mul_f32_e32 v101, 0xbfb8aa3b, v97
	v_rcp_f32_e32 v79, v79
	v_exp_f32_e32 v101, v101
	v_pk_fma_f32 v[104:105], v[180:181], v[124:125], v[104:105]
	v_mov_b32_e32 v92, v36
	v_pk_mul_f32 v[78:79], v[80:81], v[78:79]
	v_add_f32_e32 v80, 1.0, v101
	v_rcp_f32_e32 v101, v80
	v_pk_fma_f32 v[80:81], v[98:99], v[240:241], v[106:107]
	v_pk_mul_f32 v[78:79], v[104:105], v[78:79]
	v_pk_fma_f32 v[80:81], v[186:187], v[114:115], v[80:81]
	v_pk_mul_f32 v[96:97], v[96:97], v[100:101]
	v_pk_fma_f32 v[80:81], v[178:179], v[102:103], v[80:81]
	v_pk_fma_f32 v[104:105], v[188:189], v[116:117], v[120:121]
	v_pk_mul_f32 v[80:81], v[80:81], v[96:97]
	s_nop 7
	s_nop 1
	v_cvt_pk_bf16_f32 v78, v78, v80
	v_or_b32_e32 v80, 1, v160
	v_cvt_pk_bf16_f32 v79, v79, v81
	v_mad_i64_i32 v[80:81], s[34:35], v80, s60, v[210:211]
	v_lshl_add_u64 v[108:109], v[80:81], 0, v[212:213]
	v_pk_fma_f32 v[80:81], v[190:191], v[86:87], v[94:95]
	global_store_dwordx2 v[108:109], v[78:79], off
	v_pk_fma_f32 v[80:81], v[182:183], v[196:197], v[80:81]
	v_pk_fma_f32 v[104:105], v[180:181], v[204:205], v[104:105]
	v_pk_fma_f32 v[80:81], v[224:225], v[198:199], v[80:81]
	v_pk_fma_f32 v[104:105], v[220:221], v[124:125], v[104:105]
	v_mul_f32_e32 v96, 0xbfb8aa3b, v80
	v_exp_f32_e32 v100, v96
	v_pk_fma_f32 v[96:97], v[192:193], v[110:111], v[118:119]
	v_pk_fma_f32 v[180:181], v[180:181], v[116:117], v[120:121]
	v_pk_fma_f32 v[96:97], v[184:185], v[122:123], v[96:97]
	v_add_f32_e32 v78, 1.0, v100
	v_pk_fma_f32 v[96:97], v[222:223], v[126:127], v[96:97]
	v_mul_f32_e32 v100, 0xbfb8aa3b, v81
	v_mul_f32_e32 v101, 0xbfb8aa3b, v96
	v_exp_f32_e32 v101, v101
	v_rcp_f32_e32 v78, v78
	v_pk_fma_f32 v[180:181], v[220:221], v[204:205], v[180:181]
	v_mov_b32_e32 v93, v36
	v_add_f32_e32 v79, 1.0, v101
	v_exp_f32_e32 v101, v100
	v_rcp_f32_e32 v100, v79
	v_pk_fma_f32 v[180:181], v[208:209], v[124:125], v[180:181]
	v_mov_b32_e32 v36, v37
	v_add_f32_e32 v79, 1.0, v101
	v_mul_f32_e32 v101, 0xbfb8aa3b, v97
	v_rcp_f32_e32 v79, v79
	v_exp_f32_e32 v101, v101
	v_cmp_gt_i32_e32 vcc, 15, v3
	s_mov_b64 s[36:37], -1
	v_pk_mul_f32 v[78:79], v[80:81], v[78:79]
	v_add_f32_e32 v80, 1.0, v101
	v_rcp_f32_e32 v101, v80
	v_pk_fma_f32 v[80:81], v[186:187], v[98:99], v[106:107]
	v_pk_mul_f32 v[78:79], v[104:105], v[78:79]
	v_pk_fma_f32 v[80:81], v[178:179], v[114:115], v[80:81]
	v_pk_mul_f32 v[96:97], v[96:97], v[100:101]
	v_pk_fma_f32 v[80:81], v[218:219], v[102:103], v[80:81]
	s_nop 0
	v_pk_mul_f32 v[80:81], v[80:81], v[96:97]
	s_nop 7
	s_nop 1
; __device__ __forceinline__ unsigned pk2(float lo, float hi) { return f2bf(lo) | (f2bf(hi) << 16); }
; __device__ __forceinline__ float silu_fast(float x) { return x * __builtin_amdgcn_rcpf(1.f + __builtin_amdgcn_exp2f(-1.4426950408889634f * x)); }
; __device__ __forceinline__ float dpp_shr1(float x) { return __builtin_bit_cast(float, __builtin_amdgcn_update_dpp(0, __builtin_bit_cast(int, x), 0x111, 0xf, 0xf, true)); }
;     __device__ __forceinline__ void operator()(const f32x4 (&acc)[2][2][4][2], const pg8::Unit& u, int wr, int wc, int fr, int fq) const {
;     ...
;             for (int jj = 0; jj < 4; ++jj) {
;                 float g2 = dpp_shr1(g[6][jj]), g1 = dpp_shr1(g[7][jj]), v2 = dpp_shr1(v[6][jj]), v1 = dpp_shr1(v[7][jj]);
; #pragma unroll
;                 for (int e = 0; e < 8; ++e) { const float g0 = g[e][jj], v0 = v[e][jj];
;                     const float cg = bg[jj] + wg0[jj] * g2 + wg1[jj] * g1 + wg2[jj] * g0, cv = bv[jj] + wv0[jj] * v2 + wv1[jj] * v1 + wv2[jj] * v0;
;                     g[e][jj] = silu_fast(cg) * cv; g2 = g1; g1 = g0; v2 = v1; v1 = v0; } }
; #pragma unroll
;             for (int e = 0; e < 8; ++e) { v2u w; w.x = pk2(g[e][0], g[e][1]); w.y = pk2(g[e][2], g[e][3]); *(v2u*)(ACT + (size_t)(tok0 + e) * FFH + cc) = w; }
	v_cvt_pk_bf16_f32 v78, v78, v80
	v_or_b32_e32 v80, 2, v160
	v_cvt_pk_bf16_f32 v79, v79, v81
	v_mad_i64_i32 v[80:81], s[34:35], v80, s60, v[210:211]
	v_lshl_add_u64 v[104:105], v[80:81], 0, v[212:213]
	v_pk_fma_f32 v[80:81], v[182:183], v[86:87], v[94:95]
	global_store_dwordx2 v[104:105], v[78:79], off
	v_pk_fma_f32 v[80:81], v[224:225], v[196:197], v[80:81]
	v_pk_fma_f32 v[182:183], v[208:209], v[116:117], v[120:121]
	v_pk_fma_f32 v[80:81], v[214:215], v[198:199], v[80:81]
	v_pk_fma_f32 v[182:183], v[194:195], v[204:205], v[182:183]
	v_mul_f32_e32 v96, 0xbfb8aa3b, v80
	v_exp_f32_e32 v100, v96
	v_pk_fma_f32 v[96:97], v[184:185], v[110:111], v[118:119]
	v_pk_fma_f32 v[182:183], v[82:83], v[124:125], v[182:183]
	v_pk_fma_f32 v[96:97], v[222:223], v[122:123], v[96:97]
	v_add_f32_e32 v78, 1.0, v100
	v_pk_fma_f32 v[96:97], v[216:217], v[126:127], v[96:97]
	v_mul_f32_e32 v100, 0xbfb8aa3b, v81
	v_mul_f32_e32 v101, 0xbfb8aa3b, v96
	v_exp_f32_e32 v101, v101
	v_rcp_f32_e32 v78, v78
	v_pk_fma_f32 v[184:185], v[194:195], v[116:117], v[120:121]
	v_add_f32_e32 v79, 1.0, v101
	v_exp_f32_e32 v101, v100
	v_rcp_f32_e32 v100, v79
	v_pk_fma_f32 v[184:185], v[82:83], v[204:205], v[184:185]
	v_pk_fma_f32 v[82:83], v[82:83], v[116:117], v[120:121]
	v_add_f32_e32 v79, 1.0, v101
	v_mul_f32_e32 v101, 0xbfb8aa3b, v97
	v_rcp_f32_e32 v79, v79
	v_exp_f32_e32 v101, v101
	v_pk_fma_f32 v[184:185], v[162:163], v[124:125], v[184:185]
	v_pk_fma_f32 v[82:83], v[162:163], v[204:205], v[82:83]
	v_pk_mul_f32 v[78:79], v[80:81], v[78:79]
	v_add_f32_e32 v80, 1.0, v101
	v_rcp_f32_e32 v101, v80
	v_pk_fma_f32 v[80:81], v[178:179], v[98:99], v[106:107]
	v_pk_mul_f32 v[78:79], v[180:181], v[78:79]
	v_pk_fma_f32 v[80:81], v[218:219], v[114:115], v[80:81]
	v_pk_mul_f32 v[96:97], v[96:97], v[100:101]
	v_pk_fma_f32 v[80:81], v[206:207], v[102:103], v[80:81]
	v_pk_fma_f32 v[180:181], v[220:221], v[116:117], v[120:121]
	v_pk_mul_f32 v[80:81], v[80:81], v[96:97]
	s_nop 7
	s_nop 1
	v_cvt_pk_bf16_f32 v78, v78, v80
	v_or_b32_e32 v80, 3, v160
	v_cvt_pk_bf16_f32 v79, v79, v81
	v_mad_i64_i32 v[80:81], s[34:35], v80, s60, v[210:211]
	v_lshl_add_u64 v[100:101], v[80:81], 0, v[212:213]
	v_pk_fma_f32 v[80:81], v[224:225], v[86:87], v[94:95]
	global_store_dwordx2 v[100:101], v[78:79], off
	v_pk_fma_f32 v[80:81], v[214:215], v[196:197], v[80:81]
	v_pk_fma_f32 v[180:181], v[208:209], v[204:205], v[180:181]
	v_pk_fma_f32 v[80:81], v[202:203], v[198:199], v[80:81]
	v_pk_fma_f32 v[180:181], v[194:195], v[124:125], v[180:181]
	v_mul_f32_e32 v96, 0xbfb8aa3b, v80
	v_exp_f32_e32 v133, v96
	v_pk_fma_f32 v[96:97], v[222:223], v[110:111], v[118:119]
	v_pk_fma_f32 v[82:83], v[134:135], v[124:125], v[82:83]
	v_pk_fma_f32 v[96:97], v[216:217], v[122:123], v[96:97]
	v_add_f32_e32 v78, 1.0, v133
	v_pk_fma_f32 v[96:97], v[200:201], v[126:127], v[96:97]
	v_mul_f32_e32 v133, 0xbfb8aa3b, v81
	v_mul_f32_e32 v161, 0xbfb8aa3b, v96
	v_exp_f32_e32 v161, v161
	v_exp_f32_e32 v133, v133
	v_rcp_f32_e32 v78, v78
	v_add_f32_e32 v79, 1.0, v161
	v_rcp_f32_e32 v178, v79
	v_add_f32_e32 v79, 1.0, v133
	v_mul_f32_e32 v133, 0xbfb8aa3b, v97
	v_rcp_f32_e32 v79, v79
	v_exp_f32_e32 v133, v133
	v_pk_mul_f32 v[78:79], v[80:81], v[78:79]
	v_add_f32_e32 v80, 1.0, v133
	v_rcp_f32_e32 v179, v80
	v_pk_fma_f32 v[80:81], v[218:219], v[98:99], v[106:107]
	v_pk_mul_f32 v[78:79], v[180:181], v[78:79]
	v_pk_fma_f32 v[80:81], v[206:207], v[114:115], v[80:81]
	v_pk_mul_f32 v[96:97], v[96:97], v[178:179]
	v_pk_fma_f32 v[80:81], v[90:91], v[102:103], v[80:81]
	v_pk_fma_f32 v[178:179], v[216:217], v[110:111], v[118:119]
	v_pk_mul_f32 v[80:81], v[80:81], v[96:97]
	s_nop 7
	s_nop 1
	v_cvt_pk_bf16_f32 v78, v78, v80
	v_or_b32_e32 v80, 4, v160
	v_cvt_pk_bf16_f32 v79, v79, v81
	v_mad_i64_i32 v[80:81], s[34:35], v80, s60, v[210:211]
	v_lshl_add_u64 v[96:97], v[80:81], 0, v[212:213]
	v_pk_fma_f32 v[80:81], v[214:215], v[86:87], v[94:95]
	v_pk_fma_f32 v[178:179], v[200:201], v[122:123], v[178:179]
	v_pk_fma_f32 v[80:81], v[202:203], v[196:197], v[80:81]
	v_pk_fma_f32 v[178:179], v[84:85], v[126:127], v[178:179]
	v_pk_fma_f32 v[80:81], v[88:89], v[198:199], v[80:81]
	v_mul_f32_e32 v161, 0xbfb8aa3b, v178
	v_mul_f32_e32 v133, 0xbfb8aa3b, v80
	v_exp_f32_e32 v133, v133
	v_exp_f32_e32 v161, v161
	global_store_dwordx2 v[96:97], v[78:79], off
	v_add_f32_e32 v78, 1.0, v133
	v_mul_f32_e32 v133, 0xbfb8aa3b, v81
	v_exp_f32_e32 v133, v133
	v_add_f32_e32 v79, 1.0, v161
	v_rcp_f32_e32 v180, v79
	v_rcp_f32_e32 v78, v78
	v_add_f32_e32 v79, 1.0, v133
	v_mul_f32_e32 v133, 0xbfb8aa3b, v179
	v_rcp_f32_e32 v79, v79
	v_exp_f32_e32 v133, v133
	v_pk_mul_f32 v[78:79], v[80:81], v[78:79]
	v_add_f32_e32 v80, 1.0, v133
	v_rcp_f32_e32 v181, v80
	v_pk_fma_f32 v[80:81], v[206:207], v[98:99], v[106:107]
	v_pk_mul_f32 v[78:79], v[182:183], v[78:79]
	v_pk_fma_f32 v[80:81], v[90:91], v[114:115], v[80:81]
	v_pk_mul_f32 v[178:179], v[178:179], v[180:181]
	v_pk_fma_f32 v[80:81], v[76:77], v[102:103], v[80:81]
	v_and_b32_sdwa v133, v79, v234 dst_sel:DWORD dst_unused:UNUSED_PAD src0_sel:WORD_1 src1_sel:DWORD
	v_pk_mul_f32 v[80:81], v[80:81], v[178:179]
	v_pk_fma_f32 v[178:179], v[202:203], v[86:87], v[94:95]
	s_nop 0
	v_pk_fma_f32 v[178:179], v[88:89], v[196:197], v[178:179]
	s_nop 0
	v_add3_u32 v79, v79, v133, s59
	v_and_b32_sdwa v133, v81, v234 dst_sel:DWORD dst_unused:UNUSED_PAD src0_sel:WORD_1 src1_sel:DWORD
	s_nop 0
	v_pk_fma_f32 v[178:179], v[168:169], v[198:199], v[178:179]
	v_add3_u32 v81, v81, v133, s59
	s_nop 0
	v_mul_f32_e32 v133, 0xbfb8aa3b, v178
	s_nop 0
	v_exp_f32_e32 v133, v133
	v_pk_fma_f32 v[180:181], v[200:201], v[110:111], v[118:119]
	v_and_b32_e32 v81, 0xffff0000, v81
	v_cvt_pk_bf16_f32 v78, v78, v80
; __device__ __forceinline__ unsigned pk2(float lo, float hi) { return f2bf(lo) | (f2bf(hi) << 16); }
; __device__ __forceinline__ float silu_fast(float x) { return x * __builtin_amdgcn_rcpf(1.f + __builtin_amdgcn_exp2f(-1.4426950408889634f * x)); }
; __device__ __forceinline__ float dpp_shr1(float x) { return __builtin_bit_cast(float, __builtin_amdgcn_update_dpp(0, __builtin_bit_cast(int, x), 0x111, 0xf, 0xf, true)); }
;     __device__ __forceinline__ void operator()(const f32x4 (&acc)[2][2][4][2], const pg8::Unit& u, int wr, int wc, int fr, int fq) const {
;     ...
;             for (int e = 0; e < 8; ++e) { const float rs = (e < 4) ? r0[e & 3] : r1[e & 3];
; #pragma unroll
;                 for (int jj = 0; jj < 4; ++jj) { g[e][jj] = acc[e >> 2][0][e & 3][n][jj] * rs; v[e][jj] = acc[e >> 2][1][e & 3][n][jj] * rs; } }
;             if (fr == 0) {
; #pragma unroll
;                 for (int q = 0; q < 2; ++q) { v2u a, b; a.x = pk2(g[q][0], g[q][1]); a.y = pk2(g[q][2], g[q][3]); b.x = pk2(v[q][0], v[q][1]); b.y = pk2(v[q][2], v[q][3]);
;                     *(v2u*)(hb + (size_t)q * 256 + 4 * n) = a; *(v2u*)(hb + (size_t)q * 256 + 128 + 4 * n) = b; } }
;             if (fr == 15) {
; #pragma unroll
;                 for (int q = 0; q < 2; ++q) { v2u a, b; a.x = pk2(g[6 + q][0], g[6 + q][1]); a.y = pk2(g[6 + q][2], g[6 + q][3]); b.x = pk2(v[6 + q][0], v[6 + q][1]); b.y = pk2(v[6 + q][2], v[6 + q][3]);
;                     *(v2u*)(hb + (size_t)(2 + q) * 256 + 4 * n) = a; *(v2u*)(hb + (size_t)(2 + q) * 256 + 128 + 4 * n) = b; } }
;     ...
;             for (int jj = 0; jj < 4; ++jj) {
;                 float g2 = dpp_shr1(g[6][jj]), g1 = dpp_shr1(g[7][jj]), v2 = dpp_shr1(v[6][jj]), v1 = dpp_shr1(v[7][jj]);
; #pragma unroll
;                 for (int e = 0; e < 8; ++e) { const float g0 = g[e][jj], v0 = v[e][jj];
;                     const float cg = bg[jj] + wg0[jj] * g2 + wg1[jj] * g1 + wg2[jj] * g0, cv = bv[jj] + wv0[jj] * v2 + wv1[jj] * v1 + wv2[jj] * v0;
;                     g[e][jj] = silu_fast(cg) * cv; g2 = g1; g1 = g0; v2 = v1; v1 = v0; } }
; #pragma unroll
;             for (int e = 0; e < 8; ++e) { v2u w; w.x = pk2(g[e][0], g[e][1]); w.y = pk2(g[e][2], g[e][3]); *(v2u*)(ACT + (size_t)(tok0 + e) * FFH + cc) = w; }
	v_or_b32_e32 v80, 5, v160
	v_pk_fma_f32 v[180:181], v[84:85], v[122:123], v[180:181]
	v_or_b32_sdwa v79, v81, v79 dst_sel:DWORD dst_unused:UNUSED_PAD src0_sel:DWORD src1_sel:WORD_1
	v_mad_i64_i32 v[80:81], s[34:35], v80, s60, v[210:211]
	v_pk_fma_f32 v[180:181], v[136:137], v[126:127], v[180:181]
	v_lshl_add_u64 v[80:81], v[80:81], 0, v[212:213]
	v_mul_f32_e32 v161, 0xbfb8aa3b, v180
	v_exp_f32_e32 v161, v161
	global_store_dwordx2 v[80:81], v[78:79], off
	v_add_f32_e32 v78, 1.0, v133
	v_mul_f32_e32 v133, 0xbfb8aa3b, v179
	v_exp_f32_e32 v133, v133
	v_add_f32_e32 v79, 1.0, v161
	v_rcp_f32_e32 v182, v79
	v_rcp_f32_e32 v78, v78
	v_add_f32_e32 v79, 1.0, v133
	v_mul_f32_e32 v133, 0xbfb8aa3b, v181
	v_exp_f32_e32 v133, v133
	v_rcp_f32_e32 v79, v79
	v_pk_fma_f32 v[90:91], v[90:91], v[98:99], v[106:107]
	v_pk_fma_f32 v[84:85], v[84:85], v[110:111], v[118:119]
	v_add_f32_e32 v133, 1.0, v133
	v_rcp_f32_e32 v183, v133
	v_pk_mul_f32 v[78:79], v[178:179], v[78:79]
	v_pk_fma_f32 v[90:91], v[76:77], v[114:115], v[90:91]
	v_pk_mul_f32 v[78:79], v[184:185], v[78:79]
	v_pk_fma_f32 v[90:91], v[130:131], v[102:103], v[90:91]
	v_pk_mul_f32 v[178:179], v[180:181], v[182:183]
	v_and_b32_sdwa v161, v78, v234 dst_sel:DWORD dst_unused:UNUSED_PAD src0_sel:WORD_1 src1_sel:DWORD
	v_pk_mul_f32 v[90:91], v[90:91], v[178:179]
	s_nop 0
	v_add3_u32 v78, v78, v161, s59
	v_and_b32_sdwa v161, v90, v234 dst_sel:DWORD dst_unused:UNUSED_PAD src0_sel:WORD_1 src1_sel:DWORD
	s_nop 1
	v_add3_u32 v90, v90, v161, s59
	s_nop 0
	v_and_b32_e32 v90, 0xffff0000, v90
	s_nop 0
	v_or_b32_sdwa v90, v90, v78 dst_sel:DWORD dst_unused:UNUSED_PAD src0_sel:DWORD src1_sel:WORD_1
	v_or_b32_e32 v78, 6, v160
	v_pk_fma_f32 v[86:87], v[88:89], v[86:87], v[94:95]
	v_pk_fma_f32 v[84:85], v[136:137], v[122:123], v[84:85]
	v_cvt_pk_bf16_f32 v91, v79, v91
	v_mad_i64_i32 v[78:79], s[34:35], v78, s60, v[210:211]
	v_pk_fma_f32 v[86:87], v[168:169], v[196:197], v[86:87]
	v_pk_fma_f32 v[84:85], v[172:173], v[126:127], v[84:85]
	v_lshl_add_u64 v[78:79], v[78:79], 0, v[212:213]
	v_pk_fma_f32 v[86:87], v[170:171], v[198:199], v[86:87]
	v_mul_f32_e32 v89, 0xbfb8aa3b, v84
	v_mul_f32_e32 v88, 0xbfb8aa3b, v86
	v_exp_f32_e32 v89, v89
	global_store_dwordx2 v[78:79], v[90:91], off
	v_mul_f32_e32 v90, 0xbfb8aa3b, v87
	v_exp_f32_e32 v88, v88
	v_exp_f32_e32 v91, v90
	v_add_f32_e32 v89, 1.0, v89
	v_rcp_f32_e32 v90, v89
	v_add_f32_e32 v88, 1.0, v88
	v_add_f32_e32 v89, 1.0, v91
	v_rcp_f32_e32 v88, v88
	v_rcp_f32_e32 v89, v89
	v_mul_f32_e32 v91, 0xbfb8aa3b, v85
	v_exp_f32_e32 v91, v91
	v_pk_fma_f32 v[76:77], v[76:77], v[98:99], v[106:107]
	v_pk_mul_f32 v[86:87], v[86:87], v[88:89]
	v_pk_fma_f32 v[76:77], v[130:131], v[114:115], v[76:77]
	v_pk_mul_f32 v[82:83], v[82:83], v[86:87]
	v_add_f32_e32 v86, 1.0, v91
	v_rcp_f32_e32 v91, v86
	v_pk_fma_f32 v[76:77], v[138:139], v[102:103], v[76:77]
	v_pk_mul_f32 v[84:85], v[84:85], v[90:91]
	s_nop 0
	v_pk_mul_f32 v[76:77], v[76:77], v[84:85]
	s_nop 7
	s_nop 1
	v_cvt_pk_bf16_f32 v82, v82, v76
	v_or_b32_e32 v76, 7, v160
	v_cvt_pk_bf16_f32 v83, v83, v77
	v_mad_i64_i32 v[76:77], s[34:35], v76, s60, v[210:211]
	v_lshl_add_u64 v[76:77], v[76:77], 0, v[212:213]
	global_store_dwordx2 v[76:77], v[82:83], off
	v_mov_b32_e32 v82, v72
	v_mov_b32_e32 v83, v74
	v_pk_mul_f32 v[130:131], v[82:83], v[174:175]
	v_mov_b32_e32 v82, v64
	v_mov_b32_e32 v83, v66
	v_mov_b32_e32 v66, v65
	v_mov_b32_e32 v64, v68
	v_mov_b32_e32 v65, v70
	v_pk_mul_f32 v[114:115], v[64:65], v[40:41]
	v_mov_b32_e32 v64, v60
	v_mov_b32_e32 v65, v62
	v_mov_b32_e32 v70, v69
	v_mov_b32_e32 v62, v61
	v_pk_mul_f32 v[116:117], v[64:65], v[40:41]
	v_pk_mul_f32 v[118:119], v[70:71], v[40:41]
	v_pk_mul_f32 v[120:121], v[62:63], v[40:41]
	v_mov_b32_e32 v40, v56
	v_mov_b32_e32 v41, v58
	v_pk_mul_f32 v[88:89], v[40:41], v[176:177]
	v_mov_b32_e32 v40, v48
	v_mov_b32_e32 v41, v50
	v_pk_mul_f32 v[124:125], v[82:83], v[174:175]
	v_pk_mul_f32 v[82:83], v[40:41], v[176:177]
	v_mov_b32_e32 v40, v52
	v_mov_b32_e32 v41, v54
	v_mov_b32_e32 v74, v73
	v_mov_b32_e32 v58, v57
	v_mov_b32_e32 v50, v49
	v_pk_mul_f32 v[94:95], v[40:41], v[38:39]
	v_mov_b32_e32 v40, v44
	v_mov_b32_e32 v41, v46
	v_mov_b32_e32 v54, v53
	v_mov_b32_e32 v46, v45
	v_pk_mul_f32 v[126:127], v[74:75], v[174:175]
	v_pk_mul_f32 v[86:87], v[58:59], v[176:177]
	v_pk_mul_f32 v[72:73], v[50:51], v[176:177]
	v_pk_mul_f32 v[84:85], v[40:41], v[38:39]
	v_pk_mul_f32 v[90:91], v[54:55], v[38:39]
	v_pk_mul_f32 v[74:75], v[46:47], v[38:39]
	v_pk_mul_f32 v[122:123], v[66:67], v[174:175]
	v_mov_b64_e32 v[44:45], 0x408
	v_mov_b64_e32 v[46:47], 0x508
	v_mov_b64_e32 v[38:39], 0x608
	v_mov_b64_e32 v[40:41], 0x708
	v_mov_b64_e32 v[54:55], v[94:95]
	v_mov_b64_e32 v[52:53], v[90:91]
	v_mov_b64_e32 v[50:51], v[84:85]
	v_mov_b64_e32 v[48:49], v[74:75]
	v_mov_b64_e32 v[62:63], v[88:89]
	v_mov_b64_e32 v[60:61], v[86:87]
	v_mov_b64_e32 v[58:59], v[82:83]
	v_mov_b64_e32 v[56:57], v[72:73]
	s_and_saveexec_b64 s[34:35], vcc
	s_cbranch_execz .LBB0_4363
	v_cmp_eq_u32_e32 vcc, 0, v3
	s_mov_b64 s[36:37], 0
	v_mov_b64_e32 v[44:45], 0x408
	v_mov_b64_e32 v[46:47], 0x508
	v_mov_b64_e32 v[38:39], 0x608
	v_mov_b64_e32 v[40:41], 0x708
	s_and_saveexec_b64 s[38:39], vcc
	s_mov_b64 s[36:37], exec
	v_mov_b64_e32 v[44:45], 8
	v_mov_b64_e32 v[46:47], 0x108
	v_mov_b64_e32 v[38:39], 0x208
	v_mov_b64_e32 v[40:41], 0x308
	s_or_b64 exec, exec, s[38:39]
	s_orn2_b64 s[36:37], s[36:37], exec
	v_mov_b64_e32 v[54:55], v[114:115]
	v_mov_b64_e32 v[52:53], v[118:119]
	v_mov_b64_e32 v[50:51], v[116:117]
	v_mov_b64_e32 v[48:49], v[120:121]
	v_mov_b64_e32 v[62:63], v[130:131]
	v_mov_b64_e32 v[60:61], v[126:127]
	v_mov_b64_e32 v[58:59], v[124:125]
	v_mov_b64_e32 v[56:57], v[122:123]
; __device__ __forceinline__ unsigned pk2(float lo, float hi) { return f2bf(lo) | (f2bf(hi) << 16); }
;     __device__ __forceinline__ void operator()(const f32x4 (&acc)[2][2][4][2], const pg8::Unit& u, int wr, int wc, int fr, int fq) const {
;     ...
;             if (fr == 0) {
; #pragma unroll
;                 for (int q = 0; q < 2; ++q) { v2u a, b; a.x = pk2(g[q][0], g[q][1]); a.y = pk2(g[q][2], g[q][3]); b.x = pk2(v[q][0], v[q][1]); b.y = pk2(v[q][2], v[q][3]);
;                     *(v2u*)(hb + (size_t)q * 256 + 4 * n) = a; *(v2u*)(hb + (size_t)q * 256 + 128 + 4 * n) = b; } }
;             if (fr == 15) {
; #pragma unroll
;                 for (int q = 0; q < 2; ++q) { v2u a, b; a.x = pk2(g[6 + q][0], g[6 + q][1]); a.y = pk2(g[6 + q][2], g[6 + q][3]); b.x = pk2(v[6 + q][0], v[6 + q][1]); b.y = pk2(v[6 + q][2], v[6 + q][3]);
;                     *(v2u*)(hb + (size_t)(2 + q) * 256 + 4 * n) = a; *(v2u*)(hb + (size_t)(2 + q) * 256 + 128 + 4 * n) = b; } }
.LBB0_4363:
	s_or_b64 exec, exec, s[34:35]
	s_and_saveexec_b64 s[34:35], s[36:37]
	s_cbranch_execz .LBB0_4346
	s_nop 7
	s_nop 1
	v_cvt_pk_bf16_f32 v61, v63, v61
	v_cvt_pk_bf16_f32 v60, v62, v60
	s_nop 7
	s_nop 1
	v_lshl_add_u64 v[44:45], v[158:159], 0, v[44:45]
	v_cvt_pk_bf16_f32 v57, v59, v57
	v_cvt_pk_bf16_f32 v56, v58, v56
	global_store_dwordx2 v[44:45], v[60:61], off
	v_lshl_add_u64 v[44:45], v[158:159], 0, v[46:47]
	global_store_dwordx2 v[44:45], v[56:57], off
	v_and_b32_sdwa v45, v54, v234 dst_sel:DWORD dst_unused:UNUSED_PAD src0_sel:WORD_1 src1_sel:DWORD
	v_add3_u32 v46, v54, v45, s59
	s_nop 0
	v_and_b32_sdwa v47, v52, v234 dst_sel:DWORD dst_unused:UNUSED_PAD src0_sel:WORD_1 src1_sel:DWORD
	s_nop 1
	v_add3_u32 v47, v52, v47, s59
	s_nop 1
	v_and_b32_e32 v47, 0xffff0000, v47
	v_cvt_pk_bf16_f32 v45, v55, v53
	v_or_b32_sdwa v44, v47, v46 dst_sel:DWORD dst_unused:UNUSED_PAD src0_sel:DWORD src1_sel:WORD_1
	v_and_b32_sdwa v46, v51, v234 dst_sel:DWORD dst_unused:UNUSED_PAD src0_sel:WORD_1 src1_sel:DWORD
	v_and_b32_sdwa v47, v50, v234 dst_sel:DWORD dst_unused:UNUSED_PAD src0_sel:WORD_1 src1_sel:DWORD
	v_add3_u32 v50, v50, v47, s59
	v_add3_u32 v46, v51, v46, s59
	v_and_b32_sdwa v47, v49, v234 dst_sel:DWORD dst_unused:UNUSED_PAD src0_sel:WORD_1 src1_sel:DWORD
	v_and_b32_sdwa v51, v48, v234 dst_sel:DWORD dst_unused:UNUSED_PAD src0_sel:WORD_1 src1_sel:DWORD
	v_add3_u32 v47, v49, v47, s59
	v_add3_u32 v48, v48, v51, s59
	v_and_b32_e32 v47, 0xffff0000, v47
	v_and_b32_e32 v48, 0xffff0000, v48
	v_lshl_add_u64 v[38:39], v[158:159], 0, v[38:39]
	v_or_b32_sdwa v47, v47, v46 dst_sel:DWORD dst_unused:UNUSED_PAD src0_sel:DWORD src1_sel:WORD_1
	v_or_b32_sdwa v46, v48, v50 dst_sel:DWORD dst_unused:UNUSED_PAD src0_sel:DWORD src1_sel:WORD_1
	global_store_dwordx2 v[38:39], v[44:45], off
	v_lshl_add_u64 v[38:39], v[158:159], 0, v[40:41]
	global_store_dwordx2 v[38:39], v[46:47], off
	s_branch .LBB0_4346

; __device__ __forceinline__ unsigned pk2(float lo, float hi) { return f2bf(lo) | (f2bf(hi) << 16); }
; __device__ __forceinline__ void rms_row_bf16(const Ctx& c, const float* xrow, const float* gain, bf16* orow, float* copy) {
;     const f32x4* xr = (const f32x4*)xrow + c.lane; f32x4 v[8]; float s = 0.f;
; #pragma unroll
;     for (int j = 0; j < 8; ++j) { v[j] = xr[64 * j]; s += (v[j].x * v[j].x + v[j].y * v[j].y) + (v[j].z * v[j].z + v[j].w * v[j].w); }
;     const float rs = rsqrtf(wave_sum(s) * (1.f / DM) + EPS);
;     if (copy) {
; #pragma unroll
;         for (int j = 0; j < 8; ++j) ((f32x4*)copy + c.lane)[64 * j] = v[j]; }
;     const f32x4* gr = (const f32x4*)gain + c.lane; v2u* o8 = (v2u*)orow + c.lane;
; #pragma unroll
;     for (int j = 0; j < 8; ++j) { const f32x4 g = gr[64 * j]; v2u o; o.x = pk2(v[j].x * rs * g.x, v[j].y * rs * g.y); o.y = pk2(v[j].z * rs * g.z, v[j].w * rs * g.w); o8[64 * j] = o; }
.LBB0_4681:
	global_load_dwordx4 v[54:57], v[42:43], off offset:-4096
	global_load_dwordx4 v[28:31], v[42:43], off offset:-3072
	global_load_dwordx4 v[24:27], v[42:43], off offset:-2048
	global_load_dwordx4 v[16:19], v[42:43], off
	global_load_dwordx4 v[20:23], v[42:43], off offset:-1024
	global_load_dwordx4 v[12:15], v[42:43], off offset:1024
	global_load_dwordx4 v[4:7], v[42:43], off offset:3072
	global_load_dwordx4 v[8:11], v[42:43], off offset:2048
	global_load_dwordx4 v[58:61], v[32:33], off
	s_add_i32 s2, s2, s86
	v_lshl_add_u64 v[42:43], v[42:43], 0, s[6:7]
	s_cmpk_lt_i32 s2, 0x400
	s_waitcnt vmcnt(0)
	v_mov_b32_e32 v64, v55
	v_mov_b32_e32 v65, v29
	v_mov_b32_e32 v68, v57
	v_mov_b32_e32 v69, v31
	v_mov_b32_e32 v62, v54
	v_mov_b32_e32 v63, v28
	v_mov_b32_e32 v66, v56
	v_mov_b32_e32 v67, v30
	v_pk_mul_f32 v[70:71], v[26:27], v[26:27]
	v_pk_mul_f32 v[72:73], v[24:25], v[24:25]
	v_mov_b32_e32 v86, v54
	v_mov_b32_e32 v87, v56
	v_mov_b32_e32 v88, v58
	v_mov_b32_e32 v89, v60
	v_mov_b32_e32 v56, v55
	v_mov_b32_e32 v60, v59
	v_mov_b32_e32 v54, v28
	v_mov_b32_e32 v55, v30
	v_mov_b32_e32 v30, v29
	v_pk_mul_f32 v[28:29], v[64:65], v[64:65]
	v_pk_mul_f32 v[58:59], v[68:69], v[68:69]
	v_pk_mov_b32 v[64:65], v[72:73], v[70:71] op_sel:[1,0]
	v_mov_b32_e32 v73, v71
	v_pk_fma_f32 v[28:29], v[62:63], v[62:63], v[28:29]
	v_pk_fma_f32 v[58:59], v[66:67], v[66:67], v[58:59]
	v_mul_f32_e32 v74, v21, v21
	v_mul_f32_e32 v76, v23, v23
	v_pk_add_f32 v[62:63], v[64:65], v[72:73]
	v_pk_add_f32 v[28:29], v[28:29], v[58:59]
	v_mul_f32_e32 v53, v16, v16
	v_mul_f32_e32 v83, v17, v17
	v_mul_f32_e32 v85, v18, v18
	v_mul_f32_e32 v90, v19, v19
	v_pk_fma_f32 v[68:69], v[20:21], v[20:21], v[74:75] op_sel_hi:[1,1,0]
	v_pk_fma_f32 v[70:71], v[22:23], v[22:23], v[76:77] op_sel_hi:[1,1,0]
	v_pk_add_f32 v[58:59], v[62:63], v[62:63] op_sel:[0,1] op_sel_hi:[1,0]
	v_pk_add_f32 v[28:29], v[28:29], v[28:29] op_sel:[0,1] op_sel_hi:[1,0]
	v_pk_mul_f32 v[78:79], v[14:15], v[14:15]
	v_pk_mul_f32 v[80:81], v[12:13], v[12:13]
	v_mov_b32_e32 v69, v85
	v_mov_b32_e32 v71, v90
	v_mov_b32_e32 v59, v83
	v_mov_b32_e32 v29, v53
	v_pk_mov_b32 v[74:75], v[80:81], v[78:79] op_sel:[1,0]
	v_mov_b32_e32 v81, v79
	v_pk_add_f32 v[62:63], v[68:69], v[70:71]
	v_pk_add_f32 v[28:29], v[28:29], v[58:59]
	v_mul_f32_e32 v82, v9, v9
	v_mul_f32_e32 v84, v11, v11
	v_pk_add_f32 v[64:65], v[74:75], v[80:81]
	v_pk_add_f32 v[28:29], v[28:29], v[62:63]
	v_mul_f32_e32 v91, v4, v4
	v_mul_f32_e32 v92, v5, v5
	v_mul_f32_e32 v93, v6, v6
	v_mul_f32_e32 v94, v7, v7
	v_pk_fma_f32 v[76:77], v[8:9], v[8:9], v[82:83] op_sel_hi:[1,1,0]
	v_pk_fma_f32 v[78:79], v[10:11], v[10:11], v[84:85] op_sel_hi:[1,1,0]
	v_pk_add_f32 v[64:65], v[64:65], v[64:65] op_sel:[0,1] op_sel_hi:[1,0]
	v_pk_add_f32 v[28:29], v[28:29], v[28:29] op_sel:[0,1] op_sel_hi:[1,0]
	v_mov_b32_e32 v77, v93
	v_mov_b32_e32 v79, v94
	v_mov_b32_e32 v65, v92
	v_mov_b32_e32 v29, v91
	v_pk_add_f32 v[66:67], v[76:77], v[78:79]
	v_pk_add_f32 v[28:29], v[28:29], v[64:65]
	s_nop 0
	v_pk_add_f32 v[28:29], v[28:29], v[66:67]
	s_nop 0
	v_add_f32_e32 v28, v28, v29
	ds_bpermute_b32 v29, v3, v28
	s_waitcnt lgkmcnt(0)
	v_add_f32_e32 v28, v28, v29
	ds_bpermute_b32 v29, v46, v28
	s_waitcnt lgkmcnt(0)
	v_add_f32_e32 v28, v28, v29
	ds_bpermute_b32 v29, v47, v28
	s_waitcnt lgkmcnt(0)
	v_add_f32_e32 v28, v28, v29
	ds_bpermute_b32 v29, v48, v28
	s_waitcnt lgkmcnt(0)
	v_add_f32_e32 v28, v28, v29
	ds_bpermute_b32 v29, v49, v28
	s_waitcnt lgkmcnt(0)
	v_add_f32_e32 v28, v28, v29
	ds_bpermute_b32 v29, v50, v28
	s_waitcnt lgkmcnt(0)
	v_add_f32_e32 v28, v28, v29
	v_fmamk_f32 v28, v28, 0x3a000000, v51
	v_mul_f32_e32 v29, 0x4b800000, v28
	v_cmp_gt_f32_e32 vcc, s3, v28
	s_nop 1
	v_cndmask_b32_e32 v28, v28, v29, vcc
	v_rsq_f32_e32 v28, v28
	s_nop 0
	v_mul_f32_e32 v29, 0x45800000, v28
	v_cndmask_b32_e32 v28, v28, v29, vcc
	v_pk_mul_f32 v[58:59], v[86:87], v[28:29] op_sel_hi:[1,0]
	v_pk_mul_f32 v[56:57], v[56:57], v[28:29] op_sel_hi:[1,0]
	v_pk_mul_f32 v[62:63], v[54:55], v[28:29] op_sel_hi:[1,0]
	v_pk_mul_f32 v[54:55], v[88:89], v[58:59]
	v_pk_mul_f32 v[56:57], v[60:61], v[56:57]
	v_and_b32_sdwa v29, v55, v52 dst_sel:DWORD dst_unused:UNUSED_PAD src0_sel:WORD_1 src1_sel:DWORD
	v_and_b32_sdwa v53, v54, v52 dst_sel:DWORD dst_unused:UNUSED_PAD src0_sel:WORD_1 src1_sel:DWORD
	v_and_b32_sdwa v58, v57, v52 dst_sel:DWORD dst_unused:UNUSED_PAD src0_sel:WORD_1 src1_sel:DWORD
	v_and_b32_sdwa v59, v56, v52 dst_sel:DWORD dst_unused:UNUSED_PAD src0_sel:WORD_1 src1_sel:DWORD
	v_add3_u32 v53, v54, v53, s10
	v_add3_u32 v29, v55, v29, s10
	v_add3_u32 v54, v57, v58, s10
	v_add3_u32 v55, v56, v59, s10
	v_and_b32_e32 v54, 0xffff0000, v54
	v_and_b32_e32 v56, 0xffff0000, v55
	v_or_b32_sdwa v55, v54, v29 dst_sel:DWORD dst_unused:UNUSED_PAD src0_sel:DWORD src1_sel:WORD_1
	v_or_b32_sdwa v54, v56, v53 dst_sel:DWORD dst_unused:UNUSED_PAD src0_sel:DWORD src1_sel:WORD_1
	global_store_dwordx2 v[44:45], v[54:55], off
	global_load_dwordx4 v[54:57], v[32:33], off offset:1024
	v_pk_mul_f32 v[30:31], v[30:31], v[28:29] op_sel_hi:[1,0]
	s_waitcnt vmcnt(0)
; __device__ __forceinline__ unsigned pk2(float lo, float hi) { return f2bf(lo) | (f2bf(hi) << 16); }
; __device__ __forceinline__ void rms_row_bf16(const Ctx& c, const float* xrow, const float* gain, bf16* orow, float* copy) {
;     ...
;     const f32x4* gr = (const f32x4*)gain + c.lane; v2u* o8 = (v2u*)orow + c.lane;
; #pragma unroll
;     for (int j = 0; j < 8; ++j) { const f32x4 g = gr[64 * j]; v2u o; o.x = pk2(v[j].x * rs * g.x, v[j].y * rs * g.y); o.y = pk2(v[j].z * rs * g.z, v[j].w * rs * g.w); o8[64 * j] = o; }
	v_mov_b32_e32 v59, v56
	v_mov_b32_e32 v56, v55
	v_mov_b32_e32 v58, v54
	v_pk_mul_f32 v[30:31], v[56:57], v[30:31]
	v_pk_mul_f32 v[54:55], v[58:59], v[62:63]
	v_and_b32_sdwa v56, v31, v52 dst_sel:DWORD dst_unused:UNUSED_PAD src0_sel:WORD_1 src1_sel:DWORD
	s_nop 0
	v_and_b32_sdwa v29, v55, v52 dst_sel:DWORD dst_unused:UNUSED_PAD src0_sel:WORD_1 src1_sel:DWORD
	s_nop 0
	v_add3_u32 v31, v31, v56, s10
	s_nop 1
	v_add3_u32 v29, v55, v29, s10
	v_and_b32_e32 v31, 0xffff0000, v31
	s_nop 0
	v_or_b32_sdwa v31, v31, v29 dst_sel:DWORD dst_unused:UNUSED_PAD src0_sel:DWORD src1_sel:WORD_1
	v_cvt_pk_bf16_f32 v30, v54, v30
	global_store_dwordx2 v[44:45], v[30:31], off offset:512
	global_load_dwordx4 v[54:57], v[32:33], off offset:2048
	v_mov_b32_e32 v30, v24
	v_mov_b32_e32 v31, v26
	v_mov_b32_e32 v26, v25
	v_pk_mul_f32 v[24:25], v[30:31], v[28:29] op_sel_hi:[1,0]
	v_pk_mul_f32 v[26:27], v[26:27], v[28:29] op_sel_hi:[1,0]
	s_waitcnt vmcnt(0)
	v_mov_b32_e32 v31, v56
	v_mov_b32_e32 v56, v55
	v_mov_b32_e32 v30, v54
	v_pk_mul_f32 v[26:27], v[56:57], v[26:27]
	v_pk_mul_f32 v[24:25], v[30:31], v[24:25]
	v_and_b32_sdwa v31, v27, v52 dst_sel:DWORD dst_unused:UNUSED_PAD src0_sel:WORD_1 src1_sel:DWORD
	s_nop 0
	v_and_b32_sdwa v29, v25, v52 dst_sel:DWORD dst_unused:UNUSED_PAD src0_sel:WORD_1 src1_sel:DWORD
	s_nop 0
	v_add3_u32 v27, v27, v31, s10
	s_nop 1
	v_add3_u32 v25, v25, v29, s10
	v_and_b32_e32 v27, 0xffff0000, v27
	s_nop 0
	v_or_b32_sdwa v25, v27, v25 dst_sel:DWORD dst_unused:UNUSED_PAD src0_sel:DWORD src1_sel:WORD_1
	v_cvt_pk_bf16_f32 v24, v24, v26
	global_store_dwordx2 v[44:45], v[24:25], off offset:1024
	global_load_dwordx4 v[24:27], v[32:33], off offset:3072
	v_mov_b32_e32 v30, v20
	v_mov_b32_e32 v31, v22
	v_mov_b32_e32 v22, v21
	v_pk_mul_f32 v[20:21], v[30:31], v[28:29] op_sel_hi:[1,0]
	v_pk_mul_f32 v[22:23], v[22:23], v[28:29] op_sel_hi:[1,0]
	s_waitcnt vmcnt(0)
	v_mov_b32_e32 v31, v26
	v_mov_b32_e32 v26, v25
	v_mov_b32_e32 v30, v24
	v_pk_mul_f32 v[22:23], v[26:27], v[22:23]
	v_pk_mul_f32 v[20:21], v[30:31], v[20:21]
	s_nop 7
	s_nop 1
	v_cvt_pk_bf16_f32 v21, v21, v23
	v_cvt_pk_bf16_f32 v20, v20, v22
	global_store_dwordx2 v[44:45], v[20:21], off offset:1536
	global_load_dwordx4 v[20:23], v[34:35], off
	v_mov_b32_e32 v24, v16
	v_mov_b32_e32 v25, v18
	v_mov_b32_e32 v18, v17
	v_pk_mul_f32 v[16:17], v[24:25], v[28:29] op_sel_hi:[1,0]
	v_pk_mul_f32 v[18:19], v[18:19], v[28:29] op_sel_hi:[1,0]
	s_waitcnt vmcnt(0)
	v_mov_b32_e32 v25, v22
	v_mov_b32_e32 v22, v21
	v_mov_b32_e32 v24, v20
	v_pk_mul_f32 v[18:19], v[22:23], v[18:19]
	v_pk_mul_f32 v[16:17], v[24:25], v[16:17]
	s_nop 7
	s_nop 1
	v_cvt_pk_bf16_f32 v17, v17, v19
	v_cvt_pk_bf16_f32 v16, v16, v18
	global_store_dwordx2 v[44:45], v[16:17], off offset:2048
	global_load_dwordx4 v[16:19], v[36:37], off
	v_mov_b32_e32 v20, v12
	v_mov_b32_e32 v21, v14
	v_mov_b32_e32 v14, v13
	v_pk_mul_f32 v[12:13], v[20:21], v[28:29] op_sel_hi:[1,0]
	v_pk_mul_f32 v[14:15], v[14:15], v[28:29] op_sel_hi:[1,0]
	s_waitcnt vmcnt(0)
	v_mov_b32_e32 v21, v18
	v_mov_b32_e32 v18, v17
	v_mov_b32_e32 v20, v16
	v_pk_mul_f32 v[14:15], v[18:19], v[14:15]
	v_pk_mul_f32 v[12:13], v[20:21], v[12:13]
	s_nop 7
	s_nop 1
	v_cvt_pk_bf16_f32 v13, v13, v15
	v_cvt_pk_bf16_f32 v12, v12, v14
	global_store_dwordx2 v[44:45], v[12:13], off offset:2560
	global_load_dwordx4 v[12:15], v[38:39], off
	v_mov_b32_e32 v16, v8
	v_mov_b32_e32 v17, v10
	v_mov_b32_e32 v10, v9
	v_pk_mul_f32 v[8:9], v[16:17], v[28:29] op_sel_hi:[1,0]
	v_pk_mul_f32 v[10:11], v[10:11], v[28:29] op_sel_hi:[1,0]
	s_waitcnt vmcnt(0)
	v_mov_b32_e32 v17, v14
	v_mov_b32_e32 v14, v13
	v_mov_b32_e32 v16, v12
	v_pk_mul_f32 v[10:11], v[10:11], v[14:15]
	v_pk_mul_f32 v[8:9], v[8:9], v[16:17]
	s_nop 7
	s_nop 1
	v_cvt_pk_bf16_f32 v9, v9, v11
	v_cvt_pk_bf16_f32 v8, v8, v10
	global_store_dwordx2 v[44:45], v[8:9], off offset:3072
	global_load_dwordx4 v[8:11], v[40:41], off
	v_mov_b32_e32 v12, v4
	v_mov_b32_e32 v13, v6
	v_mov_b32_e32 v6, v5
	v_pk_mul_f32 v[4:5], v[12:13], v[28:29] op_sel_hi:[1,0]
	v_pk_mul_f32 v[6:7], v[6:7], v[28:29] op_sel_hi:[1,0]
	s_waitcnt vmcnt(0)
	v_mov_b32_e32 v13, v10
	v_mov_b32_e32 v10, v9
	v_mov_b32_e32 v12, v8
	v_pk_mul_f32 v[6:7], v[6:7], v[10:11]
	v_pk_mul_f32 v[4:5], v[4:5], v[12:13]
	v_and_b32_sdwa v10, v7, v52 dst_sel:DWORD dst_unused:UNUSED_PAD src0_sel:WORD_1 src1_sel:DWORD
	v_and_b32_sdwa v11, v6, v52 dst_sel:DWORD dst_unused:UNUSED_PAD src0_sel:WORD_1 src1_sel:DWORD
	v_and_b32_sdwa v8, v5, v52 dst_sel:DWORD dst_unused:UNUSED_PAD src0_sel:WORD_1 src1_sel:DWORD
	v_and_b32_sdwa v9, v4, v52 dst_sel:DWORD dst_unused:UNUSED_PAD src0_sel:WORD_1 src1_sel:DWORD
	v_add3_u32 v7, v7, v10, s10
	v_add3_u32 v6, v6, v11, s10
	v_add3_u32 v4, v4, v9, s10
	v_add3_u32 v5, v5, v8, s10
	v_and_b32_e32 v7, 0xffff0000, v7
	v_and_b32_e32 v6, 0xffff0000, v6
	v_or_b32_sdwa v5, v7, v5 dst_sel:DWORD dst_unused:UNUSED_PAD src0_sel:DWORD src1_sel:WORD_1
	v_or_b32_sdwa v4, v6, v4 dst_sel:DWORD dst_unused:UNUSED_PAD src0_sel:DWORD src1_sel:WORD_1
	global_store_dwordx2 v[44:45], v[4:5], off offset:3584
	v_lshl_add_u64 v[44:45], v[44:45], 0, s[8:9]
	s_cbranch_scc1 .LBB0_4681

; __device__ __forceinline__ unsigned pk2(float lo, float hi) { return f2bf(lo) | (f2bf(hi) << 16); }
; __device__ __forceinline__ float silu_fast(float x) { return x * __builtin_amdgcn_rcpf(1.f + __builtin_amdgcn_exp2f(-1.4426950408889634f * x)); }
; __device__ __forceinline__ float dpp_shr1(float x) { return __builtin_bit_cast(float, __builtin_amdgcn_update_dpp(0, __builtin_bit_cast(int, x), 0x111, 0xf, 0xf, true)); }
;     __device__ __forceinline__ void operator()(const f32x4 (&acc)[2][2][4][2], const pg8::Unit& u, int wr, int wc, int fr, int fq) const {
;     ...
;             const int cc = ch0 + 4 * n;
;             const f32x4 wg0 = *(CF4)(cw + cc), wg1 = *(CF4)(cw + FF2 + cc), wg2 = *(CF4)(cw + 2 * FF2 + cc), wv0 = *(CF4)(cw + FFH + cc), wv1 = *(CF4)(cw + FF2 + FFH + cc), wv2 = *(CF4)(cw + 2 * FF2 + FFH + cc);
;             const f32x4 bg = *(CF4)(cb + cc), bv = *(CF4)(cb + FFH + cc);
; #pragma unroll
;             for (int jj = 0; jj < 4; ++jj) {
;                 float g2 = dpp_shr1(g[6][jj]), g1 = dpp_shr1(g[7][jj]), v2 = dpp_shr1(v[6][jj]), v1 = dpp_shr1(v[7][jj]);
; #pragma unroll
;                 for (int e = 0; e < 8; ++e) { const float g0 = g[e][jj], v0 = v[e][jj];
;                     const float cg = bg[jj] + wg0[jj] * g2 + wg1[jj] * g1 + wg2[jj] * g0, cv = bv[jj] + wv0[jj] * v2 + wv1[jj] * v1 + wv2[jj] * v0;
;                     g[e][jj] = silu_fast(cg) * cv; g2 = g1; g1 = g0; v2 = v1; v1 = v0; } }
; #pragma unroll
;             for (int e = 0; e < 8; ++e) { v2u w; w.x = pk2(g[e][0], g[e][1]); w.y = pk2(g[e][2], g[e][3]); *(v2u*)(ACT + (size_t)(tok0 + e) * FFH + cc) = w; }
.LBB0_5579:
	s_or_b64 exec, exec, s[34:35]
	v_or_b32_e32 v34, 4, v128
	v_ashrrev_i32_e32 v35, 31, v34
	v_lshlrev_b64 v[46:47], 2, v[34:35]
	v_lshl_add_u64 v[34:35], s[6:7], 0, v[46:47]
	global_load_dwordx4 v[50:53], v[34:35], off
	v_lshl_add_u64 v[34:35], s[8:9], 0, v[46:47]
	v_lshl_add_u64 v[38:39], s[22:23], 0, v[46:47]
	global_load_dwordx4 v[54:57], v[34:35], off
	v_lshl_add_u64 v[42:43], s[18:19], 0, v[46:47]
	global_load_dwordx4 v[38:41], v[38:39], off
	v_lshl_add_u64 v[34:35], s[12:13], 0, v[46:47]
	global_load_dwordx4 v[60:63], v[34:35], off
	v_mov_b32_dpp v156, v98 row_shr:1 row_mask:0xf bank_mask:0xf bound_ctrl:1
	global_load_dwordx4 v[42:45], v[42:43], off
	v_lshl_add_u64 v[34:35], s[14:15], 0, v[46:47]
	global_load_dwordx4 v[64:67], v[34:35], off
	v_lshl_add_u64 v[34:35], s[16:17], 0, v[46:47]
	global_load_dwordx4 v[34:37], v[34:35], off
	v_lshl_add_u64 v[46:47], s[20:21], 0, v[46:47]
	global_load_dwordx4 v[46:49], v[46:47], off
	v_mov_b32_dpp v157, v99 row_shr:1 row_mask:0xf bank_mask:0xf bound_ctrl:1
	v_mov_b32_dpp v128, v96 row_shr:1 row_mask:0xf bank_mask:0xf bound_ctrl:1
	v_mov_b32_dpp v158, v102 row_shr:1 row_mask:0xf bank_mask:0xf bound_ctrl:1
	v_mov_b32_dpp v129, v97 row_shr:1 row_mask:0xf bank_mask:0xf bound_ctrl:1
	v_mov_b32_dpp v159, v103 row_shr:1 row_mask:0xf bank_mask:0xf bound_ctrl:1
	v_mov_b32_dpp v130, v100 row_shr:1 row_mask:0xf bank_mask:0xf bound_ctrl:1
	v_mov_b32_dpp v131, v101 row_shr:1 row_mask:0xf bank_mask:0xf bound_ctrl:1
	v_mov_b32_dpp v134, v70 row_shr:1 row_mask:0xf bank_mask:0xf bound_ctrl:1
	v_mov_b32_dpp v135, v71 row_shr:1 row_mask:0xf bank_mask:0xf bound_ctrl:1
	v_mov_b32_dpp v160, v68 row_shr:1 row_mask:0xf bank_mask:0xf bound_ctrl:1
	v_mov_b32_dpp v161, v69 row_shr:1 row_mask:0xf bank_mask:0xf bound_ctrl:1
	v_mov_b32_dpp v162, v94 row_shr:1 row_mask:0xf bank_mask:0xf bound_ctrl:1
	v_mov_b32_dpp v163, v95 row_shr:1 row_mask:0xf bank_mask:0xf bound_ctrl:1
	v_mov_b32_dpp v136, v92 row_shr:1 row_mask:0xf bank_mask:0xf bound_ctrl:1
	v_mov_b32_dpp v137, v93 row_shr:1 row_mask:0xf bank_mask:0xf bound_ctrl:1
	s_andn2_b64 vcc, exec, s[0:1]
	s_mov_b32 s61, s24
	s_mov_b32 s34, s26
	s_mov_b64 s[38:39], s[30:31]
	s_mov_b64 s[36:37], s[28:29]
	s_waitcnt vmcnt(0)
	v_mov_b32_e32 v105, v52
	v_mov_b32_e32 v52, v51
	v_mov_b32_e32 v104, v50
	v_mov_b32_e32 v107, v56
	v_mov_b32_e32 v56, v55
	v_mov_b32_e32 v106, v54
	v_mov_b32_e32 v108, v60
	v_mov_b32_e32 v109, v62
	v_mov_b32_e32 v62, v61
	v_mov_b32_e32 v60, v38
	v_mov_b32_e32 v61, v40
	v_mov_b32_e32 v40, v39
	v_pk_fma_f32 v[38:39], v[52:53], v[156:157], v[56:57]
	v_mov_b32_e32 v111, v66
	v_mov_b32_e32 v66, v65
	v_mov_b32_e32 v54, v34
	v_mov_b32_e32 v55, v36
	v_mov_b32_e32 v36, v35
	v_pk_fma_f32 v[34:35], v[104:105], v[128:129], v[106:107]
	v_pk_fma_f32 v[38:39], v[62:63], v[158:159], v[38:39]
	v_mov_b32_e32 v110, v64
	v_pk_fma_f32 v[34:35], v[108:109], v[130:131], v[34:35]
	v_pk_fma_f32 v[38:39], v[132:133], v[66:67], v[38:39]
	v_mov_b32_e32 v64, v42
	v_mov_b32_e32 v65, v44
	v_mov_b32_e32 v44, v43
	v_pk_fma_f32 v[42:43], v[54:55], v[134:135], v[60:61]
	v_pk_fma_f32 v[128:129], v[104:105], v[130:131], v[106:107]
	v_pk_fma_f32 v[34:35], v[124:125], v[110:111], v[34:35]
	v_mul_f32_e32 v131, 0xbfb8aa3b, v38
	v_mul_f32_e32 v135, 0xbfb8aa3b, v39
	v_mul_f32_e32 v130, 0xbfb8aa3b, v34
	v_mul_f32_e32 v134, 0xbfb8aa3b, v35
	v_exp_f32_e32 v131, v131
	v_exp_f32_e32 v135, v135
	v_exp_f32_e32 v130, v130
	v_exp_f32_e32 v134, v134
	v_add_f32_e32 v131, 1.0, v131
	v_add_f32_e32 v135, 1.0, v135
	v_add_f32_e32 v130, 1.0, v130
	v_add_f32_e32 v156, 1.0, v134
	v_rcp_f32_e32 v134, v131
	v_rcp_f32_e32 v135, v135
	v_rcp_f32_e32 v130, v130
	v_rcp_f32_e32 v131, v156
	v_mov_b32_e32 v50, v46
	v_mov_b32_e32 v51, v48
	v_mov_b32_e32 v48, v47
	v_pk_fma_f32 v[46:47], v[36:37], v[160:161], v[40:41]
	v_pk_fma_f32 v[42:43], v[64:65], v[136:137], v[42:43]
	v_pk_fma_f32 v[46:47], v[44:45], v[162:163], v[46:47]
	v_pk_mul_f32 v[38:39], v[38:39], v[134:135]
	v_pk_fma_f32 v[46:47], v[120:121], v[48:49], v[46:47]
	v_pk_fma_f32 v[42:43], v[122:123], v[50:51], v[42:43]
	v_pk_mul_f32 v[34:35], v[34:35], v[130:131]
	v_pk_mul_f32 v[38:39], v[46:47], v[38:39]
	v_pk_mul_f32 v[34:35], v[42:43], v[34:35]
	s_nop 7
	s_nop 1
	v_cvt_pk_bf16_f32 v35, v35, v39
	v_cvt_pk_bf16_f32 v34, v34, v38
	v_pk_fma_f32 v[38:39], v[124:125], v[108:109], v[128:129]
	global_store_dwordx2 v[84:85], v[34:35], off offset:8
	v_pk_fma_f32 v[38:39], v[116:117], v[110:111], v[38:39]
	v_pk_fma_f32 v[84:85], v[54:55], v[136:137], v[60:61]
	v_mul_f32_e32 v42, 0xbfb8aa3b, v38
	v_exp_f32_e32 v46, v42
	v_pk_fma_f32 v[42:43], v[52:53], v[158:159], v[56:57]
	v_pk_fma_f32 v[84:85], v[122:123], v[64:65], v[84:85]
	v_pk_fma_f32 v[42:43], v[132:133], v[62:63], v[42:43]
	v_add_f32_e32 v34, 1.0, v46
	v_pk_fma_f32 v[42:43], v[114:115], v[66:67], v[42:43]
	v_mul_f32_e32 v46, 0xbfb8aa3b, v39
	v_mul_f32_e32 v47, 0xbfb8aa3b, v42
	v_exp_f32_e32 v47, v47
	v_rcp_f32_e32 v34, v34
	v_pk_fma_f32 v[84:85], v[112:113], v[50:51], v[84:85]
	v_add_f32_e32 v35, 1.0, v47
	v_exp_f32_e32 v47, v46
	v_rcp_f32_e32 v46, v35
	v_add_f32_e32 v35, 1.0, v47
	v_mul_f32_e32 v47, 0xbfb8aa3b, v43
	v_rcp_f32_e32 v35, v35
	v_exp_f32_e32 v47, v47
	v_pk_mul_f32 v[34:35], v[38:39], v[34:35]
	v_add_f32_e32 v38, 1.0, v47
	v_rcp_f32_e32 v47, v38
	v_pk_fma_f32 v[38:39], v[36:37], v[162:163], v[40:41]
	v_pk_mul_f32 v[34:35], v[84:85], v[34:35]
	v_pk_fma_f32 v[38:39], v[120:121], v[44:45], v[38:39]
	v_pk_mul_f32 v[42:43], v[42:43], v[46:47]
	v_pk_fma_f32 v[38:39], v[118:119], v[48:49], v[38:39]
	v_pk_fma_f32 v[84:85], v[122:123], v[54:55], v[60:61]
	v_pk_mul_f32 v[38:39], v[38:39], v[42:43]
	s_nop 7
; __device__ __forceinline__ unsigned pk2(float lo, float hi) { return f2bf(lo) | (f2bf(hi) << 16); }
; __device__ __forceinline__ float silu_fast(float x) { return x * __builtin_amdgcn_rcpf(1.f + __builtin_amdgcn_exp2f(-1.4426950408889634f * x)); }
; __device__ __forceinline__ float dpp_shr1(float x) { return __builtin_bit_cast(float, __builtin_amdgcn_update_dpp(0, __builtin_bit_cast(int, x), 0x111, 0xf, 0xf, true)); }
;     __device__ __forceinline__ void operator()(const f32x4 (&acc)[2][2][4][2], const pg8::Unit& u, int wr, int wc, int fr, int fq) const {
;     ...
;             const int cc = ch0 + 4 * n;
;             const f32x4 wg0 = *(CF4)(cw + cc), wg1 = *(CF4)(cw + FF2 + cc), wg2 = *(CF4)(cw + 2 * FF2 + cc), wv0 = *(CF4)(cw + FFH + cc), wv1 = *(CF4)(cw + FF2 + FFH + cc), wv2 = *(CF4)(cw + 2 * FF2 + FFH + cc);
;             const f32x4 bg = *(CF4)(cb + cc), bv = *(CF4)(cb + FFH + cc);
; #pragma unroll
;             for (int jj = 0; jj < 4; ++jj) {
;                 float g2 = dpp_shr1(g[6][jj]), g1 = dpp_shr1(g[7][jj]), v2 = dpp_shr1(v[6][jj]), v1 = dpp_shr1(v[7][jj]);
; #pragma unroll
;                 for (int e = 0; e < 8; ++e) { const float g0 = g[e][jj], v0 = v[e][jj];
;                     const float cg = bg[jj] + wg0[jj] * g2 + wg1[jj] * g1 + wg2[jj] * g0, cv = bv[jj] + wv0[jj] * v2 + wv1[jj] * v1 + wv2[jj] * v0;
;                     g[e][jj] = silu_fast(cg) * cv; g2 = g1; g1 = g0; v2 = v1; v1 = v0; } }
; #pragma unroll
;             for (int e = 0; e < 8; ++e) { v2u w; w.x = pk2(g[e][0], g[e][1]); w.y = pk2(g[e][2], g[e][3]); *(v2u*)(ACT + (size_t)(tok0 + e) * FFH + cc) = w; }
	s_nop 1
	v_cvt_pk_bf16_f32 v35, v35, v39
	v_cvt_pk_bf16_f32 v34, v34, v38
	v_mov_b32_e32 v38, v31
	v_mov_b32_e32 v31, v32
	global_store_dwordx2 v[88:89], v[34:35], off offset:8
	v_mov_b32_e32 v34, v27
	v_mov_b32_e32 v35, v29
	v_mov_b32_e32 v27, v28
	v_pk_mul_f32 v[28:29], v[30:31], v[126:127]
	v_pk_fma_f32 v[30:31], v[124:125], v[104:105], v[106:107]
	v_mov_b32_e32 v39, v33
	v_pk_fma_f32 v[30:31], v[116:117], v[108:109], v[30:31]
	v_pk_mul_f32 v[38:39], v[38:39], v[126:127]
	v_pk_fma_f32 v[30:31], v[28:29], v[110:111], v[30:31]
	v_pk_mul_f32 v[26:27], v[26:27], v[126:127]
	v_mul_f32_e32 v32, 0xbfb8aa3b, v30
	v_exp_f32_e32 v42, v32
	v_pk_fma_f32 v[32:33], v[132:133], v[52:53], v[56:57]
	v_mul_f32_e32 v46, 0xbfb8aa3b, v31
	v_pk_fma_f32 v[32:33], v[114:115], v[62:63], v[32:33]
	v_exp_f32_e32 v47, v46
	v_pk_fma_f32 v[32:33], v[38:39], v[66:67], v[32:33]
	v_add_f32_e32 v42, 1.0, v42
	v_mul_f32_e32 v43, 0xbfb8aa3b, v32
	v_exp_f32_e32 v43, v43
	v_rcp_f32_e32 v42, v42
	v_pk_fma_f32 v[84:85], v[112:113], v[64:65], v[84:85]
	v_pk_mul_f32 v[34:35], v[34:35], v[126:127]
	v_add_f32_e32 v43, 1.0, v43
	v_rcp_f32_e32 v46, v43
	v_add_f32_e32 v43, 1.0, v47
	v_mul_f32_e32 v47, 0xbfb8aa3b, v33
	v_rcp_f32_e32 v43, v43
	v_exp_f32_e32 v47, v47
	v_pk_fma_f32 v[84:85], v[26:27], v[50:51], v[84:85]
	v_pk_mul_f32 v[30:31], v[30:31], v[42:43]
	v_add_f32_e32 v42, 1.0, v47
	v_rcp_f32_e32 v47, v42
	v_pk_fma_f32 v[42:43], v[120:121], v[36:37], v[40:41]
	v_pk_mul_f32 v[30:31], v[84:85], v[30:31]
	v_pk_fma_f32 v[42:43], v[118:119], v[44:45], v[42:43]
	v_pk_mul_f32 v[32:33], v[32:33], v[46:47]
	v_pk_fma_f32 v[42:43], v[34:35], v[48:49], v[42:43]
	v_pk_fma_f32 v[46:47], v[118:119], v[36:37], v[40:41]
	v_pk_mul_f32 v[32:33], v[42:43], v[32:33]
	s_nop 7
	s_nop 1
	v_cvt_pk_bf16_f32 v31, v31, v33
	v_cvt_pk_bf16_f32 v30, v30, v32
	v_mov_b32_e32 v32, v23
	v_mov_b32_e32 v33, v25
	v_mov_b32_e32 v23, v24
	v_pk_fma_f32 v[42:43], v[114:115], v[52:53], v[56:57]
	global_store_dwordx2 v[86:87], v[30:31], off offset:8
	v_mov_b32_e32 v30, v19
	v_mov_b32_e32 v31, v21
	v_pk_mul_f32 v[32:33], v[32:33], v[72:73]
	v_mov_b32_e32 v19, v20
	v_pk_mul_f32 v[20:21], v[22:23], v[72:73]
	v_pk_fma_f32 v[22:23], v[116:117], v[104:105], v[106:107]
	v_pk_fma_f32 v[42:43], v[38:39], v[62:63], v[42:43]
	v_pk_fma_f32 v[22:23], v[28:29], v[108:109], v[22:23]
	v_pk_fma_f32 v[42:43], v[32:33], v[66:67], v[42:43]
	v_pk_mul_f32 v[30:31], v[30:31], v[72:73]
	v_pk_mul_f32 v[18:19], v[18:19], v[72:73]
	v_pk_fma_f32 v[22:23], v[20:21], v[110:111], v[22:23]
	v_mul_f32_e32 v73, 0xbfb8aa3b, v42
	v_mul_f32_e32 v24, 0xbfb8aa3b, v22
	v_exp_f32_e32 v73, v73
	v_mul_f32_e32 v84, 0xbfb8aa3b, v23
	v_exp_f32_e32 v72, v24
	v_exp_f32_e32 v85, v84
	v_add_f32_e32 v73, 1.0, v73
	v_rcp_f32_e32 v84, v73
	v_add_f32_e32 v72, 1.0, v72
	v_add_f32_e32 v73, 1.0, v85
	v_mul_f32_e32 v85, 0xbfb8aa3b, v43
	v_rcp_f32_e32 v72, v72
	v_rcp_f32_e32 v73, v73
	v_exp_f32_e32 v85, v85
	v_pk_fma_f32 v[24:25], v[112:113], v[54:55], v[60:61]
	v_pk_mul_f32 v[22:23], v[22:23], v[72:73]
	v_add_f32_e32 v72, 1.0, v85
	v_rcp_f32_e32 v85, v72
	v_pk_fma_f32 v[24:25], v[26:27], v[64:65], v[24:25]
	v_pk_mul_f32 v[42:43], v[42:43], v[84:85]
	v_pk_fma_f32 v[24:25], v[18:19], v[50:51], v[24:25]
	s_nop 0
	v_pk_mul_f32 v[22:23], v[24:25], v[22:23]
	v_pk_fma_f32 v[24:25], v[34:35], v[44:45], v[46:47]
	s_nop 0
	v_pk_fma_f32 v[24:25], v[30:31], v[48:49], v[24:25]
	s_nop 0
	v_pk_mul_f32 v[24:25], v[24:25], v[42:43]
	s_nop 7
	s_nop 1
	v_cvt_pk_bf16_f32 v23, v23, v25
	v_cvt_pk_bf16_f32 v22, v22, v24
	v_mov_b32_e32 v24, v15
	v_mov_b32_e32 v15, v16
	global_store_dwordx2 v[82:83], v[22:23], off offset:8
	v_mov_b32_e32 v22, v11
	v_mov_b32_e32 v23, v13
	v_mov_b32_e32 v11, v12
	v_pk_mul_f32 v[12:13], v[14:15], v[90:91]
	v_pk_fma_f32 v[14:15], v[28:29], v[104:105], v[106:107]
	v_mov_b32_e32 v25, v17
	v_pk_fma_f32 v[14:15], v[20:21], v[108:109], v[14:15]
	v_pk_mul_f32 v[24:25], v[24:25], v[90:91]
	v_pk_fma_f32 v[14:15], v[12:13], v[110:111], v[14:15]
	v_pk_fma_f32 v[28:29], v[34:35], v[36:37], v[40:41]
	v_mul_f32_e32 v16, 0xbfb8aa3b, v14
	v_exp_f32_e32 v42, v16
	v_pk_fma_f32 v[16:17], v[26:27], v[54:55], v[60:61]
	v_pk_fma_f32 v[26:27], v[38:39], v[52:53], v[56:57]
	v_mul_f32_e32 v38, 0xbfb8aa3b, v15
	v_pk_fma_f32 v[26:27], v[32:33], v[62:63], v[26:27]
	v_exp_f32_e32 v39, v38
	v_pk_fma_f32 v[26:27], v[24:25], v[66:67], v[26:27]
	v_add_f32_e32 v34, 1.0, v42
	v_mul_f32_e32 v35, 0xbfb8aa3b, v26
	v_exp_f32_e32 v35, v35
	v_rcp_f32_e32 v34, v34
	v_pk_mul_f32 v[10:11], v[10:11], v[90:91]
	v_pk_fma_f32 v[16:17], v[18:19], v[64:65], v[16:17]
	v_add_f32_e32 v35, 1.0, v35
	v_rcp_f32_e32 v38, v35
	v_add_f32_e32 v35, 1.0, v39
	v_mul_f32_e32 v39, 0xbfb8aa3b, v27
	v_rcp_f32_e32 v35, v35
	v_exp_f32_e32 v39, v39
	v_pk_fma_f32 v[16:17], v[10:11], v[50:51], v[16:17]
	v_pk_mul_f32 v[22:23], v[22:23], v[90:91]
	v_pk_mul_f32 v[14:15], v[14:15], v[34:35]
	v_add_f32_e32 v34, 1.0, v39
	v_rcp_f32_e32 v39, v34
	v_pk_mul_f32 v[14:15], v[16:17], v[14:15]
	v_pk_fma_f32 v[16:17], v[30:31], v[44:45], v[28:29]
	v_pk_mul_f32 v[26:27], v[26:27], v[38:39]
	v_pk_fma_f32 v[16:17], v[22:23], v[48:49], v[16:17]
	s_nop 0
	v_pk_mul_f32 v[16:17], v[16:17], v[26:27]
	s_nop 7
; __device__ __forceinline__ unsigned pk2(float lo, float hi) { return f2bf(lo) | (f2bf(hi) << 16); }
; __device__ __forceinline__ float silu_fast(float x) { return x * __builtin_amdgcn_rcpf(1.f + __builtin_amdgcn_exp2f(-1.4426950408889634f * x)); }
; __device__ __forceinline__ float dpp_shr1(float x) { return __builtin_bit_cast(float, __builtin_amdgcn_update_dpp(0, __builtin_bit_cast(int, x), 0x111, 0xf, 0xf, true)); }
;     __device__ __forceinline__ void operator()(const f32x4 (&acc)[2][2][4][2], const pg8::Unit& u, int wr, int wc, int fr, int fq) const {
;     ...
;             for (int jj = 0; jj < 4; ++jj) {
;                 float g2 = dpp_shr1(g[6][jj]), g1 = dpp_shr1(g[7][jj]), v2 = dpp_shr1(v[6][jj]), v1 = dpp_shr1(v[7][jj]);
; #pragma unroll
;                 for (int e = 0; e < 8; ++e) { const float g0 = g[e][jj], v0 = v[e][jj];
;                     const float cg = bg[jj] + wg0[jj] * g2 + wg1[jj] * g1 + wg2[jj] * g0, cv = bv[jj] + wv0[jj] * v2 + wv1[jj] * v1 + wv2[jj] * v0;
;                     g[e][jj] = silu_fast(cg) * cv; g2 = g1; g1 = g0; v2 = v1; v1 = v0; } }
; #pragma unroll
;             for (int e = 0; e < 8; ++e) { v2u w; w.x = pk2(g[e][0], g[e][1]); w.y = pk2(g[e][2], g[e][3]); *(v2u*)(ACT + (size_t)(tok0 + e) * FFH + cc) = w; }
	s_nop 1
	v_cvt_pk_bf16_f32 v15, v15, v17
	v_cvt_pk_bf16_f32 v14, v14, v16
	v_mov_b32_e32 v16, v7
	v_mov_b32_e32 v7, v8
	global_store_dwordx2 v[80:81], v[14:15], off offset:8
	v_mov_b32_e32 v14, v3
	v_mov_b32_e32 v15, v5
	v_mov_b32_e32 v3, v4
	v_pk_mul_f32 v[4:5], v[6:7], v[58:59]
	v_pk_fma_f32 v[6:7], v[20:21], v[104:105], v[106:107]
	v_mov_b32_e32 v17, v9
	v_pk_fma_f32 v[6:7], v[12:13], v[108:109], v[6:7]
	v_pk_mul_f32 v[16:17], v[16:17], v[58:59]
	v_pk_fma_f32 v[6:7], v[4:5], v[110:111], v[6:7]
	v_pk_mul_f32 v[2:3], v[2:3], v[58:59]
	v_mul_f32_e32 v8, 0xbfb8aa3b, v6
	v_exp_f32_e32 v26, v8
	v_pk_fma_f32 v[8:9], v[18:19], v[54:55], v[60:61]
	v_pk_fma_f32 v[18:19], v[32:33], v[52:53], v[56:57]
	v_mul_f32_e32 v28, 0xbfb8aa3b, v7
	v_pk_fma_f32 v[18:19], v[24:25], v[62:63], v[18:19]
	v_exp_f32_e32 v29, v28
	v_pk_fma_f32 v[18:19], v[16:17], v[66:67], v[18:19]
	v_add_f32_e32 v26, 1.0, v26
	v_mul_f32_e32 v27, 0xbfb8aa3b, v18
	v_exp_f32_e32 v27, v27
	v_rcp_f32_e32 v26, v26
	v_pk_fma_f32 v[8:9], v[10:11], v[64:65], v[8:9]
	v_pk_fma_f32 v[20:21], v[30:31], v[36:37], v[40:41]
	v_add_f32_e32 v27, 1.0, v27
	v_rcp_f32_e32 v28, v27
	v_add_f32_e32 v27, 1.0, v29
	v_mul_f32_e32 v29, 0xbfb8aa3b, v19
	v_rcp_f32_e32 v27, v27
	v_exp_f32_e32 v29, v29
	v_pk_fma_f32 v[8:9], v[2:3], v[50:51], v[8:9]
	v_pk_mul_f32 v[14:15], v[14:15], v[58:59]
	v_pk_mul_f32 v[6:7], v[6:7], v[26:27]
	v_add_f32_e32 v26, 1.0, v29
	v_rcp_f32_e32 v29, v26
	v_pk_mul_f32 v[6:7], v[8:9], v[6:7]
	v_pk_fma_f32 v[8:9], v[22:23], v[44:45], v[20:21]
	v_pk_mul_f32 v[18:19], v[18:19], v[28:29]
	v_pk_fma_f32 v[8:9], v[14:15], v[48:49], v[8:9]
	s_nop 0
	v_pk_mul_f32 v[8:9], v[8:9], v[18:19]
	s_nop 7
	s_nop 1
	v_cvt_pk_bf16_f32 v7, v7, v9
	v_cvt_pk_bf16_f32 v6, v6, v8
	global_store_dwordx2 v[76:77], v[6:7], off offset:8
	v_pk_fma_f32 v[6:7], v[12:13], v[104:105], v[106:107]
	v_pk_fma_f32 v[12:13], v[22:23], v[36:37], v[40:41]
	v_pk_fma_f32 v[6:7], v[4:5], v[108:109], v[6:7]
	v_pk_fma_f32 v[4:5], v[4:5], v[104:105], v[106:107]
	v_pk_fma_f32 v[6:7], v[96:97], v[110:111], v[6:7]
	v_pk_fma_f32 v[4:5], v[96:97], v[108:109], v[4:5]
	v_mul_f32_e32 v8, 0xbfb8aa3b, v6
	v_exp_f32_e32 v18, v8
	v_pk_fma_f32 v[8:9], v[10:11], v[54:55], v[60:61]
	v_pk_fma_f32 v[10:11], v[24:25], v[52:53], v[56:57]
	v_mul_f32_e32 v20, 0xbfb8aa3b, v7
	v_pk_fma_f32 v[10:11], v[16:17], v[62:63], v[10:11]
	v_exp_f32_e32 v21, v20
	v_pk_fma_f32 v[10:11], v[98:99], v[66:67], v[10:11]
	v_add_f32_e32 v18, 1.0, v18
	v_mul_f32_e32 v19, 0xbfb8aa3b, v10
	v_exp_f32_e32 v19, v19
	v_rcp_f32_e32 v18, v18
	v_pk_fma_f32 v[8:9], v[2:3], v[64:65], v[8:9]
	v_pk_fma_f32 v[4:5], v[100:101], v[110:111], v[4:5]
	v_add_f32_e32 v19, 1.0, v19
	v_rcp_f32_e32 v20, v19
	v_add_f32_e32 v19, 1.0, v21
	v_mul_f32_e32 v21, 0xbfb8aa3b, v11
	v_rcp_f32_e32 v19, v19
	v_exp_f32_e32 v21, v21
	v_pk_fma_f32 v[8:9], v[70:71], v[50:51], v[8:9]
	v_pk_fma_f32 v[2:3], v[2:3], v[54:55], v[60:61]
	v_pk_mul_f32 v[6:7], v[6:7], v[18:19]
	v_add_f32_e32 v18, 1.0, v21
	v_rcp_f32_e32 v21, v18
	v_pk_mul_f32 v[6:7], v[8:9], v[6:7]
	v_pk_fma_f32 v[8:9], v[14:15], v[44:45], v[12:13]
	v_pk_fma_f32 v[2:3], v[70:71], v[64:65], v[2:3]
	v_pk_fma_f32 v[8:9], v[68:69], v[48:49], v[8:9]
	v_pk_mul_f32 v[10:11], v[10:11], v[20:21]
	v_pk_fma_f32 v[2:3], v[92:93], v[50:51], v[2:3]
	v_pk_mul_f32 v[8:9], v[8:9], v[10:11]
	s_nop 7
	s_nop 1
	v_cvt_pk_bf16_f32 v6, v6, v8
	v_mul_f32_e32 v8, 0xbfb8aa3b, v4
	v_cvt_pk_bf16_f32 v7, v7, v9
	v_exp_f32_e32 v10, v8
	v_pk_fma_f32 v[8:9], v[16:17], v[52:53], v[56:57]
	global_store_dwordx2 v[74:75], v[6:7], off offset:8
	v_pk_fma_f32 v[8:9], v[98:99], v[62:63], v[8:9]
	v_add_f32_e32 v6, 1.0, v10
	v_pk_fma_f32 v[8:9], v[102:103], v[66:67], v[8:9]
	v_mul_f32_e32 v10, 0xbfb8aa3b, v5
	v_mul_f32_e32 v11, 0xbfb8aa3b, v8
	v_exp_f32_e32 v11, v11
	v_rcp_f32_e32 v6, v6
	v_add_f32_e32 v7, 1.0, v11
	v_exp_f32_e32 v11, v10
	v_rcp_f32_e32 v10, v7
	v_add_f32_e32 v7, 1.0, v11
	v_rcp_f32_e32 v7, v7
	v_mul_f32_e32 v11, 0xbfb8aa3b, v9
	v_exp_f32_e32 v11, v11
	v_pk_mul_f32 v[4:5], v[4:5], v[6:7]
	s_nop 0
	v_pk_mul_f32 v[2:3], v[2:3], v[4:5]
	v_add_f32_e32 v4, 1.0, v11
	v_rcp_f32_e32 v11, v4
	v_pk_fma_f32 v[4:5], v[14:15], v[36:37], v[40:41]
	v_pk_mul_f32 v[6:7], v[8:9], v[10:11]
	v_pk_fma_f32 v[4:5], v[68:69], v[44:45], v[4:5]
	s_nop 0
	v_pk_fma_f32 v[4:5], v[94:95], v[48:49], v[4:5]
	s_nop 0
	v_pk_mul_f32 v[4:5], v[4:5], v[6:7]
	v_and_b32_sdwa v6, v3, v234 dst_sel:DWORD dst_unused:UNUSED_PAD src0_sel:WORD_1 src1_sel:DWORD
	v_and_b32_sdwa v7, v2, v234 dst_sel:DWORD dst_unused:UNUSED_PAD src0_sel:WORD_1 src1_sel:DWORD
	v_add3_u32 v2, v2, v7, s59
	v_add3_u32 v3, v3, v6, s59
	v_and_b32_sdwa v6, v5, v234 dst_sel:DWORD dst_unused:UNUSED_PAD src0_sel:WORD_1 src1_sel:DWORD
	v_and_b32_sdwa v7, v4, v234 dst_sel:DWORD dst_unused:UNUSED_PAD src0_sel:WORD_1 src1_sel:DWORD
	v_add3_u32 v5, v5, v6, s59
	v_add3_u32 v4, v4, v7, s59
	v_and_b32_e32 v5, 0xffff0000, v5
	v_and_b32_e32 v4, 0xffff0000, v4
	v_or_b32_sdwa v3, v5, v3 dst_sel:DWORD dst_unused:UNUSED_PAD src0_sel:DWORD src1_sel:WORD_1
	v_or_b32_sdwa v2, v4, v2 dst_sel:DWORD dst_unused:UNUSED_PAD src0_sel:DWORD src1_sel:WORD_1
	global_store_dwordx2 v[78:79], v[2:3], off offset:8
	s_cbranch_vccz .LBB0_5598

; #define PG8_STAGE(bufoff, gbase, voff) do { _Pragma("unroll") for (int _i = 0; _i < 2; ++_i) \
;         __builtin_amdgcn_global_load_lds((const unsigned*)((const char*)(gbase) + (voff)[_i]), (LAS unsigned*)(lds + (bufoff) + ldsw + _i * 8192), 16, 0, 0); } while (0)
; #define PG8_LDA(dst, b, h) do { _Pragma("unroll") for (int m = 0; m < 4; ++m) _Pragma("unroll") for (int k = 0; k < 2; ++k) dst[m][k] = *(const LAS bf16x8*)(lds + PG8_SA(b, h) + aoff + m * 2048 + k * 1024); } while (0)
; #define PG8_LDB(dst, b, h) do { _Pragma("unroll") for (int n = 0; n < 2; ++n) _Pragma("unroll") for (int k = 0; k < 2; ++k) dst[n][k] = *(const LAS bf16x8*)(lds + PG8_SB(b, h) + boff + n * 2048 + k * 1024); } while (0)
; #define PG8_MMA(ai, bj, At, Bt) do { __builtin_amdgcn_s_setprio(1); _Pragma("unroll") for (int m = 0; m < 4; ++m) _Pragma("unroll") for (int n = 0; n < 2; ++n) _Pragma("unroll") for (int k = 0; k < 2; ++k) \
;         acc[ai][bj][m][n] = __builtin_amdgcn_mfma_f32_16x16x32_bf16(Bt[n][k], At[m][k], acc[ai][bj][m][n], 0, 0, 0); __builtin_amdgcn_s_setprio(0); } while (0)
; #define PG8_WAIT_L(n) asm volatile("s_waitcnt lgkmcnt(" #n ")" ::: "memory")
; #define PG8_BAR __builtin_amdgcn_s_barrier()
; #define PG8_SCHED __builtin_amdgcn_sched_barrier(0)
; template <class PT, class Epi>
; __device__ __forceinline__ void gemm_phase_once(LAS unsigned char* lds, const PT& S, const Epi& E, bool epi_on) {
;     ...
;             PG8_LDB(B0, 0, 0); PG8_SCHED; PG8_LDA(At, 0, 0); PG8_STAGE(PG8_SA(1, 1), a1 + hstepA, voffA);
;             PG8_WAIT_L(8); PG8_BAR; PG8_WAIT_L(0); PG8_MMA(0, 0, At, B0); PG8_BAR; PG8_SCHED;
;             PG8_LDB(B1, 0, 1); PG8_STAGE(PG8_SB(0, 0), b2, voffB);
;             PG8_BAR; PG8_WAIT_L(0); PG8_MMA(0, 1, At, B1); PG8_BAR;
;             PG8_LDA(At, 0, 1); PG8_STAGE(PG8_SA(0, 0), a2, voffA);
;             PG8_BAR; PG8_WAIT_L(0); PG8_MMA(1, 0, At, B0); PG8_BAR; PG8_SCHED;
.LBB0_5583:
	ds_read_b128 v[58:61], v231
	ds_read_b128 v[70:73], v231 offset:1024
	ds_read_b128 v[156:159], v231 offset:2048
	ds_read_b128 v[160:163], v231 offset:3072
	s_add_u32 s38, s36, 0x100
	s_addc_u32 s39, s37, 0
	s_cmp_eq_u32 s65, 28
	s_cselect_b32 s43, s27, s39
	s_cselect_b32 s42, s35, s38
	s_cselect_b32 s41, s25, s64
	s_cselect_b32 s40, s62, s63
	v_lshl_add_u64 v[200:201], s[36:37], 0, v[148:149]
	s_add_i32 m0, s49, 0xc000
	ds_read_b128 v[168:171], v232
	ds_read_b128 v[172:175], v232 offset:1024
	ds_read_b128 v[176:179], v232 offset:2048
	ds_read_b128 v[180:183], v232 offset:3072
	ds_read_b128 v[184:187], v232 offset:4096
	ds_read_b128 v[188:191], v232 offset:5120
	ds_read_b128 v[192:195], v232 offset:6144
	ds_read_b128 v[196:199], v232 offset:7168
	global_load_lds_dwordx4 v[200:201], off
	v_lshl_add_u64 v[200:201], s[36:37], 0, v[150:151]
	s_add_i32 m0, s49, 0xe000
	s_nop 0
	global_load_lds_dwordx4 v[200:201], off
	s_waitcnt lgkmcnt(8)
	s_barrier
	s_waitcnt lgkmcnt(0)
	s_setprio 1
	s_waitcnt lgkmcnt(0)
	v_mfma_f32_16x16x32_bf16 v[134:137], v[58:61], v[168:171], v[134:137]
	v_mfma_f32_16x16x32_bf16 v[66:69], v[156:159], v[168:171], v[66:69]
	v_mfma_f32_16x16x32_bf16 v[126:129], v[58:61], v[176:179], v[126:129]
	v_mfma_f32_16x16x32_bf16 v[62:65], v[156:159], v[176:179], v[62:65]
	v_mfma_f32_16x16x32_bf16 v[102:105], v[58:61], v[184:187], v[102:105]
	v_mfma_f32_16x16x32_bf16 v[30:33], v[156:159], v[184:187], v[30:33]
	v_mfma_f32_16x16x32_bf16 v[98:101], v[58:61], v[192:195], v[98:101]
	v_mfma_f32_16x16x32_bf16 v[22:25], v[156:159], v[192:195], v[22:25]
	v_mfma_f32_16x16x32_bf16 v[134:137], v[70:73], v[172:175], v[134:137]
	v_mfma_f32_16x16x32_bf16 v[66:69], v[160:163], v[172:175], v[66:69]
	v_mfma_f32_16x16x32_bf16 v[126:129], v[70:73], v[180:183], v[126:129]
	v_mfma_f32_16x16x32_bf16 v[62:65], v[160:163], v[180:183], v[62:65]
	v_mfma_f32_16x16x32_bf16 v[102:105], v[70:73], v[188:191], v[102:105]
	v_mfma_f32_16x16x32_bf16 v[30:33], v[160:163], v[188:191], v[30:33]
	v_mfma_f32_16x16x32_bf16 v[98:101], v[70:73], v[196:199], v[98:101]
	v_mfma_f32_16x16x32_bf16 v[22:25], v[160:163], v[196:199], v[22:25]
	s_setprio 0
	s_barrier
	s_add_i32 s36, s57, s46
	v_lshl_add_u64 v[216:217], s[40:41], 0, v[144:145]
	s_mov_b32 m0, s36
	ds_read_b128 v[200:203], v233
	ds_read_b128 v[204:207], v233 offset:1024
	ds_read_b128 v[208:211], v233 offset:2048
	ds_read_b128 v[212:215], v233 offset:3072
	global_load_lds_dwordx4 v[216:217], off
	v_lshl_add_u64 v[218:219], s[40:41], 0, v[138:139]
	s_add_i32 m0, s36, 0x2000
	s_nop 0
	global_load_lds_dwordx4 v[218:219], off
	s_barrier
	s_waitcnt lgkmcnt(0)
	s_setprio 1
	s_waitcnt lgkmcnt(0)
	v_mfma_f32_16x16x32_bf16 v[122:125], v[200:203], v[168:171], v[122:125]
	v_mfma_f32_16x16x32_bf16 v[54:57], v[208:211], v[168:171], v[54:57]
	v_mfma_f32_16x16x32_bf16 v[114:117], v[200:203], v[176:179], v[114:117]
	v_mfma_f32_16x16x32_bf16 v[50:53], v[208:211], v[176:179], v[50:53]
	v_mfma_f32_16x16x32_bf16 v[94:97], v[200:203], v[184:187], v[94:97]
	v_mfma_f32_16x16x32_bf16 v[26:29], v[208:211], v[184:187], v[26:29]
	v_mfma_f32_16x16x32_bf16 v[90:93], v[200:203], v[192:195], v[90:93]
	v_mfma_f32_16x16x32_bf16 v[18:21], v[208:211], v[192:195], v[18:21]
	v_mfma_f32_16x16x32_bf16 v[122:125], v[204:207], v[172:175], v[122:125]
	v_mfma_f32_16x16x32_bf16 v[54:57], v[212:215], v[172:175], v[54:57]
	v_mfma_f32_16x16x32_bf16 v[114:117], v[204:207], v[180:183], v[114:117]
	v_mfma_f32_16x16x32_bf16 v[50:53], v[212:215], v[180:183], v[50:53]
	v_mfma_f32_16x16x32_bf16 v[94:97], v[204:207], v[188:191], v[94:97]
	v_mfma_f32_16x16x32_bf16 v[26:29], v[212:215], v[188:191], v[26:29]
	v_mfma_f32_16x16x32_bf16 v[90:93], v[204:207], v[196:199], v[90:93]
	v_mfma_f32_16x16x32_bf16 v[18:21], v[212:215], v[196:199], v[18:21]
	s_setprio 0
	s_mov_b32 m0, s49
	v_lshl_add_u64 v[220:221], s[42:43], 0, v[140:141]
	s_barrier
	ds_read_b128 v[168:171], v232 offset:16384
	ds_read_b128 v[172:175], v232 offset:17408
	ds_read_b128 v[176:179], v232 offset:18432
	ds_read_b128 v[180:183], v232 offset:19456
	ds_read_b128 v[184:187], v232 offset:20480
	ds_read_b128 v[188:191], v232 offset:21504
	ds_read_b128 v[192:195], v232 offset:22528
	ds_read_b128 v[196:199], v232 offset:23552
	global_load_lds_dwordx4 v[220:221], off
	v_lshl_add_u64 v[222:223], s[42:43], 0, v[142:143]
	s_mov_b32 m0, s50
	s_nop 0
	global_load_lds_dwordx4 v[222:223], off
	s_barrier
	s_waitcnt lgkmcnt(0)
	s_setprio 1
	s_waitcnt lgkmcnt(0)
	v_mfma_f32_16x16x32_bf16 v[86:89], v[58:61], v[168:171], v[86:89]
	v_mfma_f32_16x16x32_bf16 v[14:17], v[156:159], v[168:171], v[14:17]
	v_mfma_f32_16x16x32_bf16 v[82:85], v[58:61], v[176:179], v[82:85]
	v_mfma_f32_16x16x32_bf16 v[6:9], v[156:159], v[176:179], v[6:9]
	v_mfma_f32_16x16x32_bf16 v[130:133], v[58:61], v[184:187], v[130:133]
	v_mfma_f32_16x16x32_bf16 v[46:49], v[156:159], v[184:187], v[46:49]
	v_mfma_f32_16x16x32_bf16 v[42:45], v[156:159], v[192:195], v[42:45]
	v_mfma_f32_16x16x32_bf16 v[86:89], v[70:73], v[172:175], v[86:89]
	v_mfma_f32_16x16x32_bf16 v[14:17], v[160:163], v[172:175], v[14:17]
	v_mfma_f32_16x16x32_bf16 v[82:85], v[70:73], v[180:183], v[82:85]
	v_mfma_f32_16x16x32_bf16 v[6:9], v[160:163], v[180:183], v[6:9]
	v_mfma_f32_16x16x32_bf16 v[130:133], v[70:73], v[188:191], v[130:133]
	v_mfma_f32_16x16x32_bf16 v[46:49], v[160:163], v[188:191], v[46:49]
	v_mfma_f32_16x16x32_bf16 v[58:61], v[58:61], v[192:195], v[110:113]
	v_mfma_f32_16x16x32_bf16 v[42:45], v[160:163], v[196:199], v[42:45]
	v_mfma_f32_16x16x32_bf16 v[58:61], v[70:73], v[196:199], v[58:61]
	s_setprio 0
	s_barrier
; #define PG8_STAGE(bufoff, gbase, voff) do { _Pragma("unroll") for (int _i = 0; _i < 2; ++_i) \
;         __builtin_amdgcn_global_load_lds((const unsigned*)((const char*)(gbase) + (voff)[_i]), (LAS unsigned*)(lds + (bufoff) + ldsw + _i * 8192), 16, 0, 0); } while (0)
; #define PG8_LDA(dst, b, h) do { _Pragma("unroll") for (int m = 0; m < 4; ++m) _Pragma("unroll") for (int k = 0; k < 2; ++k) dst[m][k] = *(const LAS bf16x8*)(lds + PG8_SA(b, h) + aoff + m * 2048 + k * 1024); } while (0)
; #define PG8_LDB(dst, b, h) do { _Pragma("unroll") for (int n = 0; n < 2; ++n) _Pragma("unroll") for (int k = 0; k < 2; ++k) dst[n][k] = *(const LAS bf16x8*)(lds + PG8_SB(b, h) + boff + n * 2048 + k * 1024); } while (0)
; #define PG8_MMA(ai, bj, At, Bt) do { __builtin_amdgcn_s_setprio(1); _Pragma("unroll") for (int m = 0; m < 4; ++m) _Pragma("unroll") for (int n = 0; n < 2; ++n) _Pragma("unroll") for (int k = 0; k < 2; ++k) \
;         acc[ai][bj][m][n] = __builtin_amdgcn_mfma_f32_16x16x32_bf16(Bt[n][k], At[m][k], acc[ai][bj][m][n], 0, 0, 0); __builtin_amdgcn_s_setprio(0); } while (0)
; #define PG8_WAIT_V(n) asm volatile("s_waitcnt vmcnt(" #n ")" ::: "memory")
; #define PG8_WAIT_L(n) asm volatile("s_waitcnt lgkmcnt(" #n ")" ::: "memory")
; #define PG8_BAR __builtin_amdgcn_s_barrier()
; #define PG8_SCHED __builtin_amdgcn_sched_barrier(0)
; template <class PT, class Epi>
; __device__ __forceinline__ void gemm_phase_once(LAS unsigned char* lds, const PT& S, const Epi& E, bool epi_on) {
;     ...
;             PG8_STAGE(PG8_SB(0, 1), b2 + hstepB, voffB);
;             PG8_WAIT_V(6); PG8_BAR; PG8_MMA(1, 1, At, B1); PG8_BAR;
;             PG8_LDB(B0, 1, 0); PG8_SCHED; PG8_LDA(At, 1, 0); PG8_STAGE(PG8_SA(0, 1), a2 + hstepA, voffA);
;             PG8_WAIT_L(8); PG8_BAR; PG8_WAIT_L(0); PG8_MMA(0, 0, At, B0); PG8_BAR; PG8_SCHED;
;             PG8_LDB(B1, 1, 1); PG8_STAGE(PG8_SB(1, 0), b3, voffB);
;             PG8_BAR; PG8_WAIT_L(0); PG8_MMA(0, 1, At, B1); PG8_BAR;
;             PG8_LDA(At, 1, 1); PG8_STAGE(PG8_SA(1, 0), a3, voffA);
;             PG8_BAR; PG8_WAIT_L(0); PG8_MMA(1, 0, At, B0); PG8_BAR; PG8_SCHED;
	s_add_u32 s36, s40, 0x80000
	s_addc_u32 s37, s41, 0
	s_add_i32 s66, s58, s46
	v_lshl_add_u64 v[70:71], s[36:37], 0, v[144:145]
	s_mov_b32 m0, s66
	s_nop 0
	global_load_lds_dwordx4 v[70:71], off
	v_lshl_add_u64 v[70:71], s[36:37], 0, v[138:139]
	s_add_i32 m0, s66, 0x2000
	s_nop 0
	global_load_lds_dwordx4 v[70:71], off
	s_waitcnt vmcnt(6)
	s_barrier
	s_setprio 1
	v_mfma_f32_16x16x32_bf16 v[70:73], v[200:203], v[168:171], v[78:81]
	v_mfma_f32_16x16x32_bf16 v[78:81], v[200:203], v[184:187], v[118:121]
	v_mfma_f32_16x16x32_bf16 v[10:13], v[208:211], v[168:171], v[10:13]
	v_mfma_f32_16x16x32_bf16 v[74:77], v[200:203], v[176:179], v[74:77]
	v_mfma_f32_16x16x32_bf16 v[2:5], v[208:211], v[176:179], v[2:5]
	v_mfma_f32_16x16x32_bf16 v[118:121], v[204:207], v[188:191], v[78:81]
	v_mfma_f32_16x16x32_bf16 v[38:41], v[208:211], v[184:187], v[38:41]
	v_mfma_f32_16x16x32_bf16 v[78:81], v[200:203], v[192:195], v[106:109]
	v_mfma_f32_16x16x32_bf16 v[34:37], v[208:211], v[192:195], v[34:37]
	v_mfma_f32_16x16x32_bf16 v[10:13], v[212:215], v[172:175], v[10:13]
	v_mfma_f32_16x16x32_bf16 v[74:77], v[204:207], v[180:183], v[74:77]
	v_mfma_f32_16x16x32_bf16 v[2:5], v[212:215], v[180:183], v[2:5]
	v_mfma_f32_16x16x32_bf16 v[38:41], v[212:215], v[188:191], v[38:41]
	v_mfma_f32_16x16x32_bf16 v[106:109], v[204:207], v[196:199], v[78:81]
	v_mfma_f32_16x16x32_bf16 v[34:37], v[212:215], v[196:199], v[34:37]
	v_mfma_f32_16x16x32_bf16 v[70:73], v[204:207], v[172:175], v[70:73]
	s_setprio 0
	s_add_i32 s66, 0, 0x18000
	v_add_u32_e32 v160, s66, v228
	s_barrier
	ds_read_b128 v[78:81], v160
	ds_read_b128 v[110:113], v160 offset:1024
	ds_read_b128 v[156:159], v160 offset:2048
	ds_read_b128 v[160:163], v160 offset:3072
	s_add_u32 s36, s42, 0x4000
	s_addc_u32 s37, s43, 0
	s_mov_b32 m0, s51
	v_lshl_add_u64 v[200:201], s[36:37], 0, v[140:141]
	ds_read_b128 v[168:171], v232 offset:32768
	ds_read_b128 v[172:175], v232 offset:33792
	ds_read_b128 v[176:179], v232 offset:34816
	ds_read_b128 v[180:183], v232 offset:35840
	ds_read_b128 v[184:187], v232 offset:36864
	ds_read_b128 v[188:191], v232 offset:37888
	ds_read_b128 v[192:195], v232 offset:38912
	ds_read_b128 v[196:199], v232 offset:39936
	global_load_lds_dwordx4 v[200:201], off
	v_lshl_add_u64 v[200:201], s[36:37], 0, v[142:143]
	s_mov_b32 m0, s52
	s_nop 0
	global_load_lds_dwordx4 v[200:201], off
	s_waitcnt lgkmcnt(8)
	s_barrier
	s_waitcnt lgkmcnt(0)
	s_setprio 1
	s_waitcnt lgkmcnt(0)
	v_mfma_f32_16x16x32_bf16 v[134:137], v[78:81], v[168:171], v[134:137]
	v_mfma_f32_16x16x32_bf16 v[66:69], v[156:159], v[168:171], v[66:69]
	v_mfma_f32_16x16x32_bf16 v[126:129], v[78:81], v[176:179], v[126:129]
	v_mfma_f32_16x16x32_bf16 v[62:65], v[156:159], v[176:179], v[62:65]
	v_mfma_f32_16x16x32_bf16 v[102:105], v[78:81], v[184:187], v[102:105]
	v_mfma_f32_16x16x32_bf16 v[30:33], v[156:159], v[184:187], v[30:33]
	v_mfma_f32_16x16x32_bf16 v[98:101], v[78:81], v[192:195], v[98:101]
	v_mfma_f32_16x16x32_bf16 v[22:25], v[156:159], v[192:195], v[22:25]
	v_mfma_f32_16x16x32_bf16 v[134:137], v[110:113], v[172:175], v[134:137]
	v_mfma_f32_16x16x32_bf16 v[66:69], v[160:163], v[172:175], v[66:69]
	v_mfma_f32_16x16x32_bf16 v[126:129], v[110:113], v[180:183], v[126:129]
	v_mfma_f32_16x16x32_bf16 v[62:65], v[160:163], v[180:183], v[62:65]
	v_mfma_f32_16x16x32_bf16 v[102:105], v[110:113], v[188:191], v[102:105]
	v_mfma_f32_16x16x32_bf16 v[30:33], v[160:163], v[188:191], v[30:33]
	v_mfma_f32_16x16x32_bf16 v[98:101], v[110:113], v[196:199], v[98:101]
	v_mfma_f32_16x16x32_bf16 v[22:25], v[160:163], v[196:199], v[22:25]
	s_setprio 0
	s_barrier
	s_add_i32 s42, 0, 0x1c000
	s_add_i32 s36, s66, s46
	v_add_u32_e32 v165, s42, v228
	v_lshl_add_u64 v[216:217], v[216:217], 0, s[10:11]
	s_mov_b32 m0, s36
	ds_read_b128 v[200:203], v165
	ds_read_b128 v[204:207], v165 offset:1024
	ds_read_b128 v[208:211], v165 offset:2048
	ds_read_b128 v[212:215], v165 offset:3072
	global_load_lds_dwordx4 v[216:217], off
	v_lshl_add_u64 v[216:217], v[218:219], 0, s[10:11]
	s_add_i32 m0, s36, 0x2000
	s_nop 0
	global_load_lds_dwordx4 v[216:217], off
	s_barrier
	s_waitcnt lgkmcnt(0)
	s_setprio 1
	s_waitcnt lgkmcnt(0)
	v_mfma_f32_16x16x32_bf16 v[122:125], v[200:203], v[168:171], v[122:125]
	v_mfma_f32_16x16x32_bf16 v[54:57], v[208:211], v[168:171], v[54:57]
	v_mfma_f32_16x16x32_bf16 v[114:117], v[200:203], v[176:179], v[114:117]
	v_mfma_f32_16x16x32_bf16 v[50:53], v[208:211], v[176:179], v[50:53]
	v_mfma_f32_16x16x32_bf16 v[94:97], v[200:203], v[184:187], v[94:97]
	v_mfma_f32_16x16x32_bf16 v[26:29], v[208:211], v[184:187], v[26:29]
	v_mfma_f32_16x16x32_bf16 v[90:93], v[200:203], v[192:195], v[90:93]
	v_mfma_f32_16x16x32_bf16 v[18:21], v[208:211], v[192:195], v[18:21]
	v_mfma_f32_16x16x32_bf16 v[122:125], v[204:207], v[172:175], v[122:125]
	v_mfma_f32_16x16x32_bf16 v[54:57], v[212:215], v[172:175], v[54:57]
	v_mfma_f32_16x16x32_bf16 v[114:117], v[204:207], v[180:183], v[114:117]
	v_mfma_f32_16x16x32_bf16 v[50:53], v[212:215], v[180:183], v[50:53]
	v_mfma_f32_16x16x32_bf16 v[94:97], v[204:207], v[188:191], v[94:97]
	v_mfma_f32_16x16x32_bf16 v[26:29], v[212:215], v[188:191], v[26:29]
	v_mfma_f32_16x16x32_bf16 v[90:93], v[204:207], v[196:199], v[90:93]
	v_mfma_f32_16x16x32_bf16 v[18:21], v[212:215], v[196:199], v[18:21]
	s_setprio 0
	s_mov_b32 m0, s54
	v_lshl_add_u64 v[216:217], v[220:221], 0, s[10:11]
	s_barrier
	ds_read_b128 v[168:171], v232 offset:49152
	ds_read_b128 v[172:175], v232 offset:50176
	ds_read_b128 v[176:179], v232 offset:51200
	ds_read_b128 v[180:183], v232 offset:52224
	ds_read_b128 v[184:187], v232 offset:53248
	ds_read_b128 v[188:191], v232 offset:54272
	ds_read_b128 v[192:195], v232 offset:55296
	ds_read_b128 v[196:199], v232 offset:56320
	global_load_lds_dwordx4 v[216:217], off
	v_lshl_add_u64 v[216:217], v[222:223], 0, s[10:11]
	s_mov_b32 m0, s55
	s_nop 0
	global_load_lds_dwordx4 v[216:217], off
	s_barrier
; __device__ __forceinline__ unsigned pk2(float lo, float hi) { return f2bf(lo) | (f2bf(hi) << 16); }
; #define PG8_STAGE(bufoff, gbase, voff) do { _Pragma("unroll") for (int _i = 0; _i < 2; ++_i) \
;         __builtin_amdgcn_global_load_lds((const unsigned*)((const char*)(gbase) + (voff)[_i]), (LAS unsigned*)(lds + (bufoff) + ldsw + _i * 8192), 16, 0, 0); } while (0)
; #define PG8_WAIT_V(n) asm volatile("s_waitcnt vmcnt(" #n ")" ::: "memory")
; #define PG8_BAR __builtin_amdgcn_s_barrier()
; template <class PT, class Epi>
; __device__ __forceinline__ void gemm_phase_once(LAS unsigned char* lds, const PT& S, const Epi& E, bool epi_on) {
;     ...
;             PG8_BAR; PG8_WAIT_L(0); PG8_MMA(1, 0, At, B0); PG8_BAR; PG8_SCHED;
;             PG8_STAGE(PG8_SB(1, 1), b3 + hstepB, voffB);
;             PG8_WAIT_V(6); PG8_BAR; PG8_MMA(1, 1, At, B1); PG8_BAR;
;     __device__ __forceinline__ void operator()(const f32x4 (&acc)[2][2][4][2], const pg8::Unit& u, int wr, int wc, int fr, int fq) const {
;         const int ch0 = 128 * u.pn + 32 * wc + 8 * fq, tok0 = 256 * u.pm + 128 * wr + 8 * fr;
;         const f32x4 r0 = *(const f32x4*)(RS + tok0), r1 = *(const f32x4*)(RS + tok0 + 4);
;         bf16* hb = HALO + ((size_t)((u.pm * 44 + u.pn) * 2 + wr) * 4) * 256 + 32 * wc + 8 * fq;
; #pragma unroll
;         for (int n = 0; n < 2; ++n) {
;             float g[8][4], v[8][4];
; #pragma unroll
;             for (int e = 0; e < 8; ++e) { const float rs = (e < 4) ? r0[e & 3] : r1[e & 3];
; #pragma unroll
;                 for (int jj = 0; jj < 4; ++jj) { g[e][jj] = acc[e >> 2][0][e & 3][n][jj] * rs; v[e][jj] = acc[e >> 2][1][e & 3][n][jj] * rs; } }
;             if (fr == 0) {
; #pragma unroll
;                 for (int q = 0; q < 2; ++q) { v2u a, b; a.x = pk2(g[q][0], g[q][1]); a.y = pk2(g[q][2], g[q][3]); b.x = pk2(v[q][0], v[q][1]); b.y = pk2(v[q][2], v[q][3]);
;                     *(v2u*)(hb + (size_t)q * 256 + 4 * n) = a; *(v2u*)(hb + (size_t)q * 256 + 128 + 4 * n) = b; } }
;             if (fr == 15) {
; #pragma unroll
;                 for (int q = 0; q < 2; ++q) { v2u a, b; a.x = pk2(g[6 + q][0], g[6 + q][1]); a.y = pk2(g[6 + q][2], g[6 + q][3]); b.x = pk2(v[6 + q][0], v[6 + q][1]); b.y = pk2(v[6 + q][2], v[6 + q][3]);
;                     *(v2u*)(hb + (size_t)(2 + q) * 256 + 4 * n) = a; *(v2u*)(hb + (size_t)(2 + q) * 256 + 128 + 4 * n) = b; } }
	s_waitcnt lgkmcnt(0)
	s_setprio 1
	s_waitcnt lgkmcnt(0)
	v_mfma_f32_16x16x32_bf16 v[86:89], v[78:81], v[168:171], v[86:89]
	v_mfma_f32_16x16x32_bf16 v[14:17], v[156:159], v[168:171], v[14:17]
	v_mfma_f32_16x16x32_bf16 v[82:85], v[78:81], v[176:179], v[82:85]
	v_mfma_f32_16x16x32_bf16 v[6:9], v[156:159], v[176:179], v[6:9]
	v_mfma_f32_16x16x32_bf16 v[130:133], v[78:81], v[184:187], v[130:133]
	v_mfma_f32_16x16x32_bf16 v[46:49], v[156:159], v[184:187], v[46:49]
	v_mfma_f32_16x16x32_bf16 v[58:61], v[78:81], v[192:195], v[58:61]
	v_mfma_f32_16x16x32_bf16 v[42:45], v[156:159], v[192:195], v[42:45]
	v_mfma_f32_16x16x32_bf16 v[86:89], v[110:113], v[172:175], v[86:89]
	v_mfma_f32_16x16x32_bf16 v[14:17], v[160:163], v[172:175], v[14:17]
	v_mfma_f32_16x16x32_bf16 v[82:85], v[110:113], v[180:183], v[82:85]
	v_mfma_f32_16x16x32_bf16 v[6:9], v[160:163], v[180:183], v[6:9]
	v_mfma_f32_16x16x32_bf16 v[130:133], v[110:113], v[188:191], v[130:133]
	v_mfma_f32_16x16x32_bf16 v[46:49], v[160:163], v[188:191], v[46:49]
	v_mfma_f32_16x16x32_bf16 v[110:113], v[110:113], v[196:199], v[58:61]
	v_mfma_f32_16x16x32_bf16 v[42:45], v[160:163], v[196:199], v[42:45]
	s_setprio 0
	s_barrier
	s_add_u32 s36, s40, 0x80080
	s_addc_u32 s37, s41, 0
	s_add_i32 s40, s42, s46
	v_lshl_add_u64 v[58:59], s[36:37], 0, v[144:145]
	s_mov_b32 m0, s40
	s_nop 0
	global_load_lds_dwordx4 v[58:59], off
	v_lshl_add_u64 v[58:59], s[36:37], 0, v[138:139]
	s_add_i32 m0, s40, 0x2000
	s_nop 0
	global_load_lds_dwordx4 v[58:59], off
	s_waitcnt vmcnt(6)
	s_barrier
	s_setprio 1
	v_mfma_f32_16x16x32_bf16 v[58:61], v[200:203], v[168:171], v[70:73]
	v_mfma_f32_16x16x32_bf16 v[78:81], v[204:207], v[172:175], v[58:61]
	v_mfma_f32_16x16x32_bf16 v[58:61], v[200:203], v[176:179], v[74:77]
	v_mfma_f32_16x16x32_bf16 v[74:77], v[204:207], v[180:183], v[58:61]
	v_mfma_f32_16x16x32_bf16 v[58:61], v[200:203], v[184:187], v[118:121]
	v_mfma_f32_16x16x32_bf16 v[10:13], v[208:211], v[168:171], v[10:13]
	v_mfma_f32_16x16x32_bf16 v[2:5], v[208:211], v[176:179], v[2:5]
	v_mfma_f32_16x16x32_bf16 v[118:121], v[204:207], v[188:191], v[58:61]
	v_mfma_f32_16x16x32_bf16 v[38:41], v[208:211], v[184:187], v[38:41]
	v_mfma_f32_16x16x32_bf16 v[58:61], v[200:203], v[192:195], v[106:109]
	v_mfma_f32_16x16x32_bf16 v[34:37], v[208:211], v[192:195], v[34:37]
	v_mfma_f32_16x16x32_bf16 v[10:13], v[212:215], v[172:175], v[10:13]
	v_mfma_f32_16x16x32_bf16 v[2:5], v[212:215], v[180:183], v[2:5]
	v_mfma_f32_16x16x32_bf16 v[38:41], v[212:215], v[188:191], v[38:41]
	v_mfma_f32_16x16x32_bf16 v[106:109], v[204:207], v[196:199], v[58:61]
	v_mfma_f32_16x16x32_bf16 v[34:37], v[212:215], v[196:199], v[34:37]
	s_setprio 0
	s_add_i32 s65, s65, 2
	s_add_u32 s63, s63, 0x100
	s_addc_u32 s64, s64, 0
	s_cmp_lt_u32 s65, 30
	s_mov_b64 s[36:37], s[38:39]
	s_barrier
	s_cbranch_scc1 .LBB0_5583
	v_lshl_add_u32 v156, s34, 8, v229
	v_ashrrev_i32_e32 v157, 31, v156
	v_lshl_add_u64 v[70:71], v[156:157], 2, s[90:91]
	global_load_dwordx4 v[58:61], v[70:71], off offset:16
	s_nop 0
	global_load_dwordx4 v[70:73], v[70:71], off
	s_mul_i32 s25, s34, 44
	s_add_i32 s25, s25, s61
	s_lshl_b32 s25, s25, 1
	s_add_i32 s34, s25, s45
	s_ashr_i32 s35, s34, 31
	v_mov_b32_e32 v158, v130
	v_mov_b32_e32 v159, v132
	v_mov_b32_e32 v160, v118
	v_mov_b32_e32 v161, v120
	v_mov_b32_e32 v132, v131
	v_mov_b32_e32 v120, v119
	s_lshl_b64 s[34:35], s[34:35], 11
	v_cmp_lt_i32_e32 vcc, 14, v167
	v_lshl_add_u64 v[130:131], v[146:147], 0, s[34:35]
	s_mov_b64 s[34:35], 0
	s_waitcnt vmcnt(0)
	v_pk_mul_f32 v[162:163], v[158:159], v[60:61] op_sel_hi:[1,0]
	v_pk_mul_f32 v[158:159], v[160:161], v[60:61] op_sel_hi:[1,0]
	v_pk_mul_f32 v[160:161], v[132:133], v[60:61] op_sel_hi:[1,0]
	v_pk_mul_f32 v[132:133], v[120:121], v[60:61] op_sel_hi:[1,0]
	s_and_saveexec_b64 s[36:37], vcc
	s_xor_b64 s[36:37], exec, s[36:37]
	s_cbranch_execz .LBB0_5586
	v_and_b32_sdwa v120, v161, v234 dst_sel:DWORD dst_unused:UNUSED_PAD src0_sel:WORD_1 src1_sel:DWORD
	v_and_b32_sdwa v121, v160, v234 dst_sel:DWORD dst_unused:UNUSED_PAD src0_sel:WORD_1 src1_sel:DWORD
	v_and_b32_sdwa v118, v163, v234 dst_sel:DWORD dst_unused:UNUSED_PAD src0_sel:WORD_1 src1_sel:DWORD
	v_and_b32_sdwa v119, v162, v234 dst_sel:DWORD dst_unused:UNUSED_PAD src0_sel:WORD_1 src1_sel:DWORD
	v_add3_u32 v120, v161, v120, s59
	v_add3_u32 v121, v160, v121, s59
	v_add3_u32 v119, v162, v119, s59
	v_add3_u32 v118, v163, v118, s59
	v_and_b32_e32 v120, 0xffff0000, v120
	v_and_b32_e32 v157, 0xffff0000, v121
	v_or_b32_sdwa v121, v120, v118 dst_sel:DWORD dst_unused:UNUSED_PAD src0_sel:DWORD src1_sel:WORD_1
	v_or_b32_sdwa v120, v157, v119 dst_sel:DWORD dst_unused:UNUSED_PAD src0_sel:DWORD src1_sel:WORD_1
	v_and_b32_sdwa v119, v158, v234 dst_sel:DWORD dst_unused:UNUSED_PAD src0_sel:WORD_1 src1_sel:DWORD
	v_add3_u32 v157, v158, v119, s59
	s_nop 0
	v_and_b32_sdwa v165, v132, v234 dst_sel:DWORD dst_unused:UNUSED_PAD src0_sel:WORD_1 src1_sel:DWORD
	s_nop 1
	v_add3_u32 v165, v132, v165, s59
	s_nop 1
	v_and_b32_e32 v165, 0xffff0000, v165
	s_mov_b64 s[34:35], exec
	v_cvt_pk_bf16_f32 v119, v159, v133
	v_or_b32_sdwa v118, v165, v157 dst_sel:DWORD dst_unused:UNUSED_PAD src0_sel:DWORD src1_sel:WORD_1
	global_store_dwordx2 v[130:131], v[120:121], off offset:1024
; __device__ __forceinline__ unsigned pk2(float lo, float hi) { return f2bf(lo) | (f2bf(hi) << 16); }
;     __device__ __forceinline__ void operator()(const f32x4 (&acc)[2][2][4][2], const pg8::Unit& u, int wr, int wc, int fr, int fq) const {
;     ...
;             for (int e = 0; e < 8; ++e) { const float rs = (e < 4) ? r0[e & 3] : r1[e & 3];
; #pragma unroll
;                 for (int jj = 0; jj < 4; ++jj) { g[e][jj] = acc[e >> 2][0][e & 3][n][jj] * rs; v[e][jj] = acc[e >> 2][1][e & 3][n][jj] * rs; } }
;             if (fr == 0) {
; #pragma unroll
;                 for (int q = 0; q < 2; ++q) { v2u a, b; a.x = pk2(g[q][0], g[q][1]); a.y = pk2(g[q][2], g[q][3]); b.x = pk2(v[q][0], v[q][1]); b.y = pk2(v[q][2], v[q][3]);
;                     *(v2u*)(hb + (size_t)q * 256 + 4 * n) = a; *(v2u*)(hb + (size_t)q * 256 + 128 + 4 * n) = b; } }
.LBB0_5586:
	s_or_saveexec_b64 s[36:37], s[36:37]
	v_mov_b32_e32 v120, v134
	v_mov_b32_e32 v121, v136
	v_pk_mul_f32 v[188:189], v[120:121], v[70:71] op_sel_hi:[1,0]
	v_mov_b32_e32 v120, v122
	v_mov_b32_e32 v121, v124
	v_pk_mul_f32 v[186:187], v[120:121], v[70:71] op_sel_hi:[1,0]
	v_mov_b32_e32 v120, v126
	v_mov_b32_e32 v121, v128
	v_pk_mul_f32 v[180:181], v[120:121], v[70:71] op_sel:[0,1]
	v_mov_b32_e32 v120, v114
	v_mov_b32_e32 v121, v116
	v_mov_b32_e32 v116, v115
	v_mov_b32_e32 v114, v110
	v_mov_b32_e32 v115, v112
	v_mov_b32_e32 v110, v61
	v_mov_b32_e32 v136, v135
	v_pk_mul_f32 v[168:169], v[114:115], v[110:111] op_sel_hi:[1,0]
	v_mov_b32_e32 v114, v106
	v_mov_b32_e32 v115, v108
	v_mov_b32_e32 v112, v111
	v_mov_b32_e32 v108, v107
	v_pk_mul_f32 v[190:191], v[136:137], v[70:71] op_sel_hi:[1,0]
	v_mov_b32_e32 v124, v123
	v_mov_b32_e32 v128, v127
	v_pk_mul_f32 v[134:135], v[114:115], v[110:111] op_sel_hi:[1,0]
	v_pk_mul_f32 v[170:171], v[112:113], v[110:111] op_sel_hi:[1,0]
	v_pk_mul_f32 v[136:137], v[108:109], v[110:111] op_sel_hi:[1,0]
	v_pk_mul_f32 v[184:185], v[124:125], v[70:71] op_sel_hi:[1,0]
	v_pk_mul_f32 v[178:179], v[120:121], v[70:71] op_sel:[0,1]
	v_pk_mul_f32 v[182:183], v[128:129], v[70:71] op_sel:[0,1]
	v_pk_mul_f32 v[176:177], v[116:117], v[70:71] op_sel:[0,1]
	v_mov_b64_e32 v[114:115], 0x500
	v_mov_b64_e32 v[108:109], 0x600
	v_mov_b64_e32 v[106:107], 0x700
	v_mov_b64_e32 v[120:121], v[168:169]
	v_mov_b64_e32 v[116:117], v[170:171]
	v_mov_b64_e32 v[110:111], v[134:135]
	v_mov_b64_e32 v[112:113], v[136:137]
	s_xor_b64 exec, exec, s[36:37]
	s_cbranch_execz .LBB0_5590
	v_cmp_eq_u32_e32 vcc, 0, v167
	s_mov_b64 s[40:41], s[34:35]
	s_and_saveexec_b64 s[38:39], vcc
	s_cbranch_execz .LBB0_5589
	v_and_b32_sdwa v107, v188, v234 dst_sel:DWORD dst_unused:UNUSED_PAD src0_sel:WORD_1 src1_sel:DWORD
	v_add3_u32 v108, v188, v107, s59
	s_nop 0
	v_and_b32_sdwa v109, v190, v234 dst_sel:DWORD dst_unused:UNUSED_PAD src0_sel:WORD_1 src1_sel:DWORD
	s_nop 1
	v_add3_u32 v109, v190, v109, s59
	s_nop 1
	v_and_b32_e32 v109, 0xffff0000, v109
	v_and_b32_sdwa v110, v185, v234 dst_sel:DWORD dst_unused:UNUSED_PAD src0_sel:WORD_1 src1_sel:DWORD
	v_and_b32_sdwa v111, v184, v234 dst_sel:DWORD dst_unused:UNUSED_PAD src0_sel:WORD_1 src1_sel:DWORD
	v_cvt_pk_bf16_f32 v107, v189, v191
	v_or_b32_sdwa v106, v109, v108 dst_sel:DWORD dst_unused:UNUSED_PAD src0_sel:DWORD src1_sel:WORD_1
	v_and_b32_sdwa v108, v187, v234 dst_sel:DWORD dst_unused:UNUSED_PAD src0_sel:WORD_1 src1_sel:DWORD
	v_and_b32_sdwa v109, v186, v234 dst_sel:DWORD dst_unused:UNUSED_PAD src0_sel:WORD_1 src1_sel:DWORD
	v_add3_u32 v110, v185, v110, s59
	v_add3_u32 v111, v184, v111, s59
	v_add3_u32 v109, v186, v109, s59
	v_add3_u32 v108, v187, v108, s59
	v_and_b32_e32 v110, 0xffff0000, v110
	v_and_b32_e32 v111, 0xffff0000, v111
	v_or_b32_sdwa v119, v110, v108 dst_sel:DWORD dst_unused:UNUSED_PAD src0_sel:DWORD src1_sel:WORD_1
	v_or_b32_sdwa v118, v111, v109 dst_sel:DWORD dst_unused:UNUSED_PAD src0_sel:DWORD src1_sel:WORD_1
	s_or_b64 s[40:41], s[34:35], exec
	global_store_dwordx2 v[130:131], v[106:107], off

; __device__ __forceinline__ unsigned pk2(float lo, float hi) { return f2bf(lo) | (f2bf(hi) << 16); }
; __device__ __forceinline__ float dpp_shr1(float x) { return __builtin_bit_cast(float, __builtin_amdgcn_update_dpp(0, __builtin_bit_cast(int, x), 0x111, 0xf, 0xf, true)); }
;     __device__ __forceinline__ void operator()(const f32x4 (&acc)[2][2][4][2], const pg8::Unit& u, int wr, int wc, int fr, int fq) const {
;     ...
;             if (fr == 0) {
; #pragma unroll
;                 for (int q = 0; q < 2; ++q) { v2u a, b; a.x = pk2(g[q][0], g[q][1]); a.y = pk2(g[q][2], g[q][3]); b.x = pk2(v[q][0], v[q][1]); b.y = pk2(v[q][2], v[q][3]);
;                     *(v2u*)(hb + (size_t)q * 256 + 4 * n) = a; *(v2u*)(hb + (size_t)q * 256 + 128 + 4 * n) = b; } }
;             if (fr == 15) {
; #pragma unroll
;                 for (int q = 0; q < 2; ++q) { v2u a, b; a.x = pk2(g[6 + q][0], g[6 + q][1]); a.y = pk2(g[6 + q][2], g[6 + q][3]); b.x = pk2(v[6 + q][0], v[6 + q][1]); b.y = pk2(v[6 + q][2], v[6 + q][3]);
;                     *(v2u*)(hb + (size_t)(2 + q) * 256 + 4 * n) = a; *(v2u*)(hb + (size_t)(2 + q) * 256 + 128 + 4 * n) = b; } }
;             const int cc = ch0 + 4 * n;
;             const f32x4 wg0 = *(CF4)(cw + cc), wg1 = *(CF4)(cw + FF2 + cc), wg2 = *(CF4)(cw + 2 * FF2 + cc), wv0 = *(CF4)(cw + FFH + cc), wv1 = *(CF4)(cw + FF2 + FFH + cc), wv2 = *(CF4)(cw + 2 * FF2 + FFH + cc);
;             const f32x4 bg = *(CF4)(cb + cc), bv = *(CF4)(cb + FFH + cc);
; #pragma unroll
;             for (int jj = 0; jj < 4; ++jj) {
;                 float g2 = dpp_shr1(g[6][jj]), g1 = dpp_shr1(g[7][jj]), v2 = dpp_shr1(v[6][jj]), v1 = dpp_shr1(v[7][jj]);
.LBB0_5590:
	s_or_b64 exec, exec, s[36:37]
	s_and_saveexec_b64 s[36:37], s[34:35]
	s_cbranch_execz .LBB0_5592
	v_lshl_add_u64 v[114:115], v[130:131], 0, v[114:115]
	global_store_dwordx2 v[114:115], v[118:119], off
	v_and_b32_sdwa v115, v120, v234 dst_sel:DWORD dst_unused:UNUSED_PAD src0_sel:WORD_1 src1_sel:DWORD
	v_add3_u32 v118, v120, v115, s59
	s_nop 0
	v_and_b32_sdwa v119, v116, v234 dst_sel:DWORD dst_unused:UNUSED_PAD src0_sel:WORD_1 src1_sel:DWORD
	s_nop 1
	v_add3_u32 v116, v116, v119, s59
	s_nop 1
	v_and_b32_e32 v116, 0xffff0000, v116
	v_cvt_pk_bf16_f32 v115, v121, v117
	v_or_b32_sdwa v114, v116, v118 dst_sel:DWORD dst_unused:UNUSED_PAD src0_sel:DWORD src1_sel:WORD_1
	s_nop 7
	s_nop 1
	v_cvt_pk_bf16_f32 v111, v111, v113
	v_cvt_pk_bf16_f32 v110, v110, v112
	v_lshl_add_u64 v[108:109], v[130:131], 0, v[108:109]
	v_lshl_add_u64 v[106:107], v[130:131], 0, v[106:107]
	global_store_dwordx2 v[108:109], v[114:115], off
	global_store_dwordx2 v[106:107], v[110:111], off
.LBB0_5592:
	s_or_b64 exec, exec, s[36:37]
	v_lshl_or_b32 v128, s61, 7, v230
	v_ashrrev_i32_e32 v129, 31, v128
	v_lshlrev_b64 v[192:193], 2, v[128:129]
	v_lshl_add_u64 v[106:107], s[6:7], 0, v[192:193]
	v_lshl_add_u64 v[110:111], s[8:9], 0, v[192:193]
	global_load_dwordx4 v[106:109], v[106:107], off
	v_mov_b32_e32 v166, v73
	global_load_dwordx4 v[114:117], v[110:111], off
	v_lshl_add_u64 v[110:111], s[12:13], 0, v[192:193]
	global_load_dwordx4 v[118:121], v[110:111], off
	v_lshl_add_u64 v[110:111], s[14:15], 0, v[192:193]
	global_load_dwordx4 v[122:125], v[110:111], off
	v_mov_b32_e32 v110, v102
	v_mov_b32_e32 v111, v104
	v_pk_mul_f32 v[226:227], v[110:111], v[72:73] op_sel_hi:[1,0]
	v_mov_b32_e32 v110, v94
	v_mov_b32_e32 v111, v96
	v_mov_b32_e32 v96, v95
	v_lshl_add_u64 v[94:95], s[16:17], 0, v[192:193]
	v_pk_mul_f32 v[220:221], v[96:97], v[72:73] op_sel_hi:[1,0]
	global_load_dwordx4 v[94:97], v[94:95], off
	v_pk_mul_f32 v[222:223], v[110:111], v[72:73] op_sel_hi:[1,0]
	v_mov_b32_e32 v104, v103
	v_mov_b32_e32 v110, v98
	v_mov_b32_e32 v111, v100
	v_lshl_add_u64 v[102:103], s[22:23], 0, v[192:193]
	v_pk_mul_f32 v[224:225], v[104:105], v[72:73] op_sel_hi:[1,0]
	global_load_dwordx4 v[102:105], v[102:103], off
	v_pk_mul_f32 v[216:217], v[110:111], v[166:167] op_sel_hi:[1,0]
	v_lshl_add_u64 v[110:111], s[18:19], 0, v[192:193]
	global_load_dwordx4 v[110:113], v[110:111], off
	v_mov_b32_e32 v100, v99
	v_lshl_add_u64 v[98:99], s[20:21], 0, v[192:193]
	v_pk_mul_f32 v[218:219], v[100:101], v[166:167] op_sel_hi:[1,0]
	global_load_dwordx4 v[98:101], v[98:99], off
	v_mov_b32_e32 v195, v92
	v_mov_b32_e32 v92, v91
	v_mov_b32_e32 v198, v58
	v_mov_b32_e32 v199, v59
	v_pk_mul_f32 v[212:213], v[92:93], v[166:167] op_sel_hi:[1,0]
	v_mov_b32_e32 v92, v86
	v_mov_b32_e32 v93, v88
	v_mov_b32_e32 v194, v90
	v_pk_mul_f32 v[210:211], v[92:93], v[198:199] op_sel_hi:[1,0]
	v_mov_b32_e32 v92, v78
	v_mov_b32_e32 v93, v80
	v_mov_b32_e32 v80, v79
	v_mov_b32_e32 v78, v82
	v_mov_b32_e32 v79, v84
	v_pk_mul_f32 v[214:215], v[194:195], v[166:167] op_sel_hi:[1,0]
	v_mov_b32_e32 v88, v87
	v_pk_mul_f32 v[194:195], v[78:79], v[198:199] op_sel:[0,1]
	v_mov_b32_e32 v78, v74
	v_mov_b32_e32 v79, v76
	v_mov_b32_e32 v84, v83
	v_mov_b32_e32 v76, v75
	v_pk_mul_f32 v[202:203], v[92:93], v[198:199] op_sel_hi:[1,0]
	v_pk_mul_f32 v[208:209], v[88:89], v[198:199] op_sel_hi:[1,0]
	v_pk_mul_f32 v[196:197], v[80:81], v[198:199] op_sel_hi:[1,0]
	v_pk_mul_f32 v[92:93], v[78:79], v[198:199] op_sel:[0,1]
	v_pk_mul_f32 v[192:193], v[84:85], v[198:199] op_sel:[0,1]
	v_pk_mul_f32 v[78:79], v[76:77], v[198:199] op_sel:[0,1]
	v_mov_b32_dpp v74, v162 row_shr:1 row_mask:0xf bank_mask:0xf bound_ctrl:1
	v_mov_b32_dpp v75, v163 row_shr:1 row_mask:0xf bank_mask:0xf bound_ctrl:1
	v_mov_b32_dpp v76, v168 row_shr:1 row_mask:0xf bank_mask:0xf bound_ctrl:1
	v_mov_b32_dpp v84, v160 row_shr:1 row_mask:0xf bank_mask:0xf bound_ctrl:1
	v_mov_b32_dpp v77, v169 row_shr:1 row_mask:0xf bank_mask:0xf bound_ctrl:1
	v_mov_b32_dpp v85, v161 row_shr:1 row_mask:0xf bank_mask:0xf bound_ctrl:1
	v_mov_b32_dpp v86, v170 row_shr:1 row_mask:0xf bank_mask:0xf bound_ctrl:1
	v_mov_b32_dpp v87, v171 row_shr:1 row_mask:0xf bank_mask:0xf bound_ctrl:1
	v_mov_b32_dpp v80, v158 row_shr:1 row_mask:0xf bank_mask:0xf bound_ctrl:1
	v_mov_b32_dpp v81, v159 row_shr:1 row_mask:0xf bank_mask:0xf bound_ctrl:1
	v_mov_b32_dpp v82, v134 row_shr:1 row_mask:0xf bank_mask:0xf bound_ctrl:1
	v_mov_b32_dpp v83, v135 row_shr:1 row_mask:0xf bank_mask:0xf bound_ctrl:1
	v_mov_b32_dpp v88, v132 row_shr:1 row_mask:0xf bank_mask:0xf bound_ctrl:1
	v_mov_b32_dpp v89, v133 row_shr:1 row_mask:0xf bank_mask:0xf bound_ctrl:1
	v_mov_b32_dpp v236, v136 row_shr:1 row_mask:0xf bank_mask:0xf bound_ctrl:1
	v_mov_b32_dpp v237, v137 row_shr:1 row_mask:0xf bank_mask:0xf bound_ctrl:1
	v_mov_b32_e32 v172, v70
	v_mov_b32_e32 v173, v70
	v_mov_b32_e32 v70, v71
	v_mov_b32_e32 v174, v60
	v_mov_b32_e32 v175, v60
	v_mov_b32_e32 v60, v61
	v_mov_b32_e32 v126, v72
	s_waitcnt vmcnt(0)
; __device__ __forceinline__ unsigned pk2(float lo, float hi) { return f2bf(lo) | (f2bf(hi) << 16); }
; __device__ __forceinline__ float silu_fast(float x) { return x * __builtin_amdgcn_rcpf(1.f + __builtin_amdgcn_exp2f(-1.4426950408889634f * x)); }
; __device__ __forceinline__ float dpp_shr1(float x) { return __builtin_bit_cast(float, __builtin_amdgcn_update_dpp(0, __builtin_bit_cast(int, x), 0x111, 0xf, 0xf, true)); }
;     __device__ __forceinline__ void operator()(const f32x4 (&acc)[2][2][4][2], const pg8::Unit& u, int wr, int wc, int fr, int fq) const {
;     ...
;             for (int jj = 0; jj < 4; ++jj) {
;                 float g2 = dpp_shr1(g[6][jj]), g1 = dpp_shr1(g[7][jj]), v2 = dpp_shr1(v[6][jj]), v1 = dpp_shr1(v[7][jj]);
; #pragma unroll
;                 for (int e = 0; e < 8; ++e) { const float g0 = g[e][jj], v0 = v[e][jj];
;                     const float cg = bg[jj] + wg0[jj] * g2 + wg1[jj] * g1 + wg2[jj] * g0, cv = bv[jj] + wv0[jj] * v2 + wv1[jj] * v1 + wv2[jj] * v0;
;                     g[e][jj] = silu_fast(cg) * cv; g2 = g1; g1 = g0; v2 = v1; v1 = v0; } }
; #pragma unroll
;             for (int e = 0; e < 8; ++e) { v2u w; w.x = pk2(g[e][0], g[e][1]); w.y = pk2(g[e][2], g[e][3]); *(v2u*)(ACT + (size_t)(tok0 + e) * FFH + cc) = w; }
	v_mov_b32_e32 v198, v106
	v_mov_b32_e32 v199, v108
	v_mov_b32_e32 v200, v114
	v_mov_b32_e32 v201, v116
	v_pk_fma_f32 v[74:75], v[198:199], v[74:75], v[200:201]
	v_mov_b32_e32 v204, v118
	v_mov_b32_e32 v205, v120
	v_mov_b32_e32 v108, v107
	v_mov_b32_e32 v116, v115
	v_pk_fma_f32 v[74:75], v[204:205], v[76:77], v[74:75]
	v_mov_b32_e32 v206, v122
	v_mov_b32_e32 v207, v124
	v_pk_fma_f32 v[84:85], v[108:109], v[84:85], v[116:117]
	v_mov_b32_e32 v120, v119
	v_pk_fma_f32 v[74:75], v[188:189], v[206:207], v[74:75]
	v_pk_fma_f32 v[84:85], v[120:121], v[86:87], v[84:85]
	v_mov_b32_e32 v124, v123
	v_mul_f32_e32 v106, 0xbfb8aa3b, v74
	v_pk_fma_f32 v[84:85], v[190:191], v[124:125], v[84:85]
	v_exp_f32_e32 v106, v106
	v_mul_f32_e32 v107, 0xbfb8aa3b, v84
	v_exp_f32_e32 v107, v107
	v_mov_b32_e32 v114, v102
	v_add_f32_e32 v106, 1.0, v106
	v_rcp_f32_e32 v238, v106
	v_add_f32_e32 v106, 1.0, v107
	v_rcp_f32_e32 v240, v106
	v_mov_b32_e32 v106, v94
	v_mul_f32_e32 v94, 0xbfb8aa3b, v75
	v_exp_f32_e32 v94, v94
	v_mov_b32_e32 v107, v96
	v_mov_b32_e32 v115, v104
	v_pk_fma_f32 v[80:81], v[106:107], v[80:81], v[114:115]
	v_add_f32_e32 v94, 1.0, v94
	v_rcp_f32_e32 v239, v94
	v_mov_b32_e32 v122, v110
	v_mov_b32_e32 v123, v112
	v_pk_fma_f32 v[80:81], v[122:123], v[82:83], v[80:81]
	v_mov_b32_e32 v118, v98
	v_mov_b32_e32 v119, v100
	v_pk_fma_f32 v[80:81], v[186:187], v[118:119], v[80:81]
	v_pk_mul_f32 v[74:75], v[74:75], v[238:239]
	v_mov_b32_e32 v96, v95
	v_pk_mul_f32 v[74:75], v[80:81], v[74:75]
	v_mul_f32_e32 v80, 0xbfb8aa3b, v85
	v_exp_f32_e32 v94, v80
	v_mov_b32_e32 v104, v103
	v_pk_fma_f32 v[80:81], v[96:97], v[88:89], v[104:105]
	v_mov_b32_e32 v112, v111
	v_add_f32_e32 v88, 1.0, v94
	v_rcp_f32_e32 v241, v88
	v_pk_fma_f32 v[80:81], v[112:113], v[236:237], v[80:81]
	v_mov_b32_e32 v100, v99
	v_pk_fma_f32 v[80:81], v[184:185], v[100:101], v[80:81]
	v_pk_mul_f32 v[84:85], v[84:85], v[240:241]
	v_pk_fma_f32 v[76:77], v[198:199], v[76:77], v[200:201]
	v_pk_mul_f32 v[80:81], v[80:81], v[84:85]
	s_nop 7
	s_nop 1
	v_mov_b64_e32 v[94:95], s[78:79]
	v_pk_fma_f32 v[76:77], v[188:189], v[204:205], v[76:77]
	v_cvt_pk_bf16_f32 v75, v75, v81
	v_cvt_pk_bf16_f32 v74, v74, v80
	v_mad_i64_i32 v[80:81], s[34:35], v156, s60, v[94:95]
	v_lshlrev_b64 v[98:99], 1, v[128:129]
	v_pk_fma_f32 v[76:77], v[180:181], v[206:207], v[76:77]
	v_lshl_add_u64 v[84:85], v[80:81], 0, v[98:99]
	v_mul_f32_e32 v80, 0xbfb8aa3b, v76
	v_exp_f32_e32 v88, v80
	v_pk_fma_f32 v[80:81], v[108:109], v[86:87], v[116:117]
	global_store_dwordx2 v[84:85], v[74:75], off
	v_pk_fma_f32 v[80:81], v[190:191], v[120:121], v[80:81]
	v_add_f32_e32 v74, 1.0, v88
	v_pk_fma_f32 v[80:81], v[182:183], v[124:125], v[80:81]
	v_rcp_f32_e32 v74, v74
	v_mul_f32_e32 v86, 0xbfb8aa3b, v80
	v_exp_f32_e32 v86, v86
	v_pk_fma_f32 v[82:83], v[106:107], v[82:83], v[114:115]
	v_pk_fma_f32 v[102:103], v[178:179], v[106:107], v[114:115]
	v_pk_fma_f32 v[82:83], v[186:187], v[122:123], v[82:83]
	v_add_f32_e32 v75, 1.0, v86
	v_mul_f32_e32 v86, 0xbfb8aa3b, v77
	v_exp_f32_e32 v87, v86
	v_rcp_f32_e32 v86, v75
	v_pk_fma_f32 v[82:83], v[178:179], v[118:119], v[82:83]
	v_pk_fma_f32 v[102:103], v[222:223], v[122:123], v[102:103]
	v_add_f32_e32 v75, 1.0, v87
	v_mul_f32_e32 v87, 0xbfb8aa3b, v81
	v_rcp_f32_e32 v75, v75
	v_exp_f32_e32 v87, v87
	v_pk_fma_f32 v[102:103], v[214:215], v[118:119], v[102:103]
	v_pk_fma_f32 v[110:111], v[222:223], v[106:107], v[114:115]
	v_pk_mul_f32 v[74:75], v[76:77], v[74:75]
	v_add_f32_e32 v76, 1.0, v87
	v_rcp_f32_e32 v87, v76
	v_pk_fma_f32 v[76:77], v[96:97], v[236:237], v[104:105]
	v_pk_mul_f32 v[74:75], v[82:83], v[74:75]
	v_pk_fma_f32 v[76:77], v[184:185], v[112:113], v[76:77]
	v_pk_mul_f32 v[80:81], v[80:81], v[86:87]
	v_pk_fma_f32 v[76:77], v[176:177], v[100:101], v[76:77]
	v_pk_fma_f32 v[86:87], v[186:187], v[106:107], v[114:115]
	v_pk_mul_f32 v[76:77], v[76:77], v[80:81]
	s_nop 7
	s_nop 1
	v_cvt_pk_bf16_f32 v74, v74, v76
	v_or_b32_e32 v76, 1, v156
	v_cvt_pk_bf16_f32 v75, v75, v77
	v_mad_i64_i32 v[76:77], s[34:35], v76, s60, v[94:95]
	v_lshl_add_u64 v[88:89], v[76:77], 0, v[98:99]
	v_pk_fma_f32 v[76:77], v[188:189], v[198:199], v[200:201]
	global_store_dwordx2 v[88:89], v[74:75], off
	v_pk_fma_f32 v[76:77], v[180:181], v[204:205], v[76:77]
	v_pk_fma_f32 v[86:87], v[178:179], v[122:123], v[86:87]
	v_pk_fma_f32 v[76:77], v[226:227], v[206:207], v[76:77]
	v_pk_fma_f32 v[86:87], v[222:223], v[118:119], v[86:87]
	v_mul_f32_e32 v80, 0xbfb8aa3b, v76
	v_exp_f32_e32 v82, v80
	v_pk_fma_f32 v[80:81], v[190:191], v[108:109], v[116:117]
	v_pk_fma_f32 v[110:111], v[214:215], v[122:123], v[110:111]
	v_pk_fma_f32 v[80:81], v[182:183], v[120:121], v[80:81]
	v_add_f32_e32 v74, 1.0, v82
	v_pk_fma_f32 v[80:81], v[224:225], v[124:125], v[80:81]
	v_mul_f32_e32 v82, 0xbfb8aa3b, v77
	v_mul_f32_e32 v83, 0xbfb8aa3b, v80
	v_exp_f32_e32 v83, v83
	v_rcp_f32_e32 v74, v74
	v_pk_fma_f32 v[110:111], v[202:203], v[118:119], v[110:111]
	v_pk_fma_f32 v[178:179], v[202:203], v[106:107], v[114:115]
	v_add_f32_e32 v75, 1.0, v83
	v_exp_f32_e32 v83, v82
	v_rcp_f32_e32 v82, v75
	v_pk_fma_f32 v[178:179], v[92:93], v[122:123], v[178:179]
	v_mov_b32_e32 v127, v72
	v_add_f32_e32 v75, 1.0, v83
	v_mul_f32_e32 v83, 0xbfb8aa3b, v81
	v_rcp_f32_e32 v75, v75
	v_exp_f32_e32 v83, v83
	v_pk_fma_f32 v[178:179], v[158:159], v[118:119], v[178:179]
	v_mov_b32_e32 v72, v73
	v_pk_mul_f32 v[74:75], v[76:77], v[74:75]
	v_add_f32_e32 v76, 1.0, v83
	v_rcp_f32_e32 v83, v76
	v_pk_fma_f32 v[76:77], v[184:185], v[96:97], v[104:105]
	v_pk_mul_f32 v[74:75], v[86:87], v[74:75]
	v_pk_fma_f32 v[76:77], v[176:177], v[112:113], v[76:77]
	v_pk_mul_f32 v[80:81], v[80:81], v[82:83]
; __device__ __forceinline__ unsigned pk2(float lo, float hi) { return f2bf(lo) | (f2bf(hi) << 16); }
; __device__ __forceinline__ float silu_fast(float x) { return x * __builtin_amdgcn_rcpf(1.f + __builtin_amdgcn_exp2f(-1.4426950408889634f * x)); }
; __device__ __forceinline__ float dpp_shr1(float x) { return __builtin_bit_cast(float, __builtin_amdgcn_update_dpp(0, __builtin_bit_cast(int, x), 0x111, 0xf, 0xf, true)); }
;     __device__ __forceinline__ void operator()(const f32x4 (&acc)[2][2][4][2], const pg8::Unit& u, int wr, int wc, int fr, int fq) const {
;     ...
;             for (int jj = 0; jj < 4; ++jj) {
;                 float g2 = dpp_shr1(g[6][jj]), g1 = dpp_shr1(g[7][jj]), v2 = dpp_shr1(v[6][jj]), v1 = dpp_shr1(v[7][jj]);
; #pragma unroll
;                 for (int e = 0; e < 8; ++e) { const float g0 = g[e][jj], v0 = v[e][jj];
;                     const float cg = bg[jj] + wg0[jj] * g2 + wg1[jj] * g1 + wg2[jj] * g0, cv = bv[jj] + wv0[jj] * v2 + wv1[jj] * v1 + wv2[jj] * v0;
;                     g[e][jj] = silu_fast(cg) * cv; g2 = g1; g1 = g0; v2 = v1; v1 = v0; } }
; #pragma unroll
;             for (int e = 0; e < 8; ++e) { v2u w; w.x = pk2(g[e][0], g[e][1]); w.y = pk2(g[e][2], g[e][3]); *(v2u*)(ACT + (size_t)(tok0 + e) * FFH + cc) = w; }
	v_pk_fma_f32 v[76:77], v[220:221], v[100:101], v[76:77]
	v_mov_b32_e32 v90, v58
	v_pk_mul_f32 v[76:77], v[76:77], v[80:81]
	s_nop 7
	s_nop 1
	v_cvt_pk_bf16_f32 v74, v74, v76
	v_or_b32_e32 v76, 2, v156
	v_cvt_pk_bf16_f32 v75, v75, v77
	v_mad_i64_i32 v[76:77], s[34:35], v76, s60, v[94:95]
	v_lshl_add_u64 v[86:87], v[76:77], 0, v[98:99]
	v_pk_fma_f32 v[76:77], v[180:181], v[198:199], v[200:201]
	global_store_dwordx2 v[86:87], v[74:75], off
	v_pk_fma_f32 v[76:77], v[226:227], v[204:205], v[76:77]
	v_mov_b32_e32 v91, v58
	v_pk_fma_f32 v[76:77], v[216:217], v[206:207], v[76:77]
	v_mov_b32_e32 v58, v59
	v_mul_f32_e32 v80, 0xbfb8aa3b, v76
	v_exp_f32_e32 v82, v80
	v_pk_fma_f32 v[80:81], v[182:183], v[108:109], v[116:117]
	v_cmp_gt_i32_e32 vcc, 15, v167
	v_pk_fma_f32 v[80:81], v[224:225], v[120:121], v[80:81]
	v_add_f32_e32 v74, 1.0, v82
	v_pk_fma_f32 v[80:81], v[218:219], v[124:125], v[80:81]
	v_mul_f32_e32 v82, 0xbfb8aa3b, v77
	v_mul_f32_e32 v83, 0xbfb8aa3b, v80
	v_exp_f32_e32 v83, v83
	v_rcp_f32_e32 v74, v74
	s_mov_b64 s[36:37], -1
	v_add_f32_e32 v75, 1.0, v83
	v_exp_f32_e32 v83, v82
	v_rcp_f32_e32 v82, v75
	v_add_f32_e32 v75, 1.0, v83
	v_mul_f32_e32 v83, 0xbfb8aa3b, v81
	v_rcp_f32_e32 v75, v75
	v_exp_f32_e32 v83, v83
	v_pk_mul_f32 v[74:75], v[76:77], v[74:75]
	v_add_f32_e32 v76, 1.0, v83
	v_rcp_f32_e32 v83, v76
	v_pk_fma_f32 v[76:77], v[176:177], v[96:97], v[104:105]
	v_pk_mul_f32 v[74:75], v[102:103], v[74:75]
	v_pk_fma_f32 v[76:77], v[220:221], v[112:113], v[76:77]
	v_pk_mul_f32 v[80:81], v[80:81], v[82:83]
	v_pk_fma_f32 v[76:77], v[212:213], v[100:101], v[76:77]
	v_pk_fma_f32 v[176:177], v[214:215], v[106:107], v[114:115]
	v_pk_mul_f32 v[76:77], v[76:77], v[80:81]
	s_nop 7
	s_nop 1
	v_cvt_pk_bf16_f32 v74, v74, v76
	v_or_b32_e32 v76, 3, v156
	v_cvt_pk_bf16_f32 v75, v75, v77
	v_mad_i64_i32 v[76:77], s[34:35], v76, s60, v[94:95]
	v_lshl_add_u64 v[82:83], v[76:77], 0, v[98:99]
	v_pk_fma_f32 v[76:77], v[226:227], v[198:199], v[200:201]
	global_store_dwordx2 v[82:83], v[74:75], off
	v_pk_fma_f32 v[76:77], v[216:217], v[204:205], v[76:77]
	v_pk_fma_f32 v[176:177], v[202:203], v[122:123], v[176:177]
	v_pk_fma_f32 v[76:77], v[210:211], v[206:207], v[76:77]
	v_pk_fma_f32 v[176:177], v[92:93], v[118:119], v[176:177]
	v_mul_f32_e32 v80, 0xbfb8aa3b, v76
	v_exp_f32_e32 v102, v80
	v_pk_fma_f32 v[80:81], v[224:225], v[108:109], v[116:117]
	v_pk_fma_f32 v[92:93], v[92:93], v[106:107], v[114:115]
	v_pk_fma_f32 v[80:81], v[218:219], v[120:121], v[80:81]
	v_add_f32_e32 v74, 1.0, v102
	v_pk_fma_f32 v[80:81], v[208:209], v[124:125], v[80:81]
	v_mul_f32_e32 v102, 0xbfb8aa3b, v77
	v_mul_f32_e32 v103, 0xbfb8aa3b, v80
	v_exp_f32_e32 v103, v103
	v_rcp_f32_e32 v74, v74
	v_pk_fma_f32 v[92:93], v[158:159], v[122:123], v[92:93]
	v_add_f32_e32 v75, 1.0, v103
	v_exp_f32_e32 v103, v102
	v_rcp_f32_e32 v102, v75
	v_pk_fma_f32 v[92:93], v[134:135], v[118:119], v[92:93]
	v_add_f32_e32 v75, 1.0, v103
	v_mul_f32_e32 v103, 0xbfb8aa3b, v81
	v_rcp_f32_e32 v75, v75
	v_exp_f32_e32 v103, v103
	v_pk_mul_f32 v[74:75], v[76:77], v[74:75]
	v_add_f32_e32 v76, 1.0, v103
	v_rcp_f32_e32 v103, v76
	v_pk_fma_f32 v[76:77], v[220:221], v[96:97], v[104:105]
	v_pk_mul_f32 v[74:75], v[110:111], v[74:75]
	v_pk_fma_f32 v[76:77], v[212:213], v[112:113], v[76:77]
	v_pk_mul_f32 v[80:81], v[80:81], v[102:103]
	v_pk_fma_f32 v[76:77], v[196:197], v[100:101], v[76:77]
	s_nop 0
	v_pk_mul_f32 v[76:77], v[76:77], v[80:81]
	s_nop 7
	s_nop 1
	v_cvt_pk_bf16_f32 v74, v74, v76
	v_or_b32_e32 v76, 4, v156
	v_cvt_pk_bf16_f32 v75, v75, v77
	v_mad_i64_i32 v[76:77], s[34:35], v76, s60, v[94:95]
	v_lshl_add_u64 v[80:81], v[76:77], 0, v[98:99]
	v_pk_fma_f32 v[76:77], v[216:217], v[198:199], v[200:201]
	global_store_dwordx2 v[80:81], v[74:75], off
	v_pk_fma_f32 v[76:77], v[210:211], v[204:205], v[76:77]
	s_nop 0
	v_pk_fma_f32 v[76:77], v[194:195], v[206:207], v[76:77]
	s_nop 0
	v_mul_f32_e32 v102, 0xbfb8aa3b, v76
	v_exp_f32_e32 v110, v102
	v_pk_fma_f32 v[102:103], v[218:219], v[108:109], v[116:117]
	v_add_f32_e32 v74, 1.0, v110
	v_pk_fma_f32 v[102:103], v[208:209], v[120:121], v[102:103]
	v_mul_f32_e32 v110, 0xbfb8aa3b, v77
	v_pk_fma_f32 v[102:103], v[192:193], v[124:125], v[102:103]
	v_rcp_f32_e32 v74, v74
	v_mul_f32_e32 v111, 0xbfb8aa3b, v102
	v_exp_f32_e32 v111, v111
	s_nop 0
	v_add_f32_e32 v75, 1.0, v111
	v_exp_f32_e32 v111, v110
	v_rcp_f32_e32 v110, v75
	v_add_f32_e32 v75, 1.0, v111
	v_mul_f32_e32 v111, 0xbfb8aa3b, v103
	v_rcp_f32_e32 v75, v75
	v_exp_f32_e32 v111, v111
	v_pk_mul_f32 v[74:75], v[76:77], v[74:75]
	v_add_f32_e32 v76, 1.0, v111
	v_rcp_f32_e32 v111, v76
	v_pk_fma_f32 v[76:77], v[212:213], v[96:97], v[104:105]
	v_pk_mul_f32 v[74:75], v[176:177], v[74:75]
	v_pk_fma_f32 v[76:77], v[196:197], v[112:113], v[76:77]
	v_pk_mul_f32 v[102:103], v[102:103], v[110:111]
	v_pk_fma_f32 v[76:77], v[78:79], v[100:101], v[76:77]
	s_nop 0
	v_pk_mul_f32 v[76:77], v[76:77], v[102:103]
	v_and_b32_sdwa v102, v75, v234 dst_sel:DWORD dst_unused:UNUSED_PAD src0_sel:WORD_1 src1_sel:DWORD
	v_and_b32_sdwa v103, v74, v234 dst_sel:DWORD dst_unused:UNUSED_PAD src0_sel:WORD_1 src1_sel:DWORD
	v_add3_u32 v74, v74, v103, s59
	v_add3_u32 v75, v75, v102, s59
	v_and_b32_sdwa v102, v77, v234 dst_sel:DWORD dst_unused:UNUSED_PAD src0_sel:WORD_1 src1_sel:DWORD
	v_and_b32_sdwa v103, v76, v234 dst_sel:DWORD dst_unused:UNUSED_PAD src0_sel:WORD_1 src1_sel:DWORD
	v_add3_u32 v77, v77, v102, s59
	v_add3_u32 v76, v76, v103, s59
	v_pk_fma_f32 v[102:103], v[210:211], v[198:199], v[200:201]
	v_and_b32_e32 v76, 0xffff0000, v76
	v_pk_fma_f32 v[102:103], v[194:195], v[204:205], v[102:103]
	v_and_b32_e32 v77, 0xffff0000, v77
	v_pk_fma_f32 v[102:103], v[162:163], v[206:207], v[102:103]
; __device__ __forceinline__ unsigned pk2(float lo, float hi) { return f2bf(lo) | (f2bf(hi) << 16); }
;     __device__ __forceinline__ void operator()(const f32x4 (&acc)[2][2][4][2], const pg8::Unit& u, int wr, int wc, int fr, int fq) const {
;     ...
;             for (int e = 0; e < 8; ++e) { const float rs = (e < 4) ? r0[e & 3] : r1[e & 3];
; #pragma unroll
;                 for (int jj = 0; jj < 4; ++jj) { g[e][jj] = acc[e >> 2][0][e & 3][n][jj] * rs; v[e][jj] = acc[e >> 2][1][e & 3][n][jj] * rs; } }
;             if (fr == 0) {
; #pragma unroll
;                 for (int q = 0; q < 2; ++q) { v2u a, b; a.x = pk2(g[q][0], g[q][1]); a.y = pk2(g[q][2], g[q][3]); b.x = pk2(v[q][0], v[q][1]); b.y = pk2(v[q][2], v[q][3]);
;                     *(v2u*)(hb + (size_t)q * 256 + 4 * n) = a; *(v2u*)(hb + (size_t)q * 256 + 128 + 4 * n) = b; } }
;             if (fr == 15) {
; #pragma unroll
;                 for (int q = 0; q < 2; ++q) { v2u a, b; a.x = pk2(g[6 + q][0], g[6 + q][1]); a.y = pk2(g[6 + q][2], g[6 + q][3]); b.x = pk2(v[6 + q][0], v[6 + q][1]); b.y = pk2(v[6 + q][2], v[6 + q][3]);
;                     *(v2u*)(hb + (size_t)(2 + q) * 256 + 4 * n) = a; *(v2u*)(hb + (size_t)(2 + q) * 256 + 128 + 4 * n) = b; } }
;             const int cc = ch0 + 4 * n;
;             const f32x4 wg0 = *(CF4)(cw + cc), wg1 = *(CF4)(cw + FF2 + cc), wg2 = *(CF4)(cw + 2 * FF2 + cc), wv0 = *(CF4)(cw + FFH + cc), wv1 = *(CF4)(cw + FF2 + FFH + cc), wv2 = *(CF4)(cw + 2 * FF2 + FFH + cc);
;             const f32x4 bg = *(CF4)(cb + cc), bv = *(CF4)(cb + FFH + cc);
; #pragma unroll
;             for (int jj = 0; jj < 4; ++jj) {
;                 float g2 = dpp_shr1(g[6][jj]), g1 = dpp_shr1(g[7][jj]), v2 = dpp_shr1(v[6][jj]), v1 = dpp_shr1(v[7][jj]);
; #pragma unroll
;                 for (int e = 0; e < 8; ++e) { const float g0 = g[e][jj], v0 = v[e][jj];
;                     const float cg = bg[jj] + wg0[jj] * g2 + wg1[jj] * g1 + wg2[jj] * g0, cv = bv[jj] + wv0[jj] * v2 + wv1[jj] * v1 + wv2[jj] * v0;
;                     g[e][jj] = silu_fast(cg) * cv; g2 = g1; g1 = g0; v2 = v1; v1 = v0; } }
; #pragma unroll
;             for (int e = 0; e < 8; ++e) { v2u w; w.x = pk2(g[e][0], g[e][1]); w.y = pk2(g[e][2], g[e][3]); *(v2u*)(ACT + (size_t)(tok0 + e) * FFH + cc) = w; }
	v_or_b32_sdwa v74, v76, v74 dst_sel:DWORD dst_unused:UNUSED_PAD src0_sel:DWORD src1_sel:WORD_1
	v_mul_f32_e32 v110, 0xbfb8aa3b, v102
	v_exp_f32_e32 v129, v110
	v_pk_fma_f32 v[110:111], v[208:209], v[108:109], v[116:117]
	v_or_b32_e32 v76, 5, v156
	v_pk_fma_f32 v[110:111], v[192:193], v[120:121], v[110:111]
	v_or_b32_sdwa v75, v77, v75 dst_sel:DWORD dst_unused:UNUSED_PAD src0_sel:DWORD src1_sel:WORD_1
	v_mad_i64_i32 v[76:77], s[34:35], v76, s60, v[94:95]
	v_pk_fma_f32 v[110:111], v[160:161], v[124:125], v[110:111]
	v_lshl_add_u64 v[76:77], v[76:77], 0, v[98:99]
	v_mul_f32_e32 v157, 0xbfb8aa3b, v110
	v_exp_f32_e32 v157, v157
	global_store_dwordx2 v[76:77], v[74:75], off
	v_add_f32_e32 v74, 1.0, v129
	v_mul_f32_e32 v129, 0xbfb8aa3b, v103
	v_exp_f32_e32 v129, v129
	v_add_f32_e32 v75, 1.0, v157
	v_rcp_f32_e32 v176, v75
	v_rcp_f32_e32 v74, v74
	v_add_f32_e32 v75, 1.0, v129
	v_mul_f32_e32 v129, 0xbfb8aa3b, v111
	v_rcp_f32_e32 v75, v75
	v_exp_f32_e32 v129, v129
	v_pk_fma_f32 v[108:109], v[192:193], v[108:109], v[116:117]
	v_pk_mul_f32 v[74:75], v[102:103], v[74:75]
	v_add_f32_e32 v102, 1.0, v129
	v_rcp_f32_e32 v177, v102
	v_pk_fma_f32 v[102:103], v[196:197], v[96:97], v[104:105]
	v_pk_mul_f32 v[74:75], v[178:179], v[74:75]
	v_pk_fma_f32 v[102:103], v[78:79], v[112:113], v[102:103]
	v_pk_mul_f32 v[110:111], v[110:111], v[176:177]
	v_pk_fma_f32 v[102:103], v[132:133], v[100:101], v[102:103]
	v_pk_fma_f32 v[108:109], v[160:161], v[120:121], v[108:109]
	v_pk_mul_f32 v[102:103], v[102:103], v[110:111]
	s_nop 0
	v_and_b32_sdwa v110, v75, v234 dst_sel:DWORD dst_unused:UNUSED_PAD src0_sel:WORD_1 src1_sel:DWORD
	s_nop 1
	v_pk_fma_f32 v[108:109], v[170:171], v[124:125], v[108:109]
	v_add3_u32 v75, v75, v110, s59
	v_and_b32_sdwa v110, v103, v234 dst_sel:DWORD dst_unused:UNUSED_PAD src0_sel:WORD_1 src1_sel:DWORD
	s_nop 0
	v_mul_f32_e32 v116, 0xbfb8aa3b, v108
	v_add3_u32 v103, v103, v110, s59
	s_nop 0
	v_exp_f32_e32 v116, v116
	v_and_b32_e32 v103, 0xffff0000, v103
	v_cvt_pk_bf16_f32 v102, v74, v102
	v_or_b32_e32 v74, 6, v156
	v_pk_fma_f32 v[110:111], v[194:195], v[198:199], v[200:201]
	v_or_b32_sdwa v103, v103, v75 dst_sel:DWORD dst_unused:UNUSED_PAD src0_sel:DWORD src1_sel:WORD_1
	v_mad_i64_i32 v[74:75], s[34:35], v74, s60, v[94:95]
	v_pk_fma_f32 v[110:111], v[162:163], v[204:205], v[110:111]
	v_lshl_add_u64 v[74:75], v[74:75], 0, v[98:99]
	v_pk_fma_f32 v[110:111], v[168:169], v[206:207], v[110:111]
	global_store_dwordx2 v[74:75], v[102:103], off
	v_mul_f32_e32 v129, 0xbfb8aa3b, v110
	v_add_f32_e32 v103, 1.0, v116
	v_mul_f32_e32 v116, 0xbfb8aa3b, v111
	v_exp_f32_e32 v129, v129
	v_exp_f32_e32 v117, v116
	v_rcp_f32_e32 v116, v103
	v_mul_f32_e32 v106, 0xbfb8aa3b, v109
	v_add_f32_e32 v102, 1.0, v129
	v_add_f32_e32 v103, 1.0, v117
	v_rcp_f32_e32 v102, v102
	v_rcp_f32_e32 v103, v103
	v_exp_f32_e32 v106, v106
	v_pk_fma_f32 v[78:79], v[78:79], v[96:97], v[104:105]
	v_pk_mul_f32 v[102:103], v[110:111], v[102:103]
	s_nop 0
	v_pk_mul_f32 v[92:93], v[92:93], v[102:103]
	v_add_f32_e32 v102, 1.0, v106
	v_rcp_f32_e32 v117, v102
	v_pk_fma_f32 v[78:79], v[132:133], v[112:113], v[78:79]
	v_pk_mul_f32 v[96:97], v[108:109], v[116:117]
	v_pk_fma_f32 v[78:79], v[136:137], v[100:101], v[78:79]
	s_nop 0
	v_pk_mul_f32 v[78:79], v[78:79], v[96:97]
	s_nop 7
	s_nop 1
	v_cvt_pk_bf16_f32 v92, v92, v78
	v_or_b32_e32 v78, 7, v156
	v_cvt_pk_bf16_f32 v93, v93, v79
	v_mad_i64_i32 v[78:79], s[34:35], v78, s60, v[94:95]
	v_lshl_add_u64 v[78:79], v[78:79], 0, v[98:99]
	global_store_dwordx2 v[78:79], v[92:93], off
	v_mov_b32_e32 v92, v66
	v_mov_b32_e32 v93, v68
	v_pk_mul_f32 v[124:125], v[92:93], v[172:173]
	v_mov_b32_e32 v92, v54
	v_mov_b32_e32 v93, v56
	v_mov_b32_e32 v56, v55
	v_mov_b32_e32 v54, v62
	v_mov_b32_e32 v55, v64
	v_pk_mul_f32 v[116:117], v[54:55], v[70:71]
	v_mov_b32_e32 v54, v50
	v_mov_b32_e32 v55, v52
	v_mov_b32_e32 v52, v51
	v_mov_b32_e32 v50, v46
	v_mov_b32_e32 v51, v48
	v_pk_mul_f32 v[96:97], v[50:51], v[174:175]
	v_mov_b32_e32 v50, v38
	v_mov_b32_e32 v51, v40
	v_mov_b32_e32 v40, v39
	v_mov_b32_e32 v38, v42
	v_mov_b32_e32 v39, v44
	v_mov_b32_e32 v68, v67
	v_mov_b32_e32 v64, v63
	v_mov_b32_e32 v48, v47
	v_pk_mul_f32 v[100:101], v[38:39], v[60:61]
	v_mov_b32_e32 v38, v34
	v_mov_b32_e32 v39, v36
	v_mov_b32_e32 v44, v43
	v_mov_b32_e32 v36, v35
	v_pk_mul_f32 v[122:123], v[92:93], v[172:173]
	v_pk_mul_f32 v[132:133], v[68:69], v[172:173]
	v_pk_mul_f32 v[112:113], v[54:55], v[70:71]
	v_pk_mul_f32 v[114:115], v[64:65], v[70:71]
	v_pk_mul_f32 v[118:119], v[52:53], v[70:71]
	v_pk_mul_f32 v[70:71], v[50:51], v[174:175]
	v_pk_mul_f32 v[98:99], v[48:49], v[174:175]
	v_pk_mul_f32 v[68:69], v[40:41], v[174:175]
	v_pk_mul_f32 v[92:93], v[38:39], v[60:61]
	v_pk_mul_f32 v[102:103], v[44:45], v[60:61]
	v_pk_mul_f32 v[94:95], v[36:37], v[60:61]
	v_pk_mul_f32 v[120:121], v[56:57], v[172:173]
	v_mov_b64_e32 v[38:39], 0x408
	v_mov_b64_e32 v[40:41], 0x508
	v_mov_b64_e32 v[34:35], 0x608
	v_mov_b64_e32 v[36:37], 0x708
	v_mov_b64_e32 v[48:49], v[100:101]
	v_mov_b64_e32 v[46:47], v[102:103]
	v_mov_b64_e32 v[44:45], v[92:93]
	v_mov_b64_e32 v[42:43], v[94:95]
	v_mov_b64_e32 v[56:57], v[96:97]
	v_mov_b64_e32 v[54:55], v[98:99]
	v_mov_b64_e32 v[52:53], v[70:71]
	v_mov_b64_e32 v[50:51], v[68:69]
	s_and_saveexec_b64 s[34:35], vcc
	s_cbranch_execz .LBB0_5596
	v_cmp_eq_u32_e32 vcc, 0, v167
	s_mov_b64 s[36:37], 0
	v_mov_b64_e32 v[38:39], 0x408
	v_mov_b64_e32 v[40:41], 0x508
	v_mov_b64_e32 v[34:35], 0x608
	v_mov_b64_e32 v[36:37], 0x708
	s_and_saveexec_b64 s[38:39], vcc
	s_mov_b64 s[36:37], exec
	v_mov_b64_e32 v[38:39], 8
	v_mov_b64_e32 v[40:41], 0x108
	v_mov_b64_e32 v[34:35], 0x208
	v_mov_b64_e32 v[36:37], 0x308
	s_or_b64 exec, exec, s[38:39]
	s_orn2_b64 s[36:37], s[36:37], exec
	v_mov_b64_e32 v[48:49], v[116:117]
	v_mov_b64_e32 v[46:47], v[114:115]
	v_mov_b64_e32 v[44:45], v[112:113]
	v_mov_b64_e32 v[42:43], v[118:119]
	v_mov_b64_e32 v[56:57], v[124:125]
	v_mov_b64_e32 v[54:55], v[132:133]
	v_mov_b64_e32 v[52:53], v[122:123]
	v_mov_b64_e32 v[50:51], v[120:121]
; __device__ __forceinline__ unsigned pk2(float lo, float hi) { return f2bf(lo) | (f2bf(hi) << 16); }
;     __device__ __forceinline__ void operator()(const f32x4 (&acc)[2][2][4][2], const pg8::Unit& u, int wr, int wc, int fr, int fq) const {
;     ...
;             if (fr == 0) {
; #pragma unroll
;                 for (int q = 0; q < 2; ++q) { v2u a, b; a.x = pk2(g[q][0], g[q][1]); a.y = pk2(g[q][2], g[q][3]); b.x = pk2(v[q][0], v[q][1]); b.y = pk2(v[q][2], v[q][3]);
;                     *(v2u*)(hb + (size_t)q * 256 + 4 * n) = a; *(v2u*)(hb + (size_t)q * 256 + 128 + 4 * n) = b; } }
;             if (fr == 15) {
; #pragma unroll
;                 for (int q = 0; q < 2; ++q) { v2u a, b; a.x = pk2(g[6 + q][0], g[6 + q][1]); a.y = pk2(g[6 + q][2], g[6 + q][3]); b.x = pk2(v[6 + q][0], v[6 + q][1]); b.y = pk2(v[6 + q][2], v[6 + q][3]);
;                     *(v2u*)(hb + (size_t)(2 + q) * 256 + 4 * n) = a; *(v2u*)(hb + (size_t)(2 + q) * 256 + 128 + 4 * n) = b; } }
.LBB0_5596:
	s_or_b64 exec, exec, s[34:35]
	s_and_saveexec_b64 s[34:35], s[36:37]
	s_cbranch_execz .LBB0_5579
	s_nop 7
	s_nop 1
	v_cvt_pk_bf16_f32 v55, v57, v55
	v_cvt_pk_bf16_f32 v54, v56, v54
	s_nop 7
	s_nop 1
	v_lshl_add_u64 v[38:39], v[130:131], 0, v[38:39]
	v_cvt_pk_bf16_f32 v51, v53, v51
	v_cvt_pk_bf16_f32 v50, v52, v50
	global_store_dwordx2 v[38:39], v[54:55], off
	v_lshl_add_u64 v[38:39], v[130:131], 0, v[40:41]
	global_store_dwordx2 v[38:39], v[50:51], off
	v_and_b32_sdwa v39, v48, v234 dst_sel:DWORD dst_unused:UNUSED_PAD src0_sel:WORD_1 src1_sel:DWORD
	v_add3_u32 v40, v48, v39, s59
	s_nop 0
	v_and_b32_sdwa v41, v46, v234 dst_sel:DWORD dst_unused:UNUSED_PAD src0_sel:WORD_1 src1_sel:DWORD
	s_nop 1
	v_add3_u32 v41, v46, v41, s59
	s_nop 1
	v_and_b32_e32 v41, 0xffff0000, v41
	v_cvt_pk_bf16_f32 v39, v49, v47
	v_or_b32_sdwa v38, v41, v40 dst_sel:DWORD dst_unused:UNUSED_PAD src0_sel:DWORD src1_sel:WORD_1
	v_and_b32_sdwa v40, v45, v234 dst_sel:DWORD dst_unused:UNUSED_PAD src0_sel:WORD_1 src1_sel:DWORD
	v_and_b32_sdwa v41, v44, v234 dst_sel:DWORD dst_unused:UNUSED_PAD src0_sel:WORD_1 src1_sel:DWORD
	v_add3_u32 v44, v44, v41, s59
	v_add3_u32 v40, v45, v40, s59
	v_and_b32_sdwa v41, v43, v234 dst_sel:DWORD dst_unused:UNUSED_PAD src0_sel:WORD_1 src1_sel:DWORD
	v_and_b32_sdwa v45, v42, v234 dst_sel:DWORD dst_unused:UNUSED_PAD src0_sel:WORD_1 src1_sel:DWORD
	v_add3_u32 v41, v43, v41, s59
	v_add3_u32 v42, v42, v45, s59
	v_and_b32_e32 v41, 0xffff0000, v41
	v_and_b32_e32 v42, 0xffff0000, v42
	v_lshl_add_u64 v[34:35], v[130:131], 0, v[34:35]
	v_or_b32_sdwa v41, v41, v40 dst_sel:DWORD dst_unused:UNUSED_PAD src0_sel:DWORD src1_sel:WORD_1
	v_or_b32_sdwa v40, v42, v44 dst_sel:DWORD dst_unused:UNUSED_PAD src0_sel:DWORD src1_sel:WORD_1
	global_store_dwordx2 v[34:35], v[38:39], off
	v_lshl_add_u64 v[34:35], v[130:131], 0, v[36:37]
	global_store_dwordx2 v[34:35], v[40:41], off
	s_branch .LBB0_5579
